# K-loops: first 2 MFMAs of each compute segment issued before the pre-MFMA barrier (prio 0) + attention/SwiGLU epilogues
# baseline (speedup 1.0000x reference)
; #define PG8_STAGE(bufoff, gbase, voff) do { _Pragma("unroll") for (int _i = 0; _i < 2; ++_i) \
;         __builtin_amdgcn_global_load_lds((const unsigned*)((const char*)(gbase) + (voff)[_i]), (PG8_LAS unsigned*)(lds + (bufoff) + ldsw + _i * 8192), 16, 0, 0); } while (0)
; #define PG8_LDA(dst, b, h) do { _Pragma("unroll") for (int m = 0; m < 4; ++m) _Pragma("unroll") for (int k = 0; k < 2; ++k) dst[m][k] = *(const PG8_LAS bf16x8*)(lds + PG8_SA(b, h) + aoff + m * 2048 + k * 1024); } while (0)
; #define PG8_LDB(dst, b, h) do { _Pragma("unroll") for (int n = 0; n < 2; ++n) _Pragma("unroll") for (int k = 0; k < 2; ++k) dst[n][k] = *(const PG8_LAS bf16x8*)(lds + PG8_SB(b, h) + boff + n * 2048 + k * 1024); } while (0)
; #define PG8_MMA(ai, bj, At, Bt) do { __builtin_amdgcn_s_setprio(1); _Pragma("unroll") for (int m = 0; m < 4; ++m) _Pragma("unroll") for (int n = 0; n < 2; ++n) _Pragma("unroll") for (int k = 0; k < 2; ++k) \
;         acc[ai][bj][m][n] = __builtin_amdgcn_mfma_f32_16x16x32_bf16(Bt[n][k], At[m][k], acc[ai][bj][m][n], 0, 0, 0); __builtin_amdgcn_s_setprio(0); } while (0)
; #define PG8_WAIT_V(n) asm volatile("s_waitcnt vmcnt(" #n ")" ::: "memory")
; #define PG8_WAIT_L(n) asm volatile("s_waitcnt lgkmcnt(" #n ")" ::: "memory")
; #define PG8_BAR __builtin_amdgcn_s_barrier()
; #define PG8_SCHED __builtin_amdgcn_sched_barrier(0)
; template <class Epi, class Sched, bool ALIGN_EPI = false, bool SP2 = false, bool ABLK = false, bool BBLK = false>
; __device__ __forceinline__ void gemm_phase(PG8_LAS unsigned char* lds, const Gemm g, const Sched& S, const Epi& E) {
;     ...
;             PG8_LDB(B0, 0, 0); PG8_LDB(B1, 0, 1); PG8_SCHED; PG8_LDA(At, 0, 0); PG8_STAGE(PG8_SA(1, 1), a1 + hstepA, voffA);
;             PG8_WAIT_V(8); PG8_WAIT_L(0); PG8_BAR; PG8_MMA(0, 0, At, B0); PG8_MMA(0, 1, At, B1); PG8_BAR; PG8_SCHED;
;             PG8_LDA(At, 0, 1); PG8_STAGE(PG8_SB(0, 0), b2, voffB); PG8_STAGE(PG8_SB(0, 1), b2 + hstepB, voffB); PG8_STAGE(PG8_SA(0, 0), a2, voffA);
;             PG8_WAIT_V(8); PG8_WAIT_L(0); PG8_BAR; PG8_MMA(1, 0, At, B0); PG8_MMA(1, 1, At, B1); PG8_BAR; PG8_SCHED;
.LBB0_216:
	s_add_u32 s24, s22, 0x4000
	s_addc_u32 s25, s23, 0
	s_cmp_eq_u32 s81, 28
	s_cselect_b32 s28, s65, s24
	s_cselect_b32 s29, s15, s25
	s_cselect_b32 s26, s68, s72
	s_cselect_b32 s27, s13, s73
	s_add_u32 s24, s28, 0x8000
	s_addc_u32 s25, s29, 0
	s_add_i32 s75, 0, 0x10000
	v_add_u32_e32 v142, s75, v145
	s_add_i32 s80, 0, 0x14000
	ds_read_b128 v[148:151], v142
	ds_read_b128 v[152:155], v142 offset:1024
	ds_read_b128 v[156:159], v142 offset:2048
	ds_read_b128 v[160:163], v142 offset:3072
	v_add_u32_e32 v142, s80, v145
	ds_read_b128 v[164:167], v142
	ds_read_b128 v[168:171], v142 offset:1024
	ds_read_b128 v[172:175], v142 offset:2048
	ds_read_b128 v[176:179], v142 offset:3072
	v_lshl_add_u64 v[142:143], s[22:23], 0, v[138:139]
	s_add_i32 m0, s43, 0xc000
	ds_read_b128 v[180:183], v146
	ds_read_b128 v[196:199], v146 offset:1024
	ds_read_b128 v[200:203], v146 offset:2048
	ds_read_b128 v[204:207], v146 offset:3072
	ds_read_b128 v[208:211], v146 offset:4096
	ds_read_b128 v[212:215], v146 offset:5120
	ds_read_b128 v[216:219], v146 offset:6144
	ds_read_b128 v[220:223], v146 offset:7168
	global_load_lds_dwordx4 v[142:143], off
	v_lshl_add_u64 v[142:143], s[22:23], 0, v[140:141]
	s_add_i32 m0, s43, 0xe000
	s_nop 0
	global_load_lds_dwordx4 v[142:143], off
	s_waitcnt vmcnt(8)
	s_waitcnt lgkmcnt(0)
	v_mfma_f32_16x16x32_bf16 v[126:129], v[148:151], v[180:183], v[126:129]
	v_mfma_f32_16x16x32_bf16 v[118:121], v[156:159], v[180:183], v[118:121]
	s_barrier
	s_setprio 1
	s_waitcnt lgkmcnt(0)
	v_mfma_f32_16x16x32_bf16 v[110:113], v[148:151], v[200:203], v[110:113]
	v_mfma_f32_16x16x32_bf16 v[102:105], v[156:159], v[200:203], v[102:105]
	v_mfma_f32_16x16x32_bf16 v[94:97], v[148:151], v[208:211], v[94:97]
	v_mfma_f32_16x16x32_bf16 v[86:89], v[156:159], v[208:211], v[86:89]
	v_mfma_f32_16x16x32_bf16 v[78:81], v[148:151], v[216:219], v[78:81]
	v_mfma_f32_16x16x32_bf16 v[70:73], v[156:159], v[216:219], v[70:73]
	v_mfma_f32_16x16x32_bf16 v[126:129], v[152:155], v[196:199], v[126:129]
	v_mfma_f32_16x16x32_bf16 v[118:121], v[160:163], v[196:199], v[118:121]
	v_mfma_f32_16x16x32_bf16 v[110:113], v[152:155], v[204:207], v[110:113]
	v_mfma_f32_16x16x32_bf16 v[102:105], v[160:163], v[204:207], v[102:105]
	v_mfma_f32_16x16x32_bf16 v[94:97], v[152:155], v[212:215], v[94:97]
	v_mfma_f32_16x16x32_bf16 v[86:89], v[160:163], v[212:215], v[86:89]
	v_mfma_f32_16x16x32_bf16 v[78:81], v[152:155], v[220:223], v[78:81]
	v_mfma_f32_16x16x32_bf16 v[70:73], v[160:163], v[220:223], v[70:73]
	s_setprio 0
	s_setprio 1
	v_mfma_f32_16x16x32_bf16 v[122:125], v[164:167], v[180:183], v[122:125]
	v_mfma_f32_16x16x32_bf16 v[114:117], v[172:175], v[180:183], v[114:117]
	v_mfma_f32_16x16x32_bf16 v[106:109], v[164:167], v[200:203], v[106:109]
	v_mfma_f32_16x16x32_bf16 v[98:101], v[172:175], v[200:203], v[98:101]
	v_mfma_f32_16x16x32_bf16 v[90:93], v[164:167], v[208:211], v[90:93]
	v_mfma_f32_16x16x32_bf16 v[82:85], v[172:175], v[208:211], v[82:85]
	v_mfma_f32_16x16x32_bf16 v[74:77], v[164:167], v[216:219], v[74:77]
	v_mfma_f32_16x16x32_bf16 v[66:69], v[172:175], v[216:219], v[66:69]
	v_mfma_f32_16x16x32_bf16 v[122:125], v[168:171], v[196:199], v[122:125]
	v_mfma_f32_16x16x32_bf16 v[114:117], v[176:179], v[196:199], v[114:117]
	v_mfma_f32_16x16x32_bf16 v[106:109], v[168:171], v[204:207], v[106:109]
	v_mfma_f32_16x16x32_bf16 v[98:101], v[176:179], v[204:207], v[98:101]
	v_mfma_f32_16x16x32_bf16 v[90:93], v[168:171], v[212:215], v[90:93]
	v_mfma_f32_16x16x32_bf16 v[82:85], v[176:179], v[212:215], v[82:85]
	v_mfma_f32_16x16x32_bf16 v[74:77], v[168:171], v[220:223], v[74:77]
	v_mfma_f32_16x16x32_bf16 v[66:69], v[176:179], v[220:223], v[66:69]
	s_setprio 0
	s_barrier
	s_add_i32 s75, s75, s41
	v_lshl_add_u64 v[142:143], s[26:27], 0, v[134:135]
	s_mov_b32 m0, s75
	ds_read_b128 v[180:183], v146 offset:16384
	ds_read_b128 v[196:199], v146 offset:17408
	ds_read_b128 v[200:203], v146 offset:18432
	ds_read_b128 v[204:207], v146 offset:19456
	ds_read_b128 v[208:211], v146 offset:20480
	ds_read_b128 v[212:215], v146 offset:21504
	ds_read_b128 v[216:219], v146 offset:22528
	ds_read_b128 v[220:223], v146 offset:23552
	global_load_lds_dwordx4 v[142:143], off
	s_add_i32 m0, s75, 0x2000
	s_add_u32 s82, s26, 0x4000
	v_lshl_add_u64 v[142:143], s[26:27], 0, v[130:131]
	s_addc_u32 s83, s27, 0
	s_add_i32 s75, s80, s41
	global_load_lds_dwordx4 v[142:143], off
	v_lshl_add_u64 v[142:143], s[82:83], 0, v[134:135]
	s_mov_b32 m0, s75
	s_nop 0
	global_load_lds_dwordx4 v[142:143], off
	v_lshl_add_u64 v[142:143], s[82:83], 0, v[130:131]
	s_add_i32 m0, s75, 0x2000
	s_nop 0
	global_load_lds_dwordx4 v[142:143], off
	v_lshl_add_u64 v[142:143], s[28:29], 0, v[136:137]
	s_mov_b32 m0, s43
	s_nop 0
	global_load_lds_dwordx4 v[142:143], off
	v_lshl_add_u64 v[142:143], s[28:29], 0, v[132:133]
	s_mov_b32 m0, s44
	s_nop 0
	global_load_lds_dwordx4 v[142:143], off
	s_waitcnt vmcnt(8)
	s_waitcnt lgkmcnt(0)
	v_mfma_f32_16x16x32_bf16 v[62:65], v[148:151], v[180:183], v[62:65]
	v_mfma_f32_16x16x32_bf16 v[54:57], v[156:159], v[180:183], v[54:57]
	s_barrier
; #define PG8_STAGE(bufoff, gbase, voff) do { _Pragma("unroll") for (int _i = 0; _i < 2; ++_i) \
;         __builtin_amdgcn_global_load_lds((const unsigned*)((const char*)(gbase) + (voff)[_i]), (PG8_LAS unsigned*)(lds + (bufoff) + ldsw + _i * 8192), 16, 0, 0); } while (0)
; #define PG8_LDA(dst, b, h) do { _Pragma("unroll") for (int m = 0; m < 4; ++m) _Pragma("unroll") for (int k = 0; k < 2; ++k) dst[m][k] = *(const PG8_LAS bf16x8*)(lds + PG8_SA(b, h) + aoff + m * 2048 + k * 1024); } while (0)
; #define PG8_LDB(dst, b, h) do { _Pragma("unroll") for (int n = 0; n < 2; ++n) _Pragma("unroll") for (int k = 0; k < 2; ++k) dst[n][k] = *(const PG8_LAS bf16x8*)(lds + PG8_SB(b, h) + boff + n * 2048 + k * 1024); } while (0)
; #define PG8_MMA(ai, bj, At, Bt) do { __builtin_amdgcn_s_setprio(1); _Pragma("unroll") for (int m = 0; m < 4; ++m) _Pragma("unroll") for (int n = 0; n < 2; ++n) _Pragma("unroll") for (int k = 0; k < 2; ++k) \
;         acc[ai][bj][m][n] = __builtin_amdgcn_mfma_f32_16x16x32_bf16(Bt[n][k], At[m][k], acc[ai][bj][m][n], 0, 0, 0); __builtin_amdgcn_s_setprio(0); } while (0)
; #define PG8_WAIT_V(n) asm volatile("s_waitcnt vmcnt(" #n ")" ::: "memory")
; #define PG8_WAIT_L(n) asm volatile("s_waitcnt lgkmcnt(" #n ")" ::: "memory")
; #define PG8_BAR __builtin_amdgcn_s_barrier()
; #define PG8_SCHED __builtin_amdgcn_sched_barrier(0)
; template <class Epi, class Sched, bool ALIGN_EPI = false, bool SP2 = false, bool ABLK = false, bool BBLK = false>
; __device__ __forceinline__ void gemm_phase(PG8_LAS unsigned char* lds, const Gemm g, const Sched& S, const Epi& E) {
;     ...
;             PG8_WAIT_V(8); PG8_WAIT_L(0); PG8_BAR; PG8_MMA(1, 0, At, B0); PG8_MMA(1, 1, At, B1); PG8_BAR; PG8_SCHED;
;             PG8_LDB(B0, 1, 0); PG8_LDB(B1, 1, 1); PG8_SCHED; PG8_LDA(At, 1, 0); PG8_STAGE(PG8_SA(0, 1), a2 + hstepA, voffA);
;             PG8_WAIT_V(8); PG8_WAIT_L(0); PG8_BAR; PG8_MMA(0, 0, At, B0); PG8_MMA(0, 1, At, B1); PG8_BAR; PG8_SCHED;
	s_setprio 1
	s_waitcnt lgkmcnt(0)
	v_mfma_f32_16x16x32_bf16 v[46:49], v[148:151], v[200:203], v[46:49]
	v_mfma_f32_16x16x32_bf16 v[38:41], v[156:159], v[200:203], v[38:41]
	v_mfma_f32_16x16x32_bf16 v[30:33], v[148:151], v[208:211], v[30:33]
	v_mfma_f32_16x16x32_bf16 v[22:25], v[156:159], v[208:211], v[22:25]
	v_mfma_f32_16x16x32_bf16 v[14:17], v[148:151], v[216:219], v[14:17]
	v_mfma_f32_16x16x32_bf16 v[6:9], v[156:159], v[216:219], v[6:9]
	v_mfma_f32_16x16x32_bf16 v[62:65], v[152:155], v[196:199], v[62:65]
	v_mfma_f32_16x16x32_bf16 v[54:57], v[160:163], v[196:199], v[54:57]
	v_mfma_f32_16x16x32_bf16 v[46:49], v[152:155], v[204:207], v[46:49]
	v_mfma_f32_16x16x32_bf16 v[38:41], v[160:163], v[204:207], v[38:41]
	v_mfma_f32_16x16x32_bf16 v[30:33], v[152:155], v[212:215], v[30:33]
	v_mfma_f32_16x16x32_bf16 v[22:25], v[160:163], v[212:215], v[22:25]
	v_mfma_f32_16x16x32_bf16 v[14:17], v[152:155], v[220:223], v[14:17]
	v_mfma_f32_16x16x32_bf16 v[6:9], v[160:163], v[220:223], v[6:9]
	s_setprio 0
	s_setprio 1
	v_mfma_f32_16x16x32_bf16 v[58:61], v[164:167], v[180:183], v[58:61]
	v_mfma_f32_16x16x32_bf16 v[50:53], v[172:175], v[180:183], v[50:53]
	v_mfma_f32_16x16x32_bf16 v[42:45], v[164:167], v[200:203], v[42:45]
	v_mfma_f32_16x16x32_bf16 v[34:37], v[172:175], v[200:203], v[34:37]
	v_mfma_f32_16x16x32_bf16 v[26:29], v[164:167], v[208:211], v[26:29]
	v_mfma_f32_16x16x32_bf16 v[18:21], v[172:175], v[208:211], v[18:21]
	v_mfma_f32_16x16x32_bf16 v[10:13], v[164:167], v[216:219], v[10:13]
	v_mfma_f32_16x16x32_bf16 v[2:5], v[172:175], v[216:219], v[2:5]
	v_mfma_f32_16x16x32_bf16 v[58:61], v[168:171], v[196:199], v[58:61]
	v_mfma_f32_16x16x32_bf16 v[50:53], v[176:179], v[196:199], v[50:53]
	v_mfma_f32_16x16x32_bf16 v[42:45], v[168:171], v[204:207], v[42:45]
	v_mfma_f32_16x16x32_bf16 v[34:37], v[176:179], v[204:207], v[34:37]
	v_mfma_f32_16x16x32_bf16 v[26:29], v[168:171], v[212:215], v[26:29]
	v_mfma_f32_16x16x32_bf16 v[18:21], v[176:179], v[212:215], v[18:21]
	v_mfma_f32_16x16x32_bf16 v[10:13], v[168:171], v[220:223], v[10:13]
	v_mfma_f32_16x16x32_bf16 v[2:5], v[176:179], v[220:223], v[2:5]
	s_setprio 0
	s_barrier
	s_add_i32 s75, 0, 0x18000
	v_add_u32_e32 v142, s75, v145
	s_add_i32 s80, 0, 0x1c000
	ds_read_b128 v[148:151], v142
	ds_read_b128 v[152:155], v142 offset:1024
	ds_read_b128 v[156:159], v142 offset:2048
	ds_read_b128 v[160:163], v142 offset:3072
	v_add_u32_e32 v142, s80, v145
	ds_read_b128 v[164:167], v142
	ds_read_b128 v[168:171], v142 offset:1024
	ds_read_b128 v[172:175], v142 offset:2048
	ds_read_b128 v[176:179], v142 offset:3072
	s_add_u32 s28, s28, 0x4000
	s_addc_u32 s29, s29, 0
	s_mov_b32 m0, s45
	v_lshl_add_u64 v[142:143], s[28:29], 0, v[136:137]
	ds_read_b128 v[180:183], v146 offset:32768
	ds_read_b128 v[196:199], v146 offset:33792
	ds_read_b128 v[200:203], v146 offset:34816
	ds_read_b128 v[204:207], v146 offset:35840
	ds_read_b128 v[208:211], v146 offset:36864
	ds_read_b128 v[212:215], v146 offset:37888
	ds_read_b128 v[216:219], v146 offset:38912
	ds_read_b128 v[220:223], v146 offset:39936
	global_load_lds_dwordx4 v[142:143], off
	v_lshl_add_u64 v[142:143], s[28:29], 0, v[132:133]
	s_mov_b32 m0, s46
	s_nop 0
	global_load_lds_dwordx4 v[142:143], off
	s_waitcnt vmcnt(8)
	s_waitcnt lgkmcnt(0)
	v_mfma_f32_16x16x32_bf16 v[126:129], v[148:151], v[180:183], v[126:129]
	v_mfma_f32_16x16x32_bf16 v[118:121], v[156:159], v[180:183], v[118:121]
	s_barrier
	s_setprio 1
	s_waitcnt lgkmcnt(0)
	v_mfma_f32_16x16x32_bf16 v[110:113], v[148:151], v[200:203], v[110:113]
	v_mfma_f32_16x16x32_bf16 v[102:105], v[156:159], v[200:203], v[102:105]
	v_mfma_f32_16x16x32_bf16 v[94:97], v[148:151], v[208:211], v[94:97]
	v_mfma_f32_16x16x32_bf16 v[86:89], v[156:159], v[208:211], v[86:89]
	v_mfma_f32_16x16x32_bf16 v[78:81], v[148:151], v[216:219], v[78:81]
	v_mfma_f32_16x16x32_bf16 v[70:73], v[156:159], v[216:219], v[70:73]
	v_mfma_f32_16x16x32_bf16 v[126:129], v[152:155], v[196:199], v[126:129]
	v_mfma_f32_16x16x32_bf16 v[118:121], v[160:163], v[196:199], v[118:121]
	v_mfma_f32_16x16x32_bf16 v[110:113], v[152:155], v[204:207], v[110:113]
	v_mfma_f32_16x16x32_bf16 v[102:105], v[160:163], v[204:207], v[102:105]
	v_mfma_f32_16x16x32_bf16 v[94:97], v[152:155], v[212:215], v[94:97]
	v_mfma_f32_16x16x32_bf16 v[86:89], v[160:163], v[212:215], v[86:89]
	v_mfma_f32_16x16x32_bf16 v[78:81], v[152:155], v[220:223], v[78:81]
	v_mfma_f32_16x16x32_bf16 v[70:73], v[160:163], v[220:223], v[70:73]
	s_setprio 0
	s_setprio 1
	v_mfma_f32_16x16x32_bf16 v[122:125], v[164:167], v[180:183], v[122:125]
	v_mfma_f32_16x16x32_bf16 v[114:117], v[172:175], v[180:183], v[114:117]
	v_mfma_f32_16x16x32_bf16 v[106:109], v[164:167], v[200:203], v[106:109]
	v_mfma_f32_16x16x32_bf16 v[98:101], v[172:175], v[200:203], v[98:101]
	v_mfma_f32_16x16x32_bf16 v[90:93], v[164:167], v[208:211], v[90:93]
	v_mfma_f32_16x16x32_bf16 v[82:85], v[172:175], v[208:211], v[82:85]
	v_mfma_f32_16x16x32_bf16 v[74:77], v[164:167], v[216:219], v[74:77]
	v_mfma_f32_16x16x32_bf16 v[66:69], v[172:175], v[216:219], v[66:69]
	v_mfma_f32_16x16x32_bf16 v[122:125], v[168:171], v[196:199], v[122:125]
	v_mfma_f32_16x16x32_bf16 v[114:117], v[176:179], v[196:199], v[114:117]
	v_mfma_f32_16x16x32_bf16 v[106:109], v[168:171], v[204:207], v[106:109]
	v_mfma_f32_16x16x32_bf16 v[98:101], v[176:179], v[204:207], v[98:101]
	v_mfma_f32_16x16x32_bf16 v[90:93], v[168:171], v[212:215], v[90:93]
	v_mfma_f32_16x16x32_bf16 v[82:85], v[176:179], v[212:215], v[82:85]
	v_mfma_f32_16x16x32_bf16 v[74:77], v[168:171], v[220:223], v[74:77]
	v_mfma_f32_16x16x32_bf16 v[66:69], v[176:179], v[220:223], v[66:69]
	s_setprio 0
	s_barrier
; #define PG8_STAGE(bufoff, gbase, voff) do { _Pragma("unroll") for (int _i = 0; _i < 2; ++_i) \
;         __builtin_amdgcn_global_load_lds((const unsigned*)((const char*)(gbase) + (voff)[_i]), (PG8_LAS unsigned*)(lds + (bufoff) + ldsw + _i * 8192), 16, 0, 0); } while (0)
; #define PG8_LDA(dst, b, h) do { _Pragma("unroll") for (int m = 0; m < 4; ++m) _Pragma("unroll") for (int k = 0; k < 2; ++k) dst[m][k] = *(const PG8_LAS bf16x8*)(lds + PG8_SA(b, h) + aoff + m * 2048 + k * 1024); } while (0)
; #define PG8_MMA(ai, bj, At, Bt) do { __builtin_amdgcn_s_setprio(1); _Pragma("unroll") for (int m = 0; m < 4; ++m) _Pragma("unroll") for (int n = 0; n < 2; ++n) _Pragma("unroll") for (int k = 0; k < 2; ++k) \
;         acc[ai][bj][m][n] = __builtin_amdgcn_mfma_f32_16x16x32_bf16(Bt[n][k], At[m][k], acc[ai][bj][m][n], 0, 0, 0); __builtin_amdgcn_s_setprio(0); } while (0)
; #define PG8_WAIT_V(n) asm volatile("s_waitcnt vmcnt(" #n ")" ::: "memory")
; #define PG8_WAIT_L(n) asm volatile("s_waitcnt lgkmcnt(" #n ")" ::: "memory")
; #define PG8_BAR __builtin_amdgcn_s_barrier()
; #define PG8_SCHED __builtin_amdgcn_sched_barrier(0)
; template <class Epi, class Sched, bool ALIGN_EPI = false, bool SP2 = false, bool ABLK = false, bool BBLK = false>
; __device__ __forceinline__ void gemm_phase(PG8_LAS unsigned char* lds, const Gemm g, const Sched& S, const Epi& E) {
;     ...
;         for (int t = 0; t < nt; t += 2) {
;             const bool last = (t == nt - 2);
;             const char* a1 = cA + (size_t)(t + 1) * kstepA;
;             const char* a2 = last ? nA : cA + (size_t)(t + 2) * kstepA; const char* b2 = last ? nB : cB + (size_t)(t + 2) * kstepB;
;             const char* a3 = a2 + kstepA; const char* b3 = b2 + kstepB;
;             if (last && has_next) S.a_ready(nxt);
;     ...
;             PG8_LDA(At, 1, 1); PG8_STAGE(PG8_SB(1, 0), b3, voffB); PG8_STAGE(PG8_SB(1, 1), b3 + hstepB, voffB); PG8_STAGE(PG8_SA(1, 0), a3, voffA);
;             PG8_WAIT_V(8); PG8_WAIT_L(0); PG8_BAR; PG8_MMA(1, 0, At, B0); PG8_MMA(1, 1, At, B1); PG8_BAR; PG8_SCHED;
	s_add_u32 s28, s26, 0x8000
	s_addc_u32 s29, s27, 0
	s_add_i32 s75, s75, s41
	v_lshl_add_u64 v[142:143], s[28:29], 0, v[134:135]
	s_mov_b32 m0, s75
	ds_read_b128 v[180:183], v146 offset:49152
	ds_read_b128 v[196:199], v146 offset:50176
	ds_read_b128 v[200:203], v146 offset:51200
	ds_read_b128 v[204:207], v146 offset:52224
	ds_read_b128 v[208:211], v146 offset:53248
	ds_read_b128 v[212:215], v146 offset:54272
	ds_read_b128 v[216:219], v146 offset:55296
	ds_read_b128 v[220:223], v146 offset:56320
	global_load_lds_dwordx4 v[142:143], off
	s_add_i32 m0, s75, 0x2000
	s_add_u32 s26, s26, 0xc000
	v_lshl_add_u64 v[142:143], s[28:29], 0, v[130:131]
	s_addc_u32 s27, s27, 0
	s_add_i32 s28, s80, s41
	global_load_lds_dwordx4 v[142:143], off
	v_lshl_add_u64 v[142:143], s[26:27], 0, v[134:135]
	s_mov_b32 m0, s28
	s_nop 0
	global_load_lds_dwordx4 v[142:143], off
	v_lshl_add_u64 v[142:143], s[26:27], 0, v[130:131]
	s_add_i32 m0, s28, 0x2000
	s_nop 0
	global_load_lds_dwordx4 v[142:143], off
	v_lshl_add_u64 v[142:143], s[24:25], 0, v[136:137]
	s_mov_b32 m0, s51
	s_nop 0
	global_load_lds_dwordx4 v[142:143], off
	v_lshl_add_u64 v[142:143], s[24:25], 0, v[132:133]
	s_mov_b32 m0, s53
	s_nop 0
	global_load_lds_dwordx4 v[142:143], off
	s_waitcnt vmcnt(8)
	s_waitcnt lgkmcnt(0)
	v_mfma_f32_16x16x32_bf16 v[62:65], v[148:151], v[180:183], v[62:65]
	v_mfma_f32_16x16x32_bf16 v[54:57], v[156:159], v[180:183], v[54:57]
	s_barrier
	s_setprio 1
	s_waitcnt lgkmcnt(0)
	v_mfma_f32_16x16x32_bf16 v[46:49], v[148:151], v[200:203], v[46:49]
	v_mfma_f32_16x16x32_bf16 v[38:41], v[156:159], v[200:203], v[38:41]
	v_mfma_f32_16x16x32_bf16 v[30:33], v[148:151], v[208:211], v[30:33]
	v_mfma_f32_16x16x32_bf16 v[22:25], v[156:159], v[208:211], v[22:25]
	v_mfma_f32_16x16x32_bf16 v[14:17], v[148:151], v[216:219], v[14:17]
	v_mfma_f32_16x16x32_bf16 v[6:9], v[156:159], v[216:219], v[6:9]
	v_mfma_f32_16x16x32_bf16 v[62:65], v[152:155], v[196:199], v[62:65]
	v_mfma_f32_16x16x32_bf16 v[54:57], v[160:163], v[196:199], v[54:57]
	v_mfma_f32_16x16x32_bf16 v[46:49], v[152:155], v[204:207], v[46:49]
	v_mfma_f32_16x16x32_bf16 v[38:41], v[160:163], v[204:207], v[38:41]
	v_mfma_f32_16x16x32_bf16 v[30:33], v[152:155], v[212:215], v[30:33]
	v_mfma_f32_16x16x32_bf16 v[22:25], v[160:163], v[212:215], v[22:25]
	v_mfma_f32_16x16x32_bf16 v[14:17], v[152:155], v[220:223], v[14:17]
	v_mfma_f32_16x16x32_bf16 v[6:9], v[160:163], v[220:223], v[6:9]
	s_setprio 0
	s_setprio 1
	v_mfma_f32_16x16x32_bf16 v[58:61], v[164:167], v[180:183], v[58:61]
	v_mfma_f32_16x16x32_bf16 v[50:53], v[172:175], v[180:183], v[50:53]
	v_mfma_f32_16x16x32_bf16 v[42:45], v[164:167], v[200:203], v[42:45]
	v_mfma_f32_16x16x32_bf16 v[34:37], v[172:175], v[200:203], v[34:37]
	v_mfma_f32_16x16x32_bf16 v[26:29], v[164:167], v[208:211], v[26:29]
	v_mfma_f32_16x16x32_bf16 v[18:21], v[172:175], v[208:211], v[18:21]
	v_mfma_f32_16x16x32_bf16 v[10:13], v[164:167], v[216:219], v[10:13]
	v_mfma_f32_16x16x32_bf16 v[2:5], v[172:175], v[216:219], v[2:5]
	v_mfma_f32_16x16x32_bf16 v[58:61], v[168:171], v[196:199], v[58:61]
	v_mfma_f32_16x16x32_bf16 v[50:53], v[176:179], v[196:199], v[50:53]
	v_mfma_f32_16x16x32_bf16 v[42:45], v[168:171], v[204:207], v[42:45]
	v_mfma_f32_16x16x32_bf16 v[34:37], v[176:179], v[204:207], v[34:37]
	v_mfma_f32_16x16x32_bf16 v[26:29], v[168:171], v[212:215], v[26:29]
	v_mfma_f32_16x16x32_bf16 v[18:21], v[176:179], v[212:215], v[18:21]
	v_mfma_f32_16x16x32_bf16 v[10:13], v[168:171], v[220:223], v[10:13]
	v_mfma_f32_16x16x32_bf16 v[2:5], v[176:179], v[220:223], v[2:5]
	s_setprio 0
	s_barrier
	s_add_i32 s81, s81, 2
	s_add_u32 s22, s22, 0x10000
	s_addc_u32 s23, s23, 0
	s_add_u32 s72, s72, 0x10000
	s_addc_u32 s73, s73, 0
	s_cmp_gt_u32 s81, 29
	s_cbranch_scc0 .LBB0_216
	s_and_b64 vcc, exec, s[10:11]
	s_cbranch_vccz .LBB0_219
	s_barrier

; #define PG8_STAGE(bufoff, gbase, voff) do { _Pragma("unroll") for (int _i = 0; _i < 2; ++_i) \
;         __builtin_amdgcn_global_load_lds((const unsigned*)((const char*)(gbase) + (voff)[_i]), (PG8_LAS unsigned*)(lds + (bufoff) + ldsw + _i * 8192), 16, 0, 0); } while (0)
; #define PG8_LDA(dst, b, h) do { _Pragma("unroll") for (int m = 0; m < 4; ++m) _Pragma("unroll") for (int k = 0; k < 2; ++k) dst[m][k] = *(const PG8_LAS bf16x8*)(lds + PG8_SA(b, h) + aoff + m * 2048 + k * 1024); } while (0)
; #define PG8_LDB(dst, b, h) do { _Pragma("unroll") for (int n = 0; n < 2; ++n) _Pragma("unroll") for (int k = 0; k < 2; ++k) dst[n][k] = *(const PG8_LAS bf16x8*)(lds + PG8_SB(b, h) + boff + n * 2048 + k * 1024); } while (0)
; #define PG8_MMA(ai, bj, At, Bt) do { __builtin_amdgcn_s_setprio(1); _Pragma("unroll") for (int m = 0; m < 4; ++m) _Pragma("unroll") for (int n = 0; n < 2; ++n) _Pragma("unroll") for (int k = 0; k < 2; ++k) \
;         acc[ai][bj][m][n] = __builtin_amdgcn_mfma_f32_16x16x32_bf16(Bt[n][k], At[m][k], acc[ai][bj][m][n], 0, 0, 0); __builtin_amdgcn_s_setprio(0); } while (0)
; #define PG8_WAIT_V(n) asm volatile("s_waitcnt vmcnt(" #n ")" ::: "memory")
; #define PG8_WAIT_L(n) asm volatile("s_waitcnt lgkmcnt(" #n ")" ::: "memory")
; #define PG8_BAR __builtin_amdgcn_s_barrier()
; #define PG8_SCHED __builtin_amdgcn_sched_barrier(0)
; template <class Epi, class Sched, bool ALIGN_EPI = false, bool SP2 = false, bool ABLK = false, bool BBLK = false>
; __device__ __forceinline__ void gemm_phase(PG8_LAS unsigned char* lds, const Gemm g, const Sched& S, const Epi& E) {
;     ...
;             PG8_LDB(B0, 0, 0); PG8_LDB(B1, 0, 1); PG8_SCHED; PG8_LDA(At, 0, 0); PG8_STAGE(PG8_SA(1, 1), a1 + hstepA, voffA);
;             PG8_WAIT_V(8); PG8_WAIT_L(0); PG8_BAR; PG8_MMA(0, 0, At, B0); PG8_MMA(0, 1, At, B1); PG8_BAR; PG8_SCHED;
;             PG8_LDA(At, 0, 1); PG8_STAGE(PG8_SB(0, 0), b2, voffB); PG8_STAGE(PG8_SB(0, 1), b2 + hstepB, voffB); PG8_STAGE(PG8_SA(0, 0), a2, voffA);
;             PG8_WAIT_V(8); PG8_WAIT_L(0); PG8_BAR; PG8_MMA(1, 0, At, B0); PG8_MMA(1, 1, At, B1); PG8_BAR; PG8_SCHED;
.LBB0_305:
	s_add_u32 s8, s0, 0x4000
	s_addc_u32 s9, s1, 0
	s_cmpk_eq_i32 s33, 0x54
	s_cselect_b32 s36, s24, s8
	s_cselect_b32 s37, s25, s9
	s_cselect_b32 s34, s26, s29
	s_cselect_b32 s35, s27, s31
	s_add_u32 s8, s36, 0x8000
	s_addc_u32 s9, s37, 0
	s_add_i32 s40, 0, 0x10000
	s_add_i32 s44, 0, 0x14000
	v_add_u32_e32 v142, s40, v206
	v_add_u32_e32 v158, s44, v206
	ds_read_b128 v[130:133], v142
	ds_read_b128 v[134:137], v142 offset:1024
	ds_read_b128 v[138:141], v142 offset:2048
	ds_read_b128 v[142:145], v142 offset:3072
	ds_read_b128 v[146:149], v158
	ds_read_b128 v[150:153], v158 offset:1024
	ds_read_b128 v[154:157], v158 offset:2048
	ds_read_b128 v[158:161], v158 offset:3072
	v_lshl_add_u64 v[202:203], s[0:1], 0, v[184:185]
	s_add_i32 m0, s3, 0xc000
	ds_read_b128 v[162:165], v207
	ds_read_b128 v[166:169], v207 offset:1024
	ds_read_b128 v[170:173], v207 offset:2048
	ds_read_b128 v[174:177], v207 offset:3072
	ds_read_b128 v[198:201], v207 offset:4096
	ds_read_b128 v[208:211], v207 offset:5120
	ds_read_b128 v[212:215], v207 offset:6144
	ds_read_b128 v[216:219], v207 offset:7168
	global_load_lds_dwordx4 v[202:203], off
	v_lshl_add_u64 v[202:203], s[0:1], 0, v[196:197]
	s_add_i32 m0, s3, 0xe000
	s_nop 0
	global_load_lds_dwordx4 v[202:203], off
	s_waitcnt vmcnt(8)
	s_waitcnt lgkmcnt(0)
	v_mfma_f32_16x16x32_bf16 v[30:33], v[130:133], v[162:165], v[30:33]
	v_mfma_f32_16x16x32_bf16 v[22:25], v[138:141], v[162:165], v[22:25]
	s_barrier
	s_setprio 1
	s_waitcnt lgkmcnt(0)
	v_mfma_f32_16x16x32_bf16 v[10:13], v[130:133], v[170:173], v[10:13]
	v_mfma_f32_16x16x32_bf16 v[6:9], v[138:141], v[170:173], v[6:9]
	v_mfma_f32_16x16x32_bf16 v[50:53], v[130:133], v[198:201], v[50:53]
	v_mfma_f32_16x16x32_bf16 v[54:57], v[138:141], v[198:201], v[54:57]
	v_mfma_f32_16x16x32_bf16 v[74:77], v[130:133], v[212:215], v[74:77]
	v_mfma_f32_16x16x32_bf16 v[78:81], v[138:141], v[212:215], v[78:81]
	v_mfma_f32_16x16x32_bf16 v[30:33], v[134:137], v[166:169], v[30:33]
	v_mfma_f32_16x16x32_bf16 v[22:25], v[142:145], v[166:169], v[22:25]
	v_mfma_f32_16x16x32_bf16 v[10:13], v[134:137], v[174:177], v[10:13]
	v_mfma_f32_16x16x32_bf16 v[6:9], v[142:145], v[174:177], v[6:9]
	v_mfma_f32_16x16x32_bf16 v[50:53], v[134:137], v[208:211], v[50:53]
	v_mfma_f32_16x16x32_bf16 v[54:57], v[142:145], v[208:211], v[54:57]
	v_mfma_f32_16x16x32_bf16 v[74:77], v[134:137], v[216:219], v[74:77]
	v_mfma_f32_16x16x32_bf16 v[78:81], v[142:145], v[216:219], v[78:81]
	s_setprio 0
	s_setprio 1
	v_mfma_f32_16x16x32_bf16 v[26:29], v[146:149], v[162:165], v[26:29]
	v_mfma_f32_16x16x32_bf16 v[18:21], v[154:157], v[162:165], v[18:21]
	v_mfma_f32_16x16x32_bf16 v[42:45], v[146:149], v[170:173], v[42:45]
	v_mfma_f32_16x16x32_bf16 v[46:49], v[154:157], v[170:173], v[46:49]
	v_mfma_f32_16x16x32_bf16 v[66:69], v[146:149], v[198:201], v[66:69]
	v_mfma_f32_16x16x32_bf16 v[70:73], v[154:157], v[198:201], v[70:73]
	v_mfma_f32_16x16x32_bf16 v[82:85], v[146:149], v[212:215], v[82:85]
	v_mfma_f32_16x16x32_bf16 v[86:89], v[154:157], v[212:215], v[86:89]
	v_mfma_f32_16x16x32_bf16 v[26:29], v[150:153], v[166:169], v[26:29]
	v_mfma_f32_16x16x32_bf16 v[18:21], v[158:161], v[166:169], v[18:21]
	v_mfma_f32_16x16x32_bf16 v[42:45], v[150:153], v[174:177], v[42:45]
	v_mfma_f32_16x16x32_bf16 v[46:49], v[158:161], v[174:177], v[46:49]
	v_mfma_f32_16x16x32_bf16 v[66:69], v[150:153], v[208:211], v[66:69]
	v_mfma_f32_16x16x32_bf16 v[70:73], v[158:161], v[208:211], v[70:73]
	v_mfma_f32_16x16x32_bf16 v[82:85], v[150:153], v[216:219], v[82:85]
	v_mfma_f32_16x16x32_bf16 v[86:89], v[158:161], v[216:219], v[86:89]
	s_setprio 0
	s_barrier
	s_add_i32 s40, s40, s2
	v_lshl_add_u64 v[202:203], s[34:35], 0, v[186:187]
	s_mov_b32 m0, s40
	ds_read_b128 v[162:165], v207 offset:16384
	ds_read_b128 v[166:169], v207 offset:17408
	ds_read_b128 v[170:173], v207 offset:18432
	ds_read_b128 v[174:177], v207 offset:19456
	ds_read_b128 v[198:201], v207 offset:20480
	ds_read_b128 v[208:211], v207 offset:21504
	ds_read_b128 v[212:215], v207 offset:22528
	ds_read_b128 v[216:219], v207 offset:23552
	global_load_lds_dwordx4 v[202:203], off
	s_add_i32 m0, s40, 0x2000
	s_add_u32 s40, s34, 0x4000
	v_lshl_add_u64 v[202:203], s[34:35], 0, v[182:183]
	s_addc_u32 s41, s35, 0
	s_add_i32 s44, s44, s2
	global_load_lds_dwordx4 v[202:203], off
	v_lshl_add_u64 v[202:203], s[40:41], 0, v[186:187]
	s_mov_b32 m0, s44
	s_nop 0
	global_load_lds_dwordx4 v[202:203], off
	v_lshl_add_u64 v[202:203], s[40:41], 0, v[182:183]
	s_add_i32 m0, s44, 0x2000
	s_nop 0
	global_load_lds_dwordx4 v[202:203], off
	v_lshl_add_u64 v[202:203], s[36:37], 0, v[178:179]
	s_mov_b32 m0, s3
	s_nop 0
	global_load_lds_dwordx4 v[202:203], off
	v_lshl_add_u64 v[202:203], s[36:37], 0, v[180:181]
	s_mov_b32 m0, s42
	s_nop 0
	global_load_lds_dwordx4 v[202:203], off
	s_waitcnt vmcnt(8)
	s_waitcnt lgkmcnt(0)
	v_mfma_f32_16x16x32_bf16 v[106:109], v[130:133], v[162:165], v[106:109]
	v_mfma_f32_16x16x32_bf16 v[110:113], v[138:141], v[162:165], v[110:113]
	s_barrier
; #define PG8_STAGE(bufoff, gbase, voff) do { _Pragma("unroll") for (int _i = 0; _i < 2; ++_i) \
;         __builtin_amdgcn_global_load_lds((const unsigned*)((const char*)(gbase) + (voff)[_i]), (PG8_LAS unsigned*)(lds + (bufoff) + ldsw + _i * 8192), 16, 0, 0); } while (0)
; #define PG8_LDA(dst, b, h) do { _Pragma("unroll") for (int m = 0; m < 4; ++m) _Pragma("unroll") for (int k = 0; k < 2; ++k) dst[m][k] = *(const PG8_LAS bf16x8*)(lds + PG8_SA(b, h) + aoff + m * 2048 + k * 1024); } while (0)
; #define PG8_LDB(dst, b, h) do { _Pragma("unroll") for (int n = 0; n < 2; ++n) _Pragma("unroll") for (int k = 0; k < 2; ++k) dst[n][k] = *(const PG8_LAS bf16x8*)(lds + PG8_SB(b, h) + boff + n * 2048 + k * 1024); } while (0)
; #define PG8_MMA(ai, bj, At, Bt) do { __builtin_amdgcn_s_setprio(1); _Pragma("unroll") for (int m = 0; m < 4; ++m) _Pragma("unroll") for (int n = 0; n < 2; ++n) _Pragma("unroll") for (int k = 0; k < 2; ++k) \
;         acc[ai][bj][m][n] = __builtin_amdgcn_mfma_f32_16x16x32_bf16(Bt[n][k], At[m][k], acc[ai][bj][m][n], 0, 0, 0); __builtin_amdgcn_s_setprio(0); } while (0)
; #define PG8_WAIT_V(n) asm volatile("s_waitcnt vmcnt(" #n ")" ::: "memory")
; #define PG8_WAIT_L(n) asm volatile("s_waitcnt lgkmcnt(" #n ")" ::: "memory")
; #define PG8_BAR __builtin_amdgcn_s_barrier()
; #define PG8_SCHED __builtin_amdgcn_sched_barrier(0)
; template <class Epi, class Sched, bool ALIGN_EPI = false, bool SP2 = false, bool ABLK = false, bool BBLK = false>
; __device__ __forceinline__ void gemm_phase(PG8_LAS unsigned char* lds, const Gemm g, const Sched& S, const Epi& E) {
;     ...
;             PG8_WAIT_V(8); PG8_WAIT_L(0); PG8_BAR; PG8_MMA(1, 0, At, B0); PG8_MMA(1, 1, At, B1); PG8_BAR; PG8_SCHED;
;             PG8_LDB(B0, 1, 0); PG8_LDB(B1, 1, 1); PG8_SCHED; PG8_LDA(At, 1, 0); PG8_STAGE(PG8_SA(0, 1), a2 + hstepA, voffA);
;             PG8_WAIT_V(8); PG8_WAIT_L(0); PG8_BAR; PG8_MMA(0, 0, At, B0); PG8_MMA(0, 1, At, B1); PG8_BAR; PG8_SCHED;
	s_setprio 1
	s_waitcnt lgkmcnt(0)
	v_mfma_f32_16x16x32_bf16 v[122:125], v[130:133], v[170:173], v[122:125]
	v_mfma_f32_16x16x32_bf16 v[126:129], v[138:141], v[170:173], v[126:129]
	v_mfma_f32_16x16x32_bf16 v[94:97], v[130:133], v[198:201], v[94:97]
	v_mfma_f32_16x16x32_bf16 v[90:93], v[138:141], v[198:201], v[90:93]
	v_mfma_f32_16x16x32_bf16 v[38:41], v[130:133], v[212:215], v[38:41]
	v_mfma_f32_16x16x32_bf16 v[34:37], v[138:141], v[212:215], v[34:37]
	v_mfma_f32_16x16x32_bf16 v[106:109], v[134:137], v[166:169], v[106:109]
	v_mfma_f32_16x16x32_bf16 v[110:113], v[142:145], v[166:169], v[110:113]
	v_mfma_f32_16x16x32_bf16 v[122:125], v[134:137], v[174:177], v[122:125]
	v_mfma_f32_16x16x32_bf16 v[126:129], v[142:145], v[174:177], v[126:129]
	v_mfma_f32_16x16x32_bf16 v[94:97], v[134:137], v[208:211], v[94:97]
	v_mfma_f32_16x16x32_bf16 v[90:93], v[142:145], v[208:211], v[90:93]
	v_mfma_f32_16x16x32_bf16 v[38:41], v[134:137], v[216:219], v[38:41]
	v_mfma_f32_16x16x32_bf16 v[34:37], v[142:145], v[216:219], v[34:37]
	s_setprio 0
	s_setprio 1
	v_mfma_f32_16x16x32_bf16 v[114:117], v[146:149], v[162:165], v[114:117]
	v_mfma_f32_16x16x32_bf16 v[118:121], v[154:157], v[162:165], v[118:121]
	v_mfma_f32_16x16x32_bf16 v[102:105], v[146:149], v[170:173], v[102:105]
	v_mfma_f32_16x16x32_bf16 v[98:101], v[154:157], v[170:173], v[98:101]
	v_mfma_f32_16x16x32_bf16 v[62:65], v[146:149], v[198:201], v[62:65]
	v_mfma_f32_16x16x32_bf16 v[58:61], v[154:157], v[198:201], v[58:61]
	v_mfma_f32_16x16x32_bf16 v[14:17], v[146:149], v[212:215], v[14:17]
	v_mfma_f32_16x16x32_bf16 v[2:5], v[154:157], v[212:215], v[2:5]
	v_mfma_f32_16x16x32_bf16 v[114:117], v[150:153], v[166:169], v[114:117]
	v_mfma_f32_16x16x32_bf16 v[118:121], v[158:161], v[166:169], v[118:121]
	v_mfma_f32_16x16x32_bf16 v[102:105], v[150:153], v[174:177], v[102:105]
	v_mfma_f32_16x16x32_bf16 v[98:101], v[158:161], v[174:177], v[98:101]
	v_mfma_f32_16x16x32_bf16 v[62:65], v[150:153], v[208:211], v[62:65]
	v_mfma_f32_16x16x32_bf16 v[58:61], v[158:161], v[208:211], v[58:61]
	v_mfma_f32_16x16x32_bf16 v[14:17], v[150:153], v[216:219], v[14:17]
	v_mfma_f32_16x16x32_bf16 v[2:5], v[158:161], v[216:219], v[2:5]
	s_setprio 0
	s_barrier
	s_add_i32 s40, 0, 0x18000
	s_add_i32 s41, 0, 0x1c000
	v_add_u32_e32 v142, s40, v206
	v_add_u32_e32 v158, s41, v206
	ds_read_b128 v[130:133], v142
	ds_read_b128 v[134:137], v142 offset:1024
	ds_read_b128 v[138:141], v142 offset:2048
	ds_read_b128 v[142:145], v142 offset:3072
	ds_read_b128 v[146:149], v158
	ds_read_b128 v[150:153], v158 offset:1024
	ds_read_b128 v[154:157], v158 offset:2048
	ds_read_b128 v[158:161], v158 offset:3072
	s_add_u32 s36, s36, 0x4000
	s_addc_u32 s37, s37, 0
	s_mov_b32 m0, s43
	v_lshl_add_u64 v[202:203], s[36:37], 0, v[178:179]
	ds_read_b128 v[162:165], v207 offset:32768
	ds_read_b128 v[166:169], v207 offset:33792
	ds_read_b128 v[170:173], v207 offset:34816
	ds_read_b128 v[174:177], v207 offset:35840
	ds_read_b128 v[198:201], v207 offset:36864
	ds_read_b128 v[208:211], v207 offset:37888
	ds_read_b128 v[212:215], v207 offset:38912
	ds_read_b128 v[216:219], v207 offset:39936
	global_load_lds_dwordx4 v[202:203], off
	v_lshl_add_u64 v[202:203], s[36:37], 0, v[180:181]
	s_mov_b32 m0, s53
	s_nop 0
	global_load_lds_dwordx4 v[202:203], off
	s_waitcnt vmcnt(8)
	s_waitcnt lgkmcnt(0)
	v_mfma_f32_16x16x32_bf16 v[30:33], v[130:133], v[162:165], v[30:33]
	v_mfma_f32_16x16x32_bf16 v[22:25], v[138:141], v[162:165], v[22:25]
	s_barrier
	s_setprio 1
	s_waitcnt lgkmcnt(0)
	v_mfma_f32_16x16x32_bf16 v[10:13], v[130:133], v[170:173], v[10:13]
	v_mfma_f32_16x16x32_bf16 v[6:9], v[138:141], v[170:173], v[6:9]
	v_mfma_f32_16x16x32_bf16 v[50:53], v[130:133], v[198:201], v[50:53]
	v_mfma_f32_16x16x32_bf16 v[54:57], v[138:141], v[198:201], v[54:57]
	v_mfma_f32_16x16x32_bf16 v[74:77], v[130:133], v[212:215], v[74:77]
	v_mfma_f32_16x16x32_bf16 v[78:81], v[138:141], v[212:215], v[78:81]
	v_mfma_f32_16x16x32_bf16 v[30:33], v[134:137], v[166:169], v[30:33]
	v_mfma_f32_16x16x32_bf16 v[22:25], v[142:145], v[166:169], v[22:25]
	v_mfma_f32_16x16x32_bf16 v[10:13], v[134:137], v[174:177], v[10:13]
	v_mfma_f32_16x16x32_bf16 v[6:9], v[142:145], v[174:177], v[6:9]
	v_mfma_f32_16x16x32_bf16 v[50:53], v[134:137], v[208:211], v[50:53]
	v_mfma_f32_16x16x32_bf16 v[54:57], v[142:145], v[208:211], v[54:57]
	v_mfma_f32_16x16x32_bf16 v[74:77], v[134:137], v[216:219], v[74:77]
	v_mfma_f32_16x16x32_bf16 v[78:81], v[142:145], v[216:219], v[78:81]
	s_setprio 0
	s_setprio 1
	v_mfma_f32_16x16x32_bf16 v[26:29], v[146:149], v[162:165], v[26:29]
	v_mfma_f32_16x16x32_bf16 v[18:21], v[154:157], v[162:165], v[18:21]
	v_mfma_f32_16x16x32_bf16 v[42:45], v[146:149], v[170:173], v[42:45]
	v_mfma_f32_16x16x32_bf16 v[46:49], v[154:157], v[170:173], v[46:49]
	v_mfma_f32_16x16x32_bf16 v[66:69], v[146:149], v[198:201], v[66:69]
	v_mfma_f32_16x16x32_bf16 v[70:73], v[154:157], v[198:201], v[70:73]
	v_mfma_f32_16x16x32_bf16 v[82:85], v[146:149], v[212:215], v[82:85]
	v_mfma_f32_16x16x32_bf16 v[86:89], v[154:157], v[212:215], v[86:89]
	v_mfma_f32_16x16x32_bf16 v[26:29], v[150:153], v[166:169], v[26:29]
	v_mfma_f32_16x16x32_bf16 v[18:21], v[158:161], v[166:169], v[18:21]
	v_mfma_f32_16x16x32_bf16 v[42:45], v[150:153], v[174:177], v[42:45]
	v_mfma_f32_16x16x32_bf16 v[46:49], v[158:161], v[174:177], v[46:49]
	v_mfma_f32_16x16x32_bf16 v[66:69], v[150:153], v[208:211], v[66:69]
	v_mfma_f32_16x16x32_bf16 v[70:73], v[158:161], v[208:211], v[70:73]
	v_mfma_f32_16x16x32_bf16 v[82:85], v[150:153], v[216:219], v[82:85]
	v_mfma_f32_16x16x32_bf16 v[86:89], v[158:161], v[216:219], v[86:89]
	s_setprio 0
	s_barrier
; #define PG8_STAGE(bufoff, gbase, voff) do { _Pragma("unroll") for (int _i = 0; _i < 2; ++_i) \
;         __builtin_amdgcn_global_load_lds((const unsigned*)((const char*)(gbase) + (voff)[_i]), (PG8_LAS unsigned*)(lds + (bufoff) + ldsw + _i * 8192), 16, 0, 0); } while (0)
; #define PG8_LDA(dst, b, h) do { _Pragma("unroll") for (int m = 0; m < 4; ++m) _Pragma("unroll") for (int k = 0; k < 2; ++k) dst[m][k] = *(const PG8_LAS bf16x8*)(lds + PG8_SA(b, h) + aoff + m * 2048 + k * 1024); } while (0)
; #define PG8_MMA(ai, bj, At, Bt) do { __builtin_amdgcn_s_setprio(1); _Pragma("unroll") for (int m = 0; m < 4; ++m) _Pragma("unroll") for (int n = 0; n < 2; ++n) _Pragma("unroll") for (int k = 0; k < 2; ++k) \
;         acc[ai][bj][m][n] = __builtin_amdgcn_mfma_f32_16x16x32_bf16(Bt[n][k], At[m][k], acc[ai][bj][m][n], 0, 0, 0); __builtin_amdgcn_s_setprio(0); } while (0)
; #define PG8_WAIT_V(n) asm volatile("s_waitcnt vmcnt(" #n ")" ::: "memory")
; #define PG8_WAIT_L(n) asm volatile("s_waitcnt lgkmcnt(" #n ")" ::: "memory")
; #define PG8_BAR __builtin_amdgcn_s_barrier()
; #define PG8_SCHED __builtin_amdgcn_sched_barrier(0)
; template <class Epi, class Sched, bool ALIGN_EPI = false, bool SP2 = false, bool ABLK = false, bool BBLK = false>
; __device__ __forceinline__ void gemm_phase(PG8_LAS unsigned char* lds, const Gemm g, const Sched& S, const Epi& E) {
;     ...
;         for (int t = 0; t < nt; t += 2) {
;             const bool last = (t == nt - 2);
;             const char* a1 = cA + (size_t)(t + 1) * kstepA;
;             const char* a2 = last ? nA : cA + (size_t)(t + 2) * kstepA; const char* b2 = last ? nB : cB + (size_t)(t + 2) * kstepB;
;             const char* a3 = a2 + kstepA; const char* b3 = b2 + kstepB;
;             if (last && has_next) S.a_ready(nxt);
;     ...
;             PG8_LDA(At, 1, 1); PG8_STAGE(PG8_SB(1, 0), b3, voffB); PG8_STAGE(PG8_SB(1, 1), b3 + hstepB, voffB); PG8_STAGE(PG8_SA(1, 0), a3, voffA);
;             PG8_WAIT_V(8); PG8_WAIT_L(0); PG8_BAR; PG8_MMA(1, 0, At, B0); PG8_MMA(1, 1, At, B1); PG8_BAR; PG8_SCHED;
	s_add_u32 s36, s34, 0x8000
	s_addc_u32 s37, s35, 0
	s_add_i32 s40, s40, s2
	v_lshl_add_u64 v[202:203], s[36:37], 0, v[186:187]
	s_mov_b32 m0, s40
	ds_read_b128 v[162:165], v207 offset:49152
	ds_read_b128 v[166:169], v207 offset:50176
	ds_read_b128 v[170:173], v207 offset:51200
	ds_read_b128 v[174:177], v207 offset:52224
	ds_read_b128 v[198:201], v207 offset:53248
	ds_read_b128 v[208:211], v207 offset:54272
	ds_read_b128 v[212:215], v207 offset:55296
	ds_read_b128 v[216:219], v207 offset:56320
	global_load_lds_dwordx4 v[202:203], off
	s_add_i32 m0, s40, 0x2000
	s_add_u32 s34, s34, 0xc000
	v_lshl_add_u64 v[202:203], s[36:37], 0, v[182:183]
	s_addc_u32 s35, s35, 0
	s_add_i32 s36, s41, s2
	global_load_lds_dwordx4 v[202:203], off
	v_lshl_add_u64 v[202:203], s[34:35], 0, v[186:187]
	s_mov_b32 m0, s36
	s_nop 0
	global_load_lds_dwordx4 v[202:203], off
	v_lshl_add_u64 v[202:203], s[34:35], 0, v[182:183]
	s_add_i32 m0, s36, 0x2000
	s_nop 0
	global_load_lds_dwordx4 v[202:203], off
	v_lshl_add_u64 v[202:203], s[8:9], 0, v[178:179]
	s_mov_b32 m0, s92
	s_nop 0
	global_load_lds_dwordx4 v[202:203], off
	v_lshl_add_u64 v[202:203], s[8:9], 0, v[180:181]
	s_mov_b32 m0, s93
	s_nop 0
	global_load_lds_dwordx4 v[202:203], off
	s_waitcnt vmcnt(8)
	s_waitcnt lgkmcnt(0)
	v_mfma_f32_16x16x32_bf16 v[106:109], v[130:133], v[162:165], v[106:109]
	v_mfma_f32_16x16x32_bf16 v[110:113], v[138:141], v[162:165], v[110:113]
	s_barrier
	s_setprio 1
	s_waitcnt lgkmcnt(0)
	v_mfma_f32_16x16x32_bf16 v[122:125], v[130:133], v[170:173], v[122:125]
	v_mfma_f32_16x16x32_bf16 v[126:129], v[138:141], v[170:173], v[126:129]
	v_mfma_f32_16x16x32_bf16 v[94:97], v[130:133], v[198:201], v[94:97]
	v_mfma_f32_16x16x32_bf16 v[90:93], v[138:141], v[198:201], v[90:93]
	v_mfma_f32_16x16x32_bf16 v[38:41], v[130:133], v[212:215], v[38:41]
	v_mfma_f32_16x16x32_bf16 v[34:37], v[138:141], v[212:215], v[34:37]
	v_mfma_f32_16x16x32_bf16 v[106:109], v[134:137], v[166:169], v[106:109]
	v_mfma_f32_16x16x32_bf16 v[110:113], v[142:145], v[166:169], v[110:113]
	v_mfma_f32_16x16x32_bf16 v[122:125], v[134:137], v[174:177], v[122:125]
	v_mfma_f32_16x16x32_bf16 v[126:129], v[142:145], v[174:177], v[126:129]
	v_mfma_f32_16x16x32_bf16 v[94:97], v[134:137], v[208:211], v[94:97]
	v_mfma_f32_16x16x32_bf16 v[90:93], v[142:145], v[208:211], v[90:93]
	v_mfma_f32_16x16x32_bf16 v[38:41], v[134:137], v[216:219], v[38:41]
	v_mfma_f32_16x16x32_bf16 v[34:37], v[142:145], v[216:219], v[34:37]
	s_setprio 0
	s_setprio 1
	v_mfma_f32_16x16x32_bf16 v[114:117], v[146:149], v[162:165], v[114:117]
	v_mfma_f32_16x16x32_bf16 v[118:121], v[154:157], v[162:165], v[118:121]
	v_mfma_f32_16x16x32_bf16 v[102:105], v[146:149], v[170:173], v[102:105]
	v_mfma_f32_16x16x32_bf16 v[98:101], v[154:157], v[170:173], v[98:101]
	v_mfma_f32_16x16x32_bf16 v[62:65], v[146:149], v[198:201], v[62:65]
	v_mfma_f32_16x16x32_bf16 v[58:61], v[154:157], v[198:201], v[58:61]
	v_mfma_f32_16x16x32_bf16 v[14:17], v[146:149], v[212:215], v[14:17]
	v_mfma_f32_16x16x32_bf16 v[2:5], v[154:157], v[212:215], v[2:5]
	v_mfma_f32_16x16x32_bf16 v[114:117], v[150:153], v[166:169], v[114:117]
	v_mfma_f32_16x16x32_bf16 v[118:121], v[158:161], v[166:169], v[118:121]
	v_mfma_f32_16x16x32_bf16 v[102:105], v[150:153], v[174:177], v[102:105]
	v_mfma_f32_16x16x32_bf16 v[98:101], v[158:161], v[174:177], v[98:101]
	v_mfma_f32_16x16x32_bf16 v[62:65], v[150:153], v[208:211], v[62:65]
	v_mfma_f32_16x16x32_bf16 v[58:61], v[158:161], v[208:211], v[58:61]
	v_mfma_f32_16x16x32_bf16 v[14:17], v[150:153], v[216:219], v[14:17]
	v_mfma_f32_16x16x32_bf16 v[2:5], v[158:161], v[216:219], v[2:5]
	s_setprio 0
	s_barrier
	s_add_i32 s33, s33, 2
	s_add_u32 s0, s0, 0x10000
	s_addc_u32 s1, s1, 0
	s_add_u32 s29, s29, 0x10000
	s_addc_u32 s31, s31, 0
	s_cmpk_gt_u32 s33, 0x55
	s_cbranch_scc0 .LBB0_305
	s_and_b64 vcc, exec, s[18:19]
	s_cbranch_vccz .LBB0_308
	s_barrier

; #define PG8_STAGE(bufoff, gbase, voff) do { _Pragma("unroll") for (int _i = 0; _i < 2; ++_i) \
;         __builtin_amdgcn_global_load_lds((const unsigned*)((const char*)(gbase) + (voff)[_i]), (PG8_LAS unsigned*)(lds + (bufoff) + ldsw + _i * 8192), 16, 0, 0); } while (0)
; #define PG8_LDA(dst, b, h) do { _Pragma("unroll") for (int m = 0; m < 4; ++m) _Pragma("unroll") for (int k = 0; k < 2; ++k) dst[m][k] = *(const PG8_LAS bf16x8*)(lds + PG8_SA(b, h) + aoff + m * 2048 + k * 1024); } while (0)
; #define PG8_LDB(dst, b, h) do { _Pragma("unroll") for (int n = 0; n < 2; ++n) _Pragma("unroll") for (int k = 0; k < 2; ++k) dst[n][k] = *(const PG8_LAS bf16x8*)(lds + PG8_SB(b, h) + boff + n * 2048 + k * 1024); } while (0)
; #define PG8_MMA(ai, bj, At, Bt) do { __builtin_amdgcn_s_setprio(1); _Pragma("unroll") for (int m = 0; m < 4; ++m) _Pragma("unroll") for (int n = 0; n < 2; ++n) _Pragma("unroll") for (int k = 0; k < 2; ++k) \
;         acc[ai][bj][m][n] = __builtin_amdgcn_mfma_f32_16x16x32_bf16(Bt[n][k], At[m][k], acc[ai][bj][m][n], 0, 0, 0); __builtin_amdgcn_s_setprio(0); } while (0)
; #define PG8_WAIT_V(n) asm volatile("s_waitcnt vmcnt(" #n ")" ::: "memory")
; #define PG8_WAIT_L(n) asm volatile("s_waitcnt lgkmcnt(" #n ")" ::: "memory")
; #define PG8_BAR __builtin_amdgcn_s_barrier()
; #define PG8_SCHED __builtin_amdgcn_sched_barrier(0)
; template <class Epi, class Sched, bool ALIGN_EPI = false, bool SP2 = false, bool ABLK = false, bool BBLK = false>
; __device__ __forceinline__ void gemm_phase(PG8_LAS unsigned char* lds, const Gemm g, const Sched& S, const Epi& E) {
;     ...
;             PG8_LDB(B0, 0, 0); PG8_LDB(B1, 0, 1); PG8_SCHED; PG8_LDA(At, 0, 0); PG8_STAGE(PG8_SA(1, 1), a1 + hstepA, voffA);
;             PG8_WAIT_V(8); PG8_WAIT_L(0); PG8_BAR; PG8_MMA(0, 0, At, B0); PG8_MMA(0, 1, At, B1); PG8_BAR; PG8_SCHED;
;             PG8_LDA(At, 0, 1); PG8_STAGE(PG8_SB(0, 0), b2, voffB); PG8_STAGE(PG8_SB(0, 1), b2 + hstepB, voffB); PG8_STAGE(PG8_SA(0, 0), a2, voffA);
;             PG8_WAIT_V(8); PG8_WAIT_L(0); PG8_BAR; PG8_MMA(1, 0, At, B0); PG8_MMA(1, 1, At, B1); PG8_BAR; PG8_SCHED;
.LBB0_367:
	s_add_u32 s8, s0, 0x4000
	s_addc_u32 s9, s1, 0
	s_cmpk_eq_i32 s33, 0x54
	s_cselect_b32 s36, s24, s8
	s_cselect_b32 s37, s25, s9
	s_cselect_b32 s34, s26, s29
	s_cselect_b32 s35, s27, s31
	s_add_u32 s8, s36, 0x8000
	s_addc_u32 s9, s37, 0
	s_add_i32 s40, 0, 0x10000
	s_add_i32 s44, 0, 0x14000
	v_add_u32_e32 v142, s40, v206
	v_add_u32_e32 v158, s44, v206
	ds_read_b128 v[26:29], v142
	ds_read_b128 v[30:33], v142 offset:1024
	ds_read_b128 v[138:141], v142 offset:2048
	ds_read_b128 v[142:145], v142 offset:3072
	ds_read_b128 v[146:149], v158
	ds_read_b128 v[150:153], v158 offset:1024
	ds_read_b128 v[154:157], v158 offset:2048
	ds_read_b128 v[158:161], v158 offset:3072
	v_lshl_add_u64 v[202:203], s[0:1], 0, v[184:185]
	s_add_i32 m0, s83, 0xc000
	ds_read_b128 v[162:165], v207
	ds_read_b128 v[166:169], v207 offset:1024
	ds_read_b128 v[170:173], v207 offset:2048
	ds_read_b128 v[174:177], v207 offset:3072
	ds_read_b128 v[198:201], v207 offset:4096
	ds_read_b128 v[208:211], v207 offset:5120
	ds_read_b128 v[212:215], v207 offset:6144
	ds_read_b128 v[216:219], v207 offset:7168
	global_load_lds_dwordx4 v[202:203], off
	v_lshl_add_u64 v[202:203], s[0:1], 0, v[196:197]
	s_add_i32 m0, s83, 0xe000
	s_nop 0
	global_load_lds_dwordx4 v[202:203], off
	s_waitcnt vmcnt(8)
	s_waitcnt lgkmcnt(0)
	v_mfma_f32_16x16x32_bf16 v[22:25], v[26:29], v[162:165], v[22:25]
	v_mfma_f32_16x16x32_bf16 v[18:21], v[138:141], v[162:165], v[18:21]
	s_barrier
	s_setprio 1
	s_waitcnt lgkmcnt(0)
	v_mfma_f32_16x16x32_bf16 v[62:65], v[26:29], v[170:173], v[62:65]
	v_mfma_f32_16x16x32_bf16 v[58:61], v[138:141], v[170:173], v[58:61]
	v_mfma_f32_16x16x32_bf16 v[54:57], v[26:29], v[198:201], v[54:57]
	v_mfma_f32_16x16x32_bf16 v[50:53], v[138:141], v[198:201], v[50:53]
	v_mfma_f32_16x16x32_bf16 v[126:129], v[26:29], v[212:215], v[126:129]
	v_mfma_f32_16x16x32_bf16 v[122:125], v[138:141], v[212:215], v[122:125]
	v_mfma_f32_16x16x32_bf16 v[22:25], v[30:33], v[166:169], v[22:25]
	v_mfma_f32_16x16x32_bf16 v[18:21], v[142:145], v[166:169], v[18:21]
	v_mfma_f32_16x16x32_bf16 v[62:65], v[30:33], v[174:177], v[62:65]
	v_mfma_f32_16x16x32_bf16 v[58:61], v[142:145], v[174:177], v[58:61]
	v_mfma_f32_16x16x32_bf16 v[54:57], v[30:33], v[208:211], v[54:57]
	v_mfma_f32_16x16x32_bf16 v[50:53], v[142:145], v[208:211], v[50:53]
	v_mfma_f32_16x16x32_bf16 v[126:129], v[30:33], v[216:219], v[126:129]
	v_mfma_f32_16x16x32_bf16 v[122:125], v[142:145], v[216:219], v[122:125]
	s_setprio 0
	s_setprio 1
	v_mfma_f32_16x16x32_bf16 v[14:17], v[146:149], v[162:165], v[14:17]
	v_mfma_f32_16x16x32_bf16 v[10:13], v[154:157], v[162:165], v[10:13]
	v_mfma_f32_16x16x32_bf16 v[6:9], v[146:149], v[170:173], v[6:9]
	v_mfma_f32_16x16x32_bf16 v[2:5], v[154:157], v[170:173], v[2:5]
	v_mfma_f32_16x16x32_bf16 v[46:49], v[146:149], v[198:201], v[46:49]
	v_mfma_f32_16x16x32_bf16 v[42:45], v[154:157], v[198:201], v[42:45]
	v_mfma_f32_16x16x32_bf16 v[38:41], v[146:149], v[212:215], v[38:41]
	v_mfma_f32_16x16x32_bf16 v[34:37], v[154:157], v[212:215], v[34:37]
	v_mfma_f32_16x16x32_bf16 v[14:17], v[150:153], v[166:169], v[14:17]
	v_mfma_f32_16x16x32_bf16 v[10:13], v[158:161], v[166:169], v[10:13]
	v_mfma_f32_16x16x32_bf16 v[6:9], v[150:153], v[174:177], v[6:9]
	v_mfma_f32_16x16x32_bf16 v[2:5], v[158:161], v[174:177], v[2:5]
	v_mfma_f32_16x16x32_bf16 v[46:49], v[150:153], v[208:211], v[46:49]
	v_mfma_f32_16x16x32_bf16 v[42:45], v[158:161], v[208:211], v[42:45]
	v_mfma_f32_16x16x32_bf16 v[38:41], v[150:153], v[216:219], v[38:41]
	v_mfma_f32_16x16x32_bf16 v[34:37], v[158:161], v[216:219], v[34:37]
	s_setprio 0
	s_barrier
	s_add_i32 s40, s40, s81
	v_lshl_add_u64 v[202:203], s[34:35], 0, v[186:187]
	s_mov_b32 m0, s40
	ds_read_b128 v[162:165], v207 offset:16384
	ds_read_b128 v[166:169], v207 offset:17408
	ds_read_b128 v[170:173], v207 offset:18432
	ds_read_b128 v[174:177], v207 offset:19456
	ds_read_b128 v[198:201], v207 offset:20480
	ds_read_b128 v[208:211], v207 offset:21504
	ds_read_b128 v[212:215], v207 offset:22528
	ds_read_b128 v[216:219], v207 offset:23552
	global_load_lds_dwordx4 v[202:203], off
	s_add_i32 m0, s40, 0x2000
	s_add_u32 s40, s34, 0x4000
	v_lshl_add_u64 v[202:203], s[34:35], 0, v[182:183]
	s_addc_u32 s41, s35, 0
	s_add_i32 s44, s44, s81
	global_load_lds_dwordx4 v[202:203], off
	v_lshl_add_u64 v[202:203], s[40:41], 0, v[186:187]
	s_mov_b32 m0, s44
	s_nop 0
	global_load_lds_dwordx4 v[202:203], off
	v_lshl_add_u64 v[202:203], s[40:41], 0, v[182:183]
	s_add_i32 m0, s44, 0x2000
	s_nop 0
	global_load_lds_dwordx4 v[202:203], off
	v_lshl_add_u64 v[202:203], s[36:37], 0, v[178:179]
	s_mov_b32 m0, s83
	s_nop 0
	global_load_lds_dwordx4 v[202:203], off
	v_lshl_add_u64 v[202:203], s[36:37], 0, v[180:181]
	s_mov_b32 m0, s84
	s_nop 0
	global_load_lds_dwordx4 v[202:203], off
	s_waitcnt vmcnt(8)
	s_waitcnt lgkmcnt(0)
	v_mfma_f32_16x16x32_bf16 v[118:121], v[26:29], v[162:165], v[118:121]
	v_mfma_f32_16x16x32_bf16 v[114:117], v[138:141], v[162:165], v[114:117]
	s_barrier
; #define PG8_STAGE(bufoff, gbase, voff) do { _Pragma("unroll") for (int _i = 0; _i < 2; ++_i) \
;         __builtin_amdgcn_global_load_lds((const unsigned*)((const char*)(gbase) + (voff)[_i]), (PG8_LAS unsigned*)(lds + (bufoff) + ldsw + _i * 8192), 16, 0, 0); } while (0)
; #define PG8_LDA(dst, b, h) do { _Pragma("unroll") for (int m = 0; m < 4; ++m) _Pragma("unroll") for (int k = 0; k < 2; ++k) dst[m][k] = *(const PG8_LAS bf16x8*)(lds + PG8_SA(b, h) + aoff + m * 2048 + k * 1024); } while (0)
; #define PG8_LDB(dst, b, h) do { _Pragma("unroll") for (int n = 0; n < 2; ++n) _Pragma("unroll") for (int k = 0; k < 2; ++k) dst[n][k] = *(const PG8_LAS bf16x8*)(lds + PG8_SB(b, h) + boff + n * 2048 + k * 1024); } while (0)
; #define PG8_MMA(ai, bj, At, Bt) do { __builtin_amdgcn_s_setprio(1); _Pragma("unroll") for (int m = 0; m < 4; ++m) _Pragma("unroll") for (int n = 0; n < 2; ++n) _Pragma("unroll") for (int k = 0; k < 2; ++k) \
;         acc[ai][bj][m][n] = __builtin_amdgcn_mfma_f32_16x16x32_bf16(Bt[n][k], At[m][k], acc[ai][bj][m][n], 0, 0, 0); __builtin_amdgcn_s_setprio(0); } while (0)
; #define PG8_WAIT_V(n) asm volatile("s_waitcnt vmcnt(" #n ")" ::: "memory")
; #define PG8_WAIT_L(n) asm volatile("s_waitcnt lgkmcnt(" #n ")" ::: "memory")
; #define PG8_BAR __builtin_amdgcn_s_barrier()
; #define PG8_SCHED __builtin_amdgcn_sched_barrier(0)
; template <class Epi, class Sched, bool ALIGN_EPI = false, bool SP2 = false, bool ABLK = false, bool BBLK = false>
; __device__ __forceinline__ void gemm_phase(PG8_LAS unsigned char* lds, const Gemm g, const Sched& S, const Epi& E) {
;     ...
;             PG8_WAIT_V(8); PG8_WAIT_L(0); PG8_BAR; PG8_MMA(1, 0, At, B0); PG8_MMA(1, 1, At, B1); PG8_BAR; PG8_SCHED;
;             PG8_LDB(B0, 1, 0); PG8_LDB(B1, 1, 1); PG8_SCHED; PG8_LDA(At, 1, 0); PG8_STAGE(PG8_SA(0, 1), a2 + hstepA, voffA);
;             PG8_WAIT_V(8); PG8_WAIT_L(0); PG8_BAR; PG8_MMA(0, 0, At, B0); PG8_MMA(0, 1, At, B1); PG8_BAR; PG8_SCHED;
	s_setprio 1
	s_waitcnt lgkmcnt(0)
	v_mfma_f32_16x16x32_bf16 v[134:137], v[26:29], v[170:173], v[134:137]
	v_mfma_f32_16x16x32_bf16 v[130:133], v[138:141], v[170:173], v[130:133]
	v_mfma_f32_16x16x32_bf16 v[110:113], v[26:29], v[198:201], v[110:113]
	v_mfma_f32_16x16x32_bf16 v[106:109], v[138:141], v[198:201], v[106:109]
	v_mfma_f32_16x16x32_bf16 v[26:29], v[26:29], v[212:215], v[102:105]
	v_mfma_f32_16x16x32_bf16 v[118:121], v[30:33], v[166:169], v[118:121]
	v_mfma_f32_16x16x32_bf16 v[114:117], v[142:145], v[166:169], v[114:117]
	v_mfma_f32_16x16x32_bf16 v[134:137], v[30:33], v[174:177], v[134:137]
	v_mfma_f32_16x16x32_bf16 v[130:133], v[142:145], v[174:177], v[130:133]
	v_mfma_f32_16x16x32_bf16 v[110:113], v[30:33], v[208:211], v[110:113]
	v_mfma_f32_16x16x32_bf16 v[106:109], v[142:145], v[208:211], v[106:109]
	v_mfma_f32_16x16x32_bf16 v[26:29], v[30:33], v[216:219], v[26:29]
	v_mfma_f32_16x16x32_bf16 v[30:33], v[138:141], v[212:215], v[98:101]
	v_mfma_f32_16x16x32_bf16 v[30:33], v[142:145], v[216:219], v[30:33]
	s_setprio 0
	s_setprio 1
	v_mfma_f32_16x16x32_bf16 v[94:97], v[146:149], v[162:165], v[94:97]
	v_mfma_f32_16x16x32_bf16 v[90:93], v[154:157], v[162:165], v[90:93]
	v_mfma_f32_16x16x32_bf16 v[74:77], v[146:149], v[170:173], v[74:77]
	v_mfma_f32_16x16x32_bf16 v[70:73], v[154:157], v[170:173], v[70:73]
	v_mfma_f32_16x16x32_bf16 v[86:89], v[146:149], v[198:201], v[86:89]
	v_mfma_f32_16x16x32_bf16 v[82:85], v[154:157], v[198:201], v[82:85]
	v_mfma_f32_16x16x32_bf16 v[78:81], v[146:149], v[212:215], v[78:81]
	v_mfma_f32_16x16x32_bf16 v[66:69], v[154:157], v[212:215], v[66:69]
	v_mfma_f32_16x16x32_bf16 v[94:97], v[150:153], v[166:169], v[94:97]
	v_mfma_f32_16x16x32_bf16 v[90:93], v[158:161], v[166:169], v[90:93]
	v_mfma_f32_16x16x32_bf16 v[74:77], v[150:153], v[174:177], v[74:77]
	v_mfma_f32_16x16x32_bf16 v[70:73], v[158:161], v[174:177], v[70:73]
	v_mfma_f32_16x16x32_bf16 v[86:89], v[150:153], v[208:211], v[86:89]
	v_mfma_f32_16x16x32_bf16 v[82:85], v[158:161], v[208:211], v[82:85]
	v_mfma_f32_16x16x32_bf16 v[78:81], v[150:153], v[216:219], v[78:81]
	v_mfma_f32_16x16x32_bf16 v[66:69], v[158:161], v[216:219], v[66:69]
	s_setprio 0
	s_barrier
	s_add_i32 s40, 0, 0x18000
	s_add_i32 s41, 0, 0x1c000
	v_add_u32_e32 v142, s40, v206
	v_add_u32_e32 v158, s41, v206
	ds_read_b128 v[98:101], v142
	ds_read_b128 v[102:105], v142 offset:1024
	ds_read_b128 v[138:141], v142 offset:2048
	ds_read_b128 v[142:145], v142 offset:3072
	ds_read_b128 v[146:149], v158
	ds_read_b128 v[150:153], v158 offset:1024
	ds_read_b128 v[154:157], v158 offset:2048
	ds_read_b128 v[158:161], v158 offset:3072
	s_add_u32 s36, s36, 0x4000
	s_addc_u32 s37, s37, 0
	s_mov_b32 m0, s92
	v_lshl_add_u64 v[202:203], s[36:37], 0, v[178:179]
	ds_read_b128 v[162:165], v207 offset:32768
	ds_read_b128 v[166:169], v207 offset:33792
	ds_read_b128 v[170:173], v207 offset:34816
	ds_read_b128 v[174:177], v207 offset:35840
	ds_read_b128 v[198:201], v207 offset:36864
	ds_read_b128 v[208:211], v207 offset:37888
	ds_read_b128 v[212:215], v207 offset:38912
	ds_read_b128 v[216:219], v207 offset:39936
	global_load_lds_dwordx4 v[202:203], off
	v_lshl_add_u64 v[202:203], s[36:37], 0, v[180:181]
	s_mov_b32 m0, s93
	s_nop 0
	global_load_lds_dwordx4 v[202:203], off
	s_waitcnt vmcnt(8)
	s_waitcnt lgkmcnt(0)
	v_mfma_f32_16x16x32_bf16 v[22:25], v[98:101], v[162:165], v[22:25]
	v_mfma_f32_16x16x32_bf16 v[18:21], v[138:141], v[162:165], v[18:21]
	s_barrier
	s_setprio 1
	s_waitcnt lgkmcnt(0)
	v_mfma_f32_16x16x32_bf16 v[62:65], v[98:101], v[170:173], v[62:65]
	v_mfma_f32_16x16x32_bf16 v[58:61], v[138:141], v[170:173], v[58:61]
	v_mfma_f32_16x16x32_bf16 v[54:57], v[98:101], v[198:201], v[54:57]
	v_mfma_f32_16x16x32_bf16 v[50:53], v[138:141], v[198:201], v[50:53]
	v_mfma_f32_16x16x32_bf16 v[126:129], v[98:101], v[212:215], v[126:129]
	v_mfma_f32_16x16x32_bf16 v[122:125], v[138:141], v[212:215], v[122:125]
	v_mfma_f32_16x16x32_bf16 v[22:25], v[102:105], v[166:169], v[22:25]
	v_mfma_f32_16x16x32_bf16 v[18:21], v[142:145], v[166:169], v[18:21]
	v_mfma_f32_16x16x32_bf16 v[62:65], v[102:105], v[174:177], v[62:65]
	v_mfma_f32_16x16x32_bf16 v[58:61], v[142:145], v[174:177], v[58:61]
	v_mfma_f32_16x16x32_bf16 v[54:57], v[102:105], v[208:211], v[54:57]
	v_mfma_f32_16x16x32_bf16 v[50:53], v[142:145], v[208:211], v[50:53]
	v_mfma_f32_16x16x32_bf16 v[126:129], v[102:105], v[216:219], v[126:129]
	v_mfma_f32_16x16x32_bf16 v[122:125], v[142:145], v[216:219], v[122:125]
	s_setprio 0
	s_setprio 1
	v_mfma_f32_16x16x32_bf16 v[14:17], v[146:149], v[162:165], v[14:17]
	v_mfma_f32_16x16x32_bf16 v[10:13], v[154:157], v[162:165], v[10:13]
	v_mfma_f32_16x16x32_bf16 v[6:9], v[146:149], v[170:173], v[6:9]
	v_mfma_f32_16x16x32_bf16 v[2:5], v[154:157], v[170:173], v[2:5]
	v_mfma_f32_16x16x32_bf16 v[46:49], v[146:149], v[198:201], v[46:49]
	v_mfma_f32_16x16x32_bf16 v[42:45], v[154:157], v[198:201], v[42:45]
	v_mfma_f32_16x16x32_bf16 v[38:41], v[146:149], v[212:215], v[38:41]
	v_mfma_f32_16x16x32_bf16 v[34:37], v[154:157], v[212:215], v[34:37]
	v_mfma_f32_16x16x32_bf16 v[14:17], v[150:153], v[166:169], v[14:17]
	v_mfma_f32_16x16x32_bf16 v[10:13], v[158:161], v[166:169], v[10:13]
	v_mfma_f32_16x16x32_bf16 v[6:9], v[150:153], v[174:177], v[6:9]
	v_mfma_f32_16x16x32_bf16 v[2:5], v[158:161], v[174:177], v[2:5]
	v_mfma_f32_16x16x32_bf16 v[46:49], v[150:153], v[208:211], v[46:49]
	v_mfma_f32_16x16x32_bf16 v[42:45], v[158:161], v[208:211], v[42:45]
	v_mfma_f32_16x16x32_bf16 v[38:41], v[150:153], v[216:219], v[38:41]
	v_mfma_f32_16x16x32_bf16 v[34:37], v[158:161], v[216:219], v[34:37]
	s_setprio 0
	s_barrier
; #define PG8_STAGE(bufoff, gbase, voff) do { _Pragma("unroll") for (int _i = 0; _i < 2; ++_i) \
;         __builtin_amdgcn_global_load_lds((const unsigned*)((const char*)(gbase) + (voff)[_i]), (PG8_LAS unsigned*)(lds + (bufoff) + ldsw + _i * 8192), 16, 0, 0); } while (0)
; #define PG8_LDA(dst, b, h) do { _Pragma("unroll") for (int m = 0; m < 4; ++m) _Pragma("unroll") for (int k = 0; k < 2; ++k) dst[m][k] = *(const PG8_LAS bf16x8*)(lds + PG8_SA(b, h) + aoff + m * 2048 + k * 1024); } while (0)
; #define PG8_MMA(ai, bj, At, Bt) do { __builtin_amdgcn_s_setprio(1); _Pragma("unroll") for (int m = 0; m < 4; ++m) _Pragma("unroll") for (int n = 0; n < 2; ++n) _Pragma("unroll") for (int k = 0; k < 2; ++k) \
;         acc[ai][bj][m][n] = __builtin_amdgcn_mfma_f32_16x16x32_bf16(Bt[n][k], At[m][k], acc[ai][bj][m][n], 0, 0, 0); __builtin_amdgcn_s_setprio(0); } while (0)
; #define PG8_WAIT_V(n) asm volatile("s_waitcnt vmcnt(" #n ")" ::: "memory")
; #define PG8_WAIT_L(n) asm volatile("s_waitcnt lgkmcnt(" #n ")" ::: "memory")
; #define PG8_BAR __builtin_amdgcn_s_barrier()
; #define PG8_SCHED __builtin_amdgcn_sched_barrier(0)
; template <class Epi, class Sched, bool ALIGN_EPI = false, bool SP2 = false, bool ABLK = false, bool BBLK = false>
; __device__ __forceinline__ void gemm_phase(PG8_LAS unsigned char* lds, const Gemm g, const Sched& S, const Epi& E) {
;     ...
;         for (int t = 0; t < nt; t += 2) {
;             const bool last = (t == nt - 2);
;             const char* a1 = cA + (size_t)(t + 1) * kstepA;
;             const char* a2 = last ? nA : cA + (size_t)(t + 2) * kstepA; const char* b2 = last ? nB : cB + (size_t)(t + 2) * kstepB;
;             const char* a3 = a2 + kstepA; const char* b3 = b2 + kstepB;
;             if (last && has_next) S.a_ready(nxt);
;     ...
;             PG8_LDA(At, 1, 1); PG8_STAGE(PG8_SB(1, 0), b3, voffB); PG8_STAGE(PG8_SB(1, 1), b3 + hstepB, voffB); PG8_STAGE(PG8_SA(1, 0), a3, voffA);
;             PG8_WAIT_V(8); PG8_WAIT_L(0); PG8_BAR; PG8_MMA(1, 0, At, B0); PG8_MMA(1, 1, At, B1); PG8_BAR; PG8_SCHED;
	s_add_u32 s36, s34, 0x8000
	s_addc_u32 s37, s35, 0
	s_add_i32 s40, s40, s81
	v_lshl_add_u64 v[202:203], s[36:37], 0, v[186:187]
	s_mov_b32 m0, s40
	ds_read_b128 v[162:165], v207 offset:49152
	ds_read_b128 v[166:169], v207 offset:50176
	ds_read_b128 v[170:173], v207 offset:51200
	ds_read_b128 v[174:177], v207 offset:52224
	ds_read_b128 v[198:201], v207 offset:53248
	ds_read_b128 v[208:211], v207 offset:54272
	ds_read_b128 v[212:215], v207 offset:55296
	ds_read_b128 v[216:219], v207 offset:56320
	global_load_lds_dwordx4 v[202:203], off
	s_add_i32 m0, s40, 0x2000
	s_add_u32 s34, s34, 0xc000
	v_lshl_add_u64 v[202:203], s[36:37], 0, v[182:183]
	s_addc_u32 s35, s35, 0
	s_add_i32 s36, s41, s81
	global_load_lds_dwordx4 v[202:203], off
	v_lshl_add_u64 v[202:203], s[34:35], 0, v[186:187]
	s_mov_b32 m0, s36
	s_nop 0
	global_load_lds_dwordx4 v[202:203], off
	v_lshl_add_u64 v[202:203], s[34:35], 0, v[182:183]
	s_add_i32 m0, s36, 0x2000
	s_nop 0
	global_load_lds_dwordx4 v[202:203], off
	v_lshl_add_u64 v[202:203], s[8:9], 0, v[178:179]
	s_mov_b32 m0, s22
	s_nop 0
	global_load_lds_dwordx4 v[202:203], off
	v_lshl_add_u64 v[202:203], s[8:9], 0, v[180:181]
	s_mov_b32 m0, s23
	s_nop 0
	global_load_lds_dwordx4 v[202:203], off
	s_waitcnt vmcnt(8)
	s_waitcnt lgkmcnt(0)
	v_mfma_f32_16x16x32_bf16 v[118:121], v[98:101], v[162:165], v[118:121]
	v_mfma_f32_16x16x32_bf16 v[134:137], v[98:101], v[170:173], v[134:137]
	s_barrier
	s_setprio 1
	s_waitcnt lgkmcnt(0)
	v_mfma_f32_16x16x32_bf16 v[110:113], v[98:101], v[198:201], v[110:113]
	v_mfma_f32_16x16x32_bf16 v[26:29], v[98:101], v[212:215], v[26:29]
	v_mfma_f32_16x16x32_bf16 v[118:121], v[102:105], v[166:169], v[118:121]
	v_mfma_f32_16x16x32_bf16 v[114:117], v[138:141], v[162:165], v[114:117]
	v_mfma_f32_16x16x32_bf16 v[134:137], v[102:105], v[174:177], v[134:137]
	v_mfma_f32_16x16x32_bf16 v[130:133], v[138:141], v[170:173], v[130:133]
	v_mfma_f32_16x16x32_bf16 v[110:113], v[102:105], v[208:211], v[110:113]
	v_mfma_f32_16x16x32_bf16 v[106:109], v[138:141], v[198:201], v[106:109]
	v_mfma_f32_16x16x32_bf16 v[102:105], v[102:105], v[216:219], v[26:29]
	v_mfma_f32_16x16x32_bf16 v[26:29], v[138:141], v[212:215], v[30:33]
	v_mfma_f32_16x16x32_bf16 v[114:117], v[142:145], v[166:169], v[114:117]
	v_mfma_f32_16x16x32_bf16 v[130:133], v[142:145], v[174:177], v[130:133]
	v_mfma_f32_16x16x32_bf16 v[106:109], v[142:145], v[208:211], v[106:109]
	v_mfma_f32_16x16x32_bf16 v[98:101], v[142:145], v[216:219], v[26:29]
	s_setprio 0
	s_setprio 1
	v_mfma_f32_16x16x32_bf16 v[26:29], v[146:149], v[162:165], v[94:97]
	v_mfma_f32_16x16x32_bf16 v[94:97], v[150:153], v[166:169], v[26:29]
	v_mfma_f32_16x16x32_bf16 v[26:29], v[154:157], v[162:165], v[90:93]
	v_mfma_f32_16x16x32_bf16 v[90:93], v[158:161], v[166:169], v[26:29]
	v_mfma_f32_16x16x32_bf16 v[26:29], v[146:149], v[170:173], v[74:77]
	v_mfma_f32_16x16x32_bf16 v[74:77], v[150:153], v[174:177], v[26:29]
	v_mfma_f32_16x16x32_bf16 v[26:29], v[154:157], v[170:173], v[70:73]
	v_mfma_f32_16x16x32_bf16 v[70:73], v[158:161], v[174:177], v[26:29]
	v_mfma_f32_16x16x32_bf16 v[26:29], v[146:149], v[198:201], v[86:89]
	v_mfma_f32_16x16x32_bf16 v[86:89], v[150:153], v[208:211], v[26:29]
	v_mfma_f32_16x16x32_bf16 v[26:29], v[154:157], v[198:201], v[82:85]
	v_mfma_f32_16x16x32_bf16 v[82:85], v[158:161], v[208:211], v[26:29]
	v_mfma_f32_16x16x32_bf16 v[26:29], v[146:149], v[212:215], v[78:81]
	v_mfma_f32_16x16x32_bf16 v[78:81], v[150:153], v[216:219], v[26:29]
	v_mfma_f32_16x16x32_bf16 v[26:29], v[154:157], v[212:215], v[66:69]
	v_mfma_f32_16x16x32_bf16 v[66:69], v[158:161], v[216:219], v[26:29]
	s_setprio 0
	s_barrier
	s_add_i32 s33, s33, 2
	s_add_u32 s0, s0, 0x10000
	s_addc_u32 s1, s1, 0
	s_add_u32 s29, s29, 0x10000
	s_addc_u32 s31, s31, 0
	s_cmpk_gt_u32 s33, 0x55
	s_cbranch_scc0 .LBB0_367
	s_and_b64 vcc, exec, s[18:19]
	s_cbranch_vccz .LBB0_370
	s_barrier

; #define PG8_STAGE(bufoff, gbase, voff) do { _Pragma("unroll") for (int _i = 0; _i < 2; ++_i) \
;         __builtin_amdgcn_global_load_lds((const unsigned*)((const char*)(gbase) + (voff)[_i]), (PG8_LAS unsigned*)(lds + (bufoff) + ldsw + _i * 8192), 16, 0, 0); } while (0)
; #define PG8_LDA(dst, b, h) do { _Pragma("unroll") for (int m = 0; m < 4; ++m) _Pragma("unroll") for (int k = 0; k < 2; ++k) dst[m][k] = *(const PG8_LAS bf16x8*)(lds + PG8_SA(b, h) + aoff + m * 2048 + k * 1024); } while (0)
; #define PG8_LDB(dst, b, h) do { _Pragma("unroll") for (int n = 0; n < 2; ++n) _Pragma("unroll") for (int k = 0; k < 2; ++k) dst[n][k] = *(const PG8_LAS bf16x8*)(lds + PG8_SB(b, h) + boff + n * 2048 + k * 1024); } while (0)
; #define PG8_MMA(ai, bj, At, Bt) do { __builtin_amdgcn_s_setprio(1); _Pragma("unroll") for (int m = 0; m < 4; ++m) _Pragma("unroll") for (int n = 0; n < 2; ++n) _Pragma("unroll") for (int k = 0; k < 2; ++k) \
;         acc[ai][bj][m][n] = __builtin_amdgcn_mfma_f32_16x16x32_bf16(Bt[n][k], At[m][k], acc[ai][bj][m][n], 0, 0, 0); __builtin_amdgcn_s_setprio(0); } while (0)
; #define PG8_WAIT_V(n) asm volatile("s_waitcnt vmcnt(" #n ")" ::: "memory")
; #define PG8_WAIT_L(n) asm volatile("s_waitcnt lgkmcnt(" #n ")" ::: "memory")
; #define PG8_BAR __builtin_amdgcn_s_barrier()
; #define PG8_SCHED __builtin_amdgcn_sched_barrier(0)
; template <class Epi, class Sched, bool ALIGN_EPI = false, bool SP2 = false, bool ABLK = false, bool BBLK = false>
; __device__ __forceinline__ void gemm_phase(PG8_LAS unsigned char* lds, const Gemm g, const Sched& S, const Epi& E) {
;     ...
;             PG8_LDB(B0, 0, 0); PG8_LDB(B1, 0, 1); PG8_SCHED; PG8_LDA(At, 0, 0); PG8_STAGE(PG8_SA(1, 1), a1 + hstepA, voffA);
;             PG8_WAIT_V(8); PG8_WAIT_L(0); PG8_BAR; PG8_MMA(0, 0, At, B0); PG8_MMA(0, 1, At, B1); PG8_BAR; PG8_SCHED;
;             PG8_LDA(At, 0, 1); PG8_STAGE(PG8_SB(0, 0), b2, voffB); PG8_STAGE(PG8_SB(0, 1), b2 + hstepB, voffB); PG8_STAGE(PG8_SA(0, 0), a2, voffA);
;             PG8_WAIT_V(8); PG8_WAIT_L(0); PG8_BAR; PG8_MMA(1, 0, At, B0); PG8_MMA(1, 1, At, B1); PG8_BAR; PG8_SCHED;
.LBB0_594:
	s_add_u32 s30, s0, 0x4000
	s_addc_u32 s31, s1, 0
	s_cmp_eq_u32 s41, 28
	s_cselect_b32 s36, s16, s30
	s_cselect_b32 s37, s9, s31
	s_cselect_b32 s34, s23, s29
	s_cselect_b32 s35, s21, s40
	s_add_u32 s30, s36, 0x8000
	s_addc_u32 s31, s37, 0
	s_add_i32 s60, 0, 0x10000
	s_add_i32 s75, 0, 0x14000
	v_add_u32_e32 v142, s60, v169
	v_add_u32_e32 v171, s75, v169
	ds_read_b128 v[130:133], v142
	ds_read_b128 v[134:137], v142 offset:1024
	ds_read_b128 v[138:141], v142 offset:2048
	ds_read_b128 v[142:145], v142 offset:3072
	ds_read_b128 v[160:163], v171
	ds_read_b128 v[164:167], v171 offset:1024
	ds_read_b128 v[172:175], v171 offset:2048
	ds_read_b128 v[176:179], v171 offset:3072
	v_lshl_add_u64 v[184:185], s[0:1], 0, v[156:157]
	s_add_i32 m0, s83, 0xc000
	ds_read_b128 v[180:183], v170
	ds_read_b128 v[196:199], v170 offset:1024
	ds_read_b128 v[200:203], v170 offset:2048
	ds_read_b128 v[204:207], v170 offset:3072
	ds_read_b128 v[208:211], v170 offset:4096
	ds_read_b128 v[212:215], v170 offset:5120
	ds_read_b128 v[216:219], v170 offset:6144
	ds_read_b128 v[220:223], v170 offset:7168
	global_load_lds_dwordx4 v[184:185], off
	v_lshl_add_u64 v[184:185], s[0:1], 0, v[158:159]
	s_add_i32 m0, s83, 0xe000
	s_nop 0
	global_load_lds_dwordx4 v[184:185], off
	s_waitcnt vmcnt(8)
	s_waitcnt lgkmcnt(0)
	v_mfma_f32_16x16x32_bf16 v[126:129], v[130:133], v[180:183], v[126:129]
	v_mfma_f32_16x16x32_bf16 v[122:125], v[138:141], v[180:183], v[122:125]
	s_barrier
	s_setprio 1
	s_waitcnt lgkmcnt(0)
	v_mfma_f32_16x16x32_bf16 v[110:113], v[130:133], v[200:203], v[110:113]
	v_mfma_f32_16x16x32_bf16 v[106:109], v[138:141], v[200:203], v[106:109]
	v_mfma_f32_16x16x32_bf16 v[94:97], v[130:133], v[208:211], v[94:97]
	v_mfma_f32_16x16x32_bf16 v[90:93], v[138:141], v[208:211], v[90:93]
	v_mfma_f32_16x16x32_bf16 v[78:81], v[130:133], v[216:219], v[78:81]
	v_mfma_f32_16x16x32_bf16 v[74:77], v[138:141], v[216:219], v[74:77]
	v_mfma_f32_16x16x32_bf16 v[126:129], v[134:137], v[196:199], v[126:129]
	v_mfma_f32_16x16x32_bf16 v[122:125], v[142:145], v[196:199], v[122:125]
	v_mfma_f32_16x16x32_bf16 v[110:113], v[134:137], v[204:207], v[110:113]
	v_mfma_f32_16x16x32_bf16 v[106:109], v[142:145], v[204:207], v[106:109]
	v_mfma_f32_16x16x32_bf16 v[94:97], v[134:137], v[212:215], v[94:97]
	v_mfma_f32_16x16x32_bf16 v[90:93], v[142:145], v[212:215], v[90:93]
	v_mfma_f32_16x16x32_bf16 v[78:81], v[134:137], v[220:223], v[78:81]
	v_mfma_f32_16x16x32_bf16 v[74:77], v[142:145], v[220:223], v[74:77]
	s_setprio 0
	s_setprio 1
	v_mfma_f32_16x16x32_bf16 v[118:121], v[160:163], v[180:183], v[118:121]
	v_mfma_f32_16x16x32_bf16 v[114:117], v[172:175], v[180:183], v[114:117]
	v_mfma_f32_16x16x32_bf16 v[102:105], v[160:163], v[200:203], v[102:105]
	v_mfma_f32_16x16x32_bf16 v[98:101], v[172:175], v[200:203], v[98:101]
	v_mfma_f32_16x16x32_bf16 v[86:89], v[160:163], v[208:211], v[86:89]
	v_mfma_f32_16x16x32_bf16 v[82:85], v[172:175], v[208:211], v[82:85]
	v_mfma_f32_16x16x32_bf16 v[70:73], v[160:163], v[216:219], v[70:73]
	v_mfma_f32_16x16x32_bf16 v[66:69], v[172:175], v[216:219], v[66:69]
	v_mfma_f32_16x16x32_bf16 v[118:121], v[164:167], v[196:199], v[118:121]
	v_mfma_f32_16x16x32_bf16 v[114:117], v[176:179], v[196:199], v[114:117]
	v_mfma_f32_16x16x32_bf16 v[102:105], v[164:167], v[204:207], v[102:105]
	v_mfma_f32_16x16x32_bf16 v[98:101], v[176:179], v[204:207], v[98:101]
	v_mfma_f32_16x16x32_bf16 v[86:89], v[164:167], v[212:215], v[86:89]
	v_mfma_f32_16x16x32_bf16 v[82:85], v[176:179], v[212:215], v[82:85]
	v_mfma_f32_16x16x32_bf16 v[70:73], v[164:167], v[220:223], v[70:73]
	v_mfma_f32_16x16x32_bf16 v[66:69], v[176:179], v[220:223], v[66:69]
	s_setprio 0
	s_barrier
	s_add_i32 s60, s60, s81
	v_lshl_add_u64 v[184:185], s[34:35], 0, v[148:149]
	s_mov_b32 m0, s60
	ds_read_b128 v[180:183], v170 offset:16384
	ds_read_b128 v[196:199], v170 offset:17408
	ds_read_b128 v[200:203], v170 offset:18432
	ds_read_b128 v[204:207], v170 offset:19456
	ds_read_b128 v[208:211], v170 offset:20480
	ds_read_b128 v[212:215], v170 offset:21504
	ds_read_b128 v[216:219], v170 offset:22528
	ds_read_b128 v[220:223], v170 offset:23552
	global_load_lds_dwordx4 v[184:185], off
	s_add_i32 m0, s60, 0x2000
	s_add_u32 s60, s34, 0x4000
	v_lshl_add_u64 v[184:185], s[34:35], 0, v[152:153]
	s_addc_u32 s61, s35, 0
	s_add_i32 s75, s75, s81
	global_load_lds_dwordx4 v[184:185], off
	v_lshl_add_u64 v[184:185], s[60:61], 0, v[148:149]
	s_mov_b32 m0, s75
	s_nop 0
	global_load_lds_dwordx4 v[184:185], off
	v_lshl_add_u64 v[184:185], s[60:61], 0, v[152:153]
	s_add_i32 m0, s75, 0x2000
	s_nop 0
	global_load_lds_dwordx4 v[184:185], off
	v_lshl_add_u64 v[184:185], s[36:37], 0, v[146:147]
	s_mov_b32 m0, s83
	s_nop 0
	global_load_lds_dwordx4 v[184:185], off
	v_lshl_add_u64 v[184:185], s[36:37], 0, v[150:151]
	s_mov_b32 m0, s84
	s_nop 0
	global_load_lds_dwordx4 v[184:185], off
	s_waitcnt vmcnt(8)
	s_waitcnt lgkmcnt(0)
	v_mfma_f32_16x16x32_bf16 v[62:65], v[130:133], v[180:183], v[62:65]
	v_mfma_f32_16x16x32_bf16 v[58:61], v[138:141], v[180:183], v[58:61]
	s_barrier
; #define PG8_STAGE(bufoff, gbase, voff) do { _Pragma("unroll") for (int _i = 0; _i < 2; ++_i) \
;         __builtin_amdgcn_global_load_lds((const unsigned*)((const char*)(gbase) + (voff)[_i]), (PG8_LAS unsigned*)(lds + (bufoff) + ldsw + _i * 8192), 16, 0, 0); } while (0)
; #define PG8_LDA(dst, b, h) do { _Pragma("unroll") for (int m = 0; m < 4; ++m) _Pragma("unroll") for (int k = 0; k < 2; ++k) dst[m][k] = *(const PG8_LAS bf16x8*)(lds + PG8_SA(b, h) + aoff + m * 2048 + k * 1024); } while (0)
; #define PG8_LDB(dst, b, h) do { _Pragma("unroll") for (int n = 0; n < 2; ++n) _Pragma("unroll") for (int k = 0; k < 2; ++k) dst[n][k] = *(const PG8_LAS bf16x8*)(lds + PG8_SB(b, h) + boff + n * 2048 + k * 1024); } while (0)
; #define PG8_MMA(ai, bj, At, Bt) do { __builtin_amdgcn_s_setprio(1); _Pragma("unroll") for (int m = 0; m < 4; ++m) _Pragma("unroll") for (int n = 0; n < 2; ++n) _Pragma("unroll") for (int k = 0; k < 2; ++k) \
;         acc[ai][bj][m][n] = __builtin_amdgcn_mfma_f32_16x16x32_bf16(Bt[n][k], At[m][k], acc[ai][bj][m][n], 0, 0, 0); __builtin_amdgcn_s_setprio(0); } while (0)
; #define PG8_WAIT_V(n) asm volatile("s_waitcnt vmcnt(" #n ")" ::: "memory")
; #define PG8_WAIT_L(n) asm volatile("s_waitcnt lgkmcnt(" #n ")" ::: "memory")
; #define PG8_BAR __builtin_amdgcn_s_barrier()
; #define PG8_SCHED __builtin_amdgcn_sched_barrier(0)
; template <class Epi, class Sched, bool ALIGN_EPI = false, bool SP2 = false, bool ABLK = false, bool BBLK = false>
; __device__ __forceinline__ void gemm_phase(PG8_LAS unsigned char* lds, const Gemm g, const Sched& S, const Epi& E) {
;     ...
;             PG8_WAIT_V(8); PG8_WAIT_L(0); PG8_BAR; PG8_MMA(1, 0, At, B0); PG8_MMA(1, 1, At, B1); PG8_BAR; PG8_SCHED;
;             PG8_LDB(B0, 1, 0); PG8_LDB(B1, 1, 1); PG8_SCHED; PG8_LDA(At, 1, 0); PG8_STAGE(PG8_SA(0, 1), a2 + hstepA, voffA);
;             PG8_WAIT_V(8); PG8_WAIT_L(0); PG8_BAR; PG8_MMA(0, 0, At, B0); PG8_MMA(0, 1, At, B1); PG8_BAR; PG8_SCHED;
	s_setprio 1
	s_waitcnt lgkmcnt(0)
	v_mfma_f32_16x16x32_bf16 v[46:49], v[130:133], v[200:203], v[46:49]
	v_mfma_f32_16x16x32_bf16 v[42:45], v[138:141], v[200:203], v[42:45]
	v_mfma_f32_16x16x32_bf16 v[30:33], v[130:133], v[208:211], v[30:33]
	v_mfma_f32_16x16x32_bf16 v[26:29], v[138:141], v[208:211], v[26:29]
	v_mfma_f32_16x16x32_bf16 v[14:17], v[130:133], v[216:219], v[14:17]
	v_mfma_f32_16x16x32_bf16 v[10:13], v[138:141], v[216:219], v[10:13]
	v_mfma_f32_16x16x32_bf16 v[62:65], v[134:137], v[196:199], v[62:65]
	v_mfma_f32_16x16x32_bf16 v[58:61], v[142:145], v[196:199], v[58:61]
	v_mfma_f32_16x16x32_bf16 v[46:49], v[134:137], v[204:207], v[46:49]
	v_mfma_f32_16x16x32_bf16 v[42:45], v[142:145], v[204:207], v[42:45]
	v_mfma_f32_16x16x32_bf16 v[30:33], v[134:137], v[212:215], v[30:33]
	v_mfma_f32_16x16x32_bf16 v[26:29], v[142:145], v[212:215], v[26:29]
	v_mfma_f32_16x16x32_bf16 v[14:17], v[134:137], v[220:223], v[14:17]
	v_mfma_f32_16x16x32_bf16 v[10:13], v[142:145], v[220:223], v[10:13]
	s_setprio 0
	s_setprio 1
	v_mfma_f32_16x16x32_bf16 v[54:57], v[160:163], v[180:183], v[54:57]
	v_mfma_f32_16x16x32_bf16 v[50:53], v[172:175], v[180:183], v[50:53]
	v_mfma_f32_16x16x32_bf16 v[38:41], v[160:163], v[200:203], v[38:41]
	v_mfma_f32_16x16x32_bf16 v[34:37], v[172:175], v[200:203], v[34:37]
	v_mfma_f32_16x16x32_bf16 v[22:25], v[160:163], v[208:211], v[22:25]
	v_mfma_f32_16x16x32_bf16 v[18:21], v[172:175], v[208:211], v[18:21]
	v_mfma_f32_16x16x32_bf16 v[6:9], v[160:163], v[216:219], v[6:9]
	v_mfma_f32_16x16x32_bf16 v[2:5], v[172:175], v[216:219], v[2:5]
	v_mfma_f32_16x16x32_bf16 v[54:57], v[164:167], v[196:199], v[54:57]
	v_mfma_f32_16x16x32_bf16 v[50:53], v[176:179], v[196:199], v[50:53]
	v_mfma_f32_16x16x32_bf16 v[38:41], v[164:167], v[204:207], v[38:41]
	v_mfma_f32_16x16x32_bf16 v[34:37], v[176:179], v[204:207], v[34:37]
	v_mfma_f32_16x16x32_bf16 v[22:25], v[164:167], v[212:215], v[22:25]
	v_mfma_f32_16x16x32_bf16 v[18:21], v[176:179], v[212:215], v[18:21]
	v_mfma_f32_16x16x32_bf16 v[6:9], v[164:167], v[220:223], v[6:9]
	v_mfma_f32_16x16x32_bf16 v[2:5], v[176:179], v[220:223], v[2:5]
	s_setprio 0
	s_barrier
	s_add_i32 s60, 0, 0x18000
	s_add_i32 s61, 0, 0x1c000
	v_add_u32_e32 v142, s60, v169
	v_add_u32_e32 v171, s61, v169
	ds_read_b128 v[130:133], v142
	ds_read_b128 v[134:137], v142 offset:1024
	ds_read_b128 v[138:141], v142 offset:2048
	ds_read_b128 v[142:145], v142 offset:3072
	ds_read_b128 v[160:163], v171
	ds_read_b128 v[164:167], v171 offset:1024
	ds_read_b128 v[172:175], v171 offset:2048
	ds_read_b128 v[176:179], v171 offset:3072
	s_add_u32 s36, s36, 0x4000
	s_addc_u32 s37, s37, 0
	s_mov_b32 m0, s86
	v_lshl_add_u64 v[184:185], s[36:37], 0, v[146:147]
	ds_read_b128 v[180:183], v170 offset:32768
	ds_read_b128 v[196:199], v170 offset:33792
	ds_read_b128 v[200:203], v170 offset:34816
	ds_read_b128 v[204:207], v170 offset:35840
	ds_read_b128 v[208:211], v170 offset:36864
	ds_read_b128 v[212:215], v170 offset:37888
	ds_read_b128 v[216:219], v170 offset:38912
	ds_read_b128 v[220:223], v170 offset:39936
	global_load_lds_dwordx4 v[184:185], off
	v_lshl_add_u64 v[184:185], s[36:37], 0, v[150:151]
	s_mov_b32 m0, s88
	s_nop 0
	global_load_lds_dwordx4 v[184:185], off
	s_waitcnt vmcnt(8)
	s_waitcnt lgkmcnt(0)
	v_mfma_f32_16x16x32_bf16 v[126:129], v[130:133], v[180:183], v[126:129]
	v_mfma_f32_16x16x32_bf16 v[122:125], v[138:141], v[180:183], v[122:125]
	s_barrier
	s_setprio 1
	s_waitcnt lgkmcnt(0)
	v_mfma_f32_16x16x32_bf16 v[110:113], v[130:133], v[200:203], v[110:113]
	v_mfma_f32_16x16x32_bf16 v[106:109], v[138:141], v[200:203], v[106:109]
	v_mfma_f32_16x16x32_bf16 v[94:97], v[130:133], v[208:211], v[94:97]
	v_mfma_f32_16x16x32_bf16 v[90:93], v[138:141], v[208:211], v[90:93]
	v_mfma_f32_16x16x32_bf16 v[78:81], v[130:133], v[216:219], v[78:81]
	v_mfma_f32_16x16x32_bf16 v[74:77], v[138:141], v[216:219], v[74:77]
	v_mfma_f32_16x16x32_bf16 v[126:129], v[134:137], v[196:199], v[126:129]
	v_mfma_f32_16x16x32_bf16 v[122:125], v[142:145], v[196:199], v[122:125]
	v_mfma_f32_16x16x32_bf16 v[110:113], v[134:137], v[204:207], v[110:113]
	v_mfma_f32_16x16x32_bf16 v[106:109], v[142:145], v[204:207], v[106:109]
	v_mfma_f32_16x16x32_bf16 v[94:97], v[134:137], v[212:215], v[94:97]
	v_mfma_f32_16x16x32_bf16 v[90:93], v[142:145], v[212:215], v[90:93]
	v_mfma_f32_16x16x32_bf16 v[78:81], v[134:137], v[220:223], v[78:81]
	v_mfma_f32_16x16x32_bf16 v[74:77], v[142:145], v[220:223], v[74:77]
	s_setprio 0
	s_setprio 1
	v_mfma_f32_16x16x32_bf16 v[118:121], v[160:163], v[180:183], v[118:121]
	v_mfma_f32_16x16x32_bf16 v[114:117], v[172:175], v[180:183], v[114:117]
	v_mfma_f32_16x16x32_bf16 v[102:105], v[160:163], v[200:203], v[102:105]
	v_mfma_f32_16x16x32_bf16 v[98:101], v[172:175], v[200:203], v[98:101]
	v_mfma_f32_16x16x32_bf16 v[86:89], v[160:163], v[208:211], v[86:89]
	v_mfma_f32_16x16x32_bf16 v[82:85], v[172:175], v[208:211], v[82:85]
	v_mfma_f32_16x16x32_bf16 v[70:73], v[160:163], v[216:219], v[70:73]
	v_mfma_f32_16x16x32_bf16 v[66:69], v[172:175], v[216:219], v[66:69]
	v_mfma_f32_16x16x32_bf16 v[118:121], v[164:167], v[196:199], v[118:121]
	v_mfma_f32_16x16x32_bf16 v[114:117], v[176:179], v[196:199], v[114:117]
	v_mfma_f32_16x16x32_bf16 v[102:105], v[164:167], v[204:207], v[102:105]
	v_mfma_f32_16x16x32_bf16 v[98:101], v[176:179], v[204:207], v[98:101]
	v_mfma_f32_16x16x32_bf16 v[86:89], v[164:167], v[212:215], v[86:89]
	v_mfma_f32_16x16x32_bf16 v[82:85], v[176:179], v[212:215], v[82:85]
	v_mfma_f32_16x16x32_bf16 v[70:73], v[164:167], v[220:223], v[70:73]
	v_mfma_f32_16x16x32_bf16 v[66:69], v[176:179], v[220:223], v[66:69]
	s_setprio 0
	s_barrier
; #define PG8_STAGE(bufoff, gbase, voff) do { _Pragma("unroll") for (int _i = 0; _i < 2; ++_i) \
;         __builtin_amdgcn_global_load_lds((const unsigned*)((const char*)(gbase) + (voff)[_i]), (PG8_LAS unsigned*)(lds + (bufoff) + ldsw + _i * 8192), 16, 0, 0); } while (0)
; #define PG8_LDA(dst, b, h) do { _Pragma("unroll") for (int m = 0; m < 4; ++m) _Pragma("unroll") for (int k = 0; k < 2; ++k) dst[m][k] = *(const PG8_LAS bf16x8*)(lds + PG8_SA(b, h) + aoff + m * 2048 + k * 1024); } while (0)
; #define PG8_MMA(ai, bj, At, Bt) do { __builtin_amdgcn_s_setprio(1); _Pragma("unroll") for (int m = 0; m < 4; ++m) _Pragma("unroll") for (int n = 0; n < 2; ++n) _Pragma("unroll") for (int k = 0; k < 2; ++k) \
;         acc[ai][bj][m][n] = __builtin_amdgcn_mfma_f32_16x16x32_bf16(Bt[n][k], At[m][k], acc[ai][bj][m][n], 0, 0, 0); __builtin_amdgcn_s_setprio(0); } while (0)
; #define PG8_WAIT_V(n) asm volatile("s_waitcnt vmcnt(" #n ")" ::: "memory")
; #define PG8_WAIT_L(n) asm volatile("s_waitcnt lgkmcnt(" #n ")" ::: "memory")
; #define PG8_BAR __builtin_amdgcn_s_barrier()
; #define PG8_SCHED __builtin_amdgcn_sched_barrier(0)
; template <class Epi, class Sched, bool ALIGN_EPI = false, bool SP2 = false, bool ABLK = false, bool BBLK = false>
; __device__ __forceinline__ void gemm_phase(PG8_LAS unsigned char* lds, const Gemm g, const Sched& S, const Epi& E) {
;     ...
;         for (int t = 0; t < nt; t += 2) {
;             const bool last = (t == nt - 2);
;             const char* a1 = cA + (size_t)(t + 1) * kstepA;
;             const char* a2 = last ? nA : cA + (size_t)(t + 2) * kstepA; const char* b2 = last ? nB : cB + (size_t)(t + 2) * kstepB;
;             const char* a3 = a2 + kstepA; const char* b3 = b2 + kstepB;
;             if (last && has_next) S.a_ready(nxt);
;     ...
;             PG8_LDA(At, 1, 1); PG8_STAGE(PG8_SB(1, 0), b3, voffB); PG8_STAGE(PG8_SB(1, 1), b3 + hstepB, voffB); PG8_STAGE(PG8_SA(1, 0), a3, voffA);
;             PG8_WAIT_V(8); PG8_WAIT_L(0); PG8_BAR; PG8_MMA(1, 0, At, B0); PG8_MMA(1, 1, At, B1); PG8_BAR; PG8_SCHED;
	s_add_u32 s36, s34, 0x8000
	s_addc_u32 s37, s35, 0
	s_add_i32 s60, s60, s81
	v_lshl_add_u64 v[184:185], s[36:37], 0, v[148:149]
	s_mov_b32 m0, s60
	ds_read_b128 v[180:183], v170 offset:49152
	ds_read_b128 v[196:199], v170 offset:50176
	ds_read_b128 v[200:203], v170 offset:51200
	ds_read_b128 v[204:207], v170 offset:52224
	ds_read_b128 v[208:211], v170 offset:53248
	ds_read_b128 v[212:215], v170 offset:54272
	ds_read_b128 v[216:219], v170 offset:55296
	ds_read_b128 v[220:223], v170 offset:56320
	global_load_lds_dwordx4 v[184:185], off
	s_add_i32 m0, s60, 0x2000
	s_add_u32 s34, s34, 0xc000
	v_lshl_add_u64 v[184:185], s[36:37], 0, v[152:153]
	s_addc_u32 s35, s35, 0
	s_add_i32 s36, s61, s81
	global_load_lds_dwordx4 v[184:185], off
	v_lshl_add_u64 v[184:185], s[34:35], 0, v[148:149]
	s_mov_b32 m0, s36
	s_nop 0
	global_load_lds_dwordx4 v[184:185], off
	v_lshl_add_u64 v[184:185], s[34:35], 0, v[152:153]
	s_add_i32 m0, s36, 0x2000
	s_nop 0
	global_load_lds_dwordx4 v[184:185], off
	v_lshl_add_u64 v[184:185], s[30:31], 0, v[146:147]
	s_mov_b32 m0, s90
	s_nop 0
	global_load_lds_dwordx4 v[184:185], off
	v_lshl_add_u64 v[184:185], s[30:31], 0, v[150:151]
	s_mov_b32 m0, s91
	s_nop 0
	global_load_lds_dwordx4 v[184:185], off
	s_waitcnt vmcnt(8)
	s_waitcnt lgkmcnt(0)
	v_mfma_f32_16x16x32_bf16 v[62:65], v[130:133], v[180:183], v[62:65]
	v_mfma_f32_16x16x32_bf16 v[58:61], v[138:141], v[180:183], v[58:61]
	s_barrier
	s_setprio 1
	s_waitcnt lgkmcnt(0)
	v_mfma_f32_16x16x32_bf16 v[46:49], v[130:133], v[200:203], v[46:49]
	v_mfma_f32_16x16x32_bf16 v[42:45], v[138:141], v[200:203], v[42:45]
	v_mfma_f32_16x16x32_bf16 v[30:33], v[130:133], v[208:211], v[30:33]
	v_mfma_f32_16x16x32_bf16 v[26:29], v[138:141], v[208:211], v[26:29]
	v_mfma_f32_16x16x32_bf16 v[14:17], v[130:133], v[216:219], v[14:17]
	v_mfma_f32_16x16x32_bf16 v[10:13], v[138:141], v[216:219], v[10:13]
	v_mfma_f32_16x16x32_bf16 v[62:65], v[134:137], v[196:199], v[62:65]
	v_mfma_f32_16x16x32_bf16 v[58:61], v[142:145], v[196:199], v[58:61]
	v_mfma_f32_16x16x32_bf16 v[46:49], v[134:137], v[204:207], v[46:49]
	v_mfma_f32_16x16x32_bf16 v[42:45], v[142:145], v[204:207], v[42:45]
	v_mfma_f32_16x16x32_bf16 v[30:33], v[134:137], v[212:215], v[30:33]
	v_mfma_f32_16x16x32_bf16 v[26:29], v[142:145], v[212:215], v[26:29]
	v_mfma_f32_16x16x32_bf16 v[14:17], v[134:137], v[220:223], v[14:17]
	v_mfma_f32_16x16x32_bf16 v[10:13], v[142:145], v[220:223], v[10:13]
	s_setprio 0
	s_setprio 1
	v_mfma_f32_16x16x32_bf16 v[54:57], v[160:163], v[180:183], v[54:57]
	v_mfma_f32_16x16x32_bf16 v[50:53], v[172:175], v[180:183], v[50:53]
	v_mfma_f32_16x16x32_bf16 v[38:41], v[160:163], v[200:203], v[38:41]
	v_mfma_f32_16x16x32_bf16 v[34:37], v[172:175], v[200:203], v[34:37]
	v_mfma_f32_16x16x32_bf16 v[22:25], v[160:163], v[208:211], v[22:25]
	v_mfma_f32_16x16x32_bf16 v[18:21], v[172:175], v[208:211], v[18:21]
	v_mfma_f32_16x16x32_bf16 v[6:9], v[160:163], v[216:219], v[6:9]
	v_mfma_f32_16x16x32_bf16 v[2:5], v[172:175], v[216:219], v[2:5]
	v_mfma_f32_16x16x32_bf16 v[54:57], v[164:167], v[196:199], v[54:57]
	v_mfma_f32_16x16x32_bf16 v[50:53], v[176:179], v[196:199], v[50:53]
	v_mfma_f32_16x16x32_bf16 v[38:41], v[164:167], v[204:207], v[38:41]
	v_mfma_f32_16x16x32_bf16 v[34:37], v[176:179], v[204:207], v[34:37]
	v_mfma_f32_16x16x32_bf16 v[22:25], v[164:167], v[212:215], v[22:25]
	v_mfma_f32_16x16x32_bf16 v[18:21], v[176:179], v[212:215], v[18:21]
	v_mfma_f32_16x16x32_bf16 v[6:9], v[164:167], v[220:223], v[6:9]
	v_mfma_f32_16x16x32_bf16 v[2:5], v[176:179], v[220:223], v[2:5]
	s_setprio 0
	s_barrier
	s_add_i32 s41, s41, 2
	s_add_u32 s0, s0, 0x10000
	s_addc_u32 s1, s1, 0
	s_add_u32 s29, s29, 0x10000
	s_addc_u32 s40, s40, 0
	s_cmp_gt_u32 s41, 29
	s_cbranch_scc0 .LBB0_594
	s_and_b64 vcc, exec, s[18:19]
	s_cbranch_vccz .LBB0_597
	s_barrier

; #define PG8_STAGE(bufoff, gbase, voff) do { _Pragma("unroll") for (int _i = 0; _i < 2; ++_i) \
;         __builtin_amdgcn_global_load_lds((const unsigned*)((const char*)(gbase) + (voff)[_i]), (PG8_LAS unsigned*)(lds + (bufoff) + ldsw + _i * 8192), 16, 0, 0); } while (0)
; #define PG8_LDA(dst, b, h) do { _Pragma("unroll") for (int m = 0; m < 4; ++m) _Pragma("unroll") for (int k = 0; k < 2; ++k) dst[m][k] = *(const PG8_LAS bf16x8*)(lds + PG8_SA(b, h) + aoff + m * 2048 + k * 1024); } while (0)
; #define PG8_LDB(dst, b, h) do { _Pragma("unroll") for (int n = 0; n < 2; ++n) _Pragma("unroll") for (int k = 0; k < 2; ++k) dst[n][k] = *(const PG8_LAS bf16x8*)(lds + PG8_SB(b, h) + boff + n * 2048 + k * 1024); } while (0)
; #define PG8_MMA(ai, bj, At, Bt) do { __builtin_amdgcn_s_setprio(1); _Pragma("unroll") for (int m = 0; m < 4; ++m) _Pragma("unroll") for (int n = 0; n < 2; ++n) _Pragma("unroll") for (int k = 0; k < 2; ++k) \
;         acc[ai][bj][m][n] = __builtin_amdgcn_mfma_f32_16x16x32_bf16(Bt[n][k], At[m][k], acc[ai][bj][m][n], 0, 0, 0); __builtin_amdgcn_s_setprio(0); } while (0)
; #define PG8_WAIT_V(n) asm volatile("s_waitcnt vmcnt(" #n ")" ::: "memory")
; #define PG8_WAIT_L(n) asm volatile("s_waitcnt lgkmcnt(" #n ")" ::: "memory")
; #define PG8_BAR __builtin_amdgcn_s_barrier()
; #define PG8_SCHED __builtin_amdgcn_sched_barrier(0)
; template <class Epi, class Sched, bool ALIGN_EPI = false, bool SP2 = false, bool ABLK = false, bool BBLK = false>
; __device__ __forceinline__ void gemm_phase(PG8_LAS unsigned char* lds, const Gemm g, const Sched& S, const Epi& E) {
;     ...
;             PG8_LDB(B0, 0, 0); PG8_LDB(B1, 0, 1); PG8_SCHED; PG8_LDA(At, 0, 0); PG8_STAGE(PG8_SA(1, 1), a1 + hstepA, voffA);
;             PG8_WAIT_V(8); PG8_WAIT_L(0); PG8_BAR; PG8_MMA(0, 0, At, B0); PG8_MMA(0, 1, At, B1); PG8_BAR; PG8_SCHED;
;             PG8_LDA(At, 0, 1); PG8_STAGE(PG8_SB(0, 0), b2, voffB); PG8_STAGE(PG8_SB(0, 1), b2 + hstepB, voffB); PG8_STAGE(PG8_SA(0, 0), a2, voffA);
;             PG8_WAIT_V(8); PG8_WAIT_L(0); PG8_BAR; PG8_MMA(1, 0, At, B0); PG8_MMA(1, 1, At, B1); PG8_BAR; PG8_SCHED;
.LBB0_658:
	s_add_u32 s24, s22, 0x4000
	s_addc_u32 s25, s23, 0
	s_cmp_eq_u32 s73, 28
	s_cselect_b32 s28, s61, s24
	s_cselect_b32 s29, s13, s25
	s_cselect_b32 s26, s65, s68
	s_cselect_b32 s27, s1, s72
	s_add_u32 s24, s28, 0x8000
	s_addc_u32 s25, s29, 0
	s_add_i32 s75, 0, 0x10000
	s_add_i32 s82, 0, 0x14000
	v_add_u32_e32 v158, s75, v147
	v_add_u32_e32 v174, s82, v147
	ds_read_b128 v[142:145], v158
	ds_read_b128 v[150:153], v158 offset:1024
	ds_read_b128 v[154:157], v158 offset:2048
	ds_read_b128 v[158:161], v158 offset:3072
	ds_read_b128 v[162:165], v174
	ds_read_b128 v[166:169], v174 offset:1024
	ds_read_b128 v[170:173], v174 offset:2048
	ds_read_b128 v[174:177], v174 offset:3072
	v_lshl_add_u64 v[220:221], s[22:23], 0, v[138:139]
	s_add_i32 m0, s40, 0xc000
	ds_read_b128 v[178:181], v149
	ds_read_b128 v[182:185], v149 offset:1024
	ds_read_b128 v[196:199], v149 offset:2048
	ds_read_b128 v[200:203], v149 offset:3072
	ds_read_b128 v[204:207], v149 offset:4096
	ds_read_b128 v[208:211], v149 offset:5120
	ds_read_b128 v[212:215], v149 offset:6144
	ds_read_b128 v[216:219], v149 offset:7168
	global_load_lds_dwordx4 v[220:221], off
	v_lshl_add_u64 v[220:221], s[22:23], 0, v[140:141]
	s_add_i32 m0, s40, 0xe000
	s_nop 0
	global_load_lds_dwordx4 v[220:221], off
	s_waitcnt vmcnt(8)
	s_waitcnt lgkmcnt(0)
	v_mfma_f32_16x16x32_bf16 v[126:129], v[142:145], v[178:181], v[126:129]
	v_mfma_f32_16x16x32_bf16 v[122:125], v[154:157], v[178:181], v[122:125]
	s_barrier
	s_setprio 1
	s_waitcnt lgkmcnt(0)
	v_mfma_f32_16x16x32_bf16 v[114:117], v[142:145], v[196:199], v[114:117]
	v_mfma_f32_16x16x32_bf16 v[106:109], v[154:157], v[196:199], v[106:109]
	v_mfma_f32_16x16x32_bf16 v[102:105], v[142:145], v[204:207], v[102:105]
	v_mfma_f32_16x16x32_bf16 v[94:97], v[154:157], v[204:207], v[94:97]
	v_mfma_f32_16x16x32_bf16 v[86:89], v[142:145], v[212:215], v[86:89]
	v_mfma_f32_16x16x32_bf16 v[78:81], v[154:157], v[212:215], v[78:81]
	v_mfma_f32_16x16x32_bf16 v[126:129], v[150:153], v[182:185], v[126:129]
	v_mfma_f32_16x16x32_bf16 v[122:125], v[158:161], v[182:185], v[122:125]
	v_mfma_f32_16x16x32_bf16 v[114:117], v[150:153], v[200:203], v[114:117]
	v_mfma_f32_16x16x32_bf16 v[106:109], v[158:161], v[200:203], v[106:109]
	v_mfma_f32_16x16x32_bf16 v[102:105], v[150:153], v[208:211], v[102:105]
	v_mfma_f32_16x16x32_bf16 v[94:97], v[158:161], v[208:211], v[94:97]
	v_mfma_f32_16x16x32_bf16 v[86:89], v[150:153], v[216:219], v[86:89]
	v_mfma_f32_16x16x32_bf16 v[78:81], v[158:161], v[216:219], v[78:81]
	s_setprio 0
	s_setprio 1
	v_mfma_f32_16x16x32_bf16 v[118:121], v[162:165], v[178:181], v[118:121]
	v_mfma_f32_16x16x32_bf16 v[110:113], v[170:173], v[178:181], v[110:113]
	v_mfma_f32_16x16x32_bf16 v[98:101], v[162:165], v[196:199], v[98:101]
	v_mfma_f32_16x16x32_bf16 v[90:93], v[170:173], v[196:199], v[90:93]
	v_mfma_f32_16x16x32_bf16 v[82:85], v[162:165], v[204:207], v[82:85]
	v_mfma_f32_16x16x32_bf16 v[74:77], v[170:173], v[204:207], v[74:77]
	v_mfma_f32_16x16x32_bf16 v[70:73], v[162:165], v[212:215], v[70:73]
	v_mfma_f32_16x16x32_bf16 v[66:69], v[170:173], v[212:215], v[66:69]
	v_mfma_f32_16x16x32_bf16 v[118:121], v[166:169], v[182:185], v[118:121]
	v_mfma_f32_16x16x32_bf16 v[110:113], v[174:177], v[182:185], v[110:113]
	v_mfma_f32_16x16x32_bf16 v[98:101], v[166:169], v[200:203], v[98:101]
	v_mfma_f32_16x16x32_bf16 v[90:93], v[174:177], v[200:203], v[90:93]
	v_mfma_f32_16x16x32_bf16 v[82:85], v[166:169], v[208:211], v[82:85]
	v_mfma_f32_16x16x32_bf16 v[74:77], v[174:177], v[208:211], v[74:77]
	v_mfma_f32_16x16x32_bf16 v[70:73], v[166:169], v[216:219], v[70:73]
	v_mfma_f32_16x16x32_bf16 v[66:69], v[174:177], v[216:219], v[66:69]
	s_setprio 0
	s_barrier
	s_add_i32 s75, s75, s37
	v_lshl_add_u64 v[220:221], s[26:27], 0, v[134:135]
	s_mov_b32 m0, s75
	ds_read_b128 v[178:181], v149 offset:16384
	ds_read_b128 v[182:185], v149 offset:17408
	ds_read_b128 v[196:199], v149 offset:18432
	ds_read_b128 v[200:203], v149 offset:19456
	ds_read_b128 v[204:207], v149 offset:20480
	ds_read_b128 v[208:211], v149 offset:21504
	ds_read_b128 v[212:215], v149 offset:22528
	ds_read_b128 v[216:219], v149 offset:23552
	global_load_lds_dwordx4 v[220:221], off
	s_add_i32 m0, s75, 0x2000
	s_add_u32 s80, s26, 0x4000
	v_lshl_add_u64 v[220:221], s[26:27], 0, v[130:131]
	s_addc_u32 s81, s27, 0
	s_add_i32 s75, s82, s37
	global_load_lds_dwordx4 v[220:221], off
	v_lshl_add_u64 v[220:221], s[80:81], 0, v[134:135]
	s_mov_b32 m0, s75
	s_nop 0
	global_load_lds_dwordx4 v[220:221], off
	v_lshl_add_u64 v[220:221], s[80:81], 0, v[130:131]
	s_add_i32 m0, s75, 0x2000
	s_nop 0
	global_load_lds_dwordx4 v[220:221], off
	v_lshl_add_u64 v[220:221], s[28:29], 0, v[136:137]
	s_mov_b32 m0, s40
	s_nop 0
	global_load_lds_dwordx4 v[220:221], off
	v_lshl_add_u64 v[220:221], s[28:29], 0, v[132:133]
	s_mov_b32 m0, s41
	s_nop 0
	global_load_lds_dwordx4 v[220:221], off
	s_waitcnt vmcnt(8)
	s_waitcnt lgkmcnt(0)
	v_mfma_f32_16x16x32_bf16 v[62:65], v[142:145], v[178:181], v[62:65]
	v_mfma_f32_16x16x32_bf16 v[58:61], v[154:157], v[178:181], v[58:61]
	s_barrier
; #define PG8_STAGE(bufoff, gbase, voff) do { _Pragma("unroll") for (int _i = 0; _i < 2; ++_i) \
;         __builtin_amdgcn_global_load_lds((const unsigned*)((const char*)(gbase) + (voff)[_i]), (PG8_LAS unsigned*)(lds + (bufoff) + ldsw + _i * 8192), 16, 0, 0); } while (0)
; #define PG8_LDA(dst, b, h) do { _Pragma("unroll") for (int m = 0; m < 4; ++m) _Pragma("unroll") for (int k = 0; k < 2; ++k) dst[m][k] = *(const PG8_LAS bf16x8*)(lds + PG8_SA(b, h) + aoff + m * 2048 + k * 1024); } while (0)
; #define PG8_LDB(dst, b, h) do { _Pragma("unroll") for (int n = 0; n < 2; ++n) _Pragma("unroll") for (int k = 0; k < 2; ++k) dst[n][k] = *(const PG8_LAS bf16x8*)(lds + PG8_SB(b, h) + boff + n * 2048 + k * 1024); } while (0)
; #define PG8_MMA(ai, bj, At, Bt) do { __builtin_amdgcn_s_setprio(1); _Pragma("unroll") for (int m = 0; m < 4; ++m) _Pragma("unroll") for (int n = 0; n < 2; ++n) _Pragma("unroll") for (int k = 0; k < 2; ++k) \
;         acc[ai][bj][m][n] = __builtin_amdgcn_mfma_f32_16x16x32_bf16(Bt[n][k], At[m][k], acc[ai][bj][m][n], 0, 0, 0); __builtin_amdgcn_s_setprio(0); } while (0)
; #define PG8_WAIT_V(n) asm volatile("s_waitcnt vmcnt(" #n ")" ::: "memory")
; #define PG8_WAIT_L(n) asm volatile("s_waitcnt lgkmcnt(" #n ")" ::: "memory")
; #define PG8_BAR __builtin_amdgcn_s_barrier()
; #define PG8_SCHED __builtin_amdgcn_sched_barrier(0)
; template <class Epi, class Sched, bool ALIGN_EPI = false, bool SP2 = false, bool ABLK = false, bool BBLK = false>
; __device__ __forceinline__ void gemm_phase(PG8_LAS unsigned char* lds, const Gemm g, const Sched& S, const Epi& E) {
;     ...
;             PG8_WAIT_V(8); PG8_WAIT_L(0); PG8_BAR; PG8_MMA(1, 0, At, B0); PG8_MMA(1, 1, At, B1); PG8_BAR; PG8_SCHED;
;             PG8_LDB(B0, 1, 0); PG8_LDB(B1, 1, 1); PG8_SCHED; PG8_LDA(At, 1, 0); PG8_STAGE(PG8_SA(0, 1), a2 + hstepA, voffA);
;             PG8_WAIT_V(8); PG8_WAIT_L(0); PG8_BAR; PG8_MMA(0, 0, At, B0); PG8_MMA(0, 1, At, B1); PG8_BAR; PG8_SCHED;
	s_setprio 1
	s_waitcnt lgkmcnt(0)
	v_mfma_f32_16x16x32_bf16 v[50:53], v[142:145], v[196:199], v[50:53]
	v_mfma_f32_16x16x32_bf16 v[42:45], v[154:157], v[196:199], v[42:45]
	v_mfma_f32_16x16x32_bf16 v[38:41], v[142:145], v[204:207], v[38:41]
	v_mfma_f32_16x16x32_bf16 v[30:33], v[154:157], v[204:207], v[30:33]
	v_mfma_f32_16x16x32_bf16 v[22:25], v[142:145], v[212:215], v[22:25]
	v_mfma_f32_16x16x32_bf16 v[14:17], v[154:157], v[212:215], v[14:17]
	v_mfma_f32_16x16x32_bf16 v[62:65], v[150:153], v[182:185], v[62:65]
	v_mfma_f32_16x16x32_bf16 v[58:61], v[158:161], v[182:185], v[58:61]
	v_mfma_f32_16x16x32_bf16 v[50:53], v[150:153], v[200:203], v[50:53]
	v_mfma_f32_16x16x32_bf16 v[42:45], v[158:161], v[200:203], v[42:45]
	v_mfma_f32_16x16x32_bf16 v[38:41], v[150:153], v[208:211], v[38:41]
	v_mfma_f32_16x16x32_bf16 v[30:33], v[158:161], v[208:211], v[30:33]
	v_mfma_f32_16x16x32_bf16 v[22:25], v[150:153], v[216:219], v[22:25]
	v_mfma_f32_16x16x32_bf16 v[14:17], v[158:161], v[216:219], v[14:17]
	s_setprio 0
	s_setprio 1
	v_mfma_f32_16x16x32_bf16 v[54:57], v[162:165], v[178:181], v[54:57]
	v_mfma_f32_16x16x32_bf16 v[46:49], v[170:173], v[178:181], v[46:49]
	v_mfma_f32_16x16x32_bf16 v[34:37], v[162:165], v[196:199], v[34:37]
	v_mfma_f32_16x16x32_bf16 v[26:29], v[170:173], v[196:199], v[26:29]
	v_mfma_f32_16x16x32_bf16 v[18:21], v[162:165], v[204:207], v[18:21]
	v_mfma_f32_16x16x32_bf16 v[10:13], v[170:173], v[204:207], v[10:13]
	v_mfma_f32_16x16x32_bf16 v[6:9], v[162:165], v[212:215], v[6:9]
	v_mfma_f32_16x16x32_bf16 v[2:5], v[170:173], v[212:215], v[2:5]
	v_mfma_f32_16x16x32_bf16 v[54:57], v[166:169], v[182:185], v[54:57]
	v_mfma_f32_16x16x32_bf16 v[46:49], v[174:177], v[182:185], v[46:49]
	v_mfma_f32_16x16x32_bf16 v[34:37], v[166:169], v[200:203], v[34:37]
	v_mfma_f32_16x16x32_bf16 v[26:29], v[174:177], v[200:203], v[26:29]
	v_mfma_f32_16x16x32_bf16 v[18:21], v[166:169], v[208:211], v[18:21]
	v_mfma_f32_16x16x32_bf16 v[10:13], v[174:177], v[208:211], v[10:13]
	v_mfma_f32_16x16x32_bf16 v[6:9], v[166:169], v[216:219], v[6:9]
	v_mfma_f32_16x16x32_bf16 v[2:5], v[174:177], v[216:219], v[2:5]
	s_setprio 0
	s_barrier
	s_add_i32 s75, 0, 0x18000
	s_add_i32 s80, 0, 0x1c000
	v_add_u32_e32 v158, s75, v147
	v_add_u32_e32 v174, s80, v147
	ds_read_b128 v[142:145], v158
	ds_read_b128 v[150:153], v158 offset:1024
	ds_read_b128 v[154:157], v158 offset:2048
	ds_read_b128 v[158:161], v158 offset:3072
	ds_read_b128 v[162:165], v174
	ds_read_b128 v[166:169], v174 offset:1024
	ds_read_b128 v[170:173], v174 offset:2048
	ds_read_b128 v[174:177], v174 offset:3072
	s_add_u32 s28, s28, 0x4000
	s_addc_u32 s29, s29, 0
	s_mov_b32 m0, s44
	v_lshl_add_u64 v[220:221], s[28:29], 0, v[136:137]
	ds_read_b128 v[178:181], v149 offset:32768
	ds_read_b128 v[182:185], v149 offset:33792
	ds_read_b128 v[196:199], v149 offset:34816
	ds_read_b128 v[200:203], v149 offset:35840
	ds_read_b128 v[204:207], v149 offset:36864
	ds_read_b128 v[208:211], v149 offset:37888
	ds_read_b128 v[212:215], v149 offset:38912
	ds_read_b128 v[216:219], v149 offset:39936
	global_load_lds_dwordx4 v[220:221], off
	v_lshl_add_u64 v[220:221], s[28:29], 0, v[132:133]
	s_mov_b32 m0, s45
	s_nop 0
	global_load_lds_dwordx4 v[220:221], off
	s_waitcnt vmcnt(8)
	s_waitcnt lgkmcnt(0)
	v_mfma_f32_16x16x32_bf16 v[126:129], v[142:145], v[178:181], v[126:129]
	v_mfma_f32_16x16x32_bf16 v[122:125], v[154:157], v[178:181], v[122:125]
	s_barrier
	s_setprio 1
	s_waitcnt lgkmcnt(0)
	v_mfma_f32_16x16x32_bf16 v[114:117], v[142:145], v[196:199], v[114:117]
	v_mfma_f32_16x16x32_bf16 v[106:109], v[154:157], v[196:199], v[106:109]
	v_mfma_f32_16x16x32_bf16 v[102:105], v[142:145], v[204:207], v[102:105]
	v_mfma_f32_16x16x32_bf16 v[94:97], v[154:157], v[204:207], v[94:97]
	v_mfma_f32_16x16x32_bf16 v[86:89], v[142:145], v[212:215], v[86:89]
	v_mfma_f32_16x16x32_bf16 v[78:81], v[154:157], v[212:215], v[78:81]
	v_mfma_f32_16x16x32_bf16 v[126:129], v[150:153], v[182:185], v[126:129]
	v_mfma_f32_16x16x32_bf16 v[122:125], v[158:161], v[182:185], v[122:125]
	v_mfma_f32_16x16x32_bf16 v[114:117], v[150:153], v[200:203], v[114:117]
	v_mfma_f32_16x16x32_bf16 v[106:109], v[158:161], v[200:203], v[106:109]
	v_mfma_f32_16x16x32_bf16 v[102:105], v[150:153], v[208:211], v[102:105]
	v_mfma_f32_16x16x32_bf16 v[94:97], v[158:161], v[208:211], v[94:97]
	v_mfma_f32_16x16x32_bf16 v[86:89], v[150:153], v[216:219], v[86:89]
	v_mfma_f32_16x16x32_bf16 v[78:81], v[158:161], v[216:219], v[78:81]
	s_setprio 0
	s_setprio 1
	v_mfma_f32_16x16x32_bf16 v[118:121], v[162:165], v[178:181], v[118:121]
	v_mfma_f32_16x16x32_bf16 v[110:113], v[170:173], v[178:181], v[110:113]
	v_mfma_f32_16x16x32_bf16 v[98:101], v[162:165], v[196:199], v[98:101]
	v_mfma_f32_16x16x32_bf16 v[90:93], v[170:173], v[196:199], v[90:93]
	v_mfma_f32_16x16x32_bf16 v[82:85], v[162:165], v[204:207], v[82:85]
	v_mfma_f32_16x16x32_bf16 v[74:77], v[170:173], v[204:207], v[74:77]
	v_mfma_f32_16x16x32_bf16 v[70:73], v[162:165], v[212:215], v[70:73]
	v_mfma_f32_16x16x32_bf16 v[66:69], v[170:173], v[212:215], v[66:69]
	v_mfma_f32_16x16x32_bf16 v[118:121], v[166:169], v[182:185], v[118:121]
	v_mfma_f32_16x16x32_bf16 v[110:113], v[174:177], v[182:185], v[110:113]
	v_mfma_f32_16x16x32_bf16 v[98:101], v[166:169], v[200:203], v[98:101]
	v_mfma_f32_16x16x32_bf16 v[90:93], v[174:177], v[200:203], v[90:93]
	v_mfma_f32_16x16x32_bf16 v[82:85], v[166:169], v[208:211], v[82:85]
	v_mfma_f32_16x16x32_bf16 v[74:77], v[174:177], v[208:211], v[74:77]
	v_mfma_f32_16x16x32_bf16 v[70:73], v[166:169], v[216:219], v[70:73]
	v_mfma_f32_16x16x32_bf16 v[66:69], v[174:177], v[216:219], v[66:69]
	s_setprio 0
	s_barrier
; #define PG8_STAGE(bufoff, gbase, voff) do { _Pragma("unroll") for (int _i = 0; _i < 2; ++_i) \
;         __builtin_amdgcn_global_load_lds((const unsigned*)((const char*)(gbase) + (voff)[_i]), (PG8_LAS unsigned*)(lds + (bufoff) + ldsw + _i * 8192), 16, 0, 0); } while (0)
; #define PG8_LDA(dst, b, h) do { _Pragma("unroll") for (int m = 0; m < 4; ++m) _Pragma("unroll") for (int k = 0; k < 2; ++k) dst[m][k] = *(const PG8_LAS bf16x8*)(lds + PG8_SA(b, h) + aoff + m * 2048 + k * 1024); } while (0)
; #define PG8_MMA(ai, bj, At, Bt) do { __builtin_amdgcn_s_setprio(1); _Pragma("unroll") for (int m = 0; m < 4; ++m) _Pragma("unroll") for (int n = 0; n < 2; ++n) _Pragma("unroll") for (int k = 0; k < 2; ++k) \
;         acc[ai][bj][m][n] = __builtin_amdgcn_mfma_f32_16x16x32_bf16(Bt[n][k], At[m][k], acc[ai][bj][m][n], 0, 0, 0); __builtin_amdgcn_s_setprio(0); } while (0)
; #define PG8_WAIT_V(n) asm volatile("s_waitcnt vmcnt(" #n ")" ::: "memory")
; #define PG8_WAIT_L(n) asm volatile("s_waitcnt lgkmcnt(" #n ")" ::: "memory")
; #define PG8_BAR __builtin_amdgcn_s_barrier()
; #define PG8_SCHED __builtin_amdgcn_sched_barrier(0)
; template <class Epi, class Sched, bool ALIGN_EPI = false, bool SP2 = false, bool ABLK = false, bool BBLK = false>
; __device__ __forceinline__ void gemm_phase(PG8_LAS unsigned char* lds, const Gemm g, const Sched& S, const Epi& E) {
;     ...
;         for (int t = 0; t < nt; t += 2) {
;             const bool last = (t == nt - 2);
;             const char* a1 = cA + (size_t)(t + 1) * kstepA;
;             const char* a2 = last ? nA : cA + (size_t)(t + 2) * kstepA; const char* b2 = last ? nB : cB + (size_t)(t + 2) * kstepB;
;             const char* a3 = a2 + kstepA; const char* b3 = b2 + kstepB;
;             if (last && has_next) S.a_ready(nxt);
;     ...
;             PG8_LDA(At, 1, 1); PG8_STAGE(PG8_SB(1, 0), b3, voffB); PG8_STAGE(PG8_SB(1, 1), b3 + hstepB, voffB); PG8_STAGE(PG8_SA(1, 0), a3, voffA);
;             PG8_WAIT_V(8); PG8_WAIT_L(0); PG8_BAR; PG8_MMA(1, 0, At, B0); PG8_MMA(1, 1, At, B1); PG8_BAR; PG8_SCHED;
	s_add_u32 s28, s26, 0x8000
	s_addc_u32 s29, s27, 0
	s_add_i32 s75, s75, s37
	v_lshl_add_u64 v[220:221], s[28:29], 0, v[134:135]
	s_mov_b32 m0, s75
	ds_read_b128 v[178:181], v149 offset:49152
	ds_read_b128 v[182:185], v149 offset:50176
	ds_read_b128 v[196:199], v149 offset:51200
	ds_read_b128 v[200:203], v149 offset:52224
	ds_read_b128 v[204:207], v149 offset:53248
	ds_read_b128 v[208:211], v149 offset:54272
	ds_read_b128 v[212:215], v149 offset:55296
	ds_read_b128 v[216:219], v149 offset:56320
	global_load_lds_dwordx4 v[220:221], off
	s_add_i32 m0, s75, 0x2000
	s_add_u32 s26, s26, 0xc000
	v_lshl_add_u64 v[220:221], s[28:29], 0, v[130:131]
	s_addc_u32 s27, s27, 0
	s_add_i32 s28, s80, s37
	global_load_lds_dwordx4 v[220:221], off
	v_lshl_add_u64 v[220:221], s[26:27], 0, v[134:135]
	s_mov_b32 m0, s28
	s_nop 0
	global_load_lds_dwordx4 v[220:221], off
	v_lshl_add_u64 v[220:221], s[26:27], 0, v[130:131]
	s_add_i32 m0, s28, 0x2000
	s_nop 0
	global_load_lds_dwordx4 v[220:221], off
	v_lshl_add_u64 v[220:221], s[24:25], 0, v[136:137]
	s_mov_b32 m0, s46
	s_nop 0
	global_load_lds_dwordx4 v[220:221], off
	v_lshl_add_u64 v[220:221], s[24:25], 0, v[132:133]
	s_mov_b32 m0, s47
	s_nop 0
	global_load_lds_dwordx4 v[220:221], off
	s_waitcnt vmcnt(8)
	s_waitcnt lgkmcnt(0)
	v_mfma_f32_16x16x32_bf16 v[62:65], v[142:145], v[178:181], v[62:65]
	v_mfma_f32_16x16x32_bf16 v[58:61], v[154:157], v[178:181], v[58:61]
	s_barrier
	s_setprio 1
	s_waitcnt lgkmcnt(0)
	v_mfma_f32_16x16x32_bf16 v[50:53], v[142:145], v[196:199], v[50:53]
	v_mfma_f32_16x16x32_bf16 v[42:45], v[154:157], v[196:199], v[42:45]
	v_mfma_f32_16x16x32_bf16 v[38:41], v[142:145], v[204:207], v[38:41]
	v_mfma_f32_16x16x32_bf16 v[30:33], v[154:157], v[204:207], v[30:33]
	v_mfma_f32_16x16x32_bf16 v[22:25], v[142:145], v[212:215], v[22:25]
	v_mfma_f32_16x16x32_bf16 v[14:17], v[154:157], v[212:215], v[14:17]
	v_mfma_f32_16x16x32_bf16 v[62:65], v[150:153], v[182:185], v[62:65]
	v_mfma_f32_16x16x32_bf16 v[58:61], v[158:161], v[182:185], v[58:61]
	v_mfma_f32_16x16x32_bf16 v[50:53], v[150:153], v[200:203], v[50:53]
	v_mfma_f32_16x16x32_bf16 v[42:45], v[158:161], v[200:203], v[42:45]
	v_mfma_f32_16x16x32_bf16 v[38:41], v[150:153], v[208:211], v[38:41]
	v_mfma_f32_16x16x32_bf16 v[30:33], v[158:161], v[208:211], v[30:33]
	v_mfma_f32_16x16x32_bf16 v[22:25], v[150:153], v[216:219], v[22:25]
	v_mfma_f32_16x16x32_bf16 v[14:17], v[158:161], v[216:219], v[14:17]
	s_setprio 0
	s_setprio 1
	v_mfma_f32_16x16x32_bf16 v[54:57], v[162:165], v[178:181], v[54:57]
	v_mfma_f32_16x16x32_bf16 v[46:49], v[170:173], v[178:181], v[46:49]
	v_mfma_f32_16x16x32_bf16 v[34:37], v[162:165], v[196:199], v[34:37]
	v_mfma_f32_16x16x32_bf16 v[26:29], v[170:173], v[196:199], v[26:29]
	v_mfma_f32_16x16x32_bf16 v[18:21], v[162:165], v[204:207], v[18:21]
	v_mfma_f32_16x16x32_bf16 v[10:13], v[170:173], v[204:207], v[10:13]
	v_mfma_f32_16x16x32_bf16 v[6:9], v[162:165], v[212:215], v[6:9]
	v_mfma_f32_16x16x32_bf16 v[2:5], v[170:173], v[212:215], v[2:5]
	v_mfma_f32_16x16x32_bf16 v[54:57], v[166:169], v[182:185], v[54:57]
	v_mfma_f32_16x16x32_bf16 v[46:49], v[174:177], v[182:185], v[46:49]
	v_mfma_f32_16x16x32_bf16 v[34:37], v[166:169], v[200:203], v[34:37]
	v_mfma_f32_16x16x32_bf16 v[26:29], v[174:177], v[200:203], v[26:29]
	v_mfma_f32_16x16x32_bf16 v[18:21], v[166:169], v[208:211], v[18:21]
	v_mfma_f32_16x16x32_bf16 v[10:13], v[174:177], v[208:211], v[10:13]
	v_mfma_f32_16x16x32_bf16 v[6:9], v[166:169], v[216:219], v[6:9]
	v_mfma_f32_16x16x32_bf16 v[2:5], v[174:177], v[216:219], v[2:5]
	s_setprio 0
	s_barrier
	s_add_i32 s73, s73, 2
	s_add_u32 s22, s22, 0x10000
	s_addc_u32 s23, s23, 0
	s_add_u32 s68, s68, 0x10000
	s_addc_u32 s72, s72, 0
	s_cmp_gt_u32 s73, 29
	s_cbranch_scc0 .LBB0_658
	s_and_b64 vcc, exec, s[8:9]
	s_cbranch_vccz .LBB0_661
	s_barrier

; #define PG8_STAGE(bufoff, gbase, voff) do { _Pragma("unroll") for (int _i = 0; _i < 2; ++_i) \
;         __builtin_amdgcn_global_load_lds((const unsigned*)((const char*)(gbase) + (voff)[_i]), (PG8_LAS unsigned*)(lds + (bufoff) + ldsw + _i * 8192), 16, 0, 0); } while (0)
; #define PG8_LDA(dst, b, h) do { _Pragma("unroll") for (int m = 0; m < 4; ++m) _Pragma("unroll") for (int k = 0; k < 2; ++k) dst[m][k] = *(const PG8_LAS bf16x8*)(lds + PG8_SA(b, h) + aoff + m * 2048 + k * 1024); } while (0)
; #define PG8_LDB(dst, b, h) do { _Pragma("unroll") for (int n = 0; n < 2; ++n) _Pragma("unroll") for (int k = 0; k < 2; ++k) dst[n][k] = *(const PG8_LAS bf16x8*)(lds + PG8_SB(b, h) + boff + n * 2048 + k * 1024); } while (0)
; #define PG8_MMA(ai, bj, At, Bt) do { __builtin_amdgcn_s_setprio(1); _Pragma("unroll") for (int m = 0; m < 4; ++m) _Pragma("unroll") for (int n = 0; n < 2; ++n) _Pragma("unroll") for (int k = 0; k < 2; ++k) \
;         acc[ai][bj][m][n] = __builtin_amdgcn_mfma_f32_16x16x32_bf16(Bt[n][k], At[m][k], acc[ai][bj][m][n], 0, 0, 0); __builtin_amdgcn_s_setprio(0); } while (0)
; #define PG8_WAIT_V(n) asm volatile("s_waitcnt vmcnt(" #n ")" ::: "memory")
; #define PG8_BAR __builtin_amdgcn_s_barrier()
; template <class Epi, class Sched, bool ALIGN_EPI = false, bool SP2 = false, bool ABLK = false, bool BBLK = false>
; __device__ __forceinline__ void gemm_phase(PG8_LAS unsigned char* lds, const Gemm g, const Sched& S, const Epi& E) {
;     ...
;             const bool last = (t == nt - 2);
;             const char* a1 = cA + (size_t)(t + 1) * kstepA;
;             const char* a2 = last ? nA : cA + (size_t)(t + 2) * kstepA; const char* b2 = last ? nB : cB + (size_t)(t + 2) * kstepB;
;             const char* a3 = a2 + kstepA; const char* b3 = b2 + kstepB;
;             if (last && has_next) S.a_ready(nxt);
;             if constexpr (SP2) {
;             PG8_LDB(B0, 0, 0); PG8_LDB(B1, 0, 1); PG8_SCHED; PG8_LDA(At, 0, 0); PG8_STAGE(PG8_SA(1, 1), a1 + hstepA, voffA);
;             PG8_WAIT_V(8); PG8_WAIT_L(0); PG8_BAR; PG8_MMA(0, 0, At, B0); PG8_MMA(0, 1, At, B1); PG8_BAR; PG8_SCHED;
;             PG8_LDA(At, 0, 1); PG8_STAGE(PG8_SB(0, 0), b2, voffB); PG8_STAGE(PG8_SB(0, 1), b2 + hstepB, voffB); PG8_STAGE(PG8_SA(0, 0), a2, voffA);
;             PG8_WAIT_V(8); PG8_WAIT_L(0); PG8_BAR; PG8_MMA(1, 0, At, B0); PG8_MMA(1, 1, At, B1); PG8_BAR; PG8_SCHED;
.LBB0_766:
	s_add_u32 s26, s24, 0xfff80080
	s_addc_u32 s27, s25, -1
	s_add_i32 s72, 0, 0x10000
	s_cmp_eq_u32 s68, 28
	s_cselect_b32 s29, s1, s27
	s_cselect_b32 s28, s11, s26
	v_add_u32_e32 v142, s72, v145
	s_cselect_b32 s27, s13, s65
	s_cselect_b32 s26, s15, s23
	s_add_i32 s75, 0, 0x14000
	ds_read_b128 v[148:151], v142
	ds_read_b128 v[152:155], v142 offset:1024
	ds_read_b128 v[156:159], v142 offset:2048
	ds_read_b128 v[160:163], v142 offset:3072
	v_add_u32_e32 v142, s75, v145
	ds_read_b128 v[164:167], v142
	ds_read_b128 v[168:171], v142 offset:1024
	ds_read_b128 v[172:175], v142 offset:2048
	ds_read_b128 v[176:179], v142 offset:3072
	v_lshl_add_u64 v[142:143], s[24:25], 0, v[138:139]
	s_add_i32 m0, s45, 0xc000
	ds_read_b128 v[180:183], v146
	ds_read_b128 v[196:199], v146 offset:1024
	ds_read_b128 v[200:203], v146 offset:2048
	ds_read_b128 v[204:207], v146 offset:3072
	ds_read_b128 v[208:211], v146 offset:4096
	ds_read_b128 v[212:215], v146 offset:5120
	ds_read_b128 v[216:219], v146 offset:6144
	ds_read_b128 v[220:223], v146 offset:7168
	global_load_lds_dwordx4 v[142:143], off
	v_lshl_add_u64 v[142:143], s[24:25], 0, v[140:141]
	s_add_i32 m0, s45, 0xe000
	s_nop 0
	global_load_lds_dwordx4 v[142:143], off
	s_waitcnt vmcnt(8)
	s_waitcnt lgkmcnt(0)
	v_mfma_f32_16x16x32_bf16 v[126:129], v[148:151], v[180:183], v[126:129]
	v_mfma_f32_16x16x32_bf16 v[122:125], v[156:159], v[180:183], v[122:125]
	s_barrier
	s_setprio 1
	s_waitcnt lgkmcnt(0)
	v_mfma_f32_16x16x32_bf16 v[114:117], v[148:151], v[200:203], v[114:117]
	v_mfma_f32_16x16x32_bf16 v[106:109], v[156:159], v[200:203], v[106:109]
	v_mfma_f32_16x16x32_bf16 v[98:101], v[148:151], v[208:211], v[98:101]
	v_mfma_f32_16x16x32_bf16 v[90:93], v[156:159], v[208:211], v[90:93]
	v_mfma_f32_16x16x32_bf16 v[82:85], v[148:151], v[216:219], v[82:85]
	v_mfma_f32_16x16x32_bf16 v[74:77], v[156:159], v[216:219], v[74:77]
	v_mfma_f32_16x16x32_bf16 v[126:129], v[152:155], v[196:199], v[126:129]
	v_mfma_f32_16x16x32_bf16 v[122:125], v[160:163], v[196:199], v[122:125]
	v_mfma_f32_16x16x32_bf16 v[114:117], v[152:155], v[204:207], v[114:117]
	v_mfma_f32_16x16x32_bf16 v[106:109], v[160:163], v[204:207], v[106:109]
	v_mfma_f32_16x16x32_bf16 v[98:101], v[152:155], v[212:215], v[98:101]
	v_mfma_f32_16x16x32_bf16 v[90:93], v[160:163], v[212:215], v[90:93]
	v_mfma_f32_16x16x32_bf16 v[82:85], v[152:155], v[220:223], v[82:85]
	v_mfma_f32_16x16x32_bf16 v[74:77], v[160:163], v[220:223], v[74:77]
	s_setprio 0
	s_setprio 1
	v_mfma_f32_16x16x32_bf16 v[118:121], v[164:167], v[180:183], v[118:121]
	v_mfma_f32_16x16x32_bf16 v[110:113], v[172:175], v[180:183], v[110:113]
	v_mfma_f32_16x16x32_bf16 v[102:105], v[164:167], v[200:203], v[102:105]
	v_mfma_f32_16x16x32_bf16 v[94:97], v[172:175], v[200:203], v[94:97]
	v_mfma_f32_16x16x32_bf16 v[86:89], v[164:167], v[208:211], v[86:89]
	v_mfma_f32_16x16x32_bf16 v[78:81], v[172:175], v[208:211], v[78:81]
	v_mfma_f32_16x16x32_bf16 v[70:73], v[164:167], v[216:219], v[70:73]
	v_mfma_f32_16x16x32_bf16 v[66:69], v[172:175], v[216:219], v[66:69]
	v_mfma_f32_16x16x32_bf16 v[118:121], v[168:171], v[196:199], v[118:121]
	v_mfma_f32_16x16x32_bf16 v[110:113], v[176:179], v[196:199], v[110:113]
	v_mfma_f32_16x16x32_bf16 v[102:105], v[168:171], v[204:207], v[102:105]
	v_mfma_f32_16x16x32_bf16 v[94:97], v[176:179], v[204:207], v[94:97]
	v_mfma_f32_16x16x32_bf16 v[86:89], v[168:171], v[212:215], v[86:89]
	v_mfma_f32_16x16x32_bf16 v[78:81], v[176:179], v[212:215], v[78:81]
	v_mfma_f32_16x16x32_bf16 v[70:73], v[168:171], v[220:223], v[70:73]
	v_mfma_f32_16x16x32_bf16 v[66:69], v[176:179], v[220:223], v[66:69]
	s_setprio 0
	s_barrier
	s_add_i32 s72, s72, s37
	v_lshl_add_u64 v[142:143], s[26:27], 0, v[134:135]
	s_mov_b32 m0, s72
	ds_read_b128 v[180:183], v146 offset:16384
	ds_read_b128 v[196:199], v146 offset:17408
	ds_read_b128 v[200:203], v146 offset:18432
	ds_read_b128 v[204:207], v146 offset:19456
	ds_read_b128 v[208:211], v146 offset:20480
	ds_read_b128 v[212:215], v146 offset:21504
	ds_read_b128 v[216:219], v146 offset:22528
	ds_read_b128 v[220:223], v146 offset:23552
	global_load_lds_dwordx4 v[142:143], off
	s_add_i32 m0, s72, 0x2000
	s_add_u32 s72, s26, 0x80000
	v_lshl_add_u64 v[184:185], s[26:27], 0, v[130:131]
	s_addc_u32 s73, s27, 0
	s_add_i32 s75, s75, s37
	global_load_lds_dwordx4 v[184:185], off
	v_lshl_add_u64 v[224:225], s[72:73], 0, v[134:135]
	s_mov_b32 m0, s75
	v_lshl_add_u64 v[226:227], s[28:29], 0, v[132:133]
	global_load_lds_dwordx4 v[224:225], off
	v_lshl_add_u64 v[224:225], s[72:73], 0, v[130:131]
	s_add_i32 m0, s75, 0x2000
	s_nop 0
	global_load_lds_dwordx4 v[224:225], off
	v_lshl_add_u64 v[224:225], s[28:29], 0, v[136:137]
	s_mov_b32 m0, s45
	s_nop 0
	global_load_lds_dwordx4 v[224:225], off
	s_mov_b32 m0, s46
	s_nop 0
	global_load_lds_dwordx4 v[226:227], off
	s_waitcnt vmcnt(8)
	s_waitcnt lgkmcnt(0)
	v_mfma_f32_16x16x32_bf16 v[62:65], v[148:151], v[180:183], v[62:65]
	v_mfma_f32_16x16x32_bf16 v[58:61], v[156:159], v[180:183], v[58:61]
	s_barrier
; #define PG8_STAGE(bufoff, gbase, voff) do { _Pragma("unroll") for (int _i = 0; _i < 2; ++_i) \
;         __builtin_amdgcn_global_load_lds((const unsigned*)((const char*)(gbase) + (voff)[_i]), (PG8_LAS unsigned*)(lds + (bufoff) + ldsw + _i * 8192), 16, 0, 0); } while (0)
; #define PG8_LDA(dst, b, h) do { _Pragma("unroll") for (int m = 0; m < 4; ++m) _Pragma("unroll") for (int k = 0; k < 2; ++k) dst[m][k] = *(const PG8_LAS bf16x8*)(lds + PG8_SA(b, h) + aoff + m * 2048 + k * 1024); } while (0)
; #define PG8_LDB(dst, b, h) do { _Pragma("unroll") for (int n = 0; n < 2; ++n) _Pragma("unroll") for (int k = 0; k < 2; ++k) dst[n][k] = *(const PG8_LAS bf16x8*)(lds + PG8_SB(b, h) + boff + n * 2048 + k * 1024); } while (0)
; #define PG8_MMA(ai, bj, At, Bt) do { __builtin_amdgcn_s_setprio(1); _Pragma("unroll") for (int m = 0; m < 4; ++m) _Pragma("unroll") for (int n = 0; n < 2; ++n) _Pragma("unroll") for (int k = 0; k < 2; ++k) \
;         acc[ai][bj][m][n] = __builtin_amdgcn_mfma_f32_16x16x32_bf16(Bt[n][k], At[m][k], acc[ai][bj][m][n], 0, 0, 0); __builtin_amdgcn_s_setprio(0); } while (0)
; #define PG8_WAIT_V(n) asm volatile("s_waitcnt vmcnt(" #n ")" ::: "memory")
; #define PG8_WAIT_L(n) asm volatile("s_waitcnt lgkmcnt(" #n ")" ::: "memory")
; #define PG8_BAR __builtin_amdgcn_s_barrier()
; #define PG8_SCHED __builtin_amdgcn_sched_barrier(0)
; template <class Epi, class Sched, bool ALIGN_EPI = false, bool SP2 = false, bool ABLK = false, bool BBLK = false>
; __device__ __forceinline__ void gemm_phase(PG8_LAS unsigned char* lds, const Gemm g, const Sched& S, const Epi& E) {
;     ...
;             PG8_WAIT_V(8); PG8_WAIT_L(0); PG8_BAR; PG8_MMA(1, 0, At, B0); PG8_MMA(1, 1, At, B1); PG8_BAR; PG8_SCHED;
;             PG8_LDB(B0, 1, 0); PG8_LDB(B1, 1, 1); PG8_SCHED; PG8_LDA(At, 1, 0); PG8_STAGE(PG8_SA(0, 1), a2 + hstepA, voffA);
;             PG8_WAIT_V(8); PG8_WAIT_L(0); PG8_BAR; PG8_MMA(0, 0, At, B0); PG8_MMA(0, 1, At, B1); PG8_BAR; PG8_SCHED;
	s_setprio 1
	s_waitcnt lgkmcnt(0)
	v_mfma_f32_16x16x32_bf16 v[50:53], v[148:151], v[200:203], v[50:53]
	v_mfma_f32_16x16x32_bf16 v[42:45], v[156:159], v[200:203], v[42:45]
	v_mfma_f32_16x16x32_bf16 v[34:37], v[148:151], v[208:211], v[34:37]
	v_mfma_f32_16x16x32_bf16 v[26:29], v[156:159], v[208:211], v[26:29]
	v_mfma_f32_16x16x32_bf16 v[18:21], v[148:151], v[216:219], v[18:21]
	v_mfma_f32_16x16x32_bf16 v[10:13], v[156:159], v[216:219], v[10:13]
	v_mfma_f32_16x16x32_bf16 v[62:65], v[152:155], v[196:199], v[62:65]
	v_mfma_f32_16x16x32_bf16 v[58:61], v[160:163], v[196:199], v[58:61]
	v_mfma_f32_16x16x32_bf16 v[50:53], v[152:155], v[204:207], v[50:53]
	v_mfma_f32_16x16x32_bf16 v[42:45], v[160:163], v[204:207], v[42:45]
	v_mfma_f32_16x16x32_bf16 v[34:37], v[152:155], v[212:215], v[34:37]
	v_mfma_f32_16x16x32_bf16 v[26:29], v[160:163], v[212:215], v[26:29]
	v_mfma_f32_16x16x32_bf16 v[18:21], v[152:155], v[220:223], v[18:21]
	v_mfma_f32_16x16x32_bf16 v[10:13], v[160:163], v[220:223], v[10:13]
	s_setprio 0
	s_setprio 1
	v_mfma_f32_16x16x32_bf16 v[54:57], v[164:167], v[180:183], v[54:57]
	v_mfma_f32_16x16x32_bf16 v[46:49], v[172:175], v[180:183], v[46:49]
	v_mfma_f32_16x16x32_bf16 v[38:41], v[164:167], v[200:203], v[38:41]
	v_mfma_f32_16x16x32_bf16 v[30:33], v[172:175], v[200:203], v[30:33]
	v_mfma_f32_16x16x32_bf16 v[22:25], v[164:167], v[208:211], v[22:25]
	v_mfma_f32_16x16x32_bf16 v[14:17], v[172:175], v[208:211], v[14:17]
	v_mfma_f32_16x16x32_bf16 v[6:9], v[164:167], v[216:219], v[6:9]
	v_mfma_f32_16x16x32_bf16 v[2:5], v[172:175], v[216:219], v[2:5]
	v_mfma_f32_16x16x32_bf16 v[54:57], v[168:171], v[196:199], v[54:57]
	v_mfma_f32_16x16x32_bf16 v[46:49], v[176:179], v[196:199], v[46:49]
	v_mfma_f32_16x16x32_bf16 v[38:41], v[168:171], v[204:207], v[38:41]
	v_mfma_f32_16x16x32_bf16 v[30:33], v[176:179], v[204:207], v[30:33]
	v_mfma_f32_16x16x32_bf16 v[22:25], v[168:171], v[212:215], v[22:25]
	v_mfma_f32_16x16x32_bf16 v[14:17], v[176:179], v[212:215], v[14:17]
	v_mfma_f32_16x16x32_bf16 v[6:9], v[168:171], v[220:223], v[6:9]
	v_mfma_f32_16x16x32_bf16 v[2:5], v[176:179], v[220:223], v[2:5]
	s_setprio 0
	s_barrier
	s_add_i32 s72, 0, 0x18000
	v_add_u32_e32 v147, s72, v145
	s_add_i32 s73, 0, 0x1c000
	ds_read_b128 v[148:151], v147
	ds_read_b128 v[152:155], v147 offset:1024
	ds_read_b128 v[156:159], v147 offset:2048
	ds_read_b128 v[160:163], v147 offset:3072
	v_add_u32_e32 v147, s73, v145
	ds_read_b128 v[164:167], v147
	ds_read_b128 v[168:171], v147 offset:1024
	ds_read_b128 v[172:175], v147 offset:2048
	ds_read_b128 v[176:179], v147 offset:3072
	s_add_u32 s28, s28, 0x80000
	s_addc_u32 s29, s29, 0
	s_mov_b32 m0, s47
	v_lshl_add_u64 v[228:229], s[28:29], 0, v[136:137]
	ds_read_b128 v[180:183], v146 offset:32768
	ds_read_b128 v[196:199], v146 offset:33792
	ds_read_b128 v[200:203], v146 offset:34816
	ds_read_b128 v[204:207], v146 offset:35840
	ds_read_b128 v[208:211], v146 offset:36864
	ds_read_b128 v[212:215], v146 offset:37888
	ds_read_b128 v[216:219], v146 offset:38912
	ds_read_b128 v[220:223], v146 offset:39936
	global_load_lds_dwordx4 v[228:229], off
	v_lshl_add_u64 v[228:229], s[28:29], 0, v[132:133]
	s_mov_b32 m0, s50
	s_nop 0
	global_load_lds_dwordx4 v[228:229], off
	s_waitcnt vmcnt(8)
	s_waitcnt lgkmcnt(0)
	v_mfma_f32_16x16x32_bf16 v[126:129], v[148:151], v[180:183], v[126:129]
	v_mfma_f32_16x16x32_bf16 v[122:125], v[156:159], v[180:183], v[122:125]
	s_barrier
	s_setprio 1
	s_waitcnt lgkmcnt(0)
	v_mfma_f32_16x16x32_bf16 v[114:117], v[148:151], v[200:203], v[114:117]
	v_mfma_f32_16x16x32_bf16 v[106:109], v[156:159], v[200:203], v[106:109]
	v_mfma_f32_16x16x32_bf16 v[98:101], v[148:151], v[208:211], v[98:101]
	v_mfma_f32_16x16x32_bf16 v[90:93], v[156:159], v[208:211], v[90:93]
	v_mfma_f32_16x16x32_bf16 v[82:85], v[148:151], v[216:219], v[82:85]
	v_mfma_f32_16x16x32_bf16 v[74:77], v[156:159], v[216:219], v[74:77]
	v_mfma_f32_16x16x32_bf16 v[126:129], v[152:155], v[196:199], v[126:129]
	v_mfma_f32_16x16x32_bf16 v[122:125], v[160:163], v[196:199], v[122:125]
	v_mfma_f32_16x16x32_bf16 v[114:117], v[152:155], v[204:207], v[114:117]
	v_mfma_f32_16x16x32_bf16 v[106:109], v[160:163], v[204:207], v[106:109]
	v_mfma_f32_16x16x32_bf16 v[98:101], v[152:155], v[212:215], v[98:101]
	v_mfma_f32_16x16x32_bf16 v[90:93], v[160:163], v[212:215], v[90:93]
	v_mfma_f32_16x16x32_bf16 v[82:85], v[152:155], v[220:223], v[82:85]
	v_mfma_f32_16x16x32_bf16 v[74:77], v[160:163], v[220:223], v[74:77]
	s_setprio 0
	s_setprio 1
	v_mfma_f32_16x16x32_bf16 v[118:121], v[164:167], v[180:183], v[118:121]
	v_mfma_f32_16x16x32_bf16 v[110:113], v[172:175], v[180:183], v[110:113]
	v_mfma_f32_16x16x32_bf16 v[102:105], v[164:167], v[200:203], v[102:105]
	v_mfma_f32_16x16x32_bf16 v[94:97], v[172:175], v[200:203], v[94:97]
	v_mfma_f32_16x16x32_bf16 v[86:89], v[164:167], v[208:211], v[86:89]
	v_mfma_f32_16x16x32_bf16 v[78:81], v[172:175], v[208:211], v[78:81]
	v_mfma_f32_16x16x32_bf16 v[70:73], v[164:167], v[216:219], v[70:73]
	v_mfma_f32_16x16x32_bf16 v[66:69], v[172:175], v[216:219], v[66:69]
	v_mfma_f32_16x16x32_bf16 v[118:121], v[168:171], v[196:199], v[118:121]
	v_mfma_f32_16x16x32_bf16 v[110:113], v[176:179], v[196:199], v[110:113]
	v_mfma_f32_16x16x32_bf16 v[102:105], v[168:171], v[204:207], v[102:105]
	v_mfma_f32_16x16x32_bf16 v[94:97], v[176:179], v[204:207], v[94:97]
	v_mfma_f32_16x16x32_bf16 v[86:89], v[168:171], v[212:215], v[86:89]
	v_mfma_f32_16x16x32_bf16 v[78:81], v[176:179], v[212:215], v[78:81]
	v_mfma_f32_16x16x32_bf16 v[70:73], v[168:171], v[220:223], v[70:73]
	v_mfma_f32_16x16x32_bf16 v[66:69], v[176:179], v[220:223], v[66:69]
	s_setprio 0
	s_barrier
; #define PG8_STAGE(bufoff, gbase, voff) do { _Pragma("unroll") for (int _i = 0; _i < 2; ++_i) \
;         __builtin_amdgcn_global_load_lds((const unsigned*)((const char*)(gbase) + (voff)[_i]), (PG8_LAS unsigned*)(lds + (bufoff) + ldsw + _i * 8192), 16, 0, 0); } while (0)
; #define PG8_LDA(dst, b, h) do { _Pragma("unroll") for (int m = 0; m < 4; ++m) _Pragma("unroll") for (int k = 0; k < 2; ++k) dst[m][k] = *(const PG8_LAS bf16x8*)(lds + PG8_SA(b, h) + aoff + m * 2048 + k * 1024); } while (0)
; #define PG8_MMA(ai, bj, At, Bt) do { __builtin_amdgcn_s_setprio(1); _Pragma("unroll") for (int m = 0; m < 4; ++m) _Pragma("unroll") for (int n = 0; n < 2; ++n) _Pragma("unroll") for (int k = 0; k < 2; ++k) \
;         acc[ai][bj][m][n] = __builtin_amdgcn_mfma_f32_16x16x32_bf16(Bt[n][k], At[m][k], acc[ai][bj][m][n], 0, 0, 0); __builtin_amdgcn_s_setprio(0); } while (0)
; #define PG8_WAIT_V(n) asm volatile("s_waitcnt vmcnt(" #n ")" ::: "memory")
; #define PG8_WAIT_L(n) asm volatile("s_waitcnt lgkmcnt(" #n ")" ::: "memory")
; #define PG8_BAR __builtin_amdgcn_s_barrier()
; #define PG8_SCHED __builtin_amdgcn_sched_barrier(0)
; template <class Epi, class Sched, bool ALIGN_EPI = false, bool SP2 = false, bool ABLK = false, bool BBLK = false>
; __device__ __forceinline__ void gemm_phase(PG8_LAS unsigned char* lds, const Gemm g, const Sched& S, const Epi& E) {
;     ...
;             PG8_LDA(At, 1, 1); PG8_STAGE(PG8_SB(1, 0), b3, voffB); PG8_STAGE(PG8_SB(1, 1), b3 + hstepB, voffB); PG8_STAGE(PG8_SA(1, 0), a3, voffA);
;             PG8_WAIT_V(8); PG8_WAIT_L(0); PG8_BAR; PG8_MMA(1, 0, At, B0); PG8_MMA(1, 1, At, B1); PG8_BAR; PG8_SCHED;
;     ...
;         if constexpr (ALIGN_EPI) { if (wr == 0) PG8_BAR; }
	s_add_i32 s28, s72, s37
	v_lshl_add_u64 v[142:143], v[142:143], 0, s[62:63]
	s_mov_b32 m0, s28
	ds_read_b128 v[180:183], v146 offset:49152
	ds_read_b128 v[196:199], v146 offset:50176
	ds_read_b128 v[200:203], v146 offset:51200
	ds_read_b128 v[204:207], v146 offset:52224
	ds_read_b128 v[208:211], v146 offset:53248
	ds_read_b128 v[212:215], v146 offset:54272
	ds_read_b128 v[216:219], v146 offset:55296
	ds_read_b128 v[220:223], v146 offset:56320
	global_load_lds_dwordx4 v[142:143], off
	s_add_i32 m0, s28, 0x2000
	s_add_u32 s26, s26, 0x80080
	v_lshl_add_u64 v[142:143], v[184:185], 0, s[62:63]
	s_addc_u32 s27, s27, 0
	s_add_i32 s28, s73, s37
	global_load_lds_dwordx4 v[142:143], off
	v_lshl_add_u64 v[142:143], s[26:27], 0, v[134:135]
	s_mov_b32 m0, s28
	s_nop 0
	global_load_lds_dwordx4 v[142:143], off
	v_lshl_add_u64 v[142:143], s[26:27], 0, v[130:131]
	s_add_i32 m0, s28, 0x2000
	s_nop 0
	global_load_lds_dwordx4 v[142:143], off
	v_lshl_add_u64 v[142:143], v[224:225], 0, s[62:63]
	s_mov_b32 m0, s53
	s_nop 0
	global_load_lds_dwordx4 v[142:143], off
	v_lshl_add_u64 v[142:143], v[226:227], 0, s[62:63]
	s_mov_b32 m0, s56
	s_nop 0
	global_load_lds_dwordx4 v[142:143], off
	s_waitcnt vmcnt(8)
	s_waitcnt lgkmcnt(0)
	v_mfma_f32_16x16x32_bf16 v[62:65], v[148:151], v[180:183], v[62:65]
	v_mfma_f32_16x16x32_bf16 v[58:61], v[156:159], v[180:183], v[58:61]
	s_barrier
	s_setprio 1
	s_waitcnt lgkmcnt(0)
	v_mfma_f32_16x16x32_bf16 v[50:53], v[148:151], v[200:203], v[50:53]
	v_mfma_f32_16x16x32_bf16 v[42:45], v[156:159], v[200:203], v[42:45]
	v_mfma_f32_16x16x32_bf16 v[34:37], v[148:151], v[208:211], v[34:37]
	v_mfma_f32_16x16x32_bf16 v[26:29], v[156:159], v[208:211], v[26:29]
	v_mfma_f32_16x16x32_bf16 v[18:21], v[148:151], v[216:219], v[18:21]
	v_mfma_f32_16x16x32_bf16 v[10:13], v[156:159], v[216:219], v[10:13]
	v_mfma_f32_16x16x32_bf16 v[62:65], v[152:155], v[196:199], v[62:65]
	v_mfma_f32_16x16x32_bf16 v[58:61], v[160:163], v[196:199], v[58:61]
	v_mfma_f32_16x16x32_bf16 v[50:53], v[152:155], v[204:207], v[50:53]
	v_mfma_f32_16x16x32_bf16 v[42:45], v[160:163], v[204:207], v[42:45]
	v_mfma_f32_16x16x32_bf16 v[34:37], v[152:155], v[212:215], v[34:37]
	v_mfma_f32_16x16x32_bf16 v[26:29], v[160:163], v[212:215], v[26:29]
	v_mfma_f32_16x16x32_bf16 v[18:21], v[152:155], v[220:223], v[18:21]
	v_mfma_f32_16x16x32_bf16 v[10:13], v[160:163], v[220:223], v[10:13]
	s_setprio 0
	s_setprio 1
	v_mfma_f32_16x16x32_bf16 v[54:57], v[164:167], v[180:183], v[54:57]
	v_mfma_f32_16x16x32_bf16 v[46:49], v[172:175], v[180:183], v[46:49]
	v_mfma_f32_16x16x32_bf16 v[38:41], v[164:167], v[200:203], v[38:41]
	v_mfma_f32_16x16x32_bf16 v[30:33], v[172:175], v[200:203], v[30:33]
	v_mfma_f32_16x16x32_bf16 v[22:25], v[164:167], v[208:211], v[22:25]
	v_mfma_f32_16x16x32_bf16 v[14:17], v[172:175], v[208:211], v[14:17]
	v_mfma_f32_16x16x32_bf16 v[6:9], v[164:167], v[216:219], v[6:9]
	v_mfma_f32_16x16x32_bf16 v[2:5], v[172:175], v[216:219], v[2:5]
	v_mfma_f32_16x16x32_bf16 v[54:57], v[168:171], v[196:199], v[54:57]
	v_mfma_f32_16x16x32_bf16 v[46:49], v[176:179], v[196:199], v[46:49]
	v_mfma_f32_16x16x32_bf16 v[38:41], v[168:171], v[204:207], v[38:41]
	v_mfma_f32_16x16x32_bf16 v[30:33], v[176:179], v[204:207], v[30:33]
	v_mfma_f32_16x16x32_bf16 v[22:25], v[168:171], v[212:215], v[22:25]
	v_mfma_f32_16x16x32_bf16 v[14:17], v[176:179], v[212:215], v[14:17]
	v_mfma_f32_16x16x32_bf16 v[6:9], v[168:171], v[220:223], v[6:9]
	v_mfma_f32_16x16x32_bf16 v[2:5], v[176:179], v[220:223], v[2:5]
	s_setprio 0
	s_barrier
	s_add_i32 s68, s68, 2
	s_add_u32 s24, s24, 0x100
	s_addc_u32 s25, s25, 0
	s_add_u32 s23, s23, 0x100
	s_addc_u32 s65, s65, 0
	s_cmp_gt_u32 s68, 29
	s_cbranch_scc0 .LBB0_766
	s_and_b64 vcc, exec, s[8:9]
	s_cbranch_vccz .LBB0_769
	s_barrier

; #define PG8_STAGE(bufoff, gbase, voff) do { _Pragma("unroll") for (int _i = 0; _i < 2; ++_i) \
;         __builtin_amdgcn_global_load_lds((const unsigned*)((const char*)(gbase) + (voff)[_i]), (PG8_LAS unsigned*)(lds + (bufoff) + ldsw + _i * 8192), 16, 0, 0); } while (0)
; #define PG8_LDA(dst, b, h) do { _Pragma("unroll") for (int m = 0; m < 4; ++m) _Pragma("unroll") for (int k = 0; k < 2; ++k) dst[m][k] = *(const PG8_LAS bf16x8*)(lds + PG8_SA(b, h) + aoff + m * 2048 + k * 1024); } while (0)
; #define PG8_LDB(dst, b, h) do { _Pragma("unroll") for (int n = 0; n < 2; ++n) _Pragma("unroll") for (int k = 0; k < 2; ++k) dst[n][k] = *(const PG8_LAS bf16x8*)(lds + PG8_SB(b, h) + boff + n * 2048 + k * 1024); } while (0)
; #define PG8_MMA(ai, bj, At, Bt) do { __builtin_amdgcn_s_setprio(1); _Pragma("unroll") for (int m = 0; m < 4; ++m) _Pragma("unroll") for (int n = 0; n < 2; ++n) _Pragma("unroll") for (int k = 0; k < 2; ++k) \
;         acc[ai][bj][m][n] = __builtin_amdgcn_mfma_f32_16x16x32_bf16(Bt[n][k], At[m][k], acc[ai][bj][m][n], 0, 0, 0); __builtin_amdgcn_s_setprio(0); } while (0)
; #define PG8_WAIT_V(n) asm volatile("s_waitcnt vmcnt(" #n ")" ::: "memory")
; #define PG8_BAR __builtin_amdgcn_s_barrier()
; template <class Epi, class Sched, bool ALIGN_EPI = false, bool SP2 = false, bool ABLK = false, bool BBLK = false>
; __device__ __forceinline__ void gemm_phase(PG8_LAS unsigned char* lds, const Gemm g, const Sched& S, const Epi& E) {
;     ...
;             const bool last = (t == nt - 2);
;             const char* a1 = cA + (size_t)(t + 1) * kstepA;
;             const char* a2 = last ? nA : cA + (size_t)(t + 2) * kstepA; const char* b2 = last ? nB : cB + (size_t)(t + 2) * kstepB;
;             const char* a3 = a2 + kstepA; const char* b3 = b2 + kstepB;
;             if (last && has_next) S.a_ready(nxt);
;             if constexpr (SP2) {
;             PG8_LDB(B0, 0, 0); PG8_LDB(B1, 0, 1); PG8_SCHED; PG8_LDA(At, 0, 0); PG8_STAGE(PG8_SA(1, 1), a1 + hstepA, voffA);
;             PG8_WAIT_V(8); PG8_WAIT_L(0); PG8_BAR; PG8_MMA(0, 0, At, B0); PG8_MMA(0, 1, At, B1); PG8_BAR; PG8_SCHED;
;             PG8_LDA(At, 0, 1); PG8_STAGE(PG8_SB(0, 0), b2, voffB); PG8_STAGE(PG8_SB(0, 1), b2 + hstepB, voffB); PG8_STAGE(PG8_SA(0, 0), a2, voffA);
;             PG8_WAIT_V(8); PG8_WAIT_L(0); PG8_BAR; PG8_MMA(1, 0, At, B0); PG8_MMA(1, 1, At, B1); PG8_BAR; PG8_SCHED;
.LBB0_790:
	s_add_u32 s26, s24, 0xfff80080
	s_addc_u32 s27, s25, -1
	s_add_i32 s51, 0, 0x10000
	s_cmp_eq_u32 s81, 28
	s_cselect_b32 s29, s1, s27
	s_cselect_b32 s28, s11, s26
	v_add_u32_e32 v142, s51, v145
	s_cselect_b32 s27, s13, s73
	s_cselect_b32 s26, s15, s23
	s_add_i32 s75, 0, 0x14000
	ds_read_b128 v[148:151], v142
	ds_read_b128 v[152:155], v142 offset:1024
	ds_read_b128 v[156:159], v142 offset:2048
	ds_read_b128 v[160:163], v142 offset:3072
	v_add_u32_e32 v142, s75, v145
	ds_read_b128 v[164:167], v142
	ds_read_b128 v[168:171], v142 offset:1024
	ds_read_b128 v[172:175], v142 offset:2048
	ds_read_b128 v[176:179], v142 offset:3072
	v_lshl_add_u64 v[142:143], s[24:25], 0, v[138:139]
	s_add_i32 m0, s46, 0xc000
	ds_read_b128 v[180:183], v146
	ds_read_b128 v[196:199], v146 offset:1024
	ds_read_b128 v[200:203], v146 offset:2048
	ds_read_b128 v[204:207], v146 offset:3072
	ds_read_b128 v[208:211], v146 offset:4096
	ds_read_b128 v[212:215], v146 offset:5120
	ds_read_b128 v[216:219], v146 offset:6144
	ds_read_b128 v[220:223], v146 offset:7168
	global_load_lds_dwordx4 v[142:143], off
	v_lshl_add_u64 v[142:143], s[24:25], 0, v[140:141]
	s_add_i32 m0, s46, 0xe000
	s_nop 0
	global_load_lds_dwordx4 v[142:143], off
	s_waitcnt vmcnt(8)
	s_waitcnt lgkmcnt(0)
	v_mfma_f32_16x16x32_bf16 v[126:129], v[148:151], v[180:183], v[126:129]
	v_mfma_f32_16x16x32_bf16 v[122:125], v[156:159], v[180:183], v[122:125]
	s_barrier
	s_setprio 1
	s_waitcnt lgkmcnt(0)
	v_mfma_f32_16x16x32_bf16 v[114:117], v[148:151], v[200:203], v[114:117]
	v_mfma_f32_16x16x32_bf16 v[106:109], v[156:159], v[200:203], v[106:109]
	v_mfma_f32_16x16x32_bf16 v[98:101], v[148:151], v[208:211], v[98:101]
	v_mfma_f32_16x16x32_bf16 v[90:93], v[156:159], v[208:211], v[90:93]
	v_mfma_f32_16x16x32_bf16 v[82:85], v[148:151], v[216:219], v[82:85]
	v_mfma_f32_16x16x32_bf16 v[74:77], v[156:159], v[216:219], v[74:77]
	v_mfma_f32_16x16x32_bf16 v[126:129], v[152:155], v[196:199], v[126:129]
	v_mfma_f32_16x16x32_bf16 v[122:125], v[160:163], v[196:199], v[122:125]
	v_mfma_f32_16x16x32_bf16 v[114:117], v[152:155], v[204:207], v[114:117]
	v_mfma_f32_16x16x32_bf16 v[106:109], v[160:163], v[204:207], v[106:109]
	v_mfma_f32_16x16x32_bf16 v[98:101], v[152:155], v[212:215], v[98:101]
	v_mfma_f32_16x16x32_bf16 v[90:93], v[160:163], v[212:215], v[90:93]
	v_mfma_f32_16x16x32_bf16 v[82:85], v[152:155], v[220:223], v[82:85]
	v_mfma_f32_16x16x32_bf16 v[74:77], v[160:163], v[220:223], v[74:77]
	s_setprio 0
	s_setprio 1
	v_mfma_f32_16x16x32_bf16 v[118:121], v[164:167], v[180:183], v[118:121]
	v_mfma_f32_16x16x32_bf16 v[110:113], v[172:175], v[180:183], v[110:113]
	v_mfma_f32_16x16x32_bf16 v[102:105], v[164:167], v[200:203], v[102:105]
	v_mfma_f32_16x16x32_bf16 v[94:97], v[172:175], v[200:203], v[94:97]
	v_mfma_f32_16x16x32_bf16 v[86:89], v[164:167], v[208:211], v[86:89]
	v_mfma_f32_16x16x32_bf16 v[78:81], v[172:175], v[208:211], v[78:81]
	v_mfma_f32_16x16x32_bf16 v[70:73], v[164:167], v[216:219], v[70:73]
	v_mfma_f32_16x16x32_bf16 v[66:69], v[172:175], v[216:219], v[66:69]
	v_mfma_f32_16x16x32_bf16 v[118:121], v[168:171], v[196:199], v[118:121]
	v_mfma_f32_16x16x32_bf16 v[110:113], v[176:179], v[196:199], v[110:113]
	v_mfma_f32_16x16x32_bf16 v[102:105], v[168:171], v[204:207], v[102:105]
	v_mfma_f32_16x16x32_bf16 v[94:97], v[176:179], v[204:207], v[94:97]
	v_mfma_f32_16x16x32_bf16 v[86:89], v[168:171], v[212:215], v[86:89]
	v_mfma_f32_16x16x32_bf16 v[78:81], v[176:179], v[212:215], v[78:81]
	v_mfma_f32_16x16x32_bf16 v[70:73], v[168:171], v[220:223], v[70:73]
	v_mfma_f32_16x16x32_bf16 v[66:69], v[176:179], v[220:223], v[66:69]
	s_setprio 0
	s_barrier
	s_add_i32 s51, s51, s35
	v_lshl_add_u64 v[142:143], s[26:27], 0, v[132:133]
	s_mov_b32 m0, s51
	ds_read_b128 v[180:183], v146 offset:16384
	ds_read_b128 v[196:199], v146 offset:17408
	ds_read_b128 v[200:203], v146 offset:18432
	ds_read_b128 v[204:207], v146 offset:19456
	ds_read_b128 v[208:211], v146 offset:20480
	ds_read_b128 v[212:215], v146 offset:21504
	ds_read_b128 v[216:219], v146 offset:22528
	ds_read_b128 v[220:223], v146 offset:23552
	global_load_lds_dwordx4 v[142:143], off
	s_add_i32 m0, s51, 0x2000
	s_add_u32 s82, s26, 0x80000
	v_lshl_add_u64 v[184:185], s[26:27], 0, v[136:137]
	s_addc_u32 s83, s27, 0
	s_add_i32 s51, s75, s35
	global_load_lds_dwordx4 v[184:185], off
	v_lshl_add_u64 v[224:225], s[82:83], 0, v[132:133]
	s_mov_b32 m0, s51
	v_lshl_add_u64 v[226:227], s[28:29], 0, v[134:135]
	global_load_lds_dwordx4 v[224:225], off
	v_lshl_add_u64 v[224:225], s[82:83], 0, v[136:137]
	s_add_i32 m0, s51, 0x2000
	s_nop 0
	global_load_lds_dwordx4 v[224:225], off
	v_lshl_add_u64 v[224:225], s[28:29], 0, v[130:131]
	s_mov_b32 m0, s46
	s_nop 0
	global_load_lds_dwordx4 v[224:225], off
	s_mov_b32 m0, s47
	s_nop 0
	global_load_lds_dwordx4 v[226:227], off
	s_waitcnt vmcnt(8)
	s_waitcnt lgkmcnt(0)
	v_mfma_f32_16x16x32_bf16 v[62:65], v[148:151], v[180:183], v[62:65]
	v_mfma_f32_16x16x32_bf16 v[58:61], v[156:159], v[180:183], v[58:61]
	s_barrier
; #define PG8_STAGE(bufoff, gbase, voff) do { _Pragma("unroll") for (int _i = 0; _i < 2; ++_i) \
;         __builtin_amdgcn_global_load_lds((const unsigned*)((const char*)(gbase) + (voff)[_i]), (PG8_LAS unsigned*)(lds + (bufoff) + ldsw + _i * 8192), 16, 0, 0); } while (0)
; #define PG8_LDA(dst, b, h) do { _Pragma("unroll") for (int m = 0; m < 4; ++m) _Pragma("unroll") for (int k = 0; k < 2; ++k) dst[m][k] = *(const PG8_LAS bf16x8*)(lds + PG8_SA(b, h) + aoff + m * 2048 + k * 1024); } while (0)
; #define PG8_LDB(dst, b, h) do { _Pragma("unroll") for (int n = 0; n < 2; ++n) _Pragma("unroll") for (int k = 0; k < 2; ++k) dst[n][k] = *(const PG8_LAS bf16x8*)(lds + PG8_SB(b, h) + boff + n * 2048 + k * 1024); } while (0)
; #define PG8_MMA(ai, bj, At, Bt) do { __builtin_amdgcn_s_setprio(1); _Pragma("unroll") for (int m = 0; m < 4; ++m) _Pragma("unroll") for (int n = 0; n < 2; ++n) _Pragma("unroll") for (int k = 0; k < 2; ++k) \
;         acc[ai][bj][m][n] = __builtin_amdgcn_mfma_f32_16x16x32_bf16(Bt[n][k], At[m][k], acc[ai][bj][m][n], 0, 0, 0); __builtin_amdgcn_s_setprio(0); } while (0)
; #define PG8_WAIT_V(n) asm volatile("s_waitcnt vmcnt(" #n ")" ::: "memory")
; #define PG8_WAIT_L(n) asm volatile("s_waitcnt lgkmcnt(" #n ")" ::: "memory")
; #define PG8_BAR __builtin_amdgcn_s_barrier()
; #define PG8_SCHED __builtin_amdgcn_sched_barrier(0)
; template <class Epi, class Sched, bool ALIGN_EPI = false, bool SP2 = false, bool ABLK = false, bool BBLK = false>
; __device__ __forceinline__ void gemm_phase(PG8_LAS unsigned char* lds, const Gemm g, const Sched& S, const Epi& E) {
;     ...
;             PG8_WAIT_V(8); PG8_WAIT_L(0); PG8_BAR; PG8_MMA(1, 0, At, B0); PG8_MMA(1, 1, At, B1); PG8_BAR; PG8_SCHED;
;             PG8_LDB(B0, 1, 0); PG8_LDB(B1, 1, 1); PG8_SCHED; PG8_LDA(At, 1, 0); PG8_STAGE(PG8_SA(0, 1), a2 + hstepA, voffA);
;             PG8_WAIT_V(8); PG8_WAIT_L(0); PG8_BAR; PG8_MMA(0, 0, At, B0); PG8_MMA(0, 1, At, B1); PG8_BAR; PG8_SCHED;
	s_setprio 1
	s_waitcnt lgkmcnt(0)
	v_mfma_f32_16x16x32_bf16 v[50:53], v[148:151], v[200:203], v[50:53]
	v_mfma_f32_16x16x32_bf16 v[42:45], v[156:159], v[200:203], v[42:45]
	v_mfma_f32_16x16x32_bf16 v[34:37], v[148:151], v[208:211], v[34:37]
	v_mfma_f32_16x16x32_bf16 v[26:29], v[156:159], v[208:211], v[26:29]
	v_mfma_f32_16x16x32_bf16 v[18:21], v[148:151], v[216:219], v[18:21]
	v_mfma_f32_16x16x32_bf16 v[10:13], v[156:159], v[216:219], v[10:13]
	v_mfma_f32_16x16x32_bf16 v[62:65], v[152:155], v[196:199], v[62:65]
	v_mfma_f32_16x16x32_bf16 v[58:61], v[160:163], v[196:199], v[58:61]
	v_mfma_f32_16x16x32_bf16 v[50:53], v[152:155], v[204:207], v[50:53]
	v_mfma_f32_16x16x32_bf16 v[42:45], v[160:163], v[204:207], v[42:45]
	v_mfma_f32_16x16x32_bf16 v[34:37], v[152:155], v[212:215], v[34:37]
	v_mfma_f32_16x16x32_bf16 v[26:29], v[160:163], v[212:215], v[26:29]
	v_mfma_f32_16x16x32_bf16 v[18:21], v[152:155], v[220:223], v[18:21]
	v_mfma_f32_16x16x32_bf16 v[10:13], v[160:163], v[220:223], v[10:13]
	s_setprio 0
	s_setprio 1
	v_mfma_f32_16x16x32_bf16 v[54:57], v[164:167], v[180:183], v[54:57]
	v_mfma_f32_16x16x32_bf16 v[46:49], v[172:175], v[180:183], v[46:49]
	v_mfma_f32_16x16x32_bf16 v[38:41], v[164:167], v[200:203], v[38:41]
	v_mfma_f32_16x16x32_bf16 v[30:33], v[172:175], v[200:203], v[30:33]
	v_mfma_f32_16x16x32_bf16 v[22:25], v[164:167], v[208:211], v[22:25]
	v_mfma_f32_16x16x32_bf16 v[14:17], v[172:175], v[208:211], v[14:17]
	v_mfma_f32_16x16x32_bf16 v[6:9], v[164:167], v[216:219], v[6:9]
	v_mfma_f32_16x16x32_bf16 v[2:5], v[172:175], v[216:219], v[2:5]
	v_mfma_f32_16x16x32_bf16 v[54:57], v[168:171], v[196:199], v[54:57]
	v_mfma_f32_16x16x32_bf16 v[46:49], v[176:179], v[196:199], v[46:49]
	v_mfma_f32_16x16x32_bf16 v[38:41], v[168:171], v[204:207], v[38:41]
	v_mfma_f32_16x16x32_bf16 v[30:33], v[176:179], v[204:207], v[30:33]
	v_mfma_f32_16x16x32_bf16 v[22:25], v[168:171], v[212:215], v[22:25]
	v_mfma_f32_16x16x32_bf16 v[14:17], v[176:179], v[212:215], v[14:17]
	v_mfma_f32_16x16x32_bf16 v[6:9], v[168:171], v[220:223], v[6:9]
	v_mfma_f32_16x16x32_bf16 v[2:5], v[176:179], v[220:223], v[2:5]
	s_setprio 0
	s_barrier
	s_add_i32 s51, 0, 0x18000
	v_add_u32_e32 v147, s51, v145
	s_add_i32 s75, 0, 0x1c000
	ds_read_b128 v[148:151], v147
	ds_read_b128 v[152:155], v147 offset:1024
	ds_read_b128 v[156:159], v147 offset:2048
	ds_read_b128 v[160:163], v147 offset:3072
	v_add_u32_e32 v147, s75, v145
	ds_read_b128 v[164:167], v147
	ds_read_b128 v[168:171], v147 offset:1024
	ds_read_b128 v[172:175], v147 offset:2048
	ds_read_b128 v[176:179], v147 offset:3072
	s_add_u32 s28, s28, 0x80000
	s_addc_u32 s29, s29, 0
	s_mov_b32 m0, s53
	v_lshl_add_u64 v[228:229], s[28:29], 0, v[130:131]
	ds_read_b128 v[180:183], v146 offset:32768
	ds_read_b128 v[196:199], v146 offset:33792
	ds_read_b128 v[200:203], v146 offset:34816
	ds_read_b128 v[204:207], v146 offset:35840
	ds_read_b128 v[208:211], v146 offset:36864
	ds_read_b128 v[212:215], v146 offset:37888
	ds_read_b128 v[216:219], v146 offset:38912
	ds_read_b128 v[220:223], v146 offset:39936
	global_load_lds_dwordx4 v[228:229], off
	v_lshl_add_u64 v[228:229], s[28:29], 0, v[134:135]
	s_mov_b32 m0, s56
	s_nop 0
	global_load_lds_dwordx4 v[228:229], off
	s_waitcnt vmcnt(8)
	s_waitcnt lgkmcnt(0)
	v_mfma_f32_16x16x32_bf16 v[126:129], v[148:151], v[180:183], v[126:129]
	v_mfma_f32_16x16x32_bf16 v[122:125], v[156:159], v[180:183], v[122:125]
	s_barrier
	s_setprio 1
	s_waitcnt lgkmcnt(0)
	v_mfma_f32_16x16x32_bf16 v[114:117], v[148:151], v[200:203], v[114:117]
	v_mfma_f32_16x16x32_bf16 v[106:109], v[156:159], v[200:203], v[106:109]
	v_mfma_f32_16x16x32_bf16 v[98:101], v[148:151], v[208:211], v[98:101]
	v_mfma_f32_16x16x32_bf16 v[90:93], v[156:159], v[208:211], v[90:93]
	v_mfma_f32_16x16x32_bf16 v[82:85], v[148:151], v[216:219], v[82:85]
	v_mfma_f32_16x16x32_bf16 v[74:77], v[156:159], v[216:219], v[74:77]
	v_mfma_f32_16x16x32_bf16 v[126:129], v[152:155], v[196:199], v[126:129]
	v_mfma_f32_16x16x32_bf16 v[122:125], v[160:163], v[196:199], v[122:125]
	v_mfma_f32_16x16x32_bf16 v[114:117], v[152:155], v[204:207], v[114:117]
	v_mfma_f32_16x16x32_bf16 v[106:109], v[160:163], v[204:207], v[106:109]
	v_mfma_f32_16x16x32_bf16 v[98:101], v[152:155], v[212:215], v[98:101]
	v_mfma_f32_16x16x32_bf16 v[90:93], v[160:163], v[212:215], v[90:93]
	v_mfma_f32_16x16x32_bf16 v[82:85], v[152:155], v[220:223], v[82:85]
	v_mfma_f32_16x16x32_bf16 v[74:77], v[160:163], v[220:223], v[74:77]
	s_setprio 0
	s_setprio 1
	v_mfma_f32_16x16x32_bf16 v[118:121], v[164:167], v[180:183], v[118:121]
	v_mfma_f32_16x16x32_bf16 v[110:113], v[172:175], v[180:183], v[110:113]
	v_mfma_f32_16x16x32_bf16 v[102:105], v[164:167], v[200:203], v[102:105]
	v_mfma_f32_16x16x32_bf16 v[94:97], v[172:175], v[200:203], v[94:97]
	v_mfma_f32_16x16x32_bf16 v[86:89], v[164:167], v[208:211], v[86:89]
	v_mfma_f32_16x16x32_bf16 v[78:81], v[172:175], v[208:211], v[78:81]
	v_mfma_f32_16x16x32_bf16 v[70:73], v[164:167], v[216:219], v[70:73]
	v_mfma_f32_16x16x32_bf16 v[66:69], v[172:175], v[216:219], v[66:69]
	v_mfma_f32_16x16x32_bf16 v[118:121], v[168:171], v[196:199], v[118:121]
	v_mfma_f32_16x16x32_bf16 v[110:113], v[176:179], v[196:199], v[110:113]
	v_mfma_f32_16x16x32_bf16 v[102:105], v[168:171], v[204:207], v[102:105]
	v_mfma_f32_16x16x32_bf16 v[94:97], v[176:179], v[204:207], v[94:97]
	v_mfma_f32_16x16x32_bf16 v[86:89], v[168:171], v[212:215], v[86:89]
	v_mfma_f32_16x16x32_bf16 v[78:81], v[176:179], v[212:215], v[78:81]
	v_mfma_f32_16x16x32_bf16 v[70:73], v[168:171], v[220:223], v[70:73]
	v_mfma_f32_16x16x32_bf16 v[66:69], v[176:179], v[220:223], v[66:69]
	s_setprio 0
	s_barrier
; #define PG8_STAGE(bufoff, gbase, voff) do { _Pragma("unroll") for (int _i = 0; _i < 2; ++_i) \
;         __builtin_amdgcn_global_load_lds((const unsigned*)((const char*)(gbase) + (voff)[_i]), (PG8_LAS unsigned*)(lds + (bufoff) + ldsw + _i * 8192), 16, 0, 0); } while (0)
; #define PG8_LDA(dst, b, h) do { _Pragma("unroll") for (int m = 0; m < 4; ++m) _Pragma("unroll") for (int k = 0; k < 2; ++k) dst[m][k] = *(const PG8_LAS bf16x8*)(lds + PG8_SA(b, h) + aoff + m * 2048 + k * 1024); } while (0)
; #define PG8_MMA(ai, bj, At, Bt) do { __builtin_amdgcn_s_setprio(1); _Pragma("unroll") for (int m = 0; m < 4; ++m) _Pragma("unroll") for (int n = 0; n < 2; ++n) _Pragma("unroll") for (int k = 0; k < 2; ++k) \
;         acc[ai][bj][m][n] = __builtin_amdgcn_mfma_f32_16x16x32_bf16(Bt[n][k], At[m][k], acc[ai][bj][m][n], 0, 0, 0); __builtin_amdgcn_s_setprio(0); } while (0)
; #define PG8_WAIT_V(n) asm volatile("s_waitcnt vmcnt(" #n ")" ::: "memory")
; #define PG8_WAIT_L(n) asm volatile("s_waitcnt lgkmcnt(" #n ")" ::: "memory")
; #define PG8_BAR __builtin_amdgcn_s_barrier()
; #define PG8_SCHED __builtin_amdgcn_sched_barrier(0)
; template <class Epi, class Sched, bool ALIGN_EPI = false, bool SP2 = false, bool ABLK = false, bool BBLK = false>
; __device__ __forceinline__ void gemm_phase(PG8_LAS unsigned char* lds, const Gemm g, const Sched& S, const Epi& E) {
;     ...
;             PG8_LDA(At, 1, 1); PG8_STAGE(PG8_SB(1, 0), b3, voffB); PG8_STAGE(PG8_SB(1, 1), b3 + hstepB, voffB); PG8_STAGE(PG8_SA(1, 0), a3, voffA);
;             PG8_WAIT_V(8); PG8_WAIT_L(0); PG8_BAR; PG8_MMA(1, 0, At, B0); PG8_MMA(1, 1, At, B1); PG8_BAR; PG8_SCHED;
;     ...
;         if constexpr (ALIGN_EPI) { if (wr == 0) PG8_BAR; }
	s_add_i32 s28, s51, s35
	v_lshl_add_u64 v[142:143], v[142:143], 0, s[62:63]
	s_mov_b32 m0, s28
	ds_read_b128 v[180:183], v146 offset:49152
	ds_read_b128 v[196:199], v146 offset:50176
	ds_read_b128 v[200:203], v146 offset:51200
	ds_read_b128 v[204:207], v146 offset:52224
	ds_read_b128 v[208:211], v146 offset:53248
	ds_read_b128 v[212:215], v146 offset:54272
	ds_read_b128 v[216:219], v146 offset:55296
	ds_read_b128 v[220:223], v146 offset:56320
	global_load_lds_dwordx4 v[142:143], off
	s_add_i32 m0, s28, 0x2000
	s_add_u32 s26, s26, 0x80080
	v_lshl_add_u64 v[142:143], v[184:185], 0, s[62:63]
	s_addc_u32 s27, s27, 0
	s_add_i32 s28, s75, s35
	global_load_lds_dwordx4 v[142:143], off
	v_lshl_add_u64 v[142:143], s[26:27], 0, v[132:133]
	s_mov_b32 m0, s28
	s_nop 0
	global_load_lds_dwordx4 v[142:143], off
	v_lshl_add_u64 v[142:143], s[26:27], 0, v[136:137]
	s_add_i32 m0, s28, 0x2000
	s_nop 0
	global_load_lds_dwordx4 v[142:143], off
	v_lshl_add_u64 v[142:143], v[224:225], 0, s[62:63]
	s_mov_b32 m0, s61
	s_nop 0
	global_load_lds_dwordx4 v[142:143], off
	v_lshl_add_u64 v[142:143], v[226:227], 0, s[62:63]
	s_mov_b32 m0, s65
	s_nop 0
	global_load_lds_dwordx4 v[142:143], off
	s_waitcnt vmcnt(8)
	s_waitcnt lgkmcnt(0)
	v_mfma_f32_16x16x32_bf16 v[62:65], v[148:151], v[180:183], v[62:65]
	v_mfma_f32_16x16x32_bf16 v[58:61], v[156:159], v[180:183], v[58:61]
	s_barrier
	s_setprio 1
	s_waitcnt lgkmcnt(0)
	v_mfma_f32_16x16x32_bf16 v[50:53], v[148:151], v[200:203], v[50:53]
	v_mfma_f32_16x16x32_bf16 v[42:45], v[156:159], v[200:203], v[42:45]
	v_mfma_f32_16x16x32_bf16 v[34:37], v[148:151], v[208:211], v[34:37]
	v_mfma_f32_16x16x32_bf16 v[26:29], v[156:159], v[208:211], v[26:29]
	v_mfma_f32_16x16x32_bf16 v[18:21], v[148:151], v[216:219], v[18:21]
	v_mfma_f32_16x16x32_bf16 v[10:13], v[156:159], v[216:219], v[10:13]
	v_mfma_f32_16x16x32_bf16 v[62:65], v[152:155], v[196:199], v[62:65]
	v_mfma_f32_16x16x32_bf16 v[58:61], v[160:163], v[196:199], v[58:61]
	v_mfma_f32_16x16x32_bf16 v[50:53], v[152:155], v[204:207], v[50:53]
	v_mfma_f32_16x16x32_bf16 v[42:45], v[160:163], v[204:207], v[42:45]
	v_mfma_f32_16x16x32_bf16 v[34:37], v[152:155], v[212:215], v[34:37]
	v_mfma_f32_16x16x32_bf16 v[26:29], v[160:163], v[212:215], v[26:29]
	v_mfma_f32_16x16x32_bf16 v[18:21], v[152:155], v[220:223], v[18:21]
	v_mfma_f32_16x16x32_bf16 v[10:13], v[160:163], v[220:223], v[10:13]
	s_setprio 0
	s_setprio 1
	v_mfma_f32_16x16x32_bf16 v[54:57], v[164:167], v[180:183], v[54:57]
	v_mfma_f32_16x16x32_bf16 v[46:49], v[172:175], v[180:183], v[46:49]
	v_mfma_f32_16x16x32_bf16 v[38:41], v[164:167], v[200:203], v[38:41]
	v_mfma_f32_16x16x32_bf16 v[30:33], v[172:175], v[200:203], v[30:33]
	v_mfma_f32_16x16x32_bf16 v[22:25], v[164:167], v[208:211], v[22:25]
	v_mfma_f32_16x16x32_bf16 v[14:17], v[172:175], v[208:211], v[14:17]
	v_mfma_f32_16x16x32_bf16 v[6:9], v[164:167], v[216:219], v[6:9]
	v_mfma_f32_16x16x32_bf16 v[2:5], v[172:175], v[216:219], v[2:5]
	v_mfma_f32_16x16x32_bf16 v[54:57], v[168:171], v[196:199], v[54:57]
	v_mfma_f32_16x16x32_bf16 v[46:49], v[176:179], v[196:199], v[46:49]
	v_mfma_f32_16x16x32_bf16 v[38:41], v[168:171], v[204:207], v[38:41]
	v_mfma_f32_16x16x32_bf16 v[30:33], v[176:179], v[204:207], v[30:33]
	v_mfma_f32_16x16x32_bf16 v[22:25], v[168:171], v[212:215], v[22:25]
	v_mfma_f32_16x16x32_bf16 v[14:17], v[176:179], v[212:215], v[14:17]
	v_mfma_f32_16x16x32_bf16 v[6:9], v[168:171], v[220:223], v[6:9]
	v_mfma_f32_16x16x32_bf16 v[2:5], v[176:179], v[220:223], v[2:5]
	s_setprio 0
	s_barrier
	s_add_i32 s81, s81, 2
	s_add_u32 s24, s24, 0x100
	s_addc_u32 s25, s25, 0
	s_add_u32 s23, s23, 0x100
	s_addc_u32 s73, s73, 0
	s_cmp_gt_u32 s81, 29
	s_cbranch_scc0 .LBB0_790
	s_and_b64 vcc, exec, s[8:9]
	s_cbranch_vccz .LBB0_793
	s_barrier

; #define PG8_STAGE(bufoff, gbase, voff) do { _Pragma("unroll") for (int _i = 0; _i < 2; ++_i) \
;         __builtin_amdgcn_global_load_lds((const unsigned*)((const char*)(gbase) + (voff)[_i]), (PG8_LAS unsigned*)(lds + (bufoff) + ldsw + _i * 8192), 16, 0, 0); } while (0)
; #define PG8_LDA(dst, b, h) do { _Pragma("unroll") for (int m = 0; m < 4; ++m) _Pragma("unroll") for (int k = 0; k < 2; ++k) dst[m][k] = *(const PG8_LAS bf16x8*)(lds + PG8_SA(b, h) + aoff + m * 2048 + k * 1024); } while (0)
; #define PG8_LDB(dst, b, h) do { _Pragma("unroll") for (int n = 0; n < 2; ++n) _Pragma("unroll") for (int k = 0; k < 2; ++k) dst[n][k] = *(const PG8_LAS bf16x8*)(lds + PG8_SB(b, h) + boff + n * 2048 + k * 1024); } while (0)
; #define PG8_WAIT_V(n) asm volatile("s_waitcnt vmcnt(" #n ")" ::: "memory")
; #define PG8_WAIT_L(n) asm volatile("s_waitcnt lgkmcnt(" #n ")" ::: "memory")
; #define PG8_BAR __builtin_amdgcn_s_barrier()
; #define PG8_SCHED __builtin_amdgcn_sched_barrier(0)
; template <class Epi, class Sched, bool ALIGN_EPI = false, bool SP2 = false, bool ABLK = false, bool BBLK = false>
; __device__ __forceinline__ void gemm_phase(PG8_LAS unsigned char* lds, const Gemm g, const Sched& S, const Epi& E) {
;     ...
;         const bool has_next = S.next(ui + 1, nxt);
;         const char* nA = has_next ? (const char*)g.A + (size_t)nxt.pm * tstepA : cA; const char* nB = has_next ? (const char*)g.Bt + (size_t)nxt.pn * tstepB : cB;
;         for (int t = 0; t < nt; t += 2) {
;             const bool last = (t == nt - 2);
;             const char* a1 = cA + (size_t)(t + 1) * kstepA;
;             const char* a2 = last ? nA : cA + (size_t)(t + 2) * kstepA; const char* b2 = last ? nB : cB + (size_t)(t + 2) * kstepB;
;             const char* a3 = a2 + kstepA; const char* b3 = b2 + kstepB;
;             if (last && has_next) S.a_ready(nxt);
;             if constexpr (SP2) {
;             PG8_LDB(B0, 0, 0); PG8_LDB(B1, 0, 1); PG8_SCHED; PG8_LDA(At, 0, 0); PG8_STAGE(PG8_SA(1, 1), a1 + hstepA, voffA);
;             PG8_WAIT_V(8); PG8_WAIT_L(0); PG8_BAR; PG8_MMA(0, 0, At, B0); PG8_MMA(0, 1, At, B1); PG8_BAR; PG8_SCHED;
;             PG8_LDA(At, 0, 1); PG8_STAGE(PG8_SB(0, 0), b2, voffB); PG8_STAGE(PG8_SB(0, 1), b2 + hstepB, voffB); PG8_STAGE(PG8_SA(0, 0), a2, voffA);
;             PG8_WAIT_V(8); PG8_WAIT_L(0); PG8_BAR; PG8_MMA(1, 0, At, B0); PG8_MMA(1, 1, At, B1); PG8_BAR; PG8_SCHED;
.LBB0_815:
	s_add_u32 s33, s24, s27
	s_addc_u32 s34, s25, 0
	s_add_u32 s35, s33, 0x100
	s_addc_u32 s36, s34, 0
	s_and_b64 s[4:5], s[30:31], exec
	s_cselect_b32 s37, s1, s36
	s_cselect_b32 s36, s9, s35
	s_add_u32 s4, s22, s27
	s_addc_u32 s5, s23, 0
	s_add_u32 s27, s4, 0x100
	s_addc_u32 s35, s5, 0
	s_add_i32 s75, 0, 0x10000
	s_and_b64 s[4:5], s[30:31], exec
	s_cselect_b32 s61, s13, s35
	s_cselect_b32 s60, s15, s27
	s_add_i32 s31, 0, 0x14000
	s_add_u32 s94, s33, 0x10080
	s_addc_u32 s95, s34, 0
	s_add_i32 s33, s75, s72
	s_add_i32 m0, s52, 0xc000
	s_add_i32 s73, s52, 0xe000
	s_add_i32 s82, s33, 0x2000
	v_add_u32_e32 v138, s75, v141
	s_add_u32 s92, s60, 0x10000
	ds_read_b128 v[144:147], v138
	ds_read_b128 v[148:151], v138 offset:1024
	ds_read_b128 v[152:155], v138 offset:2048
	ds_read_b128 v[156:159], v138 offset:3072
	v_add_u32_e32 v138, s31, v141
	s_addc_u32 s93, s61, 0
	s_add_i32 s5, s31, s72
	ds_read_b128 v[160:163], v138
	ds_read_b128 v[164:167], v138 offset:1024
	ds_read_b128 v[168:171], v138 offset:2048
	ds_read_b128 v[172:175], v138 offset:3072
	s_add_i32 s4, s5, 0x2000
	s_add_i32 vcc_lo, 0, 0x18000
	s_add_i32 vcc_hi, 0, 0x1c000
	s_add_u32 s34, s36, 0x10000
	s_addc_u32 s35, s37, 0
	s_add_i32 s27, vcc_lo, s72
	s_add_i32 s51, s27, 0x2000
	s_add_u32 s30, s60, 0x10080
	s_addc_u32 s31, s61, 0
	s_add_i32 s75, vcc_hi, s72
	s_add_i32 s80, s75, 0x2000
	v_lshl_add_u64 v[138:139], s[94:95], 0, v[130:131]
	ds_read_b128 v[176:179], v142
	ds_read_b128 v[180:183], v142 offset:1024
	ds_read_b128 v[196:199], v142 offset:2048
	ds_read_b128 v[200:203], v142 offset:3072
	ds_read_b128 v[204:207], v142 offset:4096
	ds_read_b128 v[208:211], v142 offset:5120
	ds_read_b128 v[212:215], v142 offset:6144
	ds_read_b128 v[216:219], v142 offset:7168
	global_load_lds_dwordx4 v[138:139], off
	v_lshl_add_u64 v[138:139], s[94:95], 0, v[134:135]
	s_mov_b32 m0, s73
	s_nop 0
	global_load_lds_dwordx4 v[138:139], off
	s_waitcnt vmcnt(8)
	s_waitcnt lgkmcnt(0)
	v_mfma_f32_16x16x32_bf16 v[126:129], v[144:147], v[176:179], v[126:129]
	v_mfma_f32_16x16x32_bf16 v[122:125], v[152:155], v[176:179], v[122:125]
	s_barrier
	s_setprio 1
	s_waitcnt lgkmcnt(0)
	v_mfma_f32_16x16x32_bf16 v[114:117], v[144:147], v[196:199], v[114:117]
	v_mfma_f32_16x16x32_bf16 v[106:109], v[152:155], v[196:199], v[106:109]
	v_mfma_f32_16x16x32_bf16 v[98:101], v[144:147], v[204:207], v[98:101]
	v_mfma_f32_16x16x32_bf16 v[90:93], v[152:155], v[204:207], v[90:93]
	v_mfma_f32_16x16x32_bf16 v[82:85], v[144:147], v[212:215], v[82:85]
	v_mfma_f32_16x16x32_bf16 v[74:77], v[152:155], v[212:215], v[74:77]
	v_mfma_f32_16x16x32_bf16 v[126:129], v[148:151], v[180:183], v[126:129]
	v_mfma_f32_16x16x32_bf16 v[122:125], v[156:159], v[180:183], v[122:125]
	v_mfma_f32_16x16x32_bf16 v[114:117], v[148:151], v[200:203], v[114:117]
	v_mfma_f32_16x16x32_bf16 v[106:109], v[156:159], v[200:203], v[106:109]
	v_mfma_f32_16x16x32_bf16 v[98:101], v[148:151], v[208:211], v[98:101]
	v_mfma_f32_16x16x32_bf16 v[90:93], v[156:159], v[208:211], v[90:93]
	v_mfma_f32_16x16x32_bf16 v[82:85], v[148:151], v[216:219], v[82:85]
	v_mfma_f32_16x16x32_bf16 v[74:77], v[156:159], v[216:219], v[74:77]
	s_setprio 0
	s_setprio 1
	v_mfma_f32_16x16x32_bf16 v[118:121], v[160:163], v[176:179], v[118:121]
	v_mfma_f32_16x16x32_bf16 v[110:113], v[168:171], v[176:179], v[110:113]
	v_mfma_f32_16x16x32_bf16 v[102:105], v[160:163], v[196:199], v[102:105]
	v_mfma_f32_16x16x32_bf16 v[94:97], v[168:171], v[196:199], v[94:97]
	v_mfma_f32_16x16x32_bf16 v[86:89], v[160:163], v[204:207], v[86:89]
	v_mfma_f32_16x16x32_bf16 v[78:81], v[168:171], v[204:207], v[78:81]
	v_mfma_f32_16x16x32_bf16 v[70:73], v[160:163], v[212:215], v[70:73]
	v_mfma_f32_16x16x32_bf16 v[66:69], v[168:171], v[212:215], v[66:69]
	v_mfma_f32_16x16x32_bf16 v[118:121], v[164:167], v[180:183], v[118:121]
	v_mfma_f32_16x16x32_bf16 v[110:113], v[172:175], v[180:183], v[110:113]
	v_mfma_f32_16x16x32_bf16 v[102:105], v[164:167], v[200:203], v[102:105]
	v_mfma_f32_16x16x32_bf16 v[94:97], v[172:175], v[200:203], v[94:97]
	v_mfma_f32_16x16x32_bf16 v[86:89], v[164:167], v[208:211], v[86:89]
	v_mfma_f32_16x16x32_bf16 v[78:81], v[172:175], v[208:211], v[78:81]
	v_mfma_f32_16x16x32_bf16 v[70:73], v[164:167], v[216:219], v[70:73]
	v_mfma_f32_16x16x32_bf16 v[66:69], v[172:175], v[216:219], v[66:69]
	s_setprio 0
	s_barrier
	s_mov_b32 m0, s33
	v_lshl_add_u64 v[138:139], s[60:61], 0, v[132:133]
	ds_read_b128 v[176:179], v142 offset:16384
	ds_read_b128 v[180:183], v142 offset:17408
	ds_read_b128 v[196:199], v142 offset:18432
	ds_read_b128 v[200:203], v142 offset:19456
	ds_read_b128 v[204:207], v142 offset:20480
	ds_read_b128 v[208:211], v142 offset:21504
	ds_read_b128 v[212:215], v142 offset:22528
	ds_read_b128 v[216:219], v142 offset:23552
	global_load_lds_dwordx4 v[138:139], off
	v_lshl_add_u64 v[184:185], s[60:61], 0, v[136:137]
	s_mov_b32 m0, s82
	v_lshl_add_u64 v[220:221], s[92:93], 0, v[132:133]
	global_load_lds_dwordx4 v[184:185], off
	s_mov_b32 m0, s5
	v_lshl_add_u64 v[222:223], s[36:37], 0, v[134:135]
	global_load_lds_dwordx4 v[220:221], off
	v_lshl_add_u64 v[220:221], s[92:93], 0, v[136:137]
	s_mov_b32 m0, s4
	s_nop 0
	global_load_lds_dwordx4 v[220:221], off
	v_lshl_add_u64 v[220:221], s[36:37], 0, v[130:131]
	s_mov_b32 m0, s52
	s_nop 0
	global_load_lds_dwordx4 v[220:221], off
	s_mov_b32 m0, s81
	s_nop 0
	global_load_lds_dwordx4 v[222:223], off
	s_waitcnt vmcnt(8)
	s_waitcnt lgkmcnt(0)
	v_mfma_f32_16x16x32_bf16 v[62:65], v[144:147], v[176:179], v[62:65]
	v_mfma_f32_16x16x32_bf16 v[58:61], v[152:155], v[176:179], v[58:61]
	s_barrier
; #define PG8_STAGE(bufoff, gbase, voff) do { _Pragma("unroll") for (int _i = 0; _i < 2; ++_i) \
;         __builtin_amdgcn_global_load_lds((const unsigned*)((const char*)(gbase) + (voff)[_i]), (PG8_LAS unsigned*)(lds + (bufoff) + ldsw + _i * 8192), 16, 0, 0); } while (0)
; #define PG8_LDA(dst, b, h) do { _Pragma("unroll") for (int m = 0; m < 4; ++m) _Pragma("unroll") for (int k = 0; k < 2; ++k) dst[m][k] = *(const PG8_LAS bf16x8*)(lds + PG8_SA(b, h) + aoff + m * 2048 + k * 1024); } while (0)
; #define PG8_LDB(dst, b, h) do { _Pragma("unroll") for (int n = 0; n < 2; ++n) _Pragma("unroll") for (int k = 0; k < 2; ++k) dst[n][k] = *(const PG8_LAS bf16x8*)(lds + PG8_SB(b, h) + boff + n * 2048 + k * 1024); } while (0)
; #define PG8_MMA(ai, bj, At, Bt) do { __builtin_amdgcn_s_setprio(1); _Pragma("unroll") for (int m = 0; m < 4; ++m) _Pragma("unroll") for (int n = 0; n < 2; ++n) _Pragma("unroll") for (int k = 0; k < 2; ++k) \
;         acc[ai][bj][m][n] = __builtin_amdgcn_mfma_f32_16x16x32_bf16(Bt[n][k], At[m][k], acc[ai][bj][m][n], 0, 0, 0); __builtin_amdgcn_s_setprio(0); } while (0)
; #define PG8_WAIT_V(n) asm volatile("s_waitcnt vmcnt(" #n ")" ::: "memory")
; #define PG8_WAIT_L(n) asm volatile("s_waitcnt lgkmcnt(" #n ")" ::: "memory")
; #define PG8_BAR __builtin_amdgcn_s_barrier()
; #define PG8_SCHED __builtin_amdgcn_sched_barrier(0)
; template <class Epi, class Sched, bool ALIGN_EPI = false, bool SP2 = false, bool ABLK = false, bool BBLK = false>
; __device__ __forceinline__ void gemm_phase(PG8_LAS unsigned char* lds, const Gemm g, const Sched& S, const Epi& E) {
;     ...
;             PG8_WAIT_V(8); PG8_WAIT_L(0); PG8_BAR; PG8_MMA(1, 0, At, B0); PG8_MMA(1, 1, At, B1); PG8_BAR; PG8_SCHED;
;             PG8_LDB(B0, 1, 0); PG8_LDB(B1, 1, 1); PG8_SCHED; PG8_LDA(At, 1, 0); PG8_STAGE(PG8_SA(0, 1), a2 + hstepA, voffA);
;             PG8_WAIT_V(8); PG8_WAIT_L(0); PG8_BAR; PG8_MMA(0, 0, At, B0); PG8_MMA(0, 1, At, B1); PG8_BAR; PG8_SCHED;
	s_setprio 1
	s_waitcnt lgkmcnt(0)
	v_mfma_f32_16x16x32_bf16 v[50:53], v[144:147], v[196:199], v[50:53]
	v_mfma_f32_16x16x32_bf16 v[42:45], v[152:155], v[196:199], v[42:45]
	v_mfma_f32_16x16x32_bf16 v[34:37], v[144:147], v[204:207], v[34:37]
	v_mfma_f32_16x16x32_bf16 v[26:29], v[152:155], v[204:207], v[26:29]
	v_mfma_f32_16x16x32_bf16 v[18:21], v[144:147], v[212:215], v[18:21]
	v_mfma_f32_16x16x32_bf16 v[10:13], v[152:155], v[212:215], v[10:13]
	v_mfma_f32_16x16x32_bf16 v[62:65], v[148:151], v[180:183], v[62:65]
	v_mfma_f32_16x16x32_bf16 v[58:61], v[156:159], v[180:183], v[58:61]
	v_mfma_f32_16x16x32_bf16 v[50:53], v[148:151], v[200:203], v[50:53]
	v_mfma_f32_16x16x32_bf16 v[42:45], v[156:159], v[200:203], v[42:45]
	v_mfma_f32_16x16x32_bf16 v[34:37], v[148:151], v[208:211], v[34:37]
	v_mfma_f32_16x16x32_bf16 v[26:29], v[156:159], v[208:211], v[26:29]
	v_mfma_f32_16x16x32_bf16 v[18:21], v[148:151], v[216:219], v[18:21]
	v_mfma_f32_16x16x32_bf16 v[10:13], v[156:159], v[216:219], v[10:13]
	s_setprio 0
	s_setprio 1
	v_mfma_f32_16x16x32_bf16 v[54:57], v[160:163], v[176:179], v[54:57]
	v_mfma_f32_16x16x32_bf16 v[46:49], v[168:171], v[176:179], v[46:49]
	v_mfma_f32_16x16x32_bf16 v[38:41], v[160:163], v[196:199], v[38:41]
	v_mfma_f32_16x16x32_bf16 v[30:33], v[168:171], v[196:199], v[30:33]
	v_mfma_f32_16x16x32_bf16 v[22:25], v[160:163], v[204:207], v[22:25]
	v_mfma_f32_16x16x32_bf16 v[14:17], v[168:171], v[204:207], v[14:17]
	v_mfma_f32_16x16x32_bf16 v[6:9], v[160:163], v[212:215], v[6:9]
	v_mfma_f32_16x16x32_bf16 v[2:5], v[168:171], v[212:215], v[2:5]
	v_mfma_f32_16x16x32_bf16 v[54:57], v[164:167], v[180:183], v[54:57]
	v_mfma_f32_16x16x32_bf16 v[46:49], v[172:175], v[180:183], v[46:49]
	v_mfma_f32_16x16x32_bf16 v[38:41], v[164:167], v[200:203], v[38:41]
	v_mfma_f32_16x16x32_bf16 v[30:33], v[172:175], v[200:203], v[30:33]
	v_mfma_f32_16x16x32_bf16 v[22:25], v[164:167], v[208:211], v[22:25]
	v_mfma_f32_16x16x32_bf16 v[14:17], v[172:175], v[208:211], v[14:17]
	v_mfma_f32_16x16x32_bf16 v[6:9], v[164:167], v[216:219], v[6:9]
	v_mfma_f32_16x16x32_bf16 v[2:5], v[172:175], v[216:219], v[2:5]
	s_setprio 0
	s_barrier
	v_add_u32_e32 v143, vcc_lo, v141
	ds_read_b128 v[144:147], v143
	ds_read_b128 v[148:151], v143 offset:1024
	ds_read_b128 v[152:155], v143 offset:2048
	ds_read_b128 v[156:159], v143 offset:3072
	v_add_u32_e32 v143, vcc_hi, v141
	ds_read_b128 v[160:163], v143
	ds_read_b128 v[164:167], v143 offset:1024
	ds_read_b128 v[168:171], v143 offset:2048
	ds_read_b128 v[172:175], v143 offset:3072
	s_mov_b32 m0, s83
	v_lshl_add_u64 v[224:225], s[34:35], 0, v[130:131]
	ds_read_b128 v[176:179], v142 offset:32768
	ds_read_b128 v[180:183], v142 offset:33792
	ds_read_b128 v[196:199], v142 offset:34816
	ds_read_b128 v[200:203], v142 offset:35840
	ds_read_b128 v[204:207], v142 offset:36864
	ds_read_b128 v[208:211], v142 offset:37888
	ds_read_b128 v[212:215], v142 offset:38912
	ds_read_b128 v[216:219], v142 offset:39936
	global_load_lds_dwordx4 v[224:225], off
	v_lshl_add_u64 v[224:225], s[34:35], 0, v[134:135]
	s_mov_b32 m0, s84
	s_nop 0
	global_load_lds_dwordx4 v[224:225], off
	s_waitcnt vmcnt(8)
	s_waitcnt lgkmcnt(0)
	v_mfma_f32_16x16x32_bf16 v[126:129], v[144:147], v[176:179], v[126:129]
	v_mfma_f32_16x16x32_bf16 v[122:125], v[152:155], v[176:179], v[122:125]
	s_barrier
	s_setprio 1
	s_waitcnt lgkmcnt(0)
	v_mfma_f32_16x16x32_bf16 v[114:117], v[144:147], v[196:199], v[114:117]
	v_mfma_f32_16x16x32_bf16 v[106:109], v[152:155], v[196:199], v[106:109]
	v_mfma_f32_16x16x32_bf16 v[98:101], v[144:147], v[204:207], v[98:101]
	v_mfma_f32_16x16x32_bf16 v[90:93], v[152:155], v[204:207], v[90:93]
	v_mfma_f32_16x16x32_bf16 v[82:85], v[144:147], v[212:215], v[82:85]
	v_mfma_f32_16x16x32_bf16 v[74:77], v[152:155], v[212:215], v[74:77]
	v_mfma_f32_16x16x32_bf16 v[126:129], v[148:151], v[180:183], v[126:129]
	v_mfma_f32_16x16x32_bf16 v[122:125], v[156:159], v[180:183], v[122:125]
	v_mfma_f32_16x16x32_bf16 v[114:117], v[148:151], v[200:203], v[114:117]
	v_mfma_f32_16x16x32_bf16 v[106:109], v[156:159], v[200:203], v[106:109]
	v_mfma_f32_16x16x32_bf16 v[98:101], v[148:151], v[208:211], v[98:101]
	v_mfma_f32_16x16x32_bf16 v[90:93], v[156:159], v[208:211], v[90:93]
	v_mfma_f32_16x16x32_bf16 v[82:85], v[148:151], v[216:219], v[82:85]
	v_mfma_f32_16x16x32_bf16 v[74:77], v[156:159], v[216:219], v[74:77]
	s_setprio 0
	s_setprio 1
	v_mfma_f32_16x16x32_bf16 v[118:121], v[160:163], v[176:179], v[118:121]
	v_mfma_f32_16x16x32_bf16 v[110:113], v[168:171], v[176:179], v[110:113]
	v_mfma_f32_16x16x32_bf16 v[102:105], v[160:163], v[196:199], v[102:105]
	v_mfma_f32_16x16x32_bf16 v[94:97], v[168:171], v[196:199], v[94:97]
	v_mfma_f32_16x16x32_bf16 v[86:89], v[160:163], v[204:207], v[86:89]
	v_mfma_f32_16x16x32_bf16 v[78:81], v[168:171], v[204:207], v[78:81]
	v_mfma_f32_16x16x32_bf16 v[70:73], v[160:163], v[212:215], v[70:73]
	v_mfma_f32_16x16x32_bf16 v[66:69], v[168:171], v[212:215], v[66:69]
	v_mfma_f32_16x16x32_bf16 v[118:121], v[164:167], v[180:183], v[118:121]
	v_mfma_f32_16x16x32_bf16 v[110:113], v[172:175], v[180:183], v[110:113]
	v_mfma_f32_16x16x32_bf16 v[102:105], v[164:167], v[200:203], v[102:105]
	v_mfma_f32_16x16x32_bf16 v[94:97], v[172:175], v[200:203], v[94:97]
	v_mfma_f32_16x16x32_bf16 v[86:89], v[164:167], v[208:211], v[86:89]
	v_mfma_f32_16x16x32_bf16 v[78:81], v[172:175], v[208:211], v[78:81]
	v_mfma_f32_16x16x32_bf16 v[70:73], v[164:167], v[216:219], v[70:73]
	v_mfma_f32_16x16x32_bf16 v[66:69], v[172:175], v[216:219], v[66:69]
	s_setprio 0
	s_barrier
; #define PG8_STAGE(bufoff, gbase, voff) do { _Pragma("unroll") for (int _i = 0; _i < 2; ++_i) \
;         __builtin_amdgcn_global_load_lds((const unsigned*)((const char*)(gbase) + (voff)[_i]), (PG8_LAS unsigned*)(lds + (bufoff) + ldsw + _i * 8192), 16, 0, 0); } while (0)
; #define PG8_LDA(dst, b, h) do { _Pragma("unroll") for (int m = 0; m < 4; ++m) _Pragma("unroll") for (int k = 0; k < 2; ++k) dst[m][k] = *(const PG8_LAS bf16x8*)(lds + PG8_SA(b, h) + aoff + m * 2048 + k * 1024); } while (0)
; #define PG8_MMA(ai, bj, At, Bt) do { __builtin_amdgcn_s_setprio(1); _Pragma("unroll") for (int m = 0; m < 4; ++m) _Pragma("unroll") for (int n = 0; n < 2; ++n) _Pragma("unroll") for (int k = 0; k < 2; ++k) \
;         acc[ai][bj][m][n] = __builtin_amdgcn_mfma_f32_16x16x32_bf16(Bt[n][k], At[m][k], acc[ai][bj][m][n], 0, 0, 0); __builtin_amdgcn_s_setprio(0); } while (0)
; #define PG8_WAIT_V(n) asm volatile("s_waitcnt vmcnt(" #n ")" ::: "memory")
; #define PG8_WAIT_L(n) asm volatile("s_waitcnt lgkmcnt(" #n ")" ::: "memory")
; #define PG8_BAR __builtin_amdgcn_s_barrier()
; #define PG8_SCHED __builtin_amdgcn_sched_barrier(0)
; template <class Epi, class Sched, bool ALIGN_EPI = false, bool SP2 = false, bool ABLK = false, bool BBLK = false>
; __device__ __forceinline__ void gemm_phase(PG8_LAS unsigned char* lds, const Gemm g, const Sched& S, const Epi& E) {
;     ...
;             PG8_LDA(At, 1, 1); PG8_STAGE(PG8_SB(1, 0), b3, voffB); PG8_STAGE(PG8_SB(1, 1), b3 + hstepB, voffB); PG8_STAGE(PG8_SA(1, 0), a3, voffA);
;             PG8_WAIT_V(8); PG8_WAIT_L(0); PG8_BAR; PG8_MMA(1, 0, At, B0); PG8_MMA(1, 1, At, B1); PG8_BAR; PG8_SCHED;
;     ...
;         if constexpr (ALIGN_EPI) { if (wr == 0) PG8_BAR; }
	s_mov_b32 m0, s27
	v_lshl_add_u64 v[138:139], v[138:139], 0, s[62:63]
	ds_read_b128 v[176:179], v142 offset:49152
	ds_read_b128 v[180:183], v142 offset:50176
	ds_read_b128 v[196:199], v142 offset:51200
	ds_read_b128 v[200:203], v142 offset:52224
	ds_read_b128 v[204:207], v142 offset:53248
	ds_read_b128 v[208:211], v142 offset:54272
	ds_read_b128 v[212:215], v142 offset:55296
	ds_read_b128 v[216:219], v142 offset:56320
	global_load_lds_dwordx4 v[138:139], off
	v_lshl_add_u64 v[138:139], v[184:185], 0, s[62:63]
	s_mov_b32 m0, s51
	s_nop 0
	global_load_lds_dwordx4 v[138:139], off
	v_lshl_add_u64 v[138:139], s[30:31], 0, v[132:133]
	s_mov_b32 m0, s75
	s_nop 0
	global_load_lds_dwordx4 v[138:139], off
	v_lshl_add_u64 v[138:139], s[30:31], 0, v[136:137]
	s_mov_b32 m0, s80
	s_nop 0
	global_load_lds_dwordx4 v[138:139], off
	v_lshl_add_u64 v[138:139], v[220:221], 0, s[62:63]
	s_mov_b32 m0, s88
	s_nop 0
	global_load_lds_dwordx4 v[138:139], off
	v_lshl_add_u64 v[138:139], v[222:223], 0, s[62:63]
	s_mov_b32 m0, s89
	s_nop 0
	global_load_lds_dwordx4 v[138:139], off
	s_waitcnt vmcnt(8)
	s_waitcnt lgkmcnt(0)
	v_mfma_f32_16x16x32_bf16 v[62:65], v[144:147], v[176:179], v[62:65]
	v_mfma_f32_16x16x32_bf16 v[58:61], v[152:155], v[176:179], v[58:61]
	s_barrier
	s_setprio 1
	s_waitcnt lgkmcnt(0)
	v_mfma_f32_16x16x32_bf16 v[50:53], v[144:147], v[196:199], v[50:53]
	v_mfma_f32_16x16x32_bf16 v[42:45], v[152:155], v[196:199], v[42:45]
	v_mfma_f32_16x16x32_bf16 v[34:37], v[144:147], v[204:207], v[34:37]
	v_mfma_f32_16x16x32_bf16 v[26:29], v[152:155], v[204:207], v[26:29]
	v_mfma_f32_16x16x32_bf16 v[18:21], v[144:147], v[212:215], v[18:21]
	v_mfma_f32_16x16x32_bf16 v[10:13], v[152:155], v[212:215], v[10:13]
	v_mfma_f32_16x16x32_bf16 v[62:65], v[148:151], v[180:183], v[62:65]
	v_mfma_f32_16x16x32_bf16 v[58:61], v[156:159], v[180:183], v[58:61]
	v_mfma_f32_16x16x32_bf16 v[50:53], v[148:151], v[200:203], v[50:53]
	v_mfma_f32_16x16x32_bf16 v[42:45], v[156:159], v[200:203], v[42:45]
	v_mfma_f32_16x16x32_bf16 v[34:37], v[148:151], v[208:211], v[34:37]
	v_mfma_f32_16x16x32_bf16 v[26:29], v[156:159], v[208:211], v[26:29]
	v_mfma_f32_16x16x32_bf16 v[18:21], v[148:151], v[216:219], v[18:21]
	v_mfma_f32_16x16x32_bf16 v[10:13], v[156:159], v[216:219], v[10:13]
	s_setprio 0
	s_setprio 1
	v_mfma_f32_16x16x32_bf16 v[54:57], v[160:163], v[176:179], v[54:57]
	v_mfma_f32_16x16x32_bf16 v[46:49], v[168:171], v[176:179], v[46:49]
	v_mfma_f32_16x16x32_bf16 v[38:41], v[160:163], v[196:199], v[38:41]
	v_mfma_f32_16x16x32_bf16 v[30:33], v[168:171], v[196:199], v[30:33]
	v_mfma_f32_16x16x32_bf16 v[22:25], v[160:163], v[204:207], v[22:25]
	v_mfma_f32_16x16x32_bf16 v[14:17], v[168:171], v[204:207], v[14:17]
	v_mfma_f32_16x16x32_bf16 v[6:9], v[160:163], v[212:215], v[6:9]
	v_mfma_f32_16x16x32_bf16 v[2:5], v[168:171], v[212:215], v[2:5]
	v_mfma_f32_16x16x32_bf16 v[54:57], v[164:167], v[180:183], v[54:57]
	v_mfma_f32_16x16x32_bf16 v[46:49], v[172:175], v[180:183], v[46:49]
	v_mfma_f32_16x16x32_bf16 v[38:41], v[164:167], v[200:203], v[38:41]
	v_mfma_f32_16x16x32_bf16 v[30:33], v[172:175], v[200:203], v[30:33]
	v_mfma_f32_16x16x32_bf16 v[22:25], v[164:167], v[208:211], v[22:25]
	v_mfma_f32_16x16x32_bf16 v[14:17], v[172:175], v[208:211], v[14:17]
	v_mfma_f32_16x16x32_bf16 v[6:9], v[164:167], v[216:219], v[6:9]
	v_mfma_f32_16x16x32_bf16 v[2:5], v[172:175], v[216:219], v[2:5]
	s_setprio 0
	s_barrier
	s_movk_i32 s27, 0x100
	s_andn2_b64 vcc, exec, s[28:29]
	s_mov_b64 s[30:31], -1
	s_mov_b64 s[28:29], 0
	s_cbranch_vccz .LBB0_815
	s_and_b64 vcc, exec, s[6:7]
	s_cbranch_vccz .LBB0_818
	s_barrier

; #define PG8_STAGE(bufoff, gbase, voff) do { _Pragma("unroll") for (int _i = 0; _i < 2; ++_i) \
;         __builtin_amdgcn_global_load_lds((const unsigned*)((const char*)(gbase) + (voff)[_i]), (PG8_LAS unsigned*)(lds + (bufoff) + ldsw + _i * 8192), 16, 0, 0); } while (0)
; #define PG8_LDA(dst, b, h) do { _Pragma("unroll") for (int m = 0; m < 4; ++m) _Pragma("unroll") for (int k = 0; k < 2; ++k) dst[m][k] = *(const PG8_LAS bf16x8*)(lds + PG8_SA(b, h) + aoff + m * 2048 + k * 1024); } while (0)
; #define PG8_LDB(dst, b, h) do { _Pragma("unroll") for (int n = 0; n < 2; ++n) _Pragma("unroll") for (int k = 0; k < 2; ++k) dst[n][k] = *(const PG8_LAS bf16x8*)(lds + PG8_SB(b, h) + boff + n * 2048 + k * 1024); } while (0)
; #define PG8_WAIT_V(n) asm volatile("s_waitcnt vmcnt(" #n ")" ::: "memory")
; #define PG8_WAIT_L(n) asm volatile("s_waitcnt lgkmcnt(" #n ")" ::: "memory")
; #define PG8_BAR __builtin_amdgcn_s_barrier()
; #define PG8_SCHED __builtin_amdgcn_sched_barrier(0)
; template <class Epi, class Sched, bool ALIGN_EPI = false, bool SP2 = false, bool ABLK = false, bool BBLK = false>
; __device__ __forceinline__ void gemm_phase(PG8_LAS unsigned char* lds, const Gemm g, const Sched& S, const Epi& E) {
;     ...
;         const bool has_next = S.next(ui + 1, nxt);
;         const char* nA = has_next ? (const char*)g.A + (size_t)nxt.pm * tstepA : cA; const char* nB = has_next ? (const char*)g.Bt + (size_t)nxt.pn * tstepB : cB;
;         for (int t = 0; t < nt; t += 2) {
;             const bool last = (t == nt - 2);
;             const char* a1 = cA + (size_t)(t + 1) * kstepA;
;             const char* a2 = last ? nA : cA + (size_t)(t + 2) * kstepA; const char* b2 = last ? nB : cB + (size_t)(t + 2) * kstepB;
;             const char* a3 = a2 + kstepA; const char* b3 = b2 + kstepB;
;             if (last && has_next) S.a_ready(nxt);
;             if constexpr (SP2) {
;             PG8_LDB(B0, 0, 0); PG8_LDB(B1, 0, 1); PG8_SCHED; PG8_LDA(At, 0, 0); PG8_STAGE(PG8_SA(1, 1), a1 + hstepA, voffA);
;             PG8_WAIT_V(8); PG8_WAIT_L(0); PG8_BAR; PG8_MMA(0, 0, At, B0); PG8_MMA(0, 1, At, B1); PG8_BAR; PG8_SCHED;
;             PG8_LDA(At, 0, 1); PG8_STAGE(PG8_SB(0, 0), b2, voffB); PG8_STAGE(PG8_SB(0, 1), b2 + hstepB, voffB); PG8_STAGE(PG8_SA(0, 0), a2, voffA);
;             PG8_WAIT_V(8); PG8_WAIT_L(0); PG8_BAR; PG8_MMA(1, 0, At, B0); PG8_MMA(1, 1, At, B1); PG8_BAR; PG8_SCHED;
.LBB0_839:
	s_add_u32 s52, s22, s25
	s_addc_u32 s60, s23, 0
	s_add_u32 s34, s52, 0x100
	s_addc_u32 s35, s60, 0
	s_and_b64 s[30:31], s[28:29], exec
	s_cselect_b32 s35, s1, s35
	s_cselect_b32 s34, s7, s34
	s_add_u32 s25, s20, s25
	s_addc_u32 s30, s21, 0
	s_add_u32 s25, s25, 0x100
	s_addc_u32 s30, s30, 0
	s_add_i32 s75, 0, 0x10000
	s_and_b64 s[28:29], s[28:29], exec
	s_cselect_b32 s37, s11, s30
	s_cselect_b32 s36, s13, s25
	s_add_i32 s29, 0, 0x14000
	s_add_u32 s92, s52, 0x10080
	s_addc_u32 s93, s60, 0
	s_add_i32 s82, s75, s50
	s_add_i32 m0, s51, 0xc000
	s_add_i32 s52, s51, 0xe000
	s_add_i32 s91, s82, 0x2000
	v_add_u32_e32 v138, s75, v141
	s_add_u32 s60, s36, 0x10000
	ds_read_b128 v[144:147], v138
	ds_read_b128 v[148:151], v138 offset:1024
	ds_read_b128 v[152:155], v138 offset:2048
	ds_read_b128 v[156:159], v138 offset:3072
	v_add_u32_e32 v138, s29, v141
	s_addc_u32 s61, s37, 0
	s_add_i32 s95, s29, s50
	ds_read_b128 v[160:163], v138
	ds_read_b128 v[164:167], v138 offset:1024
	ds_read_b128 v[168:171], v138 offset:2048
	ds_read_b128 v[172:175], v138 offset:3072
	s_add_i32 s94, s95, 0x2000
	s_add_i32 s90, 0, 0x18000
	s_add_i32 s89, 0, 0x1c000
	s_add_u32 s30, s34, 0x10000
	s_addc_u32 s31, s35, 0
	s_add_i32 s88, s90, s50
	s_add_i32 s25, s88, 0x2000
	s_add_u32 s28, s36, 0x10080
	s_addc_u32 s29, s37, 0
	s_add_i32 s80, s89, s50
	s_add_i32 s75, s80, 0x2000
	v_lshl_add_u64 v[138:139], s[92:93], 0, v[130:131]
	ds_read_b128 v[176:179], v142
	ds_read_b128 v[180:183], v142 offset:1024
	ds_read_b128 v[196:199], v142 offset:2048
	ds_read_b128 v[200:203], v142 offset:3072
	ds_read_b128 v[204:207], v142 offset:4096
	ds_read_b128 v[208:211], v142 offset:5120
	ds_read_b128 v[212:215], v142 offset:6144
	ds_read_b128 v[216:219], v142 offset:7168
	global_load_lds_dwordx4 v[138:139], off
	v_lshl_add_u64 v[138:139], s[92:93], 0, v[134:135]
	s_mov_b32 m0, s52
	s_nop 0
	global_load_lds_dwordx4 v[138:139], off
	s_waitcnt vmcnt(8)
	s_waitcnt lgkmcnt(0)
	v_mfma_f32_16x16x32_bf16 v[126:129], v[144:147], v[176:179], v[126:129]
	v_mfma_f32_16x16x32_bf16 v[122:125], v[152:155], v[176:179], v[122:125]
	s_barrier
	s_setprio 1
	s_waitcnt lgkmcnt(0)
	v_mfma_f32_16x16x32_bf16 v[114:117], v[144:147], v[196:199], v[114:117]
	v_mfma_f32_16x16x32_bf16 v[106:109], v[152:155], v[196:199], v[106:109]
	v_mfma_f32_16x16x32_bf16 v[98:101], v[144:147], v[204:207], v[98:101]
	v_mfma_f32_16x16x32_bf16 v[90:93], v[152:155], v[204:207], v[90:93]
	v_mfma_f32_16x16x32_bf16 v[82:85], v[144:147], v[212:215], v[82:85]
	v_mfma_f32_16x16x32_bf16 v[74:77], v[152:155], v[212:215], v[74:77]
	v_mfma_f32_16x16x32_bf16 v[126:129], v[148:151], v[180:183], v[126:129]
	v_mfma_f32_16x16x32_bf16 v[122:125], v[156:159], v[180:183], v[122:125]
	v_mfma_f32_16x16x32_bf16 v[114:117], v[148:151], v[200:203], v[114:117]
	v_mfma_f32_16x16x32_bf16 v[106:109], v[156:159], v[200:203], v[106:109]
	v_mfma_f32_16x16x32_bf16 v[98:101], v[148:151], v[208:211], v[98:101]
	v_mfma_f32_16x16x32_bf16 v[90:93], v[156:159], v[208:211], v[90:93]
	v_mfma_f32_16x16x32_bf16 v[82:85], v[148:151], v[216:219], v[82:85]
	v_mfma_f32_16x16x32_bf16 v[74:77], v[156:159], v[216:219], v[74:77]
	s_setprio 0
	s_setprio 1
	v_mfma_f32_16x16x32_bf16 v[118:121], v[160:163], v[176:179], v[118:121]
	v_mfma_f32_16x16x32_bf16 v[110:113], v[168:171], v[176:179], v[110:113]
	v_mfma_f32_16x16x32_bf16 v[102:105], v[160:163], v[196:199], v[102:105]
	v_mfma_f32_16x16x32_bf16 v[94:97], v[168:171], v[196:199], v[94:97]
	v_mfma_f32_16x16x32_bf16 v[86:89], v[160:163], v[204:207], v[86:89]
	v_mfma_f32_16x16x32_bf16 v[78:81], v[168:171], v[204:207], v[78:81]
	v_mfma_f32_16x16x32_bf16 v[70:73], v[160:163], v[212:215], v[70:73]
	v_mfma_f32_16x16x32_bf16 v[66:69], v[168:171], v[212:215], v[66:69]
	v_mfma_f32_16x16x32_bf16 v[118:121], v[164:167], v[180:183], v[118:121]
	v_mfma_f32_16x16x32_bf16 v[110:113], v[172:175], v[180:183], v[110:113]
	v_mfma_f32_16x16x32_bf16 v[102:105], v[164:167], v[200:203], v[102:105]
	v_mfma_f32_16x16x32_bf16 v[94:97], v[172:175], v[200:203], v[94:97]
	v_mfma_f32_16x16x32_bf16 v[86:89], v[164:167], v[208:211], v[86:89]
	v_mfma_f32_16x16x32_bf16 v[78:81], v[172:175], v[208:211], v[78:81]
	v_mfma_f32_16x16x32_bf16 v[70:73], v[164:167], v[216:219], v[70:73]
	v_mfma_f32_16x16x32_bf16 v[66:69], v[172:175], v[216:219], v[66:69]
	s_setprio 0
	s_barrier
	s_mov_b32 m0, s82
	v_lshl_add_u64 v[138:139], s[36:37], 0, v[132:133]
	ds_read_b128 v[176:179], v142 offset:16384
	ds_read_b128 v[180:183], v142 offset:17408
	ds_read_b128 v[196:199], v142 offset:18432
	ds_read_b128 v[200:203], v142 offset:19456
	ds_read_b128 v[204:207], v142 offset:20480
	ds_read_b128 v[208:211], v142 offset:21504
	ds_read_b128 v[212:215], v142 offset:22528
	ds_read_b128 v[216:219], v142 offset:23552
	global_load_lds_dwordx4 v[138:139], off
	v_lshl_add_u64 v[184:185], s[36:37], 0, v[136:137]
	s_mov_b32 m0, s91
	v_lshl_add_u64 v[220:221], s[60:61], 0, v[132:133]
	global_load_lds_dwordx4 v[184:185], off
	s_mov_b32 m0, s95
	v_lshl_add_u64 v[222:223], s[34:35], 0, v[134:135]
	global_load_lds_dwordx4 v[220:221], off
	v_lshl_add_u64 v[220:221], s[60:61], 0, v[136:137]
	s_mov_b32 m0, s94
	s_nop 0
	global_load_lds_dwordx4 v[220:221], off
	v_lshl_add_u64 v[220:221], s[34:35], 0, v[130:131]
	s_mov_b32 m0, s51
	s_nop 0
	global_load_lds_dwordx4 v[220:221], off
	s_mov_b32 m0, s65
	s_nop 0
	global_load_lds_dwordx4 v[222:223], off
	s_waitcnt vmcnt(8)
	s_waitcnt lgkmcnt(0)
	v_mfma_f32_16x16x32_bf16 v[62:65], v[144:147], v[176:179], v[62:65]
	v_mfma_f32_16x16x32_bf16 v[58:61], v[152:155], v[176:179], v[58:61]
	s_barrier
; #define PG8_STAGE(bufoff, gbase, voff) do { _Pragma("unroll") for (int _i = 0; _i < 2; ++_i) \
;         __builtin_amdgcn_global_load_lds((const unsigned*)((const char*)(gbase) + (voff)[_i]), (PG8_LAS unsigned*)(lds + (bufoff) + ldsw + _i * 8192), 16, 0, 0); } while (0)
; #define PG8_LDA(dst, b, h) do { _Pragma("unroll") for (int m = 0; m < 4; ++m) _Pragma("unroll") for (int k = 0; k < 2; ++k) dst[m][k] = *(const PG8_LAS bf16x8*)(lds + PG8_SA(b, h) + aoff + m * 2048 + k * 1024); } while (0)
; #define PG8_LDB(dst, b, h) do { _Pragma("unroll") for (int n = 0; n < 2; ++n) _Pragma("unroll") for (int k = 0; k < 2; ++k) dst[n][k] = *(const PG8_LAS bf16x8*)(lds + PG8_SB(b, h) + boff + n * 2048 + k * 1024); } while (0)
; #define PG8_MMA(ai, bj, At, Bt) do { __builtin_amdgcn_s_setprio(1); _Pragma("unroll") for (int m = 0; m < 4; ++m) _Pragma("unroll") for (int n = 0; n < 2; ++n) _Pragma("unroll") for (int k = 0; k < 2; ++k) \
;         acc[ai][bj][m][n] = __builtin_amdgcn_mfma_f32_16x16x32_bf16(Bt[n][k], At[m][k], acc[ai][bj][m][n], 0, 0, 0); __builtin_amdgcn_s_setprio(0); } while (0)
; #define PG8_WAIT_V(n) asm volatile("s_waitcnt vmcnt(" #n ")" ::: "memory")
; #define PG8_WAIT_L(n) asm volatile("s_waitcnt lgkmcnt(" #n ")" ::: "memory")
; #define PG8_BAR __builtin_amdgcn_s_barrier()
; #define PG8_SCHED __builtin_amdgcn_sched_barrier(0)
; template <class Epi, class Sched, bool ALIGN_EPI = false, bool SP2 = false, bool ABLK = false, bool BBLK = false>
; __device__ __forceinline__ void gemm_phase(PG8_LAS unsigned char* lds, const Gemm g, const Sched& S, const Epi& E) {
;     ...
;             PG8_WAIT_V(8); PG8_WAIT_L(0); PG8_BAR; PG8_MMA(1, 0, At, B0); PG8_MMA(1, 1, At, B1); PG8_BAR; PG8_SCHED;
;             PG8_LDB(B0, 1, 0); PG8_LDB(B1, 1, 1); PG8_SCHED; PG8_LDA(At, 1, 0); PG8_STAGE(PG8_SA(0, 1), a2 + hstepA, voffA);
;             PG8_WAIT_V(8); PG8_WAIT_L(0); PG8_BAR; PG8_MMA(0, 0, At, B0); PG8_MMA(0, 1, At, B1); PG8_BAR; PG8_SCHED;
	s_setprio 1
	s_waitcnt lgkmcnt(0)
	v_mfma_f32_16x16x32_bf16 v[50:53], v[144:147], v[196:199], v[50:53]
	v_mfma_f32_16x16x32_bf16 v[42:45], v[152:155], v[196:199], v[42:45]
	v_mfma_f32_16x16x32_bf16 v[34:37], v[144:147], v[204:207], v[34:37]
	v_mfma_f32_16x16x32_bf16 v[26:29], v[152:155], v[204:207], v[26:29]
	v_mfma_f32_16x16x32_bf16 v[18:21], v[144:147], v[212:215], v[18:21]
	v_mfma_f32_16x16x32_bf16 v[10:13], v[152:155], v[212:215], v[10:13]
	v_mfma_f32_16x16x32_bf16 v[62:65], v[148:151], v[180:183], v[62:65]
	v_mfma_f32_16x16x32_bf16 v[58:61], v[156:159], v[180:183], v[58:61]
	v_mfma_f32_16x16x32_bf16 v[50:53], v[148:151], v[200:203], v[50:53]
	v_mfma_f32_16x16x32_bf16 v[42:45], v[156:159], v[200:203], v[42:45]
	v_mfma_f32_16x16x32_bf16 v[34:37], v[148:151], v[208:211], v[34:37]
	v_mfma_f32_16x16x32_bf16 v[26:29], v[156:159], v[208:211], v[26:29]
	v_mfma_f32_16x16x32_bf16 v[18:21], v[148:151], v[216:219], v[18:21]
	v_mfma_f32_16x16x32_bf16 v[10:13], v[156:159], v[216:219], v[10:13]
	s_setprio 0
	s_setprio 1
	v_mfma_f32_16x16x32_bf16 v[54:57], v[160:163], v[176:179], v[54:57]
	v_mfma_f32_16x16x32_bf16 v[46:49], v[168:171], v[176:179], v[46:49]
	v_mfma_f32_16x16x32_bf16 v[38:41], v[160:163], v[196:199], v[38:41]
	v_mfma_f32_16x16x32_bf16 v[30:33], v[168:171], v[196:199], v[30:33]
	v_mfma_f32_16x16x32_bf16 v[22:25], v[160:163], v[204:207], v[22:25]
	v_mfma_f32_16x16x32_bf16 v[14:17], v[168:171], v[204:207], v[14:17]
	v_mfma_f32_16x16x32_bf16 v[6:9], v[160:163], v[212:215], v[6:9]
	v_mfma_f32_16x16x32_bf16 v[2:5], v[168:171], v[212:215], v[2:5]
	v_mfma_f32_16x16x32_bf16 v[54:57], v[164:167], v[180:183], v[54:57]
	v_mfma_f32_16x16x32_bf16 v[46:49], v[172:175], v[180:183], v[46:49]
	v_mfma_f32_16x16x32_bf16 v[38:41], v[164:167], v[200:203], v[38:41]
	v_mfma_f32_16x16x32_bf16 v[30:33], v[172:175], v[200:203], v[30:33]
	v_mfma_f32_16x16x32_bf16 v[22:25], v[164:167], v[208:211], v[22:25]
	v_mfma_f32_16x16x32_bf16 v[14:17], v[172:175], v[208:211], v[14:17]
	v_mfma_f32_16x16x32_bf16 v[6:9], v[164:167], v[216:219], v[6:9]
	v_mfma_f32_16x16x32_bf16 v[2:5], v[172:175], v[216:219], v[2:5]
	s_setprio 0
	s_barrier
	v_add_u32_e32 v143, s90, v141
	ds_read_b128 v[144:147], v143
	ds_read_b128 v[148:151], v143 offset:1024
	ds_read_b128 v[152:155], v143 offset:2048
	ds_read_b128 v[156:159], v143 offset:3072
	v_add_u32_e32 v143, s89, v141
	ds_read_b128 v[160:163], v143
	ds_read_b128 v[164:167], v143 offset:1024
	ds_read_b128 v[168:171], v143 offset:2048
	ds_read_b128 v[172:175], v143 offset:3072
	s_mov_b32 m0, s68
	v_lshl_add_u64 v[224:225], s[30:31], 0, v[130:131]
	ds_read_b128 v[176:179], v142 offset:32768
	ds_read_b128 v[180:183], v142 offset:33792
	ds_read_b128 v[196:199], v142 offset:34816
	ds_read_b128 v[200:203], v142 offset:35840
	ds_read_b128 v[204:207], v142 offset:36864
	ds_read_b128 v[208:211], v142 offset:37888
	ds_read_b128 v[212:215], v142 offset:38912
	ds_read_b128 v[216:219], v142 offset:39936
	global_load_lds_dwordx4 v[224:225], off
	v_lshl_add_u64 v[224:225], s[30:31], 0, v[134:135]
	s_mov_b32 m0, s72
	s_nop 0
	global_load_lds_dwordx4 v[224:225], off
	s_waitcnt vmcnt(8)
	s_waitcnt lgkmcnt(0)
	v_mfma_f32_16x16x32_bf16 v[126:129], v[144:147], v[176:179], v[126:129]
	v_mfma_f32_16x16x32_bf16 v[122:125], v[152:155], v[176:179], v[122:125]
	s_barrier
	s_setprio 1
	s_waitcnt lgkmcnt(0)
	v_mfma_f32_16x16x32_bf16 v[114:117], v[144:147], v[196:199], v[114:117]
	v_mfma_f32_16x16x32_bf16 v[106:109], v[152:155], v[196:199], v[106:109]
	v_mfma_f32_16x16x32_bf16 v[98:101], v[144:147], v[204:207], v[98:101]
	v_mfma_f32_16x16x32_bf16 v[90:93], v[152:155], v[204:207], v[90:93]
	v_mfma_f32_16x16x32_bf16 v[82:85], v[144:147], v[212:215], v[82:85]
	v_mfma_f32_16x16x32_bf16 v[74:77], v[152:155], v[212:215], v[74:77]
	v_mfma_f32_16x16x32_bf16 v[126:129], v[148:151], v[180:183], v[126:129]
	v_mfma_f32_16x16x32_bf16 v[122:125], v[156:159], v[180:183], v[122:125]
	v_mfma_f32_16x16x32_bf16 v[114:117], v[148:151], v[200:203], v[114:117]
	v_mfma_f32_16x16x32_bf16 v[106:109], v[156:159], v[200:203], v[106:109]
	v_mfma_f32_16x16x32_bf16 v[98:101], v[148:151], v[208:211], v[98:101]
	v_mfma_f32_16x16x32_bf16 v[90:93], v[156:159], v[208:211], v[90:93]
	v_mfma_f32_16x16x32_bf16 v[82:85], v[148:151], v[216:219], v[82:85]
	v_mfma_f32_16x16x32_bf16 v[74:77], v[156:159], v[216:219], v[74:77]
	s_setprio 0
	s_setprio 1
	v_mfma_f32_16x16x32_bf16 v[118:121], v[160:163], v[176:179], v[118:121]
	v_mfma_f32_16x16x32_bf16 v[110:113], v[168:171], v[176:179], v[110:113]
	v_mfma_f32_16x16x32_bf16 v[102:105], v[160:163], v[196:199], v[102:105]
	v_mfma_f32_16x16x32_bf16 v[94:97], v[168:171], v[196:199], v[94:97]
	v_mfma_f32_16x16x32_bf16 v[86:89], v[160:163], v[204:207], v[86:89]
	v_mfma_f32_16x16x32_bf16 v[78:81], v[168:171], v[204:207], v[78:81]
	v_mfma_f32_16x16x32_bf16 v[70:73], v[160:163], v[212:215], v[70:73]
	v_mfma_f32_16x16x32_bf16 v[66:69], v[168:171], v[212:215], v[66:69]
	v_mfma_f32_16x16x32_bf16 v[118:121], v[164:167], v[180:183], v[118:121]
	v_mfma_f32_16x16x32_bf16 v[110:113], v[172:175], v[180:183], v[110:113]
	v_mfma_f32_16x16x32_bf16 v[102:105], v[164:167], v[200:203], v[102:105]
	v_mfma_f32_16x16x32_bf16 v[94:97], v[172:175], v[200:203], v[94:97]
	v_mfma_f32_16x16x32_bf16 v[86:89], v[164:167], v[208:211], v[86:89]
	v_mfma_f32_16x16x32_bf16 v[78:81], v[172:175], v[208:211], v[78:81]
	v_mfma_f32_16x16x32_bf16 v[70:73], v[164:167], v[216:219], v[70:73]
	v_mfma_f32_16x16x32_bf16 v[66:69], v[172:175], v[216:219], v[66:69]
	s_setprio 0
	s_barrier
; #define PG8_STAGE(bufoff, gbase, voff) do { _Pragma("unroll") for (int _i = 0; _i < 2; ++_i) \
;         __builtin_amdgcn_global_load_lds((const unsigned*)((const char*)(gbase) + (voff)[_i]), (PG8_LAS unsigned*)(lds + (bufoff) + ldsw + _i * 8192), 16, 0, 0); } while (0)
; #define PG8_LDA(dst, b, h) do { _Pragma("unroll") for (int m = 0; m < 4; ++m) _Pragma("unroll") for (int k = 0; k < 2; ++k) dst[m][k] = *(const PG8_LAS bf16x8*)(lds + PG8_SA(b, h) + aoff + m * 2048 + k * 1024); } while (0)
; #define PG8_MMA(ai, bj, At, Bt) do { __builtin_amdgcn_s_setprio(1); _Pragma("unroll") for (int m = 0; m < 4; ++m) _Pragma("unroll") for (int n = 0; n < 2; ++n) _Pragma("unroll") for (int k = 0; k < 2; ++k) \
;         acc[ai][bj][m][n] = __builtin_amdgcn_mfma_f32_16x16x32_bf16(Bt[n][k], At[m][k], acc[ai][bj][m][n], 0, 0, 0); __builtin_amdgcn_s_setprio(0); } while (0)
; #define PG8_WAIT_V(n) asm volatile("s_waitcnt vmcnt(" #n ")" ::: "memory")
; #define PG8_WAIT_L(n) asm volatile("s_waitcnt lgkmcnt(" #n ")" ::: "memory")
; #define PG8_BAR __builtin_amdgcn_s_barrier()
; #define PG8_SCHED __builtin_amdgcn_sched_barrier(0)
; template <class Epi, class Sched, bool ALIGN_EPI = false, bool SP2 = false, bool ABLK = false, bool BBLK = false>
; __device__ __forceinline__ void gemm_phase(PG8_LAS unsigned char* lds, const Gemm g, const Sched& S, const Epi& E) {
;     ...
;             PG8_LDA(At, 1, 1); PG8_STAGE(PG8_SB(1, 0), b3, voffB); PG8_STAGE(PG8_SB(1, 1), b3 + hstepB, voffB); PG8_STAGE(PG8_SA(1, 0), a3, voffA);
;             PG8_WAIT_V(8); PG8_WAIT_L(0); PG8_BAR; PG8_MMA(1, 0, At, B0); PG8_MMA(1, 1, At, B1); PG8_BAR; PG8_SCHED;
;     ...
;         if constexpr (ALIGN_EPI) { if (wr == 0) PG8_BAR; }
	s_mov_b32 m0, s88
	v_lshl_add_u64 v[138:139], v[138:139], 0, s[62:63]
	ds_read_b128 v[176:179], v142 offset:49152
	ds_read_b128 v[180:183], v142 offset:50176
	ds_read_b128 v[196:199], v142 offset:51200
	ds_read_b128 v[200:203], v142 offset:52224
	ds_read_b128 v[204:207], v142 offset:53248
	ds_read_b128 v[208:211], v142 offset:54272
	ds_read_b128 v[212:215], v142 offset:55296
	ds_read_b128 v[216:219], v142 offset:56320
	global_load_lds_dwordx4 v[138:139], off
	v_lshl_add_u64 v[138:139], v[184:185], 0, s[62:63]
	s_mov_b32 m0, s25
	s_nop 0
	global_load_lds_dwordx4 v[138:139], off
	v_lshl_add_u64 v[138:139], s[28:29], 0, v[132:133]
	s_mov_b32 m0, s80
	s_nop 0
	global_load_lds_dwordx4 v[138:139], off
	v_lshl_add_u64 v[138:139], s[28:29], 0, v[136:137]
	s_mov_b32 m0, s75
	s_nop 0
	global_load_lds_dwordx4 v[138:139], off
	v_lshl_add_u64 v[138:139], v[220:221], 0, s[62:63]
	s_mov_b32 m0, s81
	s_nop 0
	global_load_lds_dwordx4 v[138:139], off
	v_lshl_add_u64 v[138:139], v[222:223], 0, s[62:63]
	s_mov_b32 m0, s83
	s_nop 0
	global_load_lds_dwordx4 v[138:139], off
	s_waitcnt vmcnt(8)
	s_waitcnt lgkmcnt(0)
	v_mfma_f32_16x16x32_bf16 v[62:65], v[144:147], v[176:179], v[62:65]
	v_mfma_f32_16x16x32_bf16 v[58:61], v[152:155], v[176:179], v[58:61]
	s_barrier
	s_setprio 1
	s_waitcnt lgkmcnt(0)
	v_mfma_f32_16x16x32_bf16 v[50:53], v[144:147], v[196:199], v[50:53]
	v_mfma_f32_16x16x32_bf16 v[42:45], v[152:155], v[196:199], v[42:45]
	v_mfma_f32_16x16x32_bf16 v[34:37], v[144:147], v[204:207], v[34:37]
	v_mfma_f32_16x16x32_bf16 v[26:29], v[152:155], v[204:207], v[26:29]
	v_mfma_f32_16x16x32_bf16 v[18:21], v[144:147], v[212:215], v[18:21]
	v_mfma_f32_16x16x32_bf16 v[10:13], v[152:155], v[212:215], v[10:13]
	v_mfma_f32_16x16x32_bf16 v[62:65], v[148:151], v[180:183], v[62:65]
	v_mfma_f32_16x16x32_bf16 v[58:61], v[156:159], v[180:183], v[58:61]
	v_mfma_f32_16x16x32_bf16 v[50:53], v[148:151], v[200:203], v[50:53]
	v_mfma_f32_16x16x32_bf16 v[42:45], v[156:159], v[200:203], v[42:45]
	v_mfma_f32_16x16x32_bf16 v[34:37], v[148:151], v[208:211], v[34:37]
	v_mfma_f32_16x16x32_bf16 v[26:29], v[156:159], v[208:211], v[26:29]
	v_mfma_f32_16x16x32_bf16 v[18:21], v[148:151], v[216:219], v[18:21]
	v_mfma_f32_16x16x32_bf16 v[10:13], v[156:159], v[216:219], v[10:13]
	s_setprio 0
	s_setprio 1
	v_mfma_f32_16x16x32_bf16 v[54:57], v[160:163], v[176:179], v[54:57]
	v_mfma_f32_16x16x32_bf16 v[46:49], v[168:171], v[176:179], v[46:49]
	v_mfma_f32_16x16x32_bf16 v[38:41], v[160:163], v[196:199], v[38:41]
	v_mfma_f32_16x16x32_bf16 v[30:33], v[168:171], v[196:199], v[30:33]
	v_mfma_f32_16x16x32_bf16 v[22:25], v[160:163], v[204:207], v[22:25]
	v_mfma_f32_16x16x32_bf16 v[14:17], v[168:171], v[204:207], v[14:17]
	v_mfma_f32_16x16x32_bf16 v[6:9], v[160:163], v[212:215], v[6:9]
	v_mfma_f32_16x16x32_bf16 v[2:5], v[168:171], v[212:215], v[2:5]
	v_mfma_f32_16x16x32_bf16 v[54:57], v[164:167], v[180:183], v[54:57]
	v_mfma_f32_16x16x32_bf16 v[46:49], v[172:175], v[180:183], v[46:49]
	v_mfma_f32_16x16x32_bf16 v[38:41], v[164:167], v[200:203], v[38:41]
	v_mfma_f32_16x16x32_bf16 v[30:33], v[172:175], v[200:203], v[30:33]
	v_mfma_f32_16x16x32_bf16 v[22:25], v[164:167], v[208:211], v[22:25]
	v_mfma_f32_16x16x32_bf16 v[14:17], v[172:175], v[208:211], v[14:17]
	v_mfma_f32_16x16x32_bf16 v[6:9], v[164:167], v[216:219], v[6:9]
	v_mfma_f32_16x16x32_bf16 v[2:5], v[172:175], v[216:219], v[2:5]
	s_setprio 0
	s_barrier
	s_movk_i32 s25, 0x100
	s_andn2_b64 vcc, exec, s[26:27]
	s_mov_b64 s[28:29], -1
	s_mov_b64 s[26:27], 0
	s_cbranch_vccz .LBB0_839
	s_and_b64 vcc, exec, s[4:5]
	s_cbranch_vccz .LBB0_842
	s_barrier

; #define PG8_STAGE(bufoff, gbase, voff) do { _Pragma("unroll") for (int _i = 0; _i < 2; ++_i) \
;         __builtin_amdgcn_global_load_lds((const unsigned*)((const char*)(gbase) + (voff)[_i]), (PG8_LAS unsigned*)(lds + (bufoff) + ldsw + _i * 8192), 16, 0, 0); } while (0)
; #define PG8_LDA(dst, b, h) do { _Pragma("unroll") for (int m = 0; m < 4; ++m) _Pragma("unroll") for (int k = 0; k < 2; ++k) dst[m][k] = *(const PG8_LAS bf16x8*)(lds + PG8_SA(b, h) + aoff + m * 2048 + k * 1024); } while (0)
; #define PG8_LDB(dst, b, h) do { _Pragma("unroll") for (int n = 0; n < 2; ++n) _Pragma("unroll") for (int k = 0; k < 2; ++k) dst[n][k] = *(const PG8_LAS bf16x8*)(lds + PG8_SB(b, h) + boff + n * 2048 + k * 1024); } while (0)
; #define PG8_WAIT_V(n) asm volatile("s_waitcnt vmcnt(" #n ")" ::: "memory")
; #define PG8_WAIT_L(n) asm volatile("s_waitcnt lgkmcnt(" #n ")" ::: "memory")
; #define PG8_BAR __builtin_amdgcn_s_barrier()
; #define PG8_SCHED __builtin_amdgcn_sched_barrier(0)
; template <class Epi, class Sched, bool ALIGN_EPI = false, bool SP2 = false, bool ABLK = false, bool BBLK = false>
; __device__ __forceinline__ void gemm_phase(PG8_LAS unsigned char* lds, const Gemm g, const Sched& S, const Epi& E) {
;     ...
;         const bool has_next = S.next(ui + 1, nxt);
;         const char* nA = has_next ? (const char*)g.A + (size_t)nxt.pm * tstepA : cA; const char* nB = has_next ? (const char*)g.Bt + (size_t)nxt.pn * tstepB : cB;
;         for (int t = 0; t < nt; t += 2) {
;             const bool last = (t == nt - 2);
;             const char* a1 = cA + (size_t)(t + 1) * kstepA;
;             const char* a2 = last ? nA : cA + (size_t)(t + 2) * kstepA; const char* b2 = last ? nB : cB + (size_t)(t + 2) * kstepB;
;             const char* a3 = a2 + kstepA; const char* b3 = b2 + kstepB;
;             if (last && has_next) S.a_ready(nxt);
;             if constexpr (SP2) {
;             PG8_LDB(B0, 0, 0); PG8_LDB(B1, 0, 1); PG8_SCHED; PG8_LDA(At, 0, 0); PG8_STAGE(PG8_SA(1, 1), a1 + hstepA, voffA);
;             PG8_WAIT_V(8); PG8_WAIT_L(0); PG8_BAR; PG8_MMA(0, 0, At, B0); PG8_MMA(0, 1, At, B1); PG8_BAR; PG8_SCHED;
;             PG8_LDA(At, 0, 1); PG8_STAGE(PG8_SB(0, 0), b2, voffB); PG8_STAGE(PG8_SB(0, 1), b2 + hstepB, voffB); PG8_STAGE(PG8_SA(0, 0), a2, voffA);
;             PG8_WAIT_V(8); PG8_WAIT_L(0); PG8_BAR; PG8_MMA(1, 0, At, B0); PG8_MMA(1, 1, At, B1); PG8_BAR; PG8_SCHED;
.LBB0_912:
	s_ashr_i32 s13, s12, 31
	s_lshl_b64 s[18:19], s[12:13], 20
	s_add_u32 s18, s51, s18
	s_addc_u32 s19, s53, s19
	s_and_b64 s[20:21], s[14:15], exec
	s_cselect_b32 s29, s19, s23
	s_cselect_b32 s28, s18, s22
	s_ashr_i32 s11, s10, 31
	s_lshl_b64 s[20:21], s[10:11], 20
	s_add_u32 s20, s56, s20
	s_addc_u32 s21, s60, s21
	s_and_b64 s[26:27], s[14:15], exec
	s_cselect_b32 s27, s21, s25
	s_cselect_b32 s26, s20, s24
	s_add_i32 s75, 0, 0x10000
	v_add_u32_e32 v77, s75, v75
	ds_read_b128 v[2:5], v77
	ds_read_b128 v[6:9], v77 offset:1024
	ds_read_b128 v[10:13], v77 offset:2048
	ds_read_b128 v[14:17], v77 offset:3072
	s_add_u32 s90, s22, 0x80080
	s_addc_u32 s91, s23, 0
	s_add_i32 s80, s65, 0xc000
	v_lshl_add_u64 v[50:51], s[90:91], 0, v[70:71]
	s_mov_b32 m0, s80
	s_add_i32 s3, s65, 0xe000
	ds_read_b128 v[18:21], v76
	ds_read_b128 v[22:25], v76 offset:1024
	ds_read_b128 v[26:29], v76 offset:2048
	ds_read_b128 v[30:33], v76 offset:3072
	ds_read_b128 v[34:37], v76 offset:4096
	ds_read_b128 v[38:41], v76 offset:5120
	ds_read_b128 v[42:45], v76 offset:6144
	ds_read_b128 v[46:49], v76 offset:7168
	global_load_lds_dwordx4 v[50:51], off
	v_lshl_add_u64 v[50:51], s[90:91], 0, v[68:69]
	s_mov_b32 m0, s3
	s_nop 0
	global_load_lds_dwordx4 v[50:51], off
	s_waitcnt vmcnt(8)
	s_waitcnt lgkmcnt(0)
	v_mfma_f32_16x16x32_bf16 v[50:53], v[2:5], v[18:21], 0
	v_mfma_f32_16x16x32_bf16 v[18:21], v[10:13], v[18:21], 0
	s_barrier
	s_setprio 1
	s_waitcnt lgkmcnt(0)
	v_mfma_f32_16x16x32_bf16 v[50:53], v[6:9], v[22:25], v[50:53]
	v_mfma_f32_16x16x32_bf16 v[18:21], v[14:17], v[22:25], v[18:21]
	v_mfma_f32_16x16x32_bf16 v[22:25], v[2:5], v[26:29], 0
	v_mfma_f32_16x16x32_bf16 v[26:29], v[10:13], v[26:29], 0
	v_mfma_f32_16x16x32_bf16 v[22:25], v[6:9], v[30:33], v[22:25]
	v_mfma_f32_16x16x32_bf16 v[26:29], v[14:17], v[30:33], v[26:29]
	v_mfma_f32_16x16x32_bf16 v[30:33], v[2:5], v[34:37], 0
	v_mfma_f32_16x16x32_bf16 v[34:37], v[10:13], v[34:37], 0
	v_mfma_f32_16x16x32_bf16 v[30:33], v[6:9], v[38:41], v[30:33]
	v_mfma_f32_16x16x32_bf16 v[34:37], v[14:17], v[38:41], v[34:37]
	v_mfma_f32_16x16x32_bf16 v[38:41], v[2:5], v[42:45], 0
	v_mfma_f32_16x16x32_bf16 v[42:45], v[10:13], v[42:45], 0
	v_mfma_f32_16x16x32_bf16 v[38:41], v[6:9], v[46:49], v[38:41]
	v_mfma_f32_16x16x32_bf16 v[42:45], v[14:17], v[46:49], v[42:45]
	s_setprio 0
	s_setprio 1
	s_setprio 0
	s_barrier
	s_add_i32 s75, s75, s61
	v_lshl_add_u64 v[126:127], s[24:25], 0, v[186:187]
	s_add_i32 s11, s75, 0x2000
	v_lshl_add_u64 v[94:95], v[126:127], 0, s[58:59]
	s_mov_b32 m0, s75
	v_lshl_add_u64 v[128:129], s[24:25], 0, v[66:67]
	s_add_u32 s90, s24, 0x80100
	ds_read_b128 v[46:49], v76 offset:16384
	ds_read_b128 v[54:57], v76 offset:17408
	ds_read_b128 v[58:61], v76 offset:18432
	ds_read_b128 v[62:65], v76 offset:19456
	ds_read_b128 v[78:81], v76 offset:20480
	ds_read_b128 v[82:85], v76 offset:21504
	ds_read_b128 v[86:89], v76 offset:22528
	ds_read_b128 v[90:93], v76 offset:23552
	global_load_lds_dwordx4 v[94:95], off
	v_lshl_add_u64 v[94:95], v[128:129], 0, s[58:59]
	s_mov_b32 m0, s11
	s_addc_u32 s91, s25, 0
	global_load_lds_dwordx4 v[94:95], off
	v_lshl_add_u64 v[94:95], s[90:91], 0, v[186:187]
	s_mov_b32 m0, s68
	v_lshl_add_u64 v[130:131], s[22:23], 0, v[70:71]
	global_load_lds_dwordx4 v[94:95], off
	v_lshl_add_u64 v[94:95], s[90:91], 0, v[66:67]
	s_mov_b32 m0, s72
	v_lshl_add_u64 v[132:133], s[22:23], 0, v[68:69]
	global_load_lds_dwordx4 v[94:95], off
	v_lshl_add_u64 v[94:95], v[130:131], 0, s[58:59]
	s_mov_b32 m0, s65
	s_nop 0
	global_load_lds_dwordx4 v[94:95], off
	v_lshl_add_u64 v[94:95], v[132:133], 0, s[58:59]
	s_mov_b32 m0, s73
	s_nop 0
	global_load_lds_dwordx4 v[94:95], off
	s_waitcnt vmcnt(8)
	s_waitcnt lgkmcnt(0)
	v_mfma_f32_16x16x32_bf16 v[94:97], v[2:5], v[46:49], 0
	v_mfma_f32_16x16x32_bf16 v[46:49], v[10:13], v[46:49], 0
	s_barrier
	s_setprio 1
	s_waitcnt lgkmcnt(0)
	v_mfma_f32_16x16x32_bf16 v[94:97], v[6:9], v[54:57], v[94:97]
	v_mfma_f32_16x16x32_bf16 v[46:49], v[14:17], v[54:57], v[46:49]
	v_mfma_f32_16x16x32_bf16 v[54:57], v[2:5], v[58:61], 0
	v_mfma_f32_16x16x32_bf16 v[58:61], v[10:13], v[58:61], 0
	v_mfma_f32_16x16x32_bf16 v[54:57], v[6:9], v[62:65], v[54:57]
	v_mfma_f32_16x16x32_bf16 v[58:61], v[14:17], v[62:65], v[58:61]
	v_mfma_f32_16x16x32_bf16 v[62:65], v[2:5], v[78:81], 0
	v_mfma_f32_16x16x32_bf16 v[2:5], v[2:5], v[86:89], 0
	v_mfma_f32_16x16x32_bf16 v[62:65], v[6:9], v[82:85], v[62:65]
	v_mfma_f32_16x16x32_bf16 v[2:5], v[6:9], v[90:93], v[2:5]
	v_mfma_f32_16x16x32_bf16 v[6:9], v[10:13], v[86:89], 0
	v_mfma_f32_16x16x32_bf16 v[78:81], v[10:13], v[78:81], 0
	v_mfma_f32_16x16x32_bf16 v[6:9], v[14:17], v[90:93], v[6:9]
	v_mfma_f32_16x16x32_bf16 v[78:81], v[14:17], v[82:85], v[78:81]
	s_setprio 0
	s_setprio 1
	s_setprio 0
	s_barrier
	s_add_i32 s82, 0, 0x18000
	v_add_u32_e32 v136, s82, v75
	ds_read_b128 v[10:13], v136
	ds_read_b128 v[14:17], v136 offset:1024
	ds_read_b128 v[82:85], v136 offset:2048
	ds_read_b128 v[86:89], v136 offset:3072
	s_add_u32 s90, s22, 0x80100
	s_addc_u32 s91, s23, 0
	s_mov_b32 m0, s81
	v_lshl_add_u64 v[134:135], s[90:91], 0, v[70:71]
	ds_read_b128 v[90:93], v76 offset:32768
	ds_read_b128 v[98:101], v76 offset:33792
	ds_read_b128 v[102:105], v76 offset:34816
	ds_read_b128 v[106:109], v76 offset:35840
	ds_read_b128 v[110:113], v76 offset:36864
	ds_read_b128 v[114:117], v76 offset:37888
	ds_read_b128 v[118:121], v76 offset:38912
	ds_read_b128 v[122:125], v76 offset:39936
	global_load_lds_dwordx4 v[134:135], off
	v_lshl_add_u64 v[134:135], s[90:91], 0, v[68:69]
	s_mov_b32 m0, s83
	s_nop 0
	global_load_lds_dwordx4 v[134:135], off
	s_waitcnt vmcnt(8)
	s_waitcnt lgkmcnt(0)
	v_mfma_f32_16x16x32_bf16 v[50:53], v[10:13], v[90:93], v[50:53]
	v_mfma_f32_16x16x32_bf16 v[18:21], v[82:85], v[90:93], v[18:21]
	s_barrier
; #define PG8_STAGE(bufoff, gbase, voff) do { _Pragma("unroll") for (int _i = 0; _i < 2; ++_i) \
;         __builtin_amdgcn_global_load_lds((const unsigned*)((const char*)(gbase) + (voff)[_i]), (PG8_LAS unsigned*)(lds + (bufoff) + ldsw + _i * 8192), 16, 0, 0); } while (0)
; #define PG8_LDA(dst, b, h) do { _Pragma("unroll") for (int m = 0; m < 4; ++m) _Pragma("unroll") for (int k = 0; k < 2; ++k) dst[m][k] = *(const PG8_LAS bf16x8*)(lds + PG8_SA(b, h) + aoff + m * 2048 + k * 1024); } while (0)
; #define PG8_LDB(dst, b, h) do { _Pragma("unroll") for (int n = 0; n < 2; ++n) _Pragma("unroll") for (int k = 0; k < 2; ++k) dst[n][k] = *(const PG8_LAS bf16x8*)(lds + PG8_SB(b, h) + boff + n * 2048 + k * 1024); } while (0)
; #define PG8_MMA(ai, bj, At, Bt) do { __builtin_amdgcn_s_setprio(1); _Pragma("unroll") for (int m = 0; m < 4; ++m) _Pragma("unroll") for (int n = 0; n < 2; ++n) _Pragma("unroll") for (int k = 0; k < 2; ++k) \
;         acc[ai][bj][m][n] = __builtin_amdgcn_mfma_f32_16x16x32_bf16(Bt[n][k], At[m][k], acc[ai][bj][m][n], 0, 0, 0); __builtin_amdgcn_s_setprio(0); } while (0)
; #define PG8_WAIT_V(n) asm volatile("s_waitcnt vmcnt(" #n ")" ::: "memory")
; #define PG8_WAIT_L(n) asm volatile("s_waitcnt lgkmcnt(" #n ")" ::: "memory")
; #define PG8_BAR __builtin_amdgcn_s_barrier()
; #define PG8_SCHED __builtin_amdgcn_sched_barrier(0)
; template <class Epi, class Sched, bool ALIGN_EPI = false, bool SP2 = false, bool ABLK = false, bool BBLK = false>
; __device__ __forceinline__ void gemm_phase(PG8_LAS unsigned char* lds, const Gemm g, const Sched& S, const Epi& E) {
;     ...
;             PG8_LDA(At, 0, 1); PG8_STAGE(PG8_SB(0, 0), b2, voffB); PG8_STAGE(PG8_SB(0, 1), b2 + hstepB, voffB); PG8_STAGE(PG8_SA(0, 0), a2, voffA);
;             PG8_WAIT_V(8); PG8_WAIT_L(0); PG8_BAR; PG8_MMA(1, 0, At, B0); PG8_MMA(1, 1, At, B1); PG8_BAR; PG8_SCHED;
;             PG8_LDB(B0, 1, 0); PG8_LDB(B1, 1, 1); PG8_SCHED; PG8_LDA(At, 1, 0); PG8_STAGE(PG8_SA(0, 1), a2 + hstepA, voffA);
;             PG8_WAIT_V(8); PG8_WAIT_L(0); PG8_BAR; PG8_MMA(0, 0, At, B0); PG8_MMA(0, 1, At, B1); PG8_BAR; PG8_SCHED;
;             PG8_LDA(At, 1, 1); PG8_STAGE(PG8_SB(1, 0), b3, voffB); PG8_STAGE(PG8_SB(1, 1), b3 + hstepB, voffB); PG8_STAGE(PG8_SA(1, 0), a3, voffA);
	s_setprio 1
	s_waitcnt lgkmcnt(0)
	v_mfma_f32_16x16x32_bf16 v[22:25], v[10:13], v[102:105], v[22:25]
	v_mfma_f32_16x16x32_bf16 v[26:29], v[82:85], v[102:105], v[26:29]
	v_mfma_f32_16x16x32_bf16 v[30:33], v[10:13], v[110:113], v[30:33]
	v_mfma_f32_16x16x32_bf16 v[34:37], v[82:85], v[110:113], v[34:37]
	v_mfma_f32_16x16x32_bf16 v[38:41], v[10:13], v[118:121], v[38:41]
	v_mfma_f32_16x16x32_bf16 v[42:45], v[82:85], v[118:121], v[42:45]
	v_mfma_f32_16x16x32_bf16 v[50:53], v[14:17], v[98:101], v[50:53]
	v_mfma_f32_16x16x32_bf16 v[18:21], v[86:89], v[98:101], v[18:21]
	v_mfma_f32_16x16x32_bf16 v[22:25], v[14:17], v[106:109], v[22:25]
	v_mfma_f32_16x16x32_bf16 v[26:29], v[86:89], v[106:109], v[26:29]
	v_mfma_f32_16x16x32_bf16 v[30:33], v[14:17], v[114:117], v[30:33]
	v_mfma_f32_16x16x32_bf16 v[34:37], v[86:89], v[114:117], v[34:37]
	v_mfma_f32_16x16x32_bf16 v[38:41], v[14:17], v[122:125], v[38:41]
	v_mfma_f32_16x16x32_bf16 v[42:45], v[86:89], v[122:125], v[42:45]
	s_setprio 0
	s_setprio 1
	s_setprio 0
	s_barrier
	s_add_i32 s82, s82, s61
	s_add_i32 s13, s82, 0x2000
	v_lshl_add_u64 v[126:127], v[126:127], 0, s[70:71]
	s_mov_b32 m0, s82
	s_add_u32 s24, s24, 0x80180
	ds_read_b128 v[90:93], v76 offset:49152
	ds_read_b128 v[98:101], v76 offset:50176
	ds_read_b128 v[102:105], v76 offset:51200
	ds_read_b128 v[106:109], v76 offset:52224
	ds_read_b128 v[110:113], v76 offset:53248
	ds_read_b128 v[114:117], v76 offset:54272
	ds_read_b128 v[118:121], v76 offset:55296
	ds_read_b128 v[122:125], v76 offset:56320
	global_load_lds_dwordx4 v[126:127], off
	v_lshl_add_u64 v[126:127], v[128:129], 0, s[70:71]
	s_mov_b32 m0, s13
	s_addc_u32 s25, s25, 0
	global_load_lds_dwordx4 v[126:127], off
	v_lshl_add_u64 v[126:127], s[24:25], 0, v[186:187]
	s_mov_b32 m0, s88
	s_nop 0
	global_load_lds_dwordx4 v[126:127], off
	v_lshl_add_u64 v[126:127], s[24:25], 0, v[66:67]
	s_mov_b32 m0, s89
	s_nop 0
	global_load_lds_dwordx4 v[126:127], off
	v_lshl_add_u64 v[126:127], v[130:131], 0, s[70:71]
	s_mov_b32 m0, s84
	s_nop 0
	global_load_lds_dwordx4 v[126:127], off
	v_lshl_add_u64 v[126:127], v[132:133], 0, s[70:71]
	s_mov_b32 m0, s86
	s_nop 0
	global_load_lds_dwordx4 v[126:127], off
	s_waitcnt vmcnt(8)
	s_waitcnt lgkmcnt(0)
	v_mfma_f32_16x16x32_bf16 v[46:49], v[82:85], v[90:93], v[46:49]
	v_mfma_f32_16x16x32_bf16 v[54:57], v[10:13], v[102:105], v[54:57]
	s_barrier
	s_setprio 1
	s_waitcnt lgkmcnt(0)
	v_mfma_f32_16x16x32_bf16 v[58:61], v[82:85], v[102:105], v[58:61]
	v_mfma_f32_16x16x32_bf16 v[62:65], v[10:13], v[110:113], v[62:65]
	v_mfma_f32_16x16x32_bf16 v[2:5], v[10:13], v[118:121], v[2:5]
	v_mfma_f32_16x16x32_bf16 v[6:9], v[82:85], v[118:121], v[6:9]
	v_mfma_f32_16x16x32_bf16 v[94:97], v[10:13], v[90:93], v[94:97]
	v_mfma_f32_16x16x32_bf16 v[46:49], v[86:89], v[98:101], v[46:49]
	v_mfma_f32_16x16x32_bf16 v[54:57], v[14:17], v[106:109], v[54:57]
	v_mfma_f32_16x16x32_bf16 v[58:61], v[86:89], v[106:109], v[58:61]
	v_mfma_f32_16x16x32_bf16 v[62:65], v[14:17], v[114:117], v[62:65]
	v_mfma_f32_16x16x32_bf16 v[78:81], v[82:85], v[110:113], v[78:81]
	v_mfma_f32_16x16x32_bf16 v[2:5], v[14:17], v[122:125], v[2:5]
	v_mfma_f32_16x16x32_bf16 v[6:9], v[86:89], v[122:125], v[6:9]
	v_mfma_f32_16x16x32_bf16 v[94:97], v[14:17], v[98:101], v[94:97]
	v_mfma_f32_16x16x32_bf16 v[78:81], v[86:89], v[114:117], v[78:81]
	s_setprio 0
	s_setprio 1
	s_setprio 0
	s_barrier
	ds_read_b128 v[10:13], v77
	ds_read_b128 v[14:17], v77 offset:1024
	ds_read_b128 v[82:85], v77 offset:2048
	ds_read_b128 v[86:89], v77 offset:3072
	s_add_u32 s22, s22, 0x80180
	s_addc_u32 s23, s23, 0
	s_mov_b32 m0, s80
	v_lshl_add_u64 v[126:127], s[22:23], 0, v[70:71]
	ds_read_b128 v[90:93], v76
	ds_read_b128 v[98:101], v76 offset:1024
	ds_read_b128 v[102:105], v76 offset:2048
	ds_read_b128 v[106:109], v76 offset:3072
	ds_read_b128 v[110:113], v76 offset:4096
	ds_read_b128 v[114:117], v76 offset:5120
	ds_read_b128 v[118:121], v76 offset:6144
	ds_read_b128 v[122:125], v76 offset:7168
	global_load_lds_dwordx4 v[126:127], off
	v_lshl_add_u64 v[126:127], s[22:23], 0, v[68:69]
	s_mov_b32 m0, s3
	s_nop 0
	global_load_lds_dwordx4 v[126:127], off
	s_waitcnt vmcnt(8)
	s_waitcnt lgkmcnt(0)
	v_mfma_f32_16x16x32_bf16 v[26:29], v[82:85], v[102:105], v[26:29]
	v_mfma_f32_16x16x32_bf16 v[50:53], v[10:13], v[90:93], v[50:53]
	s_barrier
	s_setprio 1
	s_waitcnt lgkmcnt(0)
	v_mfma_f32_16x16x32_bf16 v[18:21], v[82:85], v[90:93], v[18:21]
	v_mfma_f32_16x16x32_bf16 v[90:93], v[86:89], v[106:109], v[26:29]
	v_mfma_f32_16x16x32_bf16 v[26:29], v[10:13], v[110:113], v[30:33]
	v_mfma_f32_16x16x32_bf16 v[50:53], v[14:17], v[98:101], v[50:53]
	v_mfma_f32_16x16x32_bf16 v[18:21], v[86:89], v[98:101], v[18:21]
	v_mfma_f32_16x16x32_bf16 v[98:101], v[14:17], v[114:117], v[26:29]
	v_mfma_f32_16x16x32_bf16 v[26:29], v[82:85], v[110:113], v[34:37]
	v_mfma_f32_16x16x32_bf16 v[34:37], v[86:89], v[114:117], v[26:29]
	v_mfma_f32_16x16x32_bf16 v[26:29], v[10:13], v[118:121], v[38:41]
	v_mfma_f32_16x16x32_bf16 v[22:25], v[10:13], v[102:105], v[22:25]
	v_mfma_f32_16x16x32_bf16 v[38:41], v[14:17], v[122:125], v[26:29]
	v_mfma_f32_16x16x32_bf16 v[26:29], v[82:85], v[118:121], v[42:45]
	v_mfma_f32_16x16x32_bf16 v[22:25], v[14:17], v[106:109], v[22:25]
	v_mfma_f32_16x16x32_bf16 v[42:45], v[86:89], v[122:125], v[26:29]
	s_setprio 0
	s_setprio 1
	s_setprio 0
	s_barrier
; #define PG8_STAGE(bufoff, gbase, voff) do { _Pragma("unroll") for (int _i = 0; _i < 2; ++_i) \
;         __builtin_amdgcn_global_load_lds((const unsigned*)((const char*)(gbase) + (voff)[_i]), (PG8_LAS unsigned*)(lds + (bufoff) + ldsw + _i * 8192), 16, 0, 0); } while (0)
; #define PG8_LDA(dst, b, h) do { _Pragma("unroll") for (int m = 0; m < 4; ++m) _Pragma("unroll") for (int k = 0; k < 2; ++k) dst[m][k] = *(const PG8_LAS bf16x8*)(lds + PG8_SA(b, h) + aoff + m * 2048 + k * 1024); } while (0)
; #define PG8_LDB(dst, b, h) do { _Pragma("unroll") for (int n = 0; n < 2; ++n) _Pragma("unroll") for (int k = 0; k < 2; ++k) dst[n][k] = *(const PG8_LAS bf16x8*)(lds + PG8_SB(b, h) + boff + n * 2048 + k * 1024); } while (0)
; #define PG8_MMA(ai, bj, At, Bt) do { __builtin_amdgcn_s_setprio(1); _Pragma("unroll") for (int m = 0; m < 4; ++m) _Pragma("unroll") for (int n = 0; n < 2; ++n) _Pragma("unroll") for (int k = 0; k < 2; ++k) \
;         acc[ai][bj][m][n] = __builtin_amdgcn_mfma_f32_16x16x32_bf16(Bt[n][k], At[m][k], acc[ai][bj][m][n], 0, 0, 0); __builtin_amdgcn_s_setprio(0); } while (0)
; #define PG8_WAIT_V(n) asm volatile("s_waitcnt vmcnt(" #n ")" ::: "memory")
; #define PG8_WAIT_L(n) asm volatile("s_waitcnt lgkmcnt(" #n ")" ::: "memory")
; #define PG8_BAR __builtin_amdgcn_s_barrier()
; #define PG8_SCHED __builtin_amdgcn_sched_barrier(0)
; template <class Epi, class Sched, bool ALIGN_EPI = false, bool SP2 = false, bool ABLK = false, bool BBLK = false>
; __device__ __forceinline__ void gemm_phase(PG8_LAS unsigned char* lds, const Gemm g, const Sched& S, const Epi& E) {
;     ...
;             PG8_LDB(B0, 1, 0); PG8_LDB(B1, 1, 1); PG8_SCHED; PG8_LDA(At, 1, 0); PG8_STAGE(PG8_SA(0, 1), a2 + hstepA, voffA);
;             PG8_WAIT_V(8); PG8_WAIT_L(0); PG8_BAR; PG8_MMA(0, 0, At, B0); PG8_MMA(0, 1, At, B1); PG8_BAR; PG8_SCHED;
;             PG8_LDA(At, 1, 1); PG8_STAGE(PG8_SB(1, 0), b3, voffB); PG8_STAGE(PG8_SB(1, 1), b3 + hstepB, voffB); PG8_STAGE(PG8_SA(1, 0), a3, voffA);
;             PG8_WAIT_V(8); PG8_WAIT_L(0); PG8_BAR; PG8_MMA(1, 0, At, B0); PG8_MMA(1, 1, At, B1); PG8_BAR; PG8_SCHED;
;     ...
;         if constexpr (ALIGN_EPI) { if (wr == 0) PG8_BAR; }
	s_mov_b32 m0, s75
	v_lshl_add_u64 v[138:139], s[26:27], 0, v[186:187]
	s_add_u32 s22, s26, 0x80000
	ds_read_b128 v[26:29], v76 offset:16384
	ds_read_b128 v[30:33], v76 offset:17408
	ds_read_b128 v[102:105], v76 offset:18432
	ds_read_b128 v[106:109], v76 offset:19456
	ds_read_b128 v[110:113], v76 offset:20480
	ds_read_b128 v[114:117], v76 offset:21504
	ds_read_b128 v[118:121], v76 offset:22528
	ds_read_b128 v[122:125], v76 offset:23552
	global_load_lds_dwordx4 v[138:139], off
	v_lshl_add_u64 v[140:141], s[26:27], 0, v[66:67]
	s_mov_b32 m0, s11
	s_addc_u32 s23, s27, 0
	global_load_lds_dwordx4 v[140:141], off
	v_lshl_add_u64 v[126:127], s[22:23], 0, v[186:187]
	s_mov_b32 m0, s68
	v_lshl_add_u64 v[142:143], s[28:29], 0, v[70:71]
	global_load_lds_dwordx4 v[126:127], off
	v_lshl_add_u64 v[126:127], s[22:23], 0, v[66:67]
	s_mov_b32 m0, s72
	v_lshl_add_u64 v[144:145], s[28:29], 0, v[68:69]
	global_load_lds_dwordx4 v[126:127], off
	s_mov_b32 m0, s65
	s_nop 0
	global_load_lds_dwordx4 v[142:143], off
	s_mov_b32 m0, s73
	s_nop 0
	global_load_lds_dwordx4 v[144:145], off
	s_waitcnt vmcnt(8)
	s_waitcnt lgkmcnt(0)
	v_mfma_f32_16x16x32_bf16 v[94:97], v[10:13], v[26:29], v[94:97]
	v_mfma_f32_16x16x32_bf16 v[26:29], v[82:85], v[26:29], v[46:49]
	s_barrier
	s_setprio 1
	s_waitcnt lgkmcnt(0)
	v_mfma_f32_16x16x32_bf16 v[46:49], v[86:89], v[30:33], v[26:29]
	v_mfma_f32_16x16x32_bf16 v[26:29], v[10:13], v[102:105], v[54:57]
	v_mfma_f32_16x16x32_bf16 v[54:57], v[14:17], v[106:109], v[26:29]
	v_mfma_f32_16x16x32_bf16 v[26:29], v[82:85], v[102:105], v[58:61]
	v_mfma_f32_16x16x32_bf16 v[102:105], v[86:89], v[106:109], v[26:29]
	v_mfma_f32_16x16x32_bf16 v[26:29], v[10:13], v[110:113], v[62:65]
	v_mfma_f32_16x16x32_bf16 v[2:5], v[10:13], v[118:121], v[2:5]
	v_mfma_f32_16x16x32_bf16 v[106:109], v[14:17], v[114:117], v[26:29]
	v_mfma_f32_16x16x32_bf16 v[26:29], v[82:85], v[110:113], v[78:81]
	v_mfma_f32_16x16x32_bf16 v[110:113], v[14:17], v[122:125], v[2:5]
	v_mfma_f32_16x16x32_bf16 v[2:5], v[82:85], v[118:121], v[6:9]
	v_mfma_f32_16x16x32_bf16 v[94:97], v[14:17], v[30:33], v[94:97]
	v_mfma_f32_16x16x32_bf16 v[78:81], v[86:89], v[114:117], v[26:29]
	v_mfma_f32_16x16x32_bf16 v[82:85], v[86:89], v[122:125], v[2:5]
	s_setprio 0
	s_setprio 1
	s_setprio 0
	s_barrier
	ds_read_b128 v[86:89], v136
	ds_read_b128 v[114:117], v136 offset:1024
	ds_read_b128 v[118:121], v136 offset:2048
	ds_read_b128 v[122:125], v136 offset:3072
	s_add_u32 s22, s28, 0x80000
	s_addc_u32 s23, s29, 0
	s_mov_b32 m0, s81
	v_lshl_add_u64 v[26:27], s[22:23], 0, v[70:71]
	ds_read_b128 v[2:5], v76 offset:32768
	ds_read_b128 v[6:9], v76 offset:33792
	ds_read_b128 v[10:13], v76 offset:34816
	ds_read_b128 v[14:17], v76 offset:35840
	ds_read_b128 v[58:61], v76 offset:36864
	ds_read_b128 v[62:65], v76 offset:37888
	ds_read_b128 v[126:129], v76 offset:38912
	ds_read_b128 v[130:133], v76 offset:39936
	global_load_lds_dwordx4 v[26:27], off
	v_lshl_add_u64 v[26:27], s[22:23], 0, v[68:69]
	s_mov_b32 m0, s83
	s_nop 0
	global_load_lds_dwordx4 v[26:27], off
	s_waitcnt vmcnt(8)
	s_waitcnt lgkmcnt(0)
	v_mfma_f32_16x16x32_bf16 v[26:29], v[86:89], v[2:5], v[50:53]
	v_mfma_f32_16x16x32_bf16 v[2:5], v[118:121], v[2:5], v[18:21]
	s_barrier
	s_setprio 1
	s_waitcnt lgkmcnt(0)
	v_mfma_f32_16x16x32_bf16 v[30:33], v[122:125], v[6:9], v[2:5]
	v_mfma_f32_16x16x32_bf16 v[2:5], v[86:89], v[10:13], v[22:25]
	v_mfma_f32_16x16x32_bf16 v[18:21], v[114:117], v[14:17], v[2:5]
	v_mfma_f32_16x16x32_bf16 v[2:5], v[118:121], v[10:13], v[90:93]
	v_mfma_f32_16x16x32_bf16 v[22:25], v[122:125], v[14:17], v[2:5]
	v_mfma_f32_16x16x32_bf16 v[2:5], v[86:89], v[58:61], v[98:101]
	v_mfma_f32_16x16x32_bf16 v[10:13], v[114:117], v[62:65], v[2:5]
	v_mfma_f32_16x16x32_bf16 v[2:5], v[118:121], v[58:61], v[34:37]
	v_mfma_f32_16x16x32_bf16 v[26:29], v[114:117], v[6:9], v[26:29]
	v_mfma_f32_16x16x32_bf16 v[14:17], v[122:125], v[62:65], v[2:5]
	v_mfma_f32_16x16x32_bf16 v[2:5], v[86:89], v[126:129], v[38:41]
	v_mfma_f32_16x16x32_bf16 v[6:9], v[118:121], v[126:129], v[42:45]
	v_mfma_f32_16x16x32_bf16 v[2:5], v[114:117], v[130:133], v[2:5]
	v_mfma_f32_16x16x32_bf16 v[6:9], v[122:125], v[130:133], v[6:9]
	s_setprio 0
	s_setprio 1
	s_setprio 0
	s_barrier
	s_mov_b32 m0, s82
	v_lshl_add_u64 v[50:51], v[138:139], 0, s[62:63]
	s_add_u32 s22, s26, 0x80080
	ds_read_b128 v[34:37], v76 offset:49152
	ds_read_b128 v[38:41], v76 offset:50176
	ds_read_b128 v[42:45], v76 offset:51200
	ds_read_b128 v[90:93], v76 offset:52224
	ds_read_b128 v[98:101], v76 offset:53248
	ds_read_b128 v[126:129], v76 offset:54272
	ds_read_b128 v[130:133], v76 offset:55296
	ds_read_b128 v[134:137], v76 offset:56320
	global_load_lds_dwordx4 v[50:51], off
	v_lshl_add_u64 v[50:51], v[140:141], 0, s[62:63]
	s_mov_b32 m0, s13
	s_addc_u32 s23, s27, 0
	global_load_lds_dwordx4 v[50:51], off
	v_lshl_add_u64 v[50:51], s[22:23], 0, v[186:187]
	s_mov_b32 m0, s88
	s_nop 0
	global_load_lds_dwordx4 v[50:51], off
	v_lshl_add_u64 v[50:51], s[22:23], 0, v[66:67]
	s_mov_b32 m0, s89
	s_nop 0
	global_load_lds_dwordx4 v[50:51], off
	v_lshl_add_u64 v[50:51], v[142:143], 0, s[62:63]
	s_mov_b32 m0, s84
	s_nop 0
	global_load_lds_dwordx4 v[50:51], off
	v_lshl_add_u64 v[50:51], v[144:145], 0, s[62:63]
	s_mov_b32 m0, s86
	s_nop 0
	global_load_lds_dwordx4 v[50:51], off
	s_waitcnt vmcnt(8)
	s_waitcnt lgkmcnt(0)
	v_mfma_f32_16x16x32_bf16 v[50:53], v[86:89], v[34:37], v[94:97]
	v_mfma_f32_16x16x32_bf16 v[34:37], v[118:121], v[34:37], v[46:49]
	s_barrier
	s_setprio 1
	s_waitcnt lgkmcnt(0)
	v_mfma_f32_16x16x32_bf16 v[62:65], v[122:125], v[38:41], v[34:37]
	v_mfma_f32_16x16x32_bf16 v[34:37], v[86:89], v[42:45], v[54:57]
	v_mfma_f32_16x16x32_bf16 v[58:61], v[114:117], v[38:41], v[50:53]
	v_mfma_f32_16x16x32_bf16 v[50:53], v[114:117], v[90:93], v[34:37]
	v_mfma_f32_16x16x32_bf16 v[34:37], v[118:121], v[42:45], v[102:105]
	v_mfma_f32_16x16x32_bf16 v[54:57], v[122:125], v[90:93], v[34:37]
	v_mfma_f32_16x16x32_bf16 v[34:37], v[86:89], v[98:101], v[106:109]
	v_mfma_f32_16x16x32_bf16 v[42:45], v[114:117], v[126:129], v[34:37]
	v_mfma_f32_16x16x32_bf16 v[34:37], v[118:121], v[98:101], v[78:81]
	v_mfma_f32_16x16x32_bf16 v[46:49], v[122:125], v[126:129], v[34:37]
	v_mfma_f32_16x16x32_bf16 v[34:37], v[86:89], v[130:133], v[110:113]
	v_mfma_f32_16x16x32_bf16 v[38:41], v[118:121], v[130:133], v[82:85]
	v_mfma_f32_16x16x32_bf16 v[34:37], v[114:117], v[134:137], v[34:37]
	v_mfma_f32_16x16x32_bf16 v[38:41], v[122:125], v[134:137], v[38:41]
	s_setprio 0
	s_setprio 1
	s_setprio 0
	s_barrier
	s_andn2_b64 vcc, exec, s[4:5]
	s_cbranch_vccnz .LBB0_914
	s_barrier

; #define PG8_STAGE(bufoff, gbase, voff) do { _Pragma("unroll") for (int _i = 0; _i < 2; ++_i) \
;         __builtin_amdgcn_global_load_lds((const unsigned*)((const char*)(gbase) + (voff)[_i]), (PG8_LAS unsigned*)(lds + (bufoff) + ldsw + _i * 8192), 16, 0, 0); } while (0)
; #define PG8_LDA(dst, b, h) do { _Pragma("unroll") for (int m = 0; m < 4; ++m) _Pragma("unroll") for (int k = 0; k < 2; ++k) dst[m][k] = *(const PG8_LAS bf16x8*)(lds + PG8_SA(b, h) + aoff + m * 2048 + k * 1024); } while (0)
; #define PG8_LDB(dst, b, h) do { _Pragma("unroll") for (int n = 0; n < 2; ++n) _Pragma("unroll") for (int k = 0; k < 2; ++k) dst[n][k] = *(const PG8_LAS bf16x8*)(lds + PG8_SB(b, h) + boff + n * 2048 + k * 1024); } while (0)
; #define PG8_WAIT_V(n) asm volatile("s_waitcnt vmcnt(" #n ")" ::: "memory")
; #define PG8_WAIT_L(n) asm volatile("s_waitcnt lgkmcnt(" #n ")" ::: "memory")
; #define PG8_BAR __builtin_amdgcn_s_barrier()
; #define PG8_SCHED __builtin_amdgcn_sched_barrier(0)
; template <class Epi, class Sched, bool ALIGN_EPI = false, bool SP2 = false, bool ABLK = false, bool BBLK = false>
; __device__ __forceinline__ void gemm_phase(PG8_LAS unsigned char* lds, const Gemm g, const Sched& S, const Epi& E) {
;     ...
;         const bool has_next = S.next(ui + 1, nxt);
;         const char* nA = has_next ? (const char*)g.A + (size_t)nxt.pm * tstepA : cA; const char* nB = has_next ? (const char*)g.Bt + (size_t)nxt.pn * tstepB : cB;
;         for (int t = 0; t < nt; t += 2) {
;             const bool last = (t == nt - 2);
;             const char* a1 = cA + (size_t)(t + 1) * kstepA;
;             const char* a2 = last ? nA : cA + (size_t)(t + 2) * kstepA; const char* b2 = last ? nB : cB + (size_t)(t + 2) * kstepB;
;             const char* a3 = a2 + kstepA; const char* b3 = b2 + kstepB;
;             if (last && has_next) S.a_ready(nxt);
;             if constexpr (SP2) {
;             PG8_LDB(B0, 0, 0); PG8_LDB(B1, 0, 1); PG8_SCHED; PG8_LDA(At, 0, 0); PG8_STAGE(PG8_SA(1, 1), a1 + hstepA, voffA);
;             PG8_WAIT_V(8); PG8_WAIT_L(0); PG8_BAR; PG8_MMA(0, 0, At, B0); PG8_MMA(0, 1, At, B1); PG8_BAR; PG8_SCHED;
;             PG8_LDA(At, 0, 1); PG8_STAGE(PG8_SB(0, 0), b2, voffB); PG8_STAGE(PG8_SB(0, 1), b2 + hstepB, voffB); PG8_STAGE(PG8_SA(0, 0), a2, voffA);
;             PG8_WAIT_V(8); PG8_WAIT_L(0); PG8_BAR; PG8_MMA(1, 0, At, B0); PG8_MMA(1, 1, At, B1); PG8_BAR; PG8_SCHED;
.LBB0_928:
	s_ashr_i32 s15, s14, 31
	s_lshl_b64 s[18:19], s[14:15], 17
	s_add_u32 s18, s16, s18
	s_addc_u32 s19, s33, s19
	s_and_b64 s[20:21], s[12:13], exec
	s_cselect_b32 s31, s19, s25
	s_cselect_b32 s30, s18, s24
	s_ashr_i32 s11, s10, 31
	s_lshl_b64 s[20:21], s[10:11], 17
	s_add_u32 s20, s36, s20
	s_addc_u32 s21, s37, s21
	s_and_b64 s[28:29], s[12:13], exec
	s_cselect_b32 s29, s21, s27
	s_cselect_b32 s28, s20, s26
	s_add_i32 s60, 0, 0x10000
	v_add_u32_e32 v79, s60, v77
	ds_read_b128 v[2:5], v79
	ds_read_b128 v[6:9], v79 offset:1024
	ds_read_b128 v[10:13], v79 offset:2048
	ds_read_b128 v[14:17], v79 offset:3072
	s_add_u32 s72, s24, 0x10080
	s_addc_u32 s73, s25, 0
	s_add_i32 s61, s23, 0xc000
	v_lshl_add_u64 v[50:51], s[72:73], 0, v[70:71]
	s_mov_b32 m0, s61
	s_add_i32 s11, s23, 0xe000
	ds_read_b128 v[18:21], v78
	ds_read_b128 v[22:25], v78 offset:1024
	ds_read_b128 v[26:29], v78 offset:2048
	ds_read_b128 v[30:33], v78 offset:3072
	ds_read_b128 v[34:37], v78 offset:4096
	ds_read_b128 v[38:41], v78 offset:5120
	ds_read_b128 v[42:45], v78 offset:6144
	ds_read_b128 v[46:49], v78 offset:7168
	global_load_lds_dwordx4 v[50:51], off
	v_lshl_add_u64 v[50:51], s[72:73], 0, v[68:69]
	s_mov_b32 m0, s11
	s_nop 0
	global_load_lds_dwordx4 v[50:51], off
	s_waitcnt vmcnt(8)
	s_waitcnt lgkmcnt(0)
	v_mfma_f32_16x16x32_bf16 v[50:53], v[2:5], v[18:21], 0
	v_mfma_f32_16x16x32_bf16 v[18:21], v[10:13], v[18:21], 0
	s_barrier
	s_setprio 1
	s_waitcnt lgkmcnt(0)
	v_mfma_f32_16x16x32_bf16 v[50:53], v[6:9], v[22:25], v[50:53]
	v_mfma_f32_16x16x32_bf16 v[18:21], v[14:17], v[22:25], v[18:21]
	v_mfma_f32_16x16x32_bf16 v[22:25], v[2:5], v[26:29], 0
	v_mfma_f32_16x16x32_bf16 v[26:29], v[10:13], v[26:29], 0
	v_mfma_f32_16x16x32_bf16 v[22:25], v[6:9], v[30:33], v[22:25]
	v_mfma_f32_16x16x32_bf16 v[26:29], v[14:17], v[30:33], v[26:29]
	v_mfma_f32_16x16x32_bf16 v[30:33], v[2:5], v[34:37], 0
	v_mfma_f32_16x16x32_bf16 v[34:37], v[10:13], v[34:37], 0
	v_mfma_f32_16x16x32_bf16 v[30:33], v[6:9], v[38:41], v[30:33]
	v_mfma_f32_16x16x32_bf16 v[34:37], v[14:17], v[38:41], v[34:37]
	v_mfma_f32_16x16x32_bf16 v[38:41], v[2:5], v[42:45], 0
	v_mfma_f32_16x16x32_bf16 v[42:45], v[10:13], v[42:45], 0
	v_mfma_f32_16x16x32_bf16 v[38:41], v[6:9], v[46:49], v[38:41]
	v_mfma_f32_16x16x32_bf16 v[42:45], v[14:17], v[46:49], v[42:45]
	s_setprio 0
	s_setprio 1
	s_setprio 0
	s_barrier
	s_add_i32 s60, s60, s41
	v_lshl_add_u64 v[74:75], s[26:27], 0, v[186:187]
	s_add_i32 s15, s60, 0x2000
	v_lshl_add_u64 v[96:97], v[74:75], 0, s[58:59]
	s_mov_b32 m0, s60
	v_lshl_add_u64 v[128:129], s[26:27], 0, v[66:67]
	s_add_u32 s72, s26, 0x10100
	ds_read_b128 v[46:49], v78 offset:16384
	ds_read_b128 v[54:57], v78 offset:17408
	ds_read_b128 v[58:61], v78 offset:18432
	ds_read_b128 v[62:65], v78 offset:19456
	ds_read_b128 v[80:83], v78 offset:20480
	ds_read_b128 v[84:87], v78 offset:21504
	ds_read_b128 v[88:91], v78 offset:22528
	ds_read_b128 v[92:95], v78 offset:23552
	global_load_lds_dwordx4 v[96:97], off
	v_lshl_add_u64 v[96:97], v[128:129], 0, s[58:59]
	s_mov_b32 m0, s15
	s_addc_u32 s73, s27, 0
	global_load_lds_dwordx4 v[96:97], off
	v_lshl_add_u64 v[96:97], s[72:73], 0, v[186:187]
	s_mov_b32 m0, s42
	v_lshl_add_u64 v[130:131], s[24:25], 0, v[70:71]
	global_load_lds_dwordx4 v[96:97], off
	v_lshl_add_u64 v[96:97], s[72:73], 0, v[66:67]
	s_mov_b32 m0, s43
	v_lshl_add_u64 v[132:133], s[24:25], 0, v[68:69]
	global_load_lds_dwordx4 v[96:97], off
	v_lshl_add_u64 v[96:97], v[130:131], 0, s[58:59]
	s_mov_b32 m0, s23
	s_nop 0
	global_load_lds_dwordx4 v[96:97], off
	v_lshl_add_u64 v[96:97], v[132:133], 0, s[58:59]
	s_mov_b32 m0, s44
	s_nop 0
	global_load_lds_dwordx4 v[96:97], off
	s_waitcnt vmcnt(8)
	s_waitcnt lgkmcnt(0)
	v_mfma_f32_16x16x32_bf16 v[96:99], v[2:5], v[46:49], 0
	v_mfma_f32_16x16x32_bf16 v[46:49], v[10:13], v[46:49], 0
	s_barrier
	s_setprio 1
	s_waitcnt lgkmcnt(0)
	v_mfma_f32_16x16x32_bf16 v[96:99], v[6:9], v[54:57], v[96:99]
	v_mfma_f32_16x16x32_bf16 v[46:49], v[14:17], v[54:57], v[46:49]
	v_mfma_f32_16x16x32_bf16 v[54:57], v[2:5], v[58:61], 0
	v_mfma_f32_16x16x32_bf16 v[58:61], v[10:13], v[58:61], 0
	v_mfma_f32_16x16x32_bf16 v[54:57], v[6:9], v[62:65], v[54:57]
	v_mfma_f32_16x16x32_bf16 v[58:61], v[14:17], v[62:65], v[58:61]
	v_mfma_f32_16x16x32_bf16 v[62:65], v[2:5], v[80:83], 0
	v_mfma_f32_16x16x32_bf16 v[2:5], v[2:5], v[88:91], 0
	v_mfma_f32_16x16x32_bf16 v[62:65], v[6:9], v[84:87], v[62:65]
	v_mfma_f32_16x16x32_bf16 v[2:5], v[6:9], v[92:95], v[2:5]
	v_mfma_f32_16x16x32_bf16 v[6:9], v[10:13], v[88:91], 0
	v_mfma_f32_16x16x32_bf16 v[80:83], v[10:13], v[80:83], 0
	v_mfma_f32_16x16x32_bf16 v[6:9], v[14:17], v[92:95], v[6:9]
	v_mfma_f32_16x16x32_bf16 v[80:83], v[14:17], v[84:87], v[80:83]
	s_setprio 0
	s_setprio 1
	s_setprio 0
	s_barrier
	s_add_i32 s65, 0, 0x18000
	v_add_u32_e32 v136, s65, v77
	ds_read_b128 v[10:13], v136
	ds_read_b128 v[14:17], v136 offset:1024
	ds_read_b128 v[84:87], v136 offset:2048
	ds_read_b128 v[88:91], v136 offset:3072
	s_add_u32 s72, s24, 0x10100
	s_addc_u32 s73, s25, 0
	s_mov_b32 m0, s45
	v_lshl_add_u64 v[134:135], s[72:73], 0, v[70:71]
	ds_read_b128 v[92:95], v78 offset:32768
	ds_read_b128 v[100:103], v78 offset:33792
	ds_read_b128 v[104:107], v78 offset:34816
	ds_read_b128 v[108:111], v78 offset:35840
	ds_read_b128 v[112:115], v78 offset:36864
	ds_read_b128 v[116:119], v78 offset:37888
	ds_read_b128 v[120:123], v78 offset:38912
	ds_read_b128 v[124:127], v78 offset:39936
	global_load_lds_dwordx4 v[134:135], off
	v_lshl_add_u64 v[134:135], s[72:73], 0, v[68:69]
	s_mov_b32 m0, s46
	s_nop 0
	global_load_lds_dwordx4 v[134:135], off
	s_waitcnt vmcnt(8)
	s_waitcnt lgkmcnt(0)
	v_mfma_f32_16x16x32_bf16 v[50:53], v[10:13], v[92:95], v[50:53]
	v_mfma_f32_16x16x32_bf16 v[18:21], v[84:87], v[92:95], v[18:21]
	s_barrier
; #define PG8_STAGE(bufoff, gbase, voff) do { _Pragma("unroll") for (int _i = 0; _i < 2; ++_i) \
;         __builtin_amdgcn_global_load_lds((const unsigned*)((const char*)(gbase) + (voff)[_i]), (PG8_LAS unsigned*)(lds + (bufoff) + ldsw + _i * 8192), 16, 0, 0); } while (0)
; #define PG8_LDA(dst, b, h) do { _Pragma("unroll") for (int m = 0; m < 4; ++m) _Pragma("unroll") for (int k = 0; k < 2; ++k) dst[m][k] = *(const PG8_LAS bf16x8*)(lds + PG8_SA(b, h) + aoff + m * 2048 + k * 1024); } while (0)
; #define PG8_LDB(dst, b, h) do { _Pragma("unroll") for (int n = 0; n < 2; ++n) _Pragma("unroll") for (int k = 0; k < 2; ++k) dst[n][k] = *(const PG8_LAS bf16x8*)(lds + PG8_SB(b, h) + boff + n * 2048 + k * 1024); } while (0)
; #define PG8_MMA(ai, bj, At, Bt) do { __builtin_amdgcn_s_setprio(1); _Pragma("unroll") for (int m = 0; m < 4; ++m) _Pragma("unroll") for (int n = 0; n < 2; ++n) _Pragma("unroll") for (int k = 0; k < 2; ++k) \
;         acc[ai][bj][m][n] = __builtin_amdgcn_mfma_f32_16x16x32_bf16(Bt[n][k], At[m][k], acc[ai][bj][m][n], 0, 0, 0); __builtin_amdgcn_s_setprio(0); } while (0)
; #define PG8_WAIT_V(n) asm volatile("s_waitcnt vmcnt(" #n ")" ::: "memory")
; #define PG8_WAIT_L(n) asm volatile("s_waitcnt lgkmcnt(" #n ")" ::: "memory")
; #define PG8_BAR __builtin_amdgcn_s_barrier()
; #define PG8_SCHED __builtin_amdgcn_sched_barrier(0)
; template <class Epi, class Sched, bool ALIGN_EPI = false, bool SP2 = false, bool ABLK = false, bool BBLK = false>
; __device__ __forceinline__ void gemm_phase(PG8_LAS unsigned char* lds, const Gemm g, const Sched& S, const Epi& E) {
;     ...
;             PG8_LDA(At, 0, 1); PG8_STAGE(PG8_SB(0, 0), b2, voffB); PG8_STAGE(PG8_SB(0, 1), b2 + hstepB, voffB); PG8_STAGE(PG8_SA(0, 0), a2, voffA);
;             PG8_WAIT_V(8); PG8_WAIT_L(0); PG8_BAR; PG8_MMA(1, 0, At, B0); PG8_MMA(1, 1, At, B1); PG8_BAR; PG8_SCHED;
;             PG8_LDB(B0, 1, 0); PG8_LDB(B1, 1, 1); PG8_SCHED; PG8_LDA(At, 1, 0); PG8_STAGE(PG8_SA(0, 1), a2 + hstepA, voffA);
;             PG8_WAIT_V(8); PG8_WAIT_L(0); PG8_BAR; PG8_MMA(0, 0, At, B0); PG8_MMA(0, 1, At, B1); PG8_BAR; PG8_SCHED;
;             PG8_LDA(At, 1, 1); PG8_STAGE(PG8_SB(1, 0), b3, voffB); PG8_STAGE(PG8_SB(1, 1), b3 + hstepB, voffB); PG8_STAGE(PG8_SA(1, 0), a3, voffA);
	s_setprio 1
	s_waitcnt lgkmcnt(0)
	v_mfma_f32_16x16x32_bf16 v[22:25], v[10:13], v[104:107], v[22:25]
	v_mfma_f32_16x16x32_bf16 v[26:29], v[84:87], v[104:107], v[26:29]
	v_mfma_f32_16x16x32_bf16 v[30:33], v[10:13], v[112:115], v[30:33]
	v_mfma_f32_16x16x32_bf16 v[34:37], v[84:87], v[112:115], v[34:37]
	v_mfma_f32_16x16x32_bf16 v[38:41], v[10:13], v[120:123], v[38:41]
	v_mfma_f32_16x16x32_bf16 v[42:45], v[84:87], v[120:123], v[42:45]
	v_mfma_f32_16x16x32_bf16 v[50:53], v[14:17], v[100:103], v[50:53]
	v_mfma_f32_16x16x32_bf16 v[18:21], v[88:91], v[100:103], v[18:21]
	v_mfma_f32_16x16x32_bf16 v[22:25], v[14:17], v[108:111], v[22:25]
	v_mfma_f32_16x16x32_bf16 v[26:29], v[88:91], v[108:111], v[26:29]
	v_mfma_f32_16x16x32_bf16 v[30:33], v[14:17], v[116:119], v[30:33]
	v_mfma_f32_16x16x32_bf16 v[34:37], v[88:91], v[116:119], v[34:37]
	v_mfma_f32_16x16x32_bf16 v[38:41], v[14:17], v[124:127], v[38:41]
	v_mfma_f32_16x16x32_bf16 v[42:45], v[88:91], v[124:127], v[42:45]
	s_setprio 0
	s_setprio 1
	s_setprio 0
	s_barrier
	s_add_i32 s65, s65, s41
	s_add_i32 s56, s65, 0x2000
	v_lshl_add_u64 v[74:75], v[74:75], 0, s[70:71]
	s_mov_b32 m0, s65
	s_add_u32 s26, s26, 0x10180
	ds_read_b128 v[92:95], v78 offset:49152
	ds_read_b128 v[100:103], v78 offset:50176
	ds_read_b128 v[104:107], v78 offset:51200
	ds_read_b128 v[108:111], v78 offset:52224
	ds_read_b128 v[112:115], v78 offset:53248
	ds_read_b128 v[116:119], v78 offset:54272
	ds_read_b128 v[120:123], v78 offset:55296
	ds_read_b128 v[124:127], v78 offset:56320
	global_load_lds_dwordx4 v[74:75], off
	v_lshl_add_u64 v[74:75], v[128:129], 0, s[70:71]
	s_mov_b32 m0, s56
	s_addc_u32 s27, s27, 0
	global_load_lds_dwordx4 v[74:75], off
	v_lshl_add_u64 v[74:75], s[26:27], 0, v[186:187]
	s_mov_b32 m0, s51
	s_nop 0
	global_load_lds_dwordx4 v[74:75], off
	v_lshl_add_u64 v[74:75], s[26:27], 0, v[66:67]
	s_mov_b32 m0, s53
	s_nop 0
	global_load_lds_dwordx4 v[74:75], off
	v_lshl_add_u64 v[74:75], v[130:131], 0, s[70:71]
	s_mov_b32 m0, s47
	s_nop 0
	global_load_lds_dwordx4 v[74:75], off
	v_lshl_add_u64 v[74:75], v[132:133], 0, s[70:71]
	s_mov_b32 m0, s50
	s_nop 0
	global_load_lds_dwordx4 v[74:75], off
	s_waitcnt vmcnt(8)
	s_waitcnt lgkmcnt(0)
	v_mfma_f32_16x16x32_bf16 v[46:49], v[84:87], v[92:95], v[46:49]
	v_mfma_f32_16x16x32_bf16 v[54:57], v[10:13], v[104:107], v[54:57]
	s_barrier
	s_setprio 1
	s_waitcnt lgkmcnt(0)
	v_mfma_f32_16x16x32_bf16 v[58:61], v[84:87], v[104:107], v[58:61]
	v_mfma_f32_16x16x32_bf16 v[62:65], v[10:13], v[112:115], v[62:65]
	v_mfma_f32_16x16x32_bf16 v[2:5], v[10:13], v[120:123], v[2:5]
	v_mfma_f32_16x16x32_bf16 v[6:9], v[84:87], v[120:123], v[6:9]
	v_mfma_f32_16x16x32_bf16 v[96:99], v[10:13], v[92:95], v[96:99]
	v_mfma_f32_16x16x32_bf16 v[46:49], v[88:91], v[100:103], v[46:49]
	v_mfma_f32_16x16x32_bf16 v[54:57], v[14:17], v[108:111], v[54:57]
	v_mfma_f32_16x16x32_bf16 v[58:61], v[88:91], v[108:111], v[58:61]
	v_mfma_f32_16x16x32_bf16 v[62:65], v[14:17], v[116:119], v[62:65]
	v_mfma_f32_16x16x32_bf16 v[80:83], v[84:87], v[112:115], v[80:83]
	v_mfma_f32_16x16x32_bf16 v[2:5], v[14:17], v[124:127], v[2:5]
	v_mfma_f32_16x16x32_bf16 v[6:9], v[88:91], v[124:127], v[6:9]
	v_mfma_f32_16x16x32_bf16 v[96:99], v[14:17], v[100:103], v[96:99]
	v_mfma_f32_16x16x32_bf16 v[80:83], v[88:91], v[116:119], v[80:83]
	s_setprio 0
	s_setprio 1
	s_setprio 0
	s_barrier
	ds_read_b128 v[10:13], v79
	ds_read_b128 v[14:17], v79 offset:1024
	ds_read_b128 v[84:87], v79 offset:2048
	ds_read_b128 v[88:91], v79 offset:3072
	s_add_u32 s24, s24, 0x10180
	s_addc_u32 s25, s25, 0
	s_mov_b32 m0, s61
	v_lshl_add_u64 v[74:75], s[24:25], 0, v[70:71]
	ds_read_b128 v[92:95], v78
	ds_read_b128 v[100:103], v78 offset:1024
	ds_read_b128 v[104:107], v78 offset:2048
	ds_read_b128 v[108:111], v78 offset:3072
	ds_read_b128 v[112:115], v78 offset:4096
	ds_read_b128 v[116:119], v78 offset:5120
	ds_read_b128 v[120:123], v78 offset:6144
	ds_read_b128 v[124:127], v78 offset:7168
	global_load_lds_dwordx4 v[74:75], off
	v_lshl_add_u64 v[74:75], s[24:25], 0, v[68:69]
	s_mov_b32 m0, s11
	s_nop 0
	global_load_lds_dwordx4 v[74:75], off
	s_waitcnt vmcnt(8)
	s_waitcnt lgkmcnt(0)
	v_mfma_f32_16x16x32_bf16 v[50:53], v[10:13], v[92:95], v[50:53]
	v_mfma_f32_16x16x32_bf16 v[18:21], v[84:87], v[92:95], v[18:21]
	s_barrier
	s_setprio 1
	s_waitcnt lgkmcnt(0)
	v_mfma_f32_16x16x32_bf16 v[22:25], v[10:13], v[104:107], v[22:25]
	v_mfma_f32_16x16x32_bf16 v[26:29], v[84:87], v[104:107], v[26:29]
	v_mfma_f32_16x16x32_bf16 v[30:33], v[10:13], v[112:115], v[30:33]
	v_mfma_f32_16x16x32_bf16 v[34:37], v[84:87], v[112:115], v[34:37]
	v_mfma_f32_16x16x32_bf16 v[38:41], v[10:13], v[120:123], v[38:41]
	v_mfma_f32_16x16x32_bf16 v[50:53], v[14:17], v[100:103], v[50:53]
	v_mfma_f32_16x16x32_bf16 v[18:21], v[88:91], v[100:103], v[18:21]
	v_mfma_f32_16x16x32_bf16 v[22:25], v[14:17], v[108:111], v[22:25]
	v_mfma_f32_16x16x32_bf16 v[26:29], v[88:91], v[108:111], v[26:29]
	v_mfma_f32_16x16x32_bf16 v[30:33], v[14:17], v[116:119], v[30:33]
	v_mfma_f32_16x16x32_bf16 v[34:37], v[88:91], v[116:119], v[34:37]
	v_mfma_f32_16x16x32_bf16 v[38:41], v[14:17], v[124:127], v[38:41]
	v_mfma_f32_16x16x32_bf16 v[42:45], v[84:87], v[120:123], v[42:45]
	v_mfma_f32_16x16x32_bf16 v[92:95], v[88:91], v[124:127], v[42:45]
	s_setprio 0
	s_setprio 1
	s_setprio 0
	s_barrier
; #define PG8_STAGE(bufoff, gbase, voff) do { _Pragma("unroll") for (int _i = 0; _i < 2; ++_i) \
;         __builtin_amdgcn_global_load_lds((const unsigned*)((const char*)(gbase) + (voff)[_i]), (PG8_LAS unsigned*)(lds + (bufoff) + ldsw + _i * 8192), 16, 0, 0); } while (0)
; #define PG8_LDA(dst, b, h) do { _Pragma("unroll") for (int m = 0; m < 4; ++m) _Pragma("unroll") for (int k = 0; k < 2; ++k) dst[m][k] = *(const PG8_LAS bf16x8*)(lds + PG8_SA(b, h) + aoff + m * 2048 + k * 1024); } while (0)
; #define PG8_LDB(dst, b, h) do { _Pragma("unroll") for (int n = 0; n < 2; ++n) _Pragma("unroll") for (int k = 0; k < 2; ++k) dst[n][k] = *(const PG8_LAS bf16x8*)(lds + PG8_SB(b, h) + boff + n * 2048 + k * 1024); } while (0)
; #define PG8_MMA(ai, bj, At, Bt) do { __builtin_amdgcn_s_setprio(1); _Pragma("unroll") for (int m = 0; m < 4; ++m) _Pragma("unroll") for (int n = 0; n < 2; ++n) _Pragma("unroll") for (int k = 0; k < 2; ++k) \
;         acc[ai][bj][m][n] = __builtin_amdgcn_mfma_f32_16x16x32_bf16(Bt[n][k], At[m][k], acc[ai][bj][m][n], 0, 0, 0); __builtin_amdgcn_s_setprio(0); } while (0)
; #define PG8_WAIT_V(n) asm volatile("s_waitcnt vmcnt(" #n ")" ::: "memory")
; #define PG8_WAIT_L(n) asm volatile("s_waitcnt lgkmcnt(" #n ")" ::: "memory")
; #define PG8_BAR __builtin_amdgcn_s_barrier()
; #define PG8_SCHED __builtin_amdgcn_sched_barrier(0)
; template <class Epi, class Sched, bool ALIGN_EPI = false, bool SP2 = false, bool ABLK = false, bool BBLK = false>
; __device__ __forceinline__ void gemm_phase(PG8_LAS unsigned char* lds, const Gemm g, const Sched& S, const Epi& E) {
;     ...
;             PG8_LDB(B0, 1, 0); PG8_LDB(B1, 1, 1); PG8_SCHED; PG8_LDA(At, 1, 0); PG8_STAGE(PG8_SA(0, 1), a2 + hstepA, voffA);
;             PG8_WAIT_V(8); PG8_WAIT_L(0); PG8_BAR; PG8_MMA(0, 0, At, B0); PG8_MMA(0, 1, At, B1); PG8_BAR; PG8_SCHED;
;             PG8_LDA(At, 1, 1); PG8_STAGE(PG8_SB(1, 0), b3, voffB); PG8_STAGE(PG8_SB(1, 1), b3 + hstepB, voffB); PG8_STAGE(PG8_SA(1, 0), a3, voffA);
;             PG8_WAIT_V(8); PG8_WAIT_L(0); PG8_BAR; PG8_MMA(1, 0, At, B0); PG8_MMA(1, 1, At, B1); PG8_BAR; PG8_SCHED;
;     ...
;         if constexpr (ALIGN_EPI) { if (wr == 0) PG8_BAR; }
	s_mov_b32 m0, s60
	v_lshl_add_u64 v[74:75], s[28:29], 0, v[186:187]
	s_add_u32 s24, s28, 0x10000
	ds_read_b128 v[42:45], v78 offset:16384
	ds_read_b128 v[100:103], v78 offset:17408
	ds_read_b128 v[104:107], v78 offset:18432
	ds_read_b128 v[108:111], v78 offset:19456
	ds_read_b128 v[112:115], v78 offset:20480
	ds_read_b128 v[116:119], v78 offset:21504
	ds_read_b128 v[120:123], v78 offset:22528
	ds_read_b128 v[124:127], v78 offset:23552
	global_load_lds_dwordx4 v[74:75], off
	v_lshl_add_u64 v[140:141], s[28:29], 0, v[66:67]
	s_mov_b32 m0, s15
	s_addc_u32 s25, s29, 0
	global_load_lds_dwordx4 v[140:141], off
	v_lshl_add_u64 v[128:129], s[24:25], 0, v[186:187]
	s_mov_b32 m0, s42
	v_lshl_add_u64 v[142:143], s[30:31], 0, v[70:71]
	global_load_lds_dwordx4 v[128:129], off
	v_lshl_add_u64 v[128:129], s[24:25], 0, v[66:67]
	s_mov_b32 m0, s43
	v_lshl_add_u64 v[144:145], s[30:31], 0, v[68:69]
	global_load_lds_dwordx4 v[128:129], off
	s_mov_b32 m0, s23
	s_nop 0
	global_load_lds_dwordx4 v[142:143], off
	s_mov_b32 m0, s44
	s_nop 0
	global_load_lds_dwordx4 v[144:145], off
	s_waitcnt vmcnt(8)
	s_waitcnt lgkmcnt(0)
	v_mfma_f32_16x16x32_bf16 v[96:99], v[10:13], v[42:45], v[96:99]
	v_mfma_f32_16x16x32_bf16 v[42:45], v[84:87], v[42:45], v[46:49]
	s_barrier
	s_setprio 1
	s_waitcnt lgkmcnt(0)
	v_mfma_f32_16x16x32_bf16 v[96:99], v[14:17], v[100:103], v[96:99]
	v_mfma_f32_16x16x32_bf16 v[100:103], v[88:91], v[100:103], v[42:45]
	v_mfma_f32_16x16x32_bf16 v[42:45], v[10:13], v[104:107], v[54:57]
	v_mfma_f32_16x16x32_bf16 v[128:131], v[14:17], v[108:111], v[42:45]
	v_mfma_f32_16x16x32_bf16 v[42:45], v[84:87], v[104:107], v[58:61]
	v_mfma_f32_16x16x32_bf16 v[104:107], v[88:91], v[108:111], v[42:45]
	v_mfma_f32_16x16x32_bf16 v[42:45], v[10:13], v[112:115], v[62:65]
	v_mfma_f32_16x16x32_bf16 v[2:5], v[10:13], v[120:123], v[2:5]
	v_mfma_f32_16x16x32_bf16 v[108:111], v[14:17], v[116:119], v[42:45]
	v_mfma_f32_16x16x32_bf16 v[42:45], v[84:87], v[112:115], v[80:83]
	v_mfma_f32_16x16x32_bf16 v[2:5], v[14:17], v[124:127], v[2:5]
	v_mfma_f32_16x16x32_bf16 v[6:9], v[84:87], v[120:123], v[6:9]
	v_mfma_f32_16x16x32_bf16 v[80:83], v[88:91], v[116:119], v[42:45]
	v_mfma_f32_16x16x32_bf16 v[84:87], v[88:91], v[124:127], v[6:9]
	s_setprio 0
	s_setprio 1
	s_setprio 0
	s_barrier
	s_nop 1
	ds_read_b128 v[6:9], v136
	ds_read_b128 v[88:91], v136 offset:1024
	ds_read_b128 v[112:115], v136 offset:2048
	ds_read_b128 v[116:119], v136 offset:3072
	s_add_u32 s24, s30, 0x10000
	s_addc_u32 s25, s31, 0
	s_mov_b32 m0, s45
	v_lshl_add_u64 v[54:55], s[24:25], 0, v[70:71]
	ds_read_b128 v[10:13], v78 offset:32768
	ds_read_b128 v[14:17], v78 offset:33792
	ds_read_b128 v[42:45], v78 offset:34816
	ds_read_b128 v[46:49], v78 offset:35840
	ds_read_b128 v[120:123], v78 offset:36864
	ds_read_b128 v[124:127], v78 offset:37888
	ds_read_b128 v[132:135], v78 offset:38912
	ds_read_b128 v[136:139], v78 offset:39936
	global_load_lds_dwordx4 v[54:55], off
	v_lshl_add_u64 v[54:55], s[24:25], 0, v[68:69]
	s_mov_b32 m0, s46
	s_nop 0
	global_load_lds_dwordx4 v[54:55], off
	s_waitcnt vmcnt(8)
	s_waitcnt lgkmcnt(0)
	v_mfma_f32_16x16x32_bf16 v[50:53], v[6:9], v[10:13], v[50:53]
	v_mfma_f32_16x16x32_bf16 v[10:13], v[112:115], v[10:13], v[18:21]
	s_barrier
	s_setprio 1
	s_waitcnt lgkmcnt(0)
	v_mfma_f32_16x16x32_bf16 v[58:61], v[116:119], v[14:17], v[10:13]
	v_mfma_f32_16x16x32_bf16 v[10:13], v[6:9], v[42:45], v[22:25]
	v_mfma_f32_16x16x32_bf16 v[54:57], v[88:91], v[46:49], v[10:13]
	v_mfma_f32_16x16x32_bf16 v[10:13], v[112:115], v[42:45], v[26:29]
	v_mfma_f32_16x16x32_bf16 v[62:65], v[88:91], v[14:17], v[50:53]
	v_mfma_f32_16x16x32_bf16 v[50:53], v[116:119], v[46:49], v[10:13]
	v_mfma_f32_16x16x32_bf16 v[10:13], v[6:9], v[120:123], v[30:33]
	v_mfma_f32_16x16x32_bf16 v[46:49], v[88:91], v[124:127], v[10:13]
	v_mfma_f32_16x16x32_bf16 v[10:13], v[112:115], v[120:123], v[34:37]
	v_mfma_f32_16x16x32_bf16 v[42:45], v[116:119], v[124:127], v[10:13]
	v_mfma_f32_16x16x32_bf16 v[10:13], v[6:9], v[132:135], v[38:41]
	v_mfma_f32_16x16x32_bf16 v[30:33], v[88:91], v[136:139], v[10:13]
	v_mfma_f32_16x16x32_bf16 v[10:13], v[112:115], v[132:135], v[92:95]
	v_mfma_f32_16x16x32_bf16 v[26:29], v[116:119], v[136:139], v[10:13]
	s_setprio 0
	s_setprio 1
	s_setprio 0
	s_barrier
	s_mov_b32 m0, s65
	v_lshl_add_u64 v[22:23], v[74:75], 0, s[62:63]
	s_add_u32 s24, s28, 0x10080
	ds_read_b128 v[10:13], v78 offset:49152
	ds_read_b128 v[14:17], v78 offset:50176
	ds_read_b128 v[18:21], v78 offset:51200
	ds_read_b128 v[92:95], v78 offset:52224
	ds_read_b128 v[120:123], v78 offset:53248
	ds_read_b128 v[124:127], v78 offset:54272
	ds_read_b128 v[132:135], v78 offset:55296
	ds_read_b128 v[136:139], v78 offset:56320
	global_load_lds_dwordx4 v[22:23], off
	v_lshl_add_u64 v[22:23], v[140:141], 0, s[62:63]
	s_mov_b32 m0, s56
	s_addc_u32 s25, s29, 0
	global_load_lds_dwordx4 v[22:23], off
	v_lshl_add_u64 v[22:23], s[24:25], 0, v[186:187]
	s_mov_b32 m0, s51
	s_nop 0
	global_load_lds_dwordx4 v[22:23], off
	v_lshl_add_u64 v[22:23], s[24:25], 0, v[66:67]
	s_mov_b32 m0, s53
	s_nop 0
	global_load_lds_dwordx4 v[22:23], off
	v_lshl_add_u64 v[22:23], v[142:143], 0, s[62:63]
	s_mov_b32 m0, s47
	s_nop 0
	global_load_lds_dwordx4 v[22:23], off
	v_lshl_add_u64 v[22:23], v[144:145], 0, s[62:63]
	s_mov_b32 m0, s50
	s_nop 0
	global_load_lds_dwordx4 v[22:23], off
	s_waitcnt vmcnt(8)
	s_waitcnt lgkmcnt(0)
	v_mfma_f32_16x16x32_bf16 v[22:25], v[6:9], v[10:13], v[96:99]
	v_mfma_f32_16x16x32_bf16 v[10:13], v[112:115], v[10:13], v[100:103]
	s_barrier
	s_setprio 1
	s_waitcnt lgkmcnt(0)
	v_mfma_f32_16x16x32_bf16 v[34:37], v[116:119], v[14:17], v[10:13]
	v_mfma_f32_16x16x32_bf16 v[10:13], v[6:9], v[18:21], v[128:131]
	v_mfma_f32_16x16x32_bf16 v[38:41], v[88:91], v[14:17], v[22:25]
	v_mfma_f32_16x16x32_bf16 v[22:25], v[88:91], v[92:95], v[10:13]
	v_mfma_f32_16x16x32_bf16 v[10:13], v[112:115], v[18:21], v[104:107]
	v_mfma_f32_16x16x32_bf16 v[18:21], v[116:119], v[92:95], v[10:13]
	v_mfma_f32_16x16x32_bf16 v[10:13], v[6:9], v[120:123], v[108:111]
	v_mfma_f32_16x16x32_bf16 v[2:5], v[6:9], v[132:135], v[2:5]
	v_mfma_f32_16x16x32_bf16 v[14:17], v[88:91], v[124:127], v[10:13]
	v_mfma_f32_16x16x32_bf16 v[10:13], v[112:115], v[120:123], v[80:83]
	v_mfma_f32_16x16x32_bf16 v[6:9], v[88:91], v[136:139], v[2:5]
	v_mfma_f32_16x16x32_bf16 v[2:5], v[112:115], v[132:135], v[84:87]
	v_mfma_f32_16x16x32_bf16 v[10:13], v[116:119], v[124:127], v[10:13]
	v_mfma_f32_16x16x32_bf16 v[2:5], v[116:119], v[136:139], v[2:5]
	s_setprio 0
	s_setprio 1
	s_setprio 0
	s_barrier
	s_andn2_b64 vcc, exec, s[4:5]
	s_cbranch_vccnz .LBB0_930
	s_barrier

; #define PG8_STAGE(bufoff, gbase, voff) do { _Pragma("unroll") for (int _i = 0; _i < 2; ++_i) \
;         __builtin_amdgcn_global_load_lds((const unsigned*)((const char*)(gbase) + (voff)[_i]), (PG8_LAS unsigned*)(lds + (bufoff) + ldsw + _i * 8192), 16, 0, 0); } while (0)
; #define PG8_LDA(dst, b, h) do { _Pragma("unroll") for (int m = 0; m < 4; ++m) _Pragma("unroll") for (int k = 0; k < 2; ++k) dst[m][k] = *(const PG8_LAS bf16x8*)(lds + PG8_SA(b, h) + aoff + m * 2048 + k * 1024); } while (0)
; #define PG8_LDB(dst, b, h) do { _Pragma("unroll") for (int n = 0; n < 2; ++n) _Pragma("unroll") for (int k = 0; k < 2; ++k) dst[n][k] = *(const PG8_LAS bf16x8*)(lds + PG8_SB(b, h) + boff + n * 2048 + k * 1024); } while (0)
; #define PG8_MMA(ai, bj, At, Bt) do { __builtin_amdgcn_s_setprio(1); _Pragma("unroll") for (int m = 0; m < 4; ++m) _Pragma("unroll") for (int n = 0; n < 2; ++n) _Pragma("unroll") for (int k = 0; k < 2; ++k) \
;         acc[ai][bj][m][n] = __builtin_amdgcn_mfma_f32_16x16x32_bf16(Bt[n][k], At[m][k], acc[ai][bj][m][n], 0, 0, 0); __builtin_amdgcn_s_setprio(0); } while (0)
; #define PG8_WAIT_V(n) asm volatile("s_waitcnt vmcnt(" #n ")" ::: "memory")
; #define PG8_BAR __builtin_amdgcn_s_barrier()
; template <class Epi, class Sched, bool ALIGN_EPI = false, bool SP2 = false, bool ABLK = false, bool BBLK = false>
; __device__ __forceinline__ void gemm_phase(PG8_LAS unsigned char* lds, const Gemm g, const Sched& S, const Epi& E) {
;     ...
;             const bool last = (t == nt - 2);
;             const char* a1 = cA + (size_t)(t + 1) * kstepA;
;             const char* a2 = last ? nA : cA + (size_t)(t + 2) * kstepA; const char* b2 = last ? nB : cB + (size_t)(t + 2) * kstepB;
;             const char* a3 = a2 + kstepA; const char* b3 = b2 + kstepB;
;             if (last && has_next) S.a_ready(nxt);
;             if constexpr (SP2) {
;             PG8_LDB(B0, 0, 0); PG8_LDB(B1, 0, 1); PG8_SCHED; PG8_LDA(At, 0, 0); PG8_STAGE(PG8_SA(1, 1), a1 + hstepA, voffA);
;             PG8_WAIT_V(8); PG8_WAIT_L(0); PG8_BAR; PG8_MMA(0, 0, At, B0); PG8_MMA(0, 1, At, B1); PG8_BAR; PG8_SCHED;
;             PG8_LDA(At, 0, 1); PG8_STAGE(PG8_SB(0, 0), b2, voffB); PG8_STAGE(PG8_SB(0, 1), b2 + hstepB, voffB); PG8_STAGE(PG8_SA(0, 0), a2, voffA);
;             PG8_WAIT_V(8); PG8_WAIT_L(0); PG8_BAR; PG8_MMA(1, 0, At, B0); PG8_MMA(1, 1, At, B1); PG8_BAR; PG8_SCHED;
.LBB0_1117:
	s_add_u32 s34, s0, 0xfffe0080
	s_addc_u32 s35, s1, -1
	s_add_i32 s52, 0, 0x10000
	s_cmp_eq_u32 s94, 4
	s_cselect_b32 s37, s23, s35
	s_cselect_b32 s36, s31, s34
	s_cselect_b32 s35, s21, s93
	s_cselect_b32 s34, s91, s92
	s_add_i32 s75, 0, 0x14000
	v_add_u32_e32 v142, s52, v163
	v_add_u32_e32 v160, s75, v163
	ds_read_b128 v[130:133], v142
	ds_read_b128 v[134:137], v142 offset:1024
	ds_read_b128 v[138:141], v142 offset:2048
	ds_read_b128 v[142:145], v142 offset:3072
	ds_read_b128 v[146:149], v160
	ds_read_b128 v[166:169], v160 offset:1024
	ds_read_b128 v[170:173], v160 offset:2048
	ds_read_b128 v[174:177], v160 offset:3072
	v_lshl_add_u64 v[160:161], s[0:1], 0, v[156:157]
	s_add_i32 m0, s29, 0xc000
	ds_read_b128 v[178:181], v165
	ds_read_b128 v[182:185], v165 offset:1024
	ds_read_b128 v[196:199], v165 offset:2048
	ds_read_b128 v[200:203], v165 offset:3072
	ds_read_b128 v[204:207], v165 offset:4096
	ds_read_b128 v[208:211], v165 offset:5120
	ds_read_b128 v[212:215], v165 offset:6144
	ds_read_b128 v[216:219], v165 offset:7168
	global_load_lds_dwordx4 v[160:161], off
	v_lshl_add_u64 v[160:161], s[0:1], 0, v[158:159]
	s_add_i32 m0, s29, 0xe000
	s_nop 0
	global_load_lds_dwordx4 v[160:161], off
	s_waitcnt vmcnt(8)
	s_waitcnt lgkmcnt(0)
	v_mfma_f32_16x16x32_bf16 v[126:129], v[130:133], v[178:181], v[126:129]
	v_mfma_f32_16x16x32_bf16 v[122:125], v[138:141], v[178:181], v[122:125]
	s_barrier
	s_setprio 1
	s_waitcnt lgkmcnt(0)
	v_mfma_f32_16x16x32_bf16 v[118:121], v[130:133], v[196:199], v[118:121]
	v_mfma_f32_16x16x32_bf16 v[114:117], v[138:141], v[196:199], v[114:117]
	v_mfma_f32_16x16x32_bf16 v[94:97], v[130:133], v[204:207], v[94:97]
	v_mfma_f32_16x16x32_bf16 v[90:93], v[138:141], v[204:207], v[90:93]
	v_mfma_f32_16x16x32_bf16 v[78:81], v[130:133], v[212:215], v[78:81]
	v_mfma_f32_16x16x32_bf16 v[74:77], v[138:141], v[212:215], v[74:77]
	v_mfma_f32_16x16x32_bf16 v[126:129], v[134:137], v[182:185], v[126:129]
	v_mfma_f32_16x16x32_bf16 v[122:125], v[142:145], v[182:185], v[122:125]
	v_mfma_f32_16x16x32_bf16 v[118:121], v[134:137], v[200:203], v[118:121]
	v_mfma_f32_16x16x32_bf16 v[114:117], v[142:145], v[200:203], v[114:117]
	v_mfma_f32_16x16x32_bf16 v[94:97], v[134:137], v[208:211], v[94:97]
	v_mfma_f32_16x16x32_bf16 v[90:93], v[142:145], v[208:211], v[90:93]
	v_mfma_f32_16x16x32_bf16 v[78:81], v[134:137], v[216:219], v[78:81]
	v_mfma_f32_16x16x32_bf16 v[74:77], v[142:145], v[216:219], v[74:77]
	s_setprio 0
	s_setprio 1
	v_mfma_f32_16x16x32_bf16 v[110:113], v[146:149], v[178:181], v[110:113]
	v_mfma_f32_16x16x32_bf16 v[106:109], v[170:173], v[178:181], v[106:109]
	v_mfma_f32_16x16x32_bf16 v[102:105], v[146:149], v[196:199], v[102:105]
	v_mfma_f32_16x16x32_bf16 v[98:101], v[170:173], v[196:199], v[98:101]
	v_mfma_f32_16x16x32_bf16 v[86:89], v[146:149], v[204:207], v[86:89]
	v_mfma_f32_16x16x32_bf16 v[82:85], v[170:173], v[204:207], v[82:85]
	v_mfma_f32_16x16x32_bf16 v[70:73], v[146:149], v[212:215], v[70:73]
	v_mfma_f32_16x16x32_bf16 v[66:69], v[170:173], v[212:215], v[66:69]
	v_mfma_f32_16x16x32_bf16 v[110:113], v[166:169], v[182:185], v[110:113]
	v_mfma_f32_16x16x32_bf16 v[106:109], v[174:177], v[182:185], v[106:109]
	v_mfma_f32_16x16x32_bf16 v[102:105], v[166:169], v[200:203], v[102:105]
	v_mfma_f32_16x16x32_bf16 v[98:101], v[174:177], v[200:203], v[98:101]
	v_mfma_f32_16x16x32_bf16 v[86:89], v[166:169], v[208:211], v[86:89]
	v_mfma_f32_16x16x32_bf16 v[82:85], v[174:177], v[208:211], v[82:85]
	v_mfma_f32_16x16x32_bf16 v[70:73], v[166:169], v[216:219], v[70:73]
	v_mfma_f32_16x16x32_bf16 v[66:69], v[174:177], v[216:219], v[66:69]
	s_setprio 0
	s_barrier
	s_add_i32 s52, s52, s47
	v_lshl_add_u64 v[160:161], s[34:35], 0, v[150:151]
	s_mov_b32 m0, s52
	ds_read_b128 v[178:181], v165 offset:16384
	ds_read_b128 v[182:185], v165 offset:17408
	ds_read_b128 v[196:199], v165 offset:18432
	ds_read_b128 v[200:203], v165 offset:19456
	ds_read_b128 v[204:207], v165 offset:20480
	ds_read_b128 v[208:211], v165 offset:21504
	ds_read_b128 v[212:215], v165 offset:22528
	ds_read_b128 v[216:219], v165 offset:23552
	global_load_lds_dwordx4 v[160:161], off
	s_add_i32 m0, s52, 0x2000
	s_add_u32 s96, s34, 0x4000
	v_lshl_add_u64 v[160:161], s[34:35], 0, v[154:155]
	s_addc_u32 s97, s35, 0
	s_add_i32 s52, s75, s47
	global_load_lds_dwordx4 v[160:161], off
	v_lshl_add_u64 v[160:161], s[96:97], 0, v[150:151]
	s_mov_b32 m0, s52
	v_lshl_add_u64 v[188:189], s[36:37], 0, v[152:153]
	global_load_lds_dwordx4 v[160:161], off
	v_lshl_add_u64 v[160:161], s[96:97], 0, v[154:155]
	s_add_i32 m0, s52, 0x2000
	s_nop 0
	global_load_lds_dwordx4 v[160:161], off
	v_lshl_add_u64 v[160:161], s[36:37], 0, v[186:187]
	s_mov_b32 m0, s29
	s_nop 0
	global_load_lds_dwordx4 v[160:161], off
	s_mov_b32 m0, s65
	s_nop 0
	global_load_lds_dwordx4 v[188:189], off
	s_waitcnt vmcnt(8)
	s_waitcnt lgkmcnt(0)
	v_mfma_f32_16x16x32_bf16 v[62:65], v[130:133], v[178:181], v[62:65]
	v_mfma_f32_16x16x32_bf16 v[58:61], v[138:141], v[178:181], v[58:61]
	s_barrier
; #define PG8_STAGE(bufoff, gbase, voff) do { _Pragma("unroll") for (int _i = 0; _i < 2; ++_i) \
;         __builtin_amdgcn_global_load_lds((const unsigned*)((const char*)(gbase) + (voff)[_i]), (PG8_LAS unsigned*)(lds + (bufoff) + ldsw + _i * 8192), 16, 0, 0); } while (0)
; #define PG8_LDA(dst, b, h) do { _Pragma("unroll") for (int m = 0; m < 4; ++m) _Pragma("unroll") for (int k = 0; k < 2; ++k) dst[m][k] = *(const PG8_LAS bf16x8*)(lds + PG8_SA(b, h) + aoff + m * 2048 + k * 1024); } while (0)
; #define PG8_LDB(dst, b, h) do { _Pragma("unroll") for (int n = 0; n < 2; ++n) _Pragma("unroll") for (int k = 0; k < 2; ++k) dst[n][k] = *(const PG8_LAS bf16x8*)(lds + PG8_SB(b, h) + boff + n * 2048 + k * 1024); } while (0)
; #define PG8_MMA(ai, bj, At, Bt) do { __builtin_amdgcn_s_setprio(1); _Pragma("unroll") for (int m = 0; m < 4; ++m) _Pragma("unroll") for (int n = 0; n < 2; ++n) _Pragma("unroll") for (int k = 0; k < 2; ++k) \
;         acc[ai][bj][m][n] = __builtin_amdgcn_mfma_f32_16x16x32_bf16(Bt[n][k], At[m][k], acc[ai][bj][m][n], 0, 0, 0); __builtin_amdgcn_s_setprio(0); } while (0)
; #define PG8_WAIT_V(n) asm volatile("s_waitcnt vmcnt(" #n ")" ::: "memory")
; #define PG8_WAIT_L(n) asm volatile("s_waitcnt lgkmcnt(" #n ")" ::: "memory")
; #define PG8_BAR __builtin_amdgcn_s_barrier()
; #define PG8_SCHED __builtin_amdgcn_sched_barrier(0)
; template <class Epi, class Sched, bool ALIGN_EPI = false, bool SP2 = false, bool ABLK = false, bool BBLK = false>
; __device__ __forceinline__ void gemm_phase(PG8_LAS unsigned char* lds, const Gemm g, const Sched& S, const Epi& E) {
;     ...
;             PG8_WAIT_V(8); PG8_WAIT_L(0); PG8_BAR; PG8_MMA(1, 0, At, B0); PG8_MMA(1, 1, At, B1); PG8_BAR; PG8_SCHED;
;             PG8_LDB(B0, 1, 0); PG8_LDB(B1, 1, 1); PG8_SCHED; PG8_LDA(At, 1, 0); PG8_STAGE(PG8_SA(0, 1), a2 + hstepA, voffA);
;             PG8_WAIT_V(8); PG8_WAIT_L(0); PG8_BAR; PG8_MMA(0, 0, At, B0); PG8_MMA(0, 1, At, B1); PG8_BAR; PG8_SCHED;
	s_setprio 1
	s_waitcnt lgkmcnt(0)
	v_mfma_f32_16x16x32_bf16 v[46:49], v[130:133], v[196:199], v[46:49]
	v_mfma_f32_16x16x32_bf16 v[42:45], v[138:141], v[196:199], v[42:45]
	v_mfma_f32_16x16x32_bf16 v[30:33], v[130:133], v[204:207], v[30:33]
	v_mfma_f32_16x16x32_bf16 v[26:29], v[138:141], v[204:207], v[26:29]
	v_mfma_f32_16x16x32_bf16 v[14:17], v[130:133], v[212:215], v[14:17]
	v_mfma_f32_16x16x32_bf16 v[10:13], v[138:141], v[212:215], v[10:13]
	v_mfma_f32_16x16x32_bf16 v[62:65], v[134:137], v[182:185], v[62:65]
	v_mfma_f32_16x16x32_bf16 v[58:61], v[142:145], v[182:185], v[58:61]
	v_mfma_f32_16x16x32_bf16 v[46:49], v[134:137], v[200:203], v[46:49]
	v_mfma_f32_16x16x32_bf16 v[42:45], v[142:145], v[200:203], v[42:45]
	v_mfma_f32_16x16x32_bf16 v[30:33], v[134:137], v[208:211], v[30:33]
	v_mfma_f32_16x16x32_bf16 v[26:29], v[142:145], v[208:211], v[26:29]
	v_mfma_f32_16x16x32_bf16 v[14:17], v[134:137], v[216:219], v[14:17]
	v_mfma_f32_16x16x32_bf16 v[10:13], v[142:145], v[216:219], v[10:13]
	s_setprio 0
	s_setprio 1
	v_mfma_f32_16x16x32_bf16 v[54:57], v[146:149], v[178:181], v[54:57]
	v_mfma_f32_16x16x32_bf16 v[50:53], v[170:173], v[178:181], v[50:53]
	v_mfma_f32_16x16x32_bf16 v[38:41], v[146:149], v[196:199], v[38:41]
	v_mfma_f32_16x16x32_bf16 v[34:37], v[170:173], v[196:199], v[34:37]
	v_mfma_f32_16x16x32_bf16 v[22:25], v[146:149], v[204:207], v[22:25]
	v_mfma_f32_16x16x32_bf16 v[18:21], v[170:173], v[204:207], v[18:21]
	v_mfma_f32_16x16x32_bf16 v[6:9], v[146:149], v[212:215], v[6:9]
	v_mfma_f32_16x16x32_bf16 v[2:5], v[170:173], v[212:215], v[2:5]
	v_mfma_f32_16x16x32_bf16 v[54:57], v[166:169], v[182:185], v[54:57]
	v_mfma_f32_16x16x32_bf16 v[50:53], v[174:177], v[182:185], v[50:53]
	v_mfma_f32_16x16x32_bf16 v[38:41], v[166:169], v[200:203], v[38:41]
	v_mfma_f32_16x16x32_bf16 v[34:37], v[174:177], v[200:203], v[34:37]
	v_mfma_f32_16x16x32_bf16 v[22:25], v[166:169], v[208:211], v[22:25]
	v_mfma_f32_16x16x32_bf16 v[18:21], v[174:177], v[208:211], v[18:21]
	v_mfma_f32_16x16x32_bf16 v[6:9], v[166:169], v[216:219], v[6:9]
	v_mfma_f32_16x16x32_bf16 v[2:5], v[174:177], v[216:219], v[2:5]
	s_setprio 0
	s_barrier
	s_add_i32 s52, 0, 0x18000
	s_add_i32 s75, 0, 0x1c000
	v_add_u32_e32 v142, s52, v163
	v_add_u32_e32 v174, s75, v163
	ds_read_b128 v[130:133], v142
	ds_read_b128 v[134:137], v142 offset:1024
	ds_read_b128 v[138:141], v142 offset:2048
	ds_read_b128 v[142:145], v142 offset:3072
	ds_read_b128 v[146:149], v174
	ds_read_b128 v[166:169], v174 offset:1024
	ds_read_b128 v[170:173], v174 offset:2048
	ds_read_b128 v[174:177], v174 offset:3072
	s_add_u32 s36, s36, 0x20000
	s_addc_u32 s37, s37, 0
	s_mov_b32 m0, s68
	v_lshl_add_u64 v[190:191], s[36:37], 0, v[186:187]
	ds_read_b128 v[178:181], v165 offset:32768
	ds_read_b128 v[182:185], v165 offset:33792
	ds_read_b128 v[196:199], v165 offset:34816
	ds_read_b128 v[200:203], v165 offset:35840
	ds_read_b128 v[204:207], v165 offset:36864
	ds_read_b128 v[208:211], v165 offset:37888
	ds_read_b128 v[212:215], v165 offset:38912
	ds_read_b128 v[216:219], v165 offset:39936
	global_load_lds_dwordx4 v[190:191], off
	v_lshl_add_u64 v[190:191], s[36:37], 0, v[152:153]
	s_mov_b32 m0, s72
	s_nop 0
	global_load_lds_dwordx4 v[190:191], off
	s_waitcnt vmcnt(8)
	s_waitcnt lgkmcnt(0)
	v_mfma_f32_16x16x32_bf16 v[126:129], v[130:133], v[178:181], v[126:129]
	v_mfma_f32_16x16x32_bf16 v[122:125], v[138:141], v[178:181], v[122:125]
	s_barrier
	s_setprio 1
	s_waitcnt lgkmcnt(0)
	v_mfma_f32_16x16x32_bf16 v[118:121], v[130:133], v[196:199], v[118:121]
	v_mfma_f32_16x16x32_bf16 v[114:117], v[138:141], v[196:199], v[114:117]
	v_mfma_f32_16x16x32_bf16 v[94:97], v[130:133], v[204:207], v[94:97]
	v_mfma_f32_16x16x32_bf16 v[90:93], v[138:141], v[204:207], v[90:93]
	v_mfma_f32_16x16x32_bf16 v[78:81], v[130:133], v[212:215], v[78:81]
	v_mfma_f32_16x16x32_bf16 v[74:77], v[138:141], v[212:215], v[74:77]
	v_mfma_f32_16x16x32_bf16 v[126:129], v[134:137], v[182:185], v[126:129]
	v_mfma_f32_16x16x32_bf16 v[122:125], v[142:145], v[182:185], v[122:125]
	v_mfma_f32_16x16x32_bf16 v[118:121], v[134:137], v[200:203], v[118:121]
	v_mfma_f32_16x16x32_bf16 v[114:117], v[142:145], v[200:203], v[114:117]
	v_mfma_f32_16x16x32_bf16 v[94:97], v[134:137], v[208:211], v[94:97]
	v_mfma_f32_16x16x32_bf16 v[90:93], v[142:145], v[208:211], v[90:93]
	v_mfma_f32_16x16x32_bf16 v[78:81], v[134:137], v[216:219], v[78:81]
	v_mfma_f32_16x16x32_bf16 v[74:77], v[142:145], v[216:219], v[74:77]
	s_setprio 0
	s_setprio 1
	v_mfma_f32_16x16x32_bf16 v[110:113], v[146:149], v[178:181], v[110:113]
	v_mfma_f32_16x16x32_bf16 v[106:109], v[170:173], v[178:181], v[106:109]
	v_mfma_f32_16x16x32_bf16 v[102:105], v[146:149], v[196:199], v[102:105]
	v_mfma_f32_16x16x32_bf16 v[98:101], v[170:173], v[196:199], v[98:101]
	v_mfma_f32_16x16x32_bf16 v[86:89], v[146:149], v[204:207], v[86:89]
	v_mfma_f32_16x16x32_bf16 v[82:85], v[170:173], v[204:207], v[82:85]
	v_mfma_f32_16x16x32_bf16 v[70:73], v[146:149], v[212:215], v[70:73]
	v_mfma_f32_16x16x32_bf16 v[66:69], v[170:173], v[212:215], v[66:69]
	v_mfma_f32_16x16x32_bf16 v[110:113], v[166:169], v[182:185], v[110:113]
	v_mfma_f32_16x16x32_bf16 v[106:109], v[174:177], v[182:185], v[106:109]
	v_mfma_f32_16x16x32_bf16 v[102:105], v[166:169], v[200:203], v[102:105]
	v_mfma_f32_16x16x32_bf16 v[98:101], v[174:177], v[200:203], v[98:101]
	v_mfma_f32_16x16x32_bf16 v[86:89], v[166:169], v[208:211], v[86:89]
	v_mfma_f32_16x16x32_bf16 v[82:85], v[174:177], v[208:211], v[82:85]
	v_mfma_f32_16x16x32_bf16 v[70:73], v[166:169], v[216:219], v[70:73]
	v_mfma_f32_16x16x32_bf16 v[66:69], v[174:177], v[216:219], v[66:69]
	s_setprio 0
	s_barrier
; #define PG8_STAGE(bufoff, gbase, voff) do { _Pragma("unroll") for (int _i = 0; _i < 2; ++_i) \
;         __builtin_amdgcn_global_load_lds((const unsigned*)((const char*)(gbase) + (voff)[_i]), (PG8_LAS unsigned*)(lds + (bufoff) + ldsw + _i * 8192), 16, 0, 0); } while (0)
; #define PG8_LDA(dst, b, h) do { _Pragma("unroll") for (int m = 0; m < 4; ++m) _Pragma("unroll") for (int k = 0; k < 2; ++k) dst[m][k] = *(const PG8_LAS bf16x8*)(lds + PG8_SA(b, h) + aoff + m * 2048 + k * 1024); } while (0)
; #define PG8_MMA(ai, bj, At, Bt) do { __builtin_amdgcn_s_setprio(1); _Pragma("unroll") for (int m = 0; m < 4; ++m) _Pragma("unroll") for (int n = 0; n < 2; ++n) _Pragma("unroll") for (int k = 0; k < 2; ++k) \
;         acc[ai][bj][m][n] = __builtin_amdgcn_mfma_f32_16x16x32_bf16(Bt[n][k], At[m][k], acc[ai][bj][m][n], 0, 0, 0); __builtin_amdgcn_s_setprio(0); } while (0)
; #define PG8_WAIT_V(n) asm volatile("s_waitcnt vmcnt(" #n ")" ::: "memory")
; #define PG8_WAIT_L(n) asm volatile("s_waitcnt lgkmcnt(" #n ")" ::: "memory")
; #define PG8_BAR __builtin_amdgcn_s_barrier()
; #define PG8_SCHED __builtin_amdgcn_sched_barrier(0)
; template <class Epi, class Sched, bool ALIGN_EPI = false, bool SP2 = false, bool ABLK = false, bool BBLK = false>
; __device__ __forceinline__ void gemm_phase(PG8_LAS unsigned char* lds, const Gemm g, const Sched& S, const Epi& E) {
;     ...
;         for (int t = 0; t < nt; t += 2) {
;     ...
;             PG8_LDA(At, 1, 1); PG8_STAGE(PG8_SB(1, 0), b3, voffB); PG8_STAGE(PG8_SB(1, 1), b3 + hstepB, voffB); PG8_STAGE(PG8_SA(1, 0), a3, voffA);
;             PG8_WAIT_V(8); PG8_WAIT_L(0); PG8_BAR; PG8_MMA(1, 0, At, B0); PG8_MMA(1, 1, At, B1); PG8_BAR; PG8_SCHED;
	s_add_u32 s36, s34, 0x8000
	s_addc_u32 s37, s35, 0
	s_add_i32 s52, s52, s47
	v_lshl_add_u64 v[190:191], s[36:37], 0, v[150:151]
	s_mov_b32 m0, s52
	ds_read_b128 v[178:181], v165 offset:49152
	ds_read_b128 v[182:185], v165 offset:50176
	ds_read_b128 v[196:199], v165 offset:51200
	ds_read_b128 v[200:203], v165 offset:52224
	ds_read_b128 v[204:207], v165 offset:53248
	ds_read_b128 v[208:211], v165 offset:54272
	ds_read_b128 v[212:215], v165 offset:55296
	ds_read_b128 v[216:219], v165 offset:56320
	global_load_lds_dwordx4 v[190:191], off
	s_add_i32 m0, s52, 0x2000
	s_add_u32 s34, s34, 0xc000
	v_lshl_add_u64 v[190:191], s[36:37], 0, v[154:155]
	s_addc_u32 s35, s35, 0
	s_add_i32 s36, s75, s47
	global_load_lds_dwordx4 v[190:191], off
	v_lshl_add_u64 v[190:191], s[34:35], 0, v[150:151]
	s_mov_b32 m0, s36
	v_lshl_add_u64 v[160:161], v[160:161], 0, s[62:63]
	global_load_lds_dwordx4 v[190:191], off
	v_lshl_add_u64 v[190:191], s[34:35], 0, v[154:155]
	s_add_i32 m0, s36, 0x2000
	s_nop 0
	global_load_lds_dwordx4 v[190:191], off
	s_mov_b32 m0, s86
	s_nop 0
	global_load_lds_dwordx4 v[160:161], off
	v_lshl_add_u64 v[160:161], v[188:189], 0, s[62:63]
	s_mov_b32 m0, s88
	s_nop 0
	global_load_lds_dwordx4 v[160:161], off
	s_waitcnt vmcnt(8)
	s_waitcnt lgkmcnt(0)
	v_mfma_f32_16x16x32_bf16 v[62:65], v[130:133], v[178:181], v[62:65]
	v_mfma_f32_16x16x32_bf16 v[58:61], v[138:141], v[178:181], v[58:61]
	s_barrier
	s_setprio 1
	s_waitcnt lgkmcnt(0)
	v_mfma_f32_16x16x32_bf16 v[46:49], v[130:133], v[196:199], v[46:49]
	v_mfma_f32_16x16x32_bf16 v[42:45], v[138:141], v[196:199], v[42:45]
	v_mfma_f32_16x16x32_bf16 v[30:33], v[130:133], v[204:207], v[30:33]
	v_mfma_f32_16x16x32_bf16 v[26:29], v[138:141], v[204:207], v[26:29]
	v_mfma_f32_16x16x32_bf16 v[14:17], v[130:133], v[212:215], v[14:17]
	v_mfma_f32_16x16x32_bf16 v[10:13], v[138:141], v[212:215], v[10:13]
	v_mfma_f32_16x16x32_bf16 v[62:65], v[134:137], v[182:185], v[62:65]
	v_mfma_f32_16x16x32_bf16 v[58:61], v[142:145], v[182:185], v[58:61]
	v_mfma_f32_16x16x32_bf16 v[46:49], v[134:137], v[200:203], v[46:49]
	v_mfma_f32_16x16x32_bf16 v[42:45], v[142:145], v[200:203], v[42:45]
	v_mfma_f32_16x16x32_bf16 v[30:33], v[134:137], v[208:211], v[30:33]
	v_mfma_f32_16x16x32_bf16 v[26:29], v[142:145], v[208:211], v[26:29]
	v_mfma_f32_16x16x32_bf16 v[14:17], v[134:137], v[216:219], v[14:17]
	v_mfma_f32_16x16x32_bf16 v[10:13], v[142:145], v[216:219], v[10:13]
	s_setprio 0
	s_setprio 1
	v_mfma_f32_16x16x32_bf16 v[54:57], v[146:149], v[178:181], v[54:57]
	v_mfma_f32_16x16x32_bf16 v[50:53], v[170:173], v[178:181], v[50:53]
	v_mfma_f32_16x16x32_bf16 v[38:41], v[146:149], v[196:199], v[38:41]
	v_mfma_f32_16x16x32_bf16 v[34:37], v[170:173], v[196:199], v[34:37]
	v_mfma_f32_16x16x32_bf16 v[22:25], v[146:149], v[204:207], v[22:25]
	v_mfma_f32_16x16x32_bf16 v[18:21], v[170:173], v[204:207], v[18:21]
	v_mfma_f32_16x16x32_bf16 v[6:9], v[146:149], v[212:215], v[6:9]
	v_mfma_f32_16x16x32_bf16 v[2:5], v[170:173], v[212:215], v[2:5]
	v_mfma_f32_16x16x32_bf16 v[54:57], v[166:169], v[182:185], v[54:57]
	v_mfma_f32_16x16x32_bf16 v[50:53], v[174:177], v[182:185], v[50:53]
	v_mfma_f32_16x16x32_bf16 v[38:41], v[166:169], v[200:203], v[38:41]
	v_mfma_f32_16x16x32_bf16 v[34:37], v[174:177], v[200:203], v[34:37]
	v_mfma_f32_16x16x32_bf16 v[22:25], v[166:169], v[208:211], v[22:25]
	v_mfma_f32_16x16x32_bf16 v[18:21], v[174:177], v[208:211], v[18:21]
	v_mfma_f32_16x16x32_bf16 v[6:9], v[166:169], v[216:219], v[6:9]
	v_mfma_f32_16x16x32_bf16 v[2:5], v[174:177], v[216:219], v[2:5]
	s_setprio 0
	s_barrier
	s_add_i32 s94, s94, 2
	s_add_u32 s92, s92, 0x10000
	s_addc_u32 s93, s93, 0
	s_add_u32 s0, s0, 0x100
	s_addc_u32 s1, s1, 0
	s_cmp_gt_u32 s94, 5
	s_cbranch_scc0 .LBB0_1117
	s_and_b64 vcc, exec, s[18:19]
	s_cbranch_vccz .LBB0_1120
	s_barrier

; #define PG8_STAGE(bufoff, gbase, voff) do { _Pragma("unroll") for (int _i = 0; _i < 2; ++_i) \
;         __builtin_amdgcn_global_load_lds((const unsigned*)((const char*)(gbase) + (voff)[_i]), (PG8_LAS unsigned*)(lds + (bufoff) + ldsw + _i * 8192), 16, 0, 0); } while (0)
; #define PG8_LDA(dst, b, h) do { _Pragma("unroll") for (int m = 0; m < 4; ++m) _Pragma("unroll") for (int k = 0; k < 2; ++k) dst[m][k] = *(const PG8_LAS bf16x8*)(lds + PG8_SA(b, h) + aoff + m * 2048 + k * 1024); } while (0)
; #define PG8_LDB(dst, b, h) do { _Pragma("unroll") for (int n = 0; n < 2; ++n) _Pragma("unroll") for (int k = 0; k < 2; ++k) dst[n][k] = *(const PG8_LAS bf16x8*)(lds + PG8_SB(b, h) + boff + n * 2048 + k * 1024); } while (0)
; #define PG8_MMA(ai, bj, At, Bt) do { __builtin_amdgcn_s_setprio(1); _Pragma("unroll") for (int m = 0; m < 4; ++m) _Pragma("unroll") for (int n = 0; n < 2; ++n) _Pragma("unroll") for (int k = 0; k < 2; ++k) \
;         acc[ai][bj][m][n] = __builtin_amdgcn_mfma_f32_16x16x32_bf16(Bt[n][k], At[m][k], acc[ai][bj][m][n], 0, 0, 0); __builtin_amdgcn_s_setprio(0); } while (0)
; #define PG8_WAIT_V(n) asm volatile("s_waitcnt vmcnt(" #n ")" ::: "memory")
; #define PG8_BAR __builtin_amdgcn_s_barrier()
; template <class Epi, class Sched, bool ALIGN_EPI = false, bool SP2 = false, bool ABLK = false, bool BBLK = false>
; __device__ __forceinline__ void gemm_phase(PG8_LAS unsigned char* lds, const Gemm g, const Sched& S, const Epi& E) {
;     ...
;             const bool last = (t == nt - 2);
;             const char* a1 = cA + (size_t)(t + 1) * kstepA;
;             const char* a2 = last ? nA : cA + (size_t)(t + 2) * kstepA; const char* b2 = last ? nB : cB + (size_t)(t + 2) * kstepB;
;             const char* a3 = a2 + kstepA; const char* b3 = b2 + kstepB;
;             if (last && has_next) S.a_ready(nxt);
;             if constexpr (SP2) {
;             PG8_LDB(B0, 0, 0); PG8_LDB(B1, 0, 1); PG8_SCHED; PG8_LDA(At, 0, 0); PG8_STAGE(PG8_SA(1, 1), a1 + hstepA, voffA);
;             PG8_WAIT_V(8); PG8_WAIT_L(0); PG8_BAR; PG8_MMA(0, 0, At, B0); PG8_MMA(0, 1, At, B1); PG8_BAR; PG8_SCHED;
;             PG8_LDA(At, 0, 1); PG8_STAGE(PG8_SB(0, 0), b2, voffB); PG8_STAGE(PG8_SB(0, 1), b2 + hstepB, voffB); PG8_STAGE(PG8_SA(0, 0), a2, voffA);
;             PG8_WAIT_V(8); PG8_WAIT_L(0); PG8_BAR; PG8_MMA(1, 0, At, B0); PG8_MMA(1, 1, At, B1); PG8_BAR; PG8_SCHED;
.LBB0_1140:
	s_add_u32 s34, s0, 0xfffc0080
	s_addc_u32 s35, s1, -1
	s_add_i32 s52, 0, 0x10000
	s_cmp_eq_u32 s94, 12
	s_cselect_b32 s37, s23, s35
	s_cselect_b32 s36, s31, s34
	s_cselect_b32 s35, s21, s93
	s_cselect_b32 s34, s91, s92
	s_add_i32 s75, 0, 0x14000
	v_add_u32_e32 v142, s52, v223
	v_add_u32_e32 v158, s75, v223
	ds_read_b128 v[130:133], v142
	ds_read_b128 v[134:137], v142 offset:1024
	ds_read_b128 v[138:141], v142 offset:2048
	ds_read_b128 v[142:145], v142 offset:3072
	ds_read_b128 v[146:149], v158
	ds_read_b128 v[150:153], v158 offset:1024
	ds_read_b128 v[154:157], v158 offset:2048
	ds_read_b128 v[158:161], v158 offset:3072
	v_lshl_add_u64 v[188:189], s[0:1], 0, v[202:203]
	s_add_i32 m0, s29, 0xc000
	ds_read_b128 v[162:165], v225
	ds_read_b128 v[166:169], v225 offset:1024
	ds_read_b128 v[170:173], v225 offset:2048
	ds_read_b128 v[174:177], v225 offset:3072
	ds_read_b128 v[178:181], v225 offset:4096
	ds_read_b128 v[182:185], v225 offset:5120
	ds_read_b128 v[206:209], v225 offset:6144
	ds_read_b128 v[210:213], v225 offset:7168
	global_load_lds_dwordx4 v[188:189], off
	v_lshl_add_u64 v[188:189], s[0:1], 0, v[204:205]
	s_add_i32 m0, s29, 0xe000
	s_nop 0
	global_load_lds_dwordx4 v[188:189], off
	s_waitcnt vmcnt(8)
	s_waitcnt lgkmcnt(0)
	v_mfma_f32_16x16x32_bf16 v[126:129], v[130:133], v[162:165], v[126:129]
	v_mfma_f32_16x16x32_bf16 v[122:125], v[138:141], v[162:165], v[122:125]
	s_barrier
	s_setprio 1
	s_waitcnt lgkmcnt(0)
	v_mfma_f32_16x16x32_bf16 v[110:113], v[130:133], v[170:173], v[110:113]
	v_mfma_f32_16x16x32_bf16 v[106:109], v[138:141], v[170:173], v[106:109]
	v_mfma_f32_16x16x32_bf16 v[94:97], v[130:133], v[178:181], v[94:97]
	v_mfma_f32_16x16x32_bf16 v[90:93], v[138:141], v[178:181], v[90:93]
	v_mfma_f32_16x16x32_bf16 v[78:81], v[130:133], v[206:209], v[78:81]
	v_mfma_f32_16x16x32_bf16 v[74:77], v[138:141], v[206:209], v[74:77]
	v_mfma_f32_16x16x32_bf16 v[126:129], v[134:137], v[166:169], v[126:129]
	v_mfma_f32_16x16x32_bf16 v[122:125], v[142:145], v[166:169], v[122:125]
	v_mfma_f32_16x16x32_bf16 v[110:113], v[134:137], v[174:177], v[110:113]
	v_mfma_f32_16x16x32_bf16 v[106:109], v[142:145], v[174:177], v[106:109]
	v_mfma_f32_16x16x32_bf16 v[94:97], v[134:137], v[182:185], v[94:97]
	v_mfma_f32_16x16x32_bf16 v[90:93], v[142:145], v[182:185], v[90:93]
	v_mfma_f32_16x16x32_bf16 v[78:81], v[134:137], v[210:213], v[78:81]
	v_mfma_f32_16x16x32_bf16 v[74:77], v[142:145], v[210:213], v[74:77]
	s_setprio 0
	s_setprio 1
	v_mfma_f32_16x16x32_bf16 v[118:121], v[146:149], v[162:165], v[118:121]
	v_mfma_f32_16x16x32_bf16 v[114:117], v[154:157], v[162:165], v[114:117]
	v_mfma_f32_16x16x32_bf16 v[102:105], v[146:149], v[170:173], v[102:105]
	v_mfma_f32_16x16x32_bf16 v[98:101], v[154:157], v[170:173], v[98:101]
	v_mfma_f32_16x16x32_bf16 v[86:89], v[146:149], v[178:181], v[86:89]
	v_mfma_f32_16x16x32_bf16 v[82:85], v[154:157], v[178:181], v[82:85]
	v_mfma_f32_16x16x32_bf16 v[70:73], v[146:149], v[206:209], v[70:73]
	v_mfma_f32_16x16x32_bf16 v[66:69], v[154:157], v[206:209], v[66:69]
	v_mfma_f32_16x16x32_bf16 v[118:121], v[150:153], v[166:169], v[118:121]
	v_mfma_f32_16x16x32_bf16 v[114:117], v[158:161], v[166:169], v[114:117]
	v_mfma_f32_16x16x32_bf16 v[102:105], v[150:153], v[174:177], v[102:105]
	v_mfma_f32_16x16x32_bf16 v[98:101], v[158:161], v[174:177], v[98:101]
	v_mfma_f32_16x16x32_bf16 v[86:89], v[150:153], v[182:185], v[86:89]
	v_mfma_f32_16x16x32_bf16 v[82:85], v[158:161], v[182:185], v[82:85]
	v_mfma_f32_16x16x32_bf16 v[70:73], v[150:153], v[210:213], v[70:73]
	v_mfma_f32_16x16x32_bf16 v[66:69], v[158:161], v[210:213], v[66:69]
	s_setprio 0
	s_barrier
	s_add_i32 s52, s52, s45
	v_lshl_add_u64 v[188:189], s[34:35], 0, v[196:197]
	s_mov_b32 m0, s52
	ds_read_b128 v[162:165], v225 offset:16384
	ds_read_b128 v[166:169], v225 offset:17408
	ds_read_b128 v[170:173], v225 offset:18432
	ds_read_b128 v[174:177], v225 offset:19456
	ds_read_b128 v[178:181], v225 offset:20480
	ds_read_b128 v[182:185], v225 offset:21504
	ds_read_b128 v[206:209], v225 offset:22528
	ds_read_b128 v[210:213], v225 offset:23552
	global_load_lds_dwordx4 v[188:189], off
	s_add_i32 m0, s52, 0x2000
	s_add_u32 s96, s34, 0x4000
	v_lshl_add_u64 v[188:189], s[34:35], 0, v[200:201]
	s_addc_u32 s97, s35, 0
	s_add_i32 s52, s75, s45
	global_load_lds_dwordx4 v[188:189], off
	v_lshl_add_u64 v[188:189], s[96:97], 0, v[196:197]
	s_mov_b32 m0, s52
	v_lshl_add_u64 v[190:191], s[36:37], 0, v[198:199]
	global_load_lds_dwordx4 v[188:189], off
	v_lshl_add_u64 v[188:189], s[96:97], 0, v[200:201]
	s_add_i32 m0, s52, 0x2000
	s_nop 0
	global_load_lds_dwordx4 v[188:189], off
	v_lshl_add_u64 v[188:189], s[36:37], 0, v[186:187]
	s_mov_b32 m0, s29
	s_nop 0
	global_load_lds_dwordx4 v[188:189], off
	s_mov_b32 m0, s65
	s_nop 0
	global_load_lds_dwordx4 v[190:191], off
	s_waitcnt vmcnt(8)
	s_waitcnt lgkmcnt(0)
	v_mfma_f32_16x16x32_bf16 v[62:65], v[130:133], v[162:165], v[62:65]
	v_mfma_f32_16x16x32_bf16 v[58:61], v[138:141], v[162:165], v[58:61]
	s_barrier
; #define PG8_STAGE(bufoff, gbase, voff) do { _Pragma("unroll") for (int _i = 0; _i < 2; ++_i) \
;         __builtin_amdgcn_global_load_lds((const unsigned*)((const char*)(gbase) + (voff)[_i]), (PG8_LAS unsigned*)(lds + (bufoff) + ldsw + _i * 8192), 16, 0, 0); } while (0)
; #define PG8_LDA(dst, b, h) do { _Pragma("unroll") for (int m = 0; m < 4; ++m) _Pragma("unroll") for (int k = 0; k < 2; ++k) dst[m][k] = *(const PG8_LAS bf16x8*)(lds + PG8_SA(b, h) + aoff + m * 2048 + k * 1024); } while (0)
; #define PG8_LDB(dst, b, h) do { _Pragma("unroll") for (int n = 0; n < 2; ++n) _Pragma("unroll") for (int k = 0; k < 2; ++k) dst[n][k] = *(const PG8_LAS bf16x8*)(lds + PG8_SB(b, h) + boff + n * 2048 + k * 1024); } while (0)
; #define PG8_MMA(ai, bj, At, Bt) do { __builtin_amdgcn_s_setprio(1); _Pragma("unroll") for (int m = 0; m < 4; ++m) _Pragma("unroll") for (int n = 0; n < 2; ++n) _Pragma("unroll") for (int k = 0; k < 2; ++k) \
;         acc[ai][bj][m][n] = __builtin_amdgcn_mfma_f32_16x16x32_bf16(Bt[n][k], At[m][k], acc[ai][bj][m][n], 0, 0, 0); __builtin_amdgcn_s_setprio(0); } while (0)
; #define PG8_WAIT_V(n) asm volatile("s_waitcnt vmcnt(" #n ")" ::: "memory")
; #define PG8_WAIT_L(n) asm volatile("s_waitcnt lgkmcnt(" #n ")" ::: "memory")
; #define PG8_BAR __builtin_amdgcn_s_barrier()
; #define PG8_SCHED __builtin_amdgcn_sched_barrier(0)
; template <class Epi, class Sched, bool ALIGN_EPI = false, bool SP2 = false, bool ABLK = false, bool BBLK = false>
; __device__ __forceinline__ void gemm_phase(PG8_LAS unsigned char* lds, const Gemm g, const Sched& S, const Epi& E) {
;     ...
;             PG8_WAIT_V(8); PG8_WAIT_L(0); PG8_BAR; PG8_MMA(1, 0, At, B0); PG8_MMA(1, 1, At, B1); PG8_BAR; PG8_SCHED;
;             PG8_LDB(B0, 1, 0); PG8_LDB(B1, 1, 1); PG8_SCHED; PG8_LDA(At, 1, 0); PG8_STAGE(PG8_SA(0, 1), a2 + hstepA, voffA);
;             PG8_WAIT_V(8); PG8_WAIT_L(0); PG8_BAR; PG8_MMA(0, 0, At, B0); PG8_MMA(0, 1, At, B1); PG8_BAR; PG8_SCHED;
	s_setprio 1
	s_waitcnt lgkmcnt(0)
	v_mfma_f32_16x16x32_bf16 v[46:49], v[130:133], v[170:173], v[46:49]
	v_mfma_f32_16x16x32_bf16 v[42:45], v[138:141], v[170:173], v[42:45]
	v_mfma_f32_16x16x32_bf16 v[30:33], v[130:133], v[178:181], v[30:33]
	v_mfma_f32_16x16x32_bf16 v[26:29], v[138:141], v[178:181], v[26:29]
	v_mfma_f32_16x16x32_bf16 v[14:17], v[130:133], v[206:209], v[14:17]
	v_mfma_f32_16x16x32_bf16 v[10:13], v[138:141], v[206:209], v[10:13]
	v_mfma_f32_16x16x32_bf16 v[62:65], v[134:137], v[166:169], v[62:65]
	v_mfma_f32_16x16x32_bf16 v[58:61], v[142:145], v[166:169], v[58:61]
	v_mfma_f32_16x16x32_bf16 v[46:49], v[134:137], v[174:177], v[46:49]
	v_mfma_f32_16x16x32_bf16 v[42:45], v[142:145], v[174:177], v[42:45]
	v_mfma_f32_16x16x32_bf16 v[30:33], v[134:137], v[182:185], v[30:33]
	v_mfma_f32_16x16x32_bf16 v[26:29], v[142:145], v[182:185], v[26:29]
	v_mfma_f32_16x16x32_bf16 v[14:17], v[134:137], v[210:213], v[14:17]
	v_mfma_f32_16x16x32_bf16 v[10:13], v[142:145], v[210:213], v[10:13]
	s_setprio 0
	s_setprio 1
	v_mfma_f32_16x16x32_bf16 v[54:57], v[146:149], v[162:165], v[54:57]
	v_mfma_f32_16x16x32_bf16 v[50:53], v[154:157], v[162:165], v[50:53]
	v_mfma_f32_16x16x32_bf16 v[38:41], v[146:149], v[170:173], v[38:41]
	v_mfma_f32_16x16x32_bf16 v[34:37], v[154:157], v[170:173], v[34:37]
	v_mfma_f32_16x16x32_bf16 v[22:25], v[146:149], v[178:181], v[22:25]
	v_mfma_f32_16x16x32_bf16 v[18:21], v[154:157], v[178:181], v[18:21]
	v_mfma_f32_16x16x32_bf16 v[6:9], v[146:149], v[206:209], v[6:9]
	v_mfma_f32_16x16x32_bf16 v[2:5], v[154:157], v[206:209], v[2:5]
	v_mfma_f32_16x16x32_bf16 v[54:57], v[150:153], v[166:169], v[54:57]
	v_mfma_f32_16x16x32_bf16 v[50:53], v[158:161], v[166:169], v[50:53]
	v_mfma_f32_16x16x32_bf16 v[38:41], v[150:153], v[174:177], v[38:41]
	v_mfma_f32_16x16x32_bf16 v[34:37], v[158:161], v[174:177], v[34:37]
	v_mfma_f32_16x16x32_bf16 v[22:25], v[150:153], v[182:185], v[22:25]
	v_mfma_f32_16x16x32_bf16 v[18:21], v[158:161], v[182:185], v[18:21]
	v_mfma_f32_16x16x32_bf16 v[6:9], v[150:153], v[210:213], v[6:9]
	v_mfma_f32_16x16x32_bf16 v[2:5], v[158:161], v[210:213], v[2:5]
	s_setprio 0
	s_barrier
	s_add_i32 s52, 0, 0x18000
	s_add_i32 s75, 0, 0x1c000
	v_add_u32_e32 v142, s52, v223
	v_add_u32_e32 v158, s75, v223
	ds_read_b128 v[130:133], v142
	ds_read_b128 v[134:137], v142 offset:1024
	ds_read_b128 v[138:141], v142 offset:2048
	ds_read_b128 v[142:145], v142 offset:3072
	ds_read_b128 v[146:149], v158
	ds_read_b128 v[150:153], v158 offset:1024
	ds_read_b128 v[154:157], v158 offset:2048
	ds_read_b128 v[158:161], v158 offset:3072
	s_add_u32 s36, s36, 0x40000
	s_addc_u32 s37, s37, 0
	s_mov_b32 m0, s68
	v_lshl_add_u64 v[192:193], s[36:37], 0, v[186:187]
	ds_read_b128 v[162:165], v225 offset:32768
	ds_read_b128 v[166:169], v225 offset:33792
	ds_read_b128 v[170:173], v225 offset:34816
	ds_read_b128 v[174:177], v225 offset:35840
	ds_read_b128 v[178:181], v225 offset:36864
	ds_read_b128 v[182:185], v225 offset:37888
	ds_read_b128 v[206:209], v225 offset:38912
	ds_read_b128 v[210:213], v225 offset:39936
	global_load_lds_dwordx4 v[192:193], off
	v_lshl_add_u64 v[192:193], s[36:37], 0, v[198:199]
	s_mov_b32 m0, s72
	s_nop 0
	global_load_lds_dwordx4 v[192:193], off
	s_waitcnt vmcnt(8)
	s_waitcnt lgkmcnt(0)
	v_mfma_f32_16x16x32_bf16 v[126:129], v[130:133], v[162:165], v[126:129]
	v_mfma_f32_16x16x32_bf16 v[122:125], v[138:141], v[162:165], v[122:125]
	s_barrier
	s_setprio 1
	s_waitcnt lgkmcnt(0)
	v_mfma_f32_16x16x32_bf16 v[110:113], v[130:133], v[170:173], v[110:113]
	v_mfma_f32_16x16x32_bf16 v[106:109], v[138:141], v[170:173], v[106:109]
	v_mfma_f32_16x16x32_bf16 v[94:97], v[130:133], v[178:181], v[94:97]
	v_mfma_f32_16x16x32_bf16 v[90:93], v[138:141], v[178:181], v[90:93]
	v_mfma_f32_16x16x32_bf16 v[78:81], v[130:133], v[206:209], v[78:81]
	v_mfma_f32_16x16x32_bf16 v[74:77], v[138:141], v[206:209], v[74:77]
	v_mfma_f32_16x16x32_bf16 v[126:129], v[134:137], v[166:169], v[126:129]
	v_mfma_f32_16x16x32_bf16 v[122:125], v[142:145], v[166:169], v[122:125]
	v_mfma_f32_16x16x32_bf16 v[110:113], v[134:137], v[174:177], v[110:113]
	v_mfma_f32_16x16x32_bf16 v[106:109], v[142:145], v[174:177], v[106:109]
	v_mfma_f32_16x16x32_bf16 v[94:97], v[134:137], v[182:185], v[94:97]
	v_mfma_f32_16x16x32_bf16 v[90:93], v[142:145], v[182:185], v[90:93]
	v_mfma_f32_16x16x32_bf16 v[78:81], v[134:137], v[210:213], v[78:81]
	v_mfma_f32_16x16x32_bf16 v[74:77], v[142:145], v[210:213], v[74:77]
	s_setprio 0
	s_setprio 1
	v_mfma_f32_16x16x32_bf16 v[118:121], v[146:149], v[162:165], v[118:121]
	v_mfma_f32_16x16x32_bf16 v[114:117], v[154:157], v[162:165], v[114:117]
	v_mfma_f32_16x16x32_bf16 v[102:105], v[146:149], v[170:173], v[102:105]
	v_mfma_f32_16x16x32_bf16 v[98:101], v[154:157], v[170:173], v[98:101]
	v_mfma_f32_16x16x32_bf16 v[86:89], v[146:149], v[178:181], v[86:89]
	v_mfma_f32_16x16x32_bf16 v[82:85], v[154:157], v[178:181], v[82:85]
	v_mfma_f32_16x16x32_bf16 v[70:73], v[146:149], v[206:209], v[70:73]
	v_mfma_f32_16x16x32_bf16 v[66:69], v[154:157], v[206:209], v[66:69]
	v_mfma_f32_16x16x32_bf16 v[118:121], v[150:153], v[166:169], v[118:121]
	v_mfma_f32_16x16x32_bf16 v[114:117], v[158:161], v[166:169], v[114:117]
	v_mfma_f32_16x16x32_bf16 v[102:105], v[150:153], v[174:177], v[102:105]
	v_mfma_f32_16x16x32_bf16 v[98:101], v[158:161], v[174:177], v[98:101]
	v_mfma_f32_16x16x32_bf16 v[86:89], v[150:153], v[182:185], v[86:89]
	v_mfma_f32_16x16x32_bf16 v[82:85], v[158:161], v[182:185], v[82:85]
	v_mfma_f32_16x16x32_bf16 v[70:73], v[150:153], v[210:213], v[70:73]
	v_mfma_f32_16x16x32_bf16 v[66:69], v[158:161], v[210:213], v[66:69]
	s_setprio 0
	s_barrier
; #define PG8_STAGE(bufoff, gbase, voff) do { _Pragma("unroll") for (int _i = 0; _i < 2; ++_i) \
;         __builtin_amdgcn_global_load_lds((const unsigned*)((const char*)(gbase) + (voff)[_i]), (PG8_LAS unsigned*)(lds + (bufoff) + ldsw + _i * 8192), 16, 0, 0); } while (0)
; #define PG8_LDA(dst, b, h) do { _Pragma("unroll") for (int m = 0; m < 4; ++m) _Pragma("unroll") for (int k = 0; k < 2; ++k) dst[m][k] = *(const PG8_LAS bf16x8*)(lds + PG8_SA(b, h) + aoff + m * 2048 + k * 1024); } while (0)
; #define PG8_MMA(ai, bj, At, Bt) do { __builtin_amdgcn_s_setprio(1); _Pragma("unroll") for (int m = 0; m < 4; ++m) _Pragma("unroll") for (int n = 0; n < 2; ++n) _Pragma("unroll") for (int k = 0; k < 2; ++k) \
;         acc[ai][bj][m][n] = __builtin_amdgcn_mfma_f32_16x16x32_bf16(Bt[n][k], At[m][k], acc[ai][bj][m][n], 0, 0, 0); __builtin_amdgcn_s_setprio(0); } while (0)
; #define PG8_WAIT_V(n) asm volatile("s_waitcnt vmcnt(" #n ")" ::: "memory")
; #define PG8_WAIT_L(n) asm volatile("s_waitcnt lgkmcnt(" #n ")" ::: "memory")
; #define PG8_BAR __builtin_amdgcn_s_barrier()
; #define PG8_SCHED __builtin_amdgcn_sched_barrier(0)
; template <class Epi, class Sched, bool ALIGN_EPI = false, bool SP2 = false, bool ABLK = false, bool BBLK = false>
; __device__ __forceinline__ void gemm_phase(PG8_LAS unsigned char* lds, const Gemm g, const Sched& S, const Epi& E) {
;     ...
;             PG8_LDA(At, 1, 1); PG8_STAGE(PG8_SB(1, 0), b3, voffB); PG8_STAGE(PG8_SB(1, 1), b3 + hstepB, voffB); PG8_STAGE(PG8_SA(1, 0), a3, voffA);
;             PG8_WAIT_V(8); PG8_WAIT_L(0); PG8_BAR; PG8_MMA(1, 0, At, B0); PG8_MMA(1, 1, At, B1); PG8_BAR; PG8_SCHED;
;     ...
;         if constexpr (ALIGN_EPI) { if (wr == 0) PG8_BAR; }
	s_add_u32 s36, s34, 0x8000
	s_addc_u32 s37, s35, 0
	s_add_i32 s52, s52, s45
	v_lshl_add_u64 v[192:193], s[36:37], 0, v[196:197]
	s_mov_b32 m0, s52
	ds_read_b128 v[162:165], v225 offset:49152
	ds_read_b128 v[166:169], v225 offset:50176
	ds_read_b128 v[170:173], v225 offset:51200
	ds_read_b128 v[174:177], v225 offset:52224
	ds_read_b128 v[178:181], v225 offset:53248
	ds_read_b128 v[182:185], v225 offset:54272
	ds_read_b128 v[206:209], v225 offset:55296
	ds_read_b128 v[210:213], v225 offset:56320
	global_load_lds_dwordx4 v[192:193], off
	s_add_i32 m0, s52, 0x2000
	s_add_u32 s34, s34, 0xc000
	v_lshl_add_u64 v[192:193], s[36:37], 0, v[200:201]
	s_addc_u32 s35, s35, 0
	s_add_i32 s36, s75, s45
	global_load_lds_dwordx4 v[192:193], off
	v_lshl_add_u64 v[192:193], s[34:35], 0, v[196:197]
	s_mov_b32 m0, s36
	v_lshl_add_u64 v[188:189], v[188:189], 0, s[62:63]
	global_load_lds_dwordx4 v[192:193], off
	v_lshl_add_u64 v[192:193], s[34:35], 0, v[200:201]
	s_add_i32 m0, s36, 0x2000
	s_nop 0
	global_load_lds_dwordx4 v[192:193], off
	s_mov_b32 m0, s86
	s_nop 0
	global_load_lds_dwordx4 v[188:189], off
	v_lshl_add_u64 v[188:189], v[190:191], 0, s[62:63]
	s_mov_b32 m0, s88
	s_nop 0
	global_load_lds_dwordx4 v[188:189], off
	s_waitcnt vmcnt(8)
	s_waitcnt lgkmcnt(0)
	v_mfma_f32_16x16x32_bf16 v[62:65], v[130:133], v[162:165], v[62:65]
	v_mfma_f32_16x16x32_bf16 v[58:61], v[138:141], v[162:165], v[58:61]
	s_barrier
	s_setprio 1
	s_waitcnt lgkmcnt(0)
	v_mfma_f32_16x16x32_bf16 v[46:49], v[130:133], v[170:173], v[46:49]
	v_mfma_f32_16x16x32_bf16 v[42:45], v[138:141], v[170:173], v[42:45]
	v_mfma_f32_16x16x32_bf16 v[30:33], v[130:133], v[178:181], v[30:33]
	v_mfma_f32_16x16x32_bf16 v[26:29], v[138:141], v[178:181], v[26:29]
	v_mfma_f32_16x16x32_bf16 v[14:17], v[130:133], v[206:209], v[14:17]
	v_mfma_f32_16x16x32_bf16 v[10:13], v[138:141], v[206:209], v[10:13]
	v_mfma_f32_16x16x32_bf16 v[62:65], v[134:137], v[166:169], v[62:65]
	v_mfma_f32_16x16x32_bf16 v[58:61], v[142:145], v[166:169], v[58:61]
	v_mfma_f32_16x16x32_bf16 v[46:49], v[134:137], v[174:177], v[46:49]
	v_mfma_f32_16x16x32_bf16 v[42:45], v[142:145], v[174:177], v[42:45]
	v_mfma_f32_16x16x32_bf16 v[30:33], v[134:137], v[182:185], v[30:33]
	v_mfma_f32_16x16x32_bf16 v[26:29], v[142:145], v[182:185], v[26:29]
	v_mfma_f32_16x16x32_bf16 v[14:17], v[134:137], v[210:213], v[14:17]
	v_mfma_f32_16x16x32_bf16 v[10:13], v[142:145], v[210:213], v[10:13]
	s_setprio 0
	s_setprio 1
	v_mfma_f32_16x16x32_bf16 v[54:57], v[146:149], v[162:165], v[54:57]
	v_mfma_f32_16x16x32_bf16 v[50:53], v[154:157], v[162:165], v[50:53]
	v_mfma_f32_16x16x32_bf16 v[38:41], v[146:149], v[170:173], v[38:41]
	v_mfma_f32_16x16x32_bf16 v[34:37], v[154:157], v[170:173], v[34:37]
	v_mfma_f32_16x16x32_bf16 v[22:25], v[146:149], v[178:181], v[22:25]
	v_mfma_f32_16x16x32_bf16 v[18:21], v[154:157], v[178:181], v[18:21]
	v_mfma_f32_16x16x32_bf16 v[6:9], v[146:149], v[206:209], v[6:9]
	v_mfma_f32_16x16x32_bf16 v[2:5], v[154:157], v[206:209], v[2:5]
	v_mfma_f32_16x16x32_bf16 v[54:57], v[150:153], v[166:169], v[54:57]
	v_mfma_f32_16x16x32_bf16 v[50:53], v[158:161], v[166:169], v[50:53]
	v_mfma_f32_16x16x32_bf16 v[38:41], v[150:153], v[174:177], v[38:41]
	v_mfma_f32_16x16x32_bf16 v[34:37], v[158:161], v[174:177], v[34:37]
	v_mfma_f32_16x16x32_bf16 v[22:25], v[150:153], v[182:185], v[22:25]
	v_mfma_f32_16x16x32_bf16 v[18:21], v[158:161], v[182:185], v[18:21]
	v_mfma_f32_16x16x32_bf16 v[6:9], v[150:153], v[210:213], v[6:9]
	v_mfma_f32_16x16x32_bf16 v[2:5], v[158:161], v[210:213], v[2:5]
	s_setprio 0
	s_barrier
	s_add_i32 s94, s94, 2
	s_add_u32 s92, s92, 0x10000
	s_addc_u32 s93, s93, 0
	s_add_u32 s0, s0, 0x100
	s_addc_u32 s1, s1, 0
	s_cmp_gt_u32 s94, 13
	s_cbranch_scc0 .LBB0_1140
	s_and_b64 vcc, exec, s[14:15]
	s_cbranch_vccz .LBB0_1143
	s_barrier

; #define PG8_STAGE(bufoff, gbase, voff) do { _Pragma("unroll") for (int _i = 0; _i < 2; ++_i) \
;         __builtin_amdgcn_global_load_lds((const unsigned*)((const char*)(gbase) + (voff)[_i]), (PG8_LAS unsigned*)(lds + (bufoff) + ldsw + _i * 8192), 16, 0, 0); } while (0)
; #define PG8_LDA(dst, b, h) do { _Pragma("unroll") for (int m = 0; m < 4; ++m) _Pragma("unroll") for (int k = 0; k < 2; ++k) dst[m][k] = *(const PG8_LAS bf16x8*)(lds + PG8_SA(b, h) + aoff + m * 2048 + k * 1024); } while (0)
; #define PG8_LDB(dst, b, h) do { _Pragma("unroll") for (int n = 0; n < 2; ++n) _Pragma("unroll") for (int k = 0; k < 2; ++k) dst[n][k] = *(const PG8_LAS bf16x8*)(lds + PG8_SB(b, h) + boff + n * 2048 + k * 1024); } while (0)
; #define PG8_MMA(ai, bj, At, Bt) do { __builtin_amdgcn_s_setprio(1); _Pragma("unroll") for (int m = 0; m < 4; ++m) _Pragma("unroll") for (int n = 0; n < 2; ++n) _Pragma("unroll") for (int k = 0; k < 2; ++k) \
;         acc[ai][bj][m][n] = __builtin_amdgcn_mfma_f32_16x16x32_bf16(Bt[n][k], At[m][k], acc[ai][bj][m][n], 0, 0, 0); __builtin_amdgcn_s_setprio(0); } while (0)
; template <class Epi, class Sched, bool ALIGN_EPI = false, bool SP2 = false, bool ABLK = false, bool BBLK = false>
; __device__ __forceinline__ void gemm_phase(PG8_LAS unsigned char* lds, const Gemm g, const Sched& S, const Epi& E) {
;     ...
;             const bool last = (t == nt - 2);
;             const char* a1 = cA + (size_t)(t + 1) * kstepA;
;             const char* a2 = last ? nA : cA + (size_t)(t + 2) * kstepA; const char* b2 = last ? nB : cB + (size_t)(t + 2) * kstepB;
;             const char* a3 = a2 + kstepA; const char* b3 = b2 + kstepB;
;             if (last && has_next) S.a_ready(nxt);
;             if constexpr (SP2) {
;             PG8_LDB(B0, 0, 0); PG8_LDB(B1, 0, 1); PG8_SCHED; PG8_LDA(At, 0, 0); PG8_STAGE(PG8_SA(1, 1), a1 + hstepA, voffA);
;             PG8_WAIT_V(8); PG8_WAIT_L(0); PG8_BAR; PG8_MMA(0, 0, At, B0); PG8_MMA(0, 1, At, B1); PG8_BAR; PG8_SCHED;
;             PG8_LDA(At, 0, 1); PG8_STAGE(PG8_SB(0, 0), b2, voffB); PG8_STAGE(PG8_SB(0, 1), b2 + hstepB, voffB); PG8_STAGE(PG8_SA(0, 0), a2, voffA);
;             PG8_WAIT_V(8); PG8_WAIT_L(0); PG8_BAR; PG8_MMA(1, 0, At, B0); PG8_MMA(1, 1, At, B1); PG8_BAR; PG8_SCHED;
;             PG8_LDB(B0, 1, 0); PG8_LDB(B1, 1, 1); PG8_SCHED; PG8_LDA(At, 1, 0); PG8_STAGE(PG8_SA(0, 1), a2 + hstepA, voffA);
.LBB0_1163:
	s_add_u32 s30, s0, 0xfffe0080
	s_addc_u32 s31, s1, -1
	s_add_i32 s52, 0, 0x10000
	s_cmp_eq_u32 s86, 4
	s_cselect_b32 s35, s21, s31
	s_cselect_b32 s34, s29, s30
	s_cselect_b32 s31, s19, s84
	s_cselect_b32 s30, s61, s83
	s_add_i32 s75, 0, 0x14000
	v_add_u32_e32 v142, s52, v223
	v_add_u32_e32 v158, s75, v223
	ds_read_b128 v[130:133], v142
	ds_read_b128 v[134:137], v142 offset:1024
	ds_read_b128 v[138:141], v142 offset:2048
	ds_read_b128 v[142:145], v142 offset:3072
	ds_read_b128 v[146:149], v158
	ds_read_b128 v[150:153], v158 offset:1024
	ds_read_b128 v[154:157], v158 offset:2048
	ds_read_b128 v[158:161], v158 offset:3072
	v_lshl_add_u64 v[188:189], s[0:1], 0, v[202:203]
	s_add_i32 m0, s27, 0xc000
	ds_read_b128 v[162:165], v225
	ds_read_b128 v[166:169], v225 offset:1024
	ds_read_b128 v[170:173], v225 offset:2048
	ds_read_b128 v[174:177], v225 offset:3072
	ds_read_b128 v[178:181], v225 offset:4096
	ds_read_b128 v[182:185], v225 offset:5120
	ds_read_b128 v[206:209], v225 offset:6144
	ds_read_b128 v[210:213], v225 offset:7168
	global_load_lds_dwordx4 v[188:189], off
	v_lshl_add_u64 v[188:189], s[0:1], 0, v[204:205]
	s_add_i32 m0, s27, 0xe000
	s_nop 0
	global_load_lds_dwordx4 v[188:189], off
	s_waitcnt vmcnt(8)
	s_waitcnt lgkmcnt(0)
	v_mfma_f32_16x16x32_bf16 v[126:129], v[130:133], v[162:165], v[126:129]
	v_mfma_f32_16x16x32_bf16 v[122:125], v[138:141], v[162:165], v[122:125]
	s_barrier
	s_setprio 1
	s_waitcnt lgkmcnt(0)
	v_mfma_f32_16x16x32_bf16 v[110:113], v[130:133], v[170:173], v[110:113]
	v_mfma_f32_16x16x32_bf16 v[106:109], v[138:141], v[170:173], v[106:109]
	v_mfma_f32_16x16x32_bf16 v[94:97], v[130:133], v[178:181], v[94:97]
	v_mfma_f32_16x16x32_bf16 v[90:93], v[138:141], v[178:181], v[90:93]
	v_mfma_f32_16x16x32_bf16 v[78:81], v[130:133], v[206:209], v[78:81]
	v_mfma_f32_16x16x32_bf16 v[74:77], v[138:141], v[206:209], v[74:77]
	v_mfma_f32_16x16x32_bf16 v[126:129], v[134:137], v[166:169], v[126:129]
	v_mfma_f32_16x16x32_bf16 v[122:125], v[142:145], v[166:169], v[122:125]
	v_mfma_f32_16x16x32_bf16 v[110:113], v[134:137], v[174:177], v[110:113]
	v_mfma_f32_16x16x32_bf16 v[106:109], v[142:145], v[174:177], v[106:109]
	v_mfma_f32_16x16x32_bf16 v[94:97], v[134:137], v[182:185], v[94:97]
	v_mfma_f32_16x16x32_bf16 v[90:93], v[142:145], v[182:185], v[90:93]
	v_mfma_f32_16x16x32_bf16 v[78:81], v[134:137], v[210:213], v[78:81]
	v_mfma_f32_16x16x32_bf16 v[74:77], v[142:145], v[210:213], v[74:77]
	s_setprio 0
	s_setprio 1
	v_mfma_f32_16x16x32_bf16 v[118:121], v[146:149], v[162:165], v[118:121]
	v_mfma_f32_16x16x32_bf16 v[114:117], v[154:157], v[162:165], v[114:117]
	v_mfma_f32_16x16x32_bf16 v[102:105], v[146:149], v[170:173], v[102:105]
	v_mfma_f32_16x16x32_bf16 v[98:101], v[154:157], v[170:173], v[98:101]
	v_mfma_f32_16x16x32_bf16 v[86:89], v[146:149], v[178:181], v[86:89]
	v_mfma_f32_16x16x32_bf16 v[82:85], v[154:157], v[178:181], v[82:85]
	v_mfma_f32_16x16x32_bf16 v[70:73], v[146:149], v[206:209], v[70:73]
	v_mfma_f32_16x16x32_bf16 v[66:69], v[154:157], v[206:209], v[66:69]
	v_mfma_f32_16x16x32_bf16 v[118:121], v[150:153], v[166:169], v[118:121]
	v_mfma_f32_16x16x32_bf16 v[114:117], v[158:161], v[166:169], v[114:117]
	v_mfma_f32_16x16x32_bf16 v[102:105], v[150:153], v[174:177], v[102:105]
	v_mfma_f32_16x16x32_bf16 v[98:101], v[158:161], v[174:177], v[98:101]
	v_mfma_f32_16x16x32_bf16 v[86:89], v[150:153], v[182:185], v[86:89]
	v_mfma_f32_16x16x32_bf16 v[82:85], v[158:161], v[182:185], v[82:85]
	v_mfma_f32_16x16x32_bf16 v[70:73], v[150:153], v[210:213], v[70:73]
	v_mfma_f32_16x16x32_bf16 v[66:69], v[158:161], v[210:213], v[66:69]
	s_setprio 0
	s_barrier
	s_add_i32 s52, s52, s45
	v_lshl_add_u64 v[188:189], s[30:31], 0, v[196:197]
	s_mov_b32 m0, s52
	ds_read_b128 v[162:165], v225 offset:16384
	ds_read_b128 v[166:169], v225 offset:17408
	ds_read_b128 v[170:173], v225 offset:18432
	ds_read_b128 v[174:177], v225 offset:19456
	ds_read_b128 v[178:181], v225 offset:20480
	ds_read_b128 v[182:185], v225 offset:21504
	ds_read_b128 v[206:209], v225 offset:22528
	ds_read_b128 v[210:213], v225 offset:23552
	global_load_lds_dwordx4 v[188:189], off
	s_add_i32 m0, s52, 0x2000
	s_add_u32 s88, s30, 0x4000
	v_lshl_add_u64 v[188:189], s[30:31], 0, v[200:201]
	s_addc_u32 s89, s31, 0
	s_add_i32 s52, s75, s45
	global_load_lds_dwordx4 v[188:189], off
	v_lshl_add_u64 v[188:189], s[88:89], 0, v[196:197]
	s_mov_b32 m0, s52
	v_lshl_add_u64 v[190:191], s[34:35], 0, v[198:199]
	global_load_lds_dwordx4 v[188:189], off
	v_lshl_add_u64 v[188:189], s[88:89], 0, v[200:201]
	s_add_i32 m0, s52, 0x2000
	s_nop 0
	global_load_lds_dwordx4 v[188:189], off
	v_lshl_add_u64 v[188:189], s[34:35], 0, v[186:187]
	s_mov_b32 m0, s27
	s_nop 0
	global_load_lds_dwordx4 v[188:189], off
	s_mov_b32 m0, s46
	s_nop 0
	global_load_lds_dwordx4 v[190:191], off
	s_waitcnt vmcnt(8)
	s_waitcnt lgkmcnt(0)
	v_mfma_f32_16x16x32_bf16 v[62:65], v[130:133], v[162:165], v[62:65]
	v_mfma_f32_16x16x32_bf16 v[58:61], v[138:141], v[162:165], v[58:61]
	s_barrier
; #define PG8_STAGE(bufoff, gbase, voff) do { _Pragma("unroll") for (int _i = 0; _i < 2; ++_i) \
;         __builtin_amdgcn_global_load_lds((const unsigned*)((const char*)(gbase) + (voff)[_i]), (PG8_LAS unsigned*)(lds + (bufoff) + ldsw + _i * 8192), 16, 0, 0); } while (0)
; #define PG8_LDA(dst, b, h) do { _Pragma("unroll") for (int m = 0; m < 4; ++m) _Pragma("unroll") for (int k = 0; k < 2; ++k) dst[m][k] = *(const PG8_LAS bf16x8*)(lds + PG8_SA(b, h) + aoff + m * 2048 + k * 1024); } while (0)
; #define PG8_LDB(dst, b, h) do { _Pragma("unroll") for (int n = 0; n < 2; ++n) _Pragma("unroll") for (int k = 0; k < 2; ++k) dst[n][k] = *(const PG8_LAS bf16x8*)(lds + PG8_SB(b, h) + boff + n * 2048 + k * 1024); } while (0)
; #define PG8_MMA(ai, bj, At, Bt) do { __builtin_amdgcn_s_setprio(1); _Pragma("unroll") for (int m = 0; m < 4; ++m) _Pragma("unroll") for (int n = 0; n < 2; ++n) _Pragma("unroll") for (int k = 0; k < 2; ++k) \
;         acc[ai][bj][m][n] = __builtin_amdgcn_mfma_f32_16x16x32_bf16(Bt[n][k], At[m][k], acc[ai][bj][m][n], 0, 0, 0); __builtin_amdgcn_s_setprio(0); } while (0)
; #define PG8_WAIT_V(n) asm volatile("s_waitcnt vmcnt(" #n ")" ::: "memory")
; #define PG8_WAIT_L(n) asm volatile("s_waitcnt lgkmcnt(" #n ")" ::: "memory")
; #define PG8_BAR __builtin_amdgcn_s_barrier()
; #define PG8_SCHED __builtin_amdgcn_sched_barrier(0)
; template <class Epi, class Sched, bool ALIGN_EPI = false, bool SP2 = false, bool ABLK = false, bool BBLK = false>
; __device__ __forceinline__ void gemm_phase(PG8_LAS unsigned char* lds, const Gemm g, const Sched& S, const Epi& E) {
;     ...
;             PG8_WAIT_V(8); PG8_WAIT_L(0); PG8_BAR; PG8_MMA(1, 0, At, B0); PG8_MMA(1, 1, At, B1); PG8_BAR; PG8_SCHED;
;             PG8_LDB(B0, 1, 0); PG8_LDB(B1, 1, 1); PG8_SCHED; PG8_LDA(At, 1, 0); PG8_STAGE(PG8_SA(0, 1), a2 + hstepA, voffA);
;             PG8_WAIT_V(8); PG8_WAIT_L(0); PG8_BAR; PG8_MMA(0, 0, At, B0); PG8_MMA(0, 1, At, B1); PG8_BAR; PG8_SCHED;
	s_setprio 1
	s_waitcnt lgkmcnt(0)
	v_mfma_f32_16x16x32_bf16 v[46:49], v[130:133], v[170:173], v[46:49]
	v_mfma_f32_16x16x32_bf16 v[42:45], v[138:141], v[170:173], v[42:45]
	v_mfma_f32_16x16x32_bf16 v[30:33], v[130:133], v[178:181], v[30:33]
	v_mfma_f32_16x16x32_bf16 v[26:29], v[138:141], v[178:181], v[26:29]
	v_mfma_f32_16x16x32_bf16 v[14:17], v[130:133], v[206:209], v[14:17]
	v_mfma_f32_16x16x32_bf16 v[10:13], v[138:141], v[206:209], v[10:13]
	v_mfma_f32_16x16x32_bf16 v[62:65], v[134:137], v[166:169], v[62:65]
	v_mfma_f32_16x16x32_bf16 v[58:61], v[142:145], v[166:169], v[58:61]
	v_mfma_f32_16x16x32_bf16 v[46:49], v[134:137], v[174:177], v[46:49]
	v_mfma_f32_16x16x32_bf16 v[42:45], v[142:145], v[174:177], v[42:45]
	v_mfma_f32_16x16x32_bf16 v[30:33], v[134:137], v[182:185], v[30:33]
	v_mfma_f32_16x16x32_bf16 v[26:29], v[142:145], v[182:185], v[26:29]
	v_mfma_f32_16x16x32_bf16 v[14:17], v[134:137], v[210:213], v[14:17]
	v_mfma_f32_16x16x32_bf16 v[10:13], v[142:145], v[210:213], v[10:13]
	s_setprio 0
	s_setprio 1
	v_mfma_f32_16x16x32_bf16 v[54:57], v[146:149], v[162:165], v[54:57]
	v_mfma_f32_16x16x32_bf16 v[50:53], v[154:157], v[162:165], v[50:53]
	v_mfma_f32_16x16x32_bf16 v[38:41], v[146:149], v[170:173], v[38:41]
	v_mfma_f32_16x16x32_bf16 v[34:37], v[154:157], v[170:173], v[34:37]
	v_mfma_f32_16x16x32_bf16 v[22:25], v[146:149], v[178:181], v[22:25]
	v_mfma_f32_16x16x32_bf16 v[18:21], v[154:157], v[178:181], v[18:21]
	v_mfma_f32_16x16x32_bf16 v[6:9], v[146:149], v[206:209], v[6:9]
	v_mfma_f32_16x16x32_bf16 v[2:5], v[154:157], v[206:209], v[2:5]
	v_mfma_f32_16x16x32_bf16 v[54:57], v[150:153], v[166:169], v[54:57]
	v_mfma_f32_16x16x32_bf16 v[50:53], v[158:161], v[166:169], v[50:53]
	v_mfma_f32_16x16x32_bf16 v[38:41], v[150:153], v[174:177], v[38:41]
	v_mfma_f32_16x16x32_bf16 v[34:37], v[158:161], v[174:177], v[34:37]
	v_mfma_f32_16x16x32_bf16 v[22:25], v[150:153], v[182:185], v[22:25]
	v_mfma_f32_16x16x32_bf16 v[18:21], v[158:161], v[182:185], v[18:21]
	v_mfma_f32_16x16x32_bf16 v[6:9], v[150:153], v[210:213], v[6:9]
	v_mfma_f32_16x16x32_bf16 v[2:5], v[158:161], v[210:213], v[2:5]
	s_setprio 0
	s_barrier
	s_add_i32 s52, 0, 0x18000
	s_add_i32 s75, 0, 0x1c000
	v_add_u32_e32 v142, s52, v223
	v_add_u32_e32 v158, s75, v223
	ds_read_b128 v[130:133], v142
	ds_read_b128 v[134:137], v142 offset:1024
	ds_read_b128 v[138:141], v142 offset:2048
	ds_read_b128 v[142:145], v142 offset:3072
	ds_read_b128 v[146:149], v158
	ds_read_b128 v[150:153], v158 offset:1024
	ds_read_b128 v[154:157], v158 offset:2048
	ds_read_b128 v[158:161], v158 offset:3072
	s_add_u32 s34, s34, 0x20000
	s_addc_u32 s35, s35, 0
	s_mov_b32 m0, s47
	v_lshl_add_u64 v[192:193], s[34:35], 0, v[186:187]
	ds_read_b128 v[162:165], v225 offset:32768
	ds_read_b128 v[166:169], v225 offset:33792
	ds_read_b128 v[170:173], v225 offset:34816
	ds_read_b128 v[174:177], v225 offset:35840
	ds_read_b128 v[178:181], v225 offset:36864
	ds_read_b128 v[182:185], v225 offset:37888
	ds_read_b128 v[206:209], v225 offset:38912
	ds_read_b128 v[210:213], v225 offset:39936
	global_load_lds_dwordx4 v[192:193], off
	v_lshl_add_u64 v[192:193], s[34:35], 0, v[198:199]
	s_mov_b32 m0, s65
	s_nop 0
	global_load_lds_dwordx4 v[192:193], off
	s_waitcnt vmcnt(8)
	s_waitcnt lgkmcnt(0)
	v_mfma_f32_16x16x32_bf16 v[126:129], v[130:133], v[162:165], v[126:129]
	v_mfma_f32_16x16x32_bf16 v[122:125], v[138:141], v[162:165], v[122:125]
	s_barrier
	s_setprio 1
	s_waitcnt lgkmcnt(0)
	v_mfma_f32_16x16x32_bf16 v[110:113], v[130:133], v[170:173], v[110:113]
	v_mfma_f32_16x16x32_bf16 v[106:109], v[138:141], v[170:173], v[106:109]
	v_mfma_f32_16x16x32_bf16 v[94:97], v[130:133], v[178:181], v[94:97]
	v_mfma_f32_16x16x32_bf16 v[90:93], v[138:141], v[178:181], v[90:93]
	v_mfma_f32_16x16x32_bf16 v[78:81], v[130:133], v[206:209], v[78:81]
	v_mfma_f32_16x16x32_bf16 v[74:77], v[138:141], v[206:209], v[74:77]
	v_mfma_f32_16x16x32_bf16 v[126:129], v[134:137], v[166:169], v[126:129]
	v_mfma_f32_16x16x32_bf16 v[122:125], v[142:145], v[166:169], v[122:125]
	v_mfma_f32_16x16x32_bf16 v[110:113], v[134:137], v[174:177], v[110:113]
	v_mfma_f32_16x16x32_bf16 v[106:109], v[142:145], v[174:177], v[106:109]
	v_mfma_f32_16x16x32_bf16 v[94:97], v[134:137], v[182:185], v[94:97]
	v_mfma_f32_16x16x32_bf16 v[90:93], v[142:145], v[182:185], v[90:93]
	v_mfma_f32_16x16x32_bf16 v[78:81], v[134:137], v[210:213], v[78:81]
	v_mfma_f32_16x16x32_bf16 v[74:77], v[142:145], v[210:213], v[74:77]
	s_setprio 0
	s_setprio 1
	v_mfma_f32_16x16x32_bf16 v[118:121], v[146:149], v[162:165], v[118:121]
	v_mfma_f32_16x16x32_bf16 v[114:117], v[154:157], v[162:165], v[114:117]
	v_mfma_f32_16x16x32_bf16 v[102:105], v[146:149], v[170:173], v[102:105]
	v_mfma_f32_16x16x32_bf16 v[98:101], v[154:157], v[170:173], v[98:101]
	v_mfma_f32_16x16x32_bf16 v[86:89], v[146:149], v[178:181], v[86:89]
	v_mfma_f32_16x16x32_bf16 v[82:85], v[154:157], v[178:181], v[82:85]
	v_mfma_f32_16x16x32_bf16 v[70:73], v[146:149], v[206:209], v[70:73]
	v_mfma_f32_16x16x32_bf16 v[66:69], v[154:157], v[206:209], v[66:69]
	v_mfma_f32_16x16x32_bf16 v[118:121], v[150:153], v[166:169], v[118:121]
	v_mfma_f32_16x16x32_bf16 v[114:117], v[158:161], v[166:169], v[114:117]
	v_mfma_f32_16x16x32_bf16 v[102:105], v[150:153], v[174:177], v[102:105]
	v_mfma_f32_16x16x32_bf16 v[98:101], v[158:161], v[174:177], v[98:101]
	v_mfma_f32_16x16x32_bf16 v[86:89], v[150:153], v[182:185], v[86:89]
	v_mfma_f32_16x16x32_bf16 v[82:85], v[158:161], v[182:185], v[82:85]
	v_mfma_f32_16x16x32_bf16 v[70:73], v[150:153], v[210:213], v[70:73]
	v_mfma_f32_16x16x32_bf16 v[66:69], v[158:161], v[210:213], v[66:69]
	s_setprio 0
	s_barrier
; #define PG8_STAGE(bufoff, gbase, voff) do { _Pragma("unroll") for (int _i = 0; _i < 2; ++_i) \
;         __builtin_amdgcn_global_load_lds((const unsigned*)((const char*)(gbase) + (voff)[_i]), (PG8_LAS unsigned*)(lds + (bufoff) + ldsw + _i * 8192), 16, 0, 0); } while (0)
; #define PG8_LDA(dst, b, h) do { _Pragma("unroll") for (int m = 0; m < 4; ++m) _Pragma("unroll") for (int k = 0; k < 2; ++k) dst[m][k] = *(const PG8_LAS bf16x8*)(lds + PG8_SA(b, h) + aoff + m * 2048 + k * 1024); } while (0)
; #define PG8_MMA(ai, bj, At, Bt) do { __builtin_amdgcn_s_setprio(1); _Pragma("unroll") for (int m = 0; m < 4; ++m) _Pragma("unroll") for (int n = 0; n < 2; ++n) _Pragma("unroll") for (int k = 0; k < 2; ++k) \
;         acc[ai][bj][m][n] = __builtin_amdgcn_mfma_f32_16x16x32_bf16(Bt[n][k], At[m][k], acc[ai][bj][m][n], 0, 0, 0); __builtin_amdgcn_s_setprio(0); } while (0)
; #define PG8_WAIT_V(n) asm volatile("s_waitcnt vmcnt(" #n ")" ::: "memory")
; #define PG8_WAIT_L(n) asm volatile("s_waitcnt lgkmcnt(" #n ")" ::: "memory")
; #define PG8_BAR __builtin_amdgcn_s_barrier()
; #define PG8_SCHED __builtin_amdgcn_sched_barrier(0)
; template <class Epi, class Sched, bool ALIGN_EPI = false, bool SP2 = false, bool ABLK = false, bool BBLK = false>
; __device__ __forceinline__ void gemm_phase(PG8_LAS unsigned char* lds, const Gemm g, const Sched& S, const Epi& E) {
;     ...
;             PG8_LDA(At, 1, 1); PG8_STAGE(PG8_SB(1, 0), b3, voffB); PG8_STAGE(PG8_SB(1, 1), b3 + hstepB, voffB); PG8_STAGE(PG8_SA(1, 0), a3, voffA);
;             PG8_WAIT_V(8); PG8_WAIT_L(0); PG8_BAR; PG8_MMA(1, 0, At, B0); PG8_MMA(1, 1, At, B1); PG8_BAR; PG8_SCHED;
;     ...
;         if constexpr (ALIGN_EPI) { if (wr == 0) PG8_BAR; }
	s_add_u32 s34, s30, 0x8000
	s_addc_u32 s35, s31, 0
	s_add_i32 s52, s52, s45
	v_lshl_add_u64 v[192:193], s[34:35], 0, v[196:197]
	s_mov_b32 m0, s52
	ds_read_b128 v[162:165], v225 offset:49152
	ds_read_b128 v[166:169], v225 offset:50176
	ds_read_b128 v[170:173], v225 offset:51200
	ds_read_b128 v[174:177], v225 offset:52224
	ds_read_b128 v[178:181], v225 offset:53248
	ds_read_b128 v[182:185], v225 offset:54272
	ds_read_b128 v[206:209], v225 offset:55296
	ds_read_b128 v[210:213], v225 offset:56320
	global_load_lds_dwordx4 v[192:193], off
	s_add_i32 m0, s52, 0x2000
	s_add_u32 s30, s30, 0xc000
	v_lshl_add_u64 v[192:193], s[34:35], 0, v[200:201]
	s_addc_u32 s31, s31, 0
	s_add_i32 s34, s75, s45
	global_load_lds_dwordx4 v[192:193], off
	v_lshl_add_u64 v[192:193], s[30:31], 0, v[196:197]
	s_mov_b32 m0, s34
	v_lshl_add_u64 v[188:189], v[188:189], 0, s[62:63]
	global_load_lds_dwordx4 v[192:193], off
	v_lshl_add_u64 v[192:193], s[30:31], 0, v[200:201]
	s_add_i32 m0, s34, 0x2000
	s_nop 0
	global_load_lds_dwordx4 v[192:193], off
	s_mov_b32 m0, s72
	s_nop 0
	global_load_lds_dwordx4 v[188:189], off
	v_lshl_add_u64 v[188:189], v[190:191], 0, s[62:63]
	s_mov_b32 m0, s73
	s_nop 0
	global_load_lds_dwordx4 v[188:189], off
	s_waitcnt vmcnt(8)
	s_waitcnt lgkmcnt(0)
	v_mfma_f32_16x16x32_bf16 v[62:65], v[130:133], v[162:165], v[62:65]
	v_mfma_f32_16x16x32_bf16 v[58:61], v[138:141], v[162:165], v[58:61]
	s_barrier
	s_setprio 1
	s_waitcnt lgkmcnt(0)
	v_mfma_f32_16x16x32_bf16 v[46:49], v[130:133], v[170:173], v[46:49]
	v_mfma_f32_16x16x32_bf16 v[42:45], v[138:141], v[170:173], v[42:45]
	v_mfma_f32_16x16x32_bf16 v[30:33], v[130:133], v[178:181], v[30:33]
	v_mfma_f32_16x16x32_bf16 v[26:29], v[138:141], v[178:181], v[26:29]
	v_mfma_f32_16x16x32_bf16 v[14:17], v[130:133], v[206:209], v[14:17]
	v_mfma_f32_16x16x32_bf16 v[10:13], v[138:141], v[206:209], v[10:13]
	v_mfma_f32_16x16x32_bf16 v[62:65], v[134:137], v[166:169], v[62:65]
	v_mfma_f32_16x16x32_bf16 v[58:61], v[142:145], v[166:169], v[58:61]
	v_mfma_f32_16x16x32_bf16 v[46:49], v[134:137], v[174:177], v[46:49]
	v_mfma_f32_16x16x32_bf16 v[42:45], v[142:145], v[174:177], v[42:45]
	v_mfma_f32_16x16x32_bf16 v[30:33], v[134:137], v[182:185], v[30:33]
	v_mfma_f32_16x16x32_bf16 v[26:29], v[142:145], v[182:185], v[26:29]
	v_mfma_f32_16x16x32_bf16 v[14:17], v[134:137], v[210:213], v[14:17]
	v_mfma_f32_16x16x32_bf16 v[10:13], v[142:145], v[210:213], v[10:13]
	s_setprio 0
	s_setprio 1
	v_mfma_f32_16x16x32_bf16 v[54:57], v[146:149], v[162:165], v[54:57]
	v_mfma_f32_16x16x32_bf16 v[50:53], v[154:157], v[162:165], v[50:53]
	v_mfma_f32_16x16x32_bf16 v[38:41], v[146:149], v[170:173], v[38:41]
	v_mfma_f32_16x16x32_bf16 v[34:37], v[154:157], v[170:173], v[34:37]
	v_mfma_f32_16x16x32_bf16 v[22:25], v[146:149], v[178:181], v[22:25]
	v_mfma_f32_16x16x32_bf16 v[18:21], v[154:157], v[178:181], v[18:21]
	v_mfma_f32_16x16x32_bf16 v[6:9], v[146:149], v[206:209], v[6:9]
	v_mfma_f32_16x16x32_bf16 v[2:5], v[154:157], v[206:209], v[2:5]
	v_mfma_f32_16x16x32_bf16 v[54:57], v[150:153], v[166:169], v[54:57]
	v_mfma_f32_16x16x32_bf16 v[50:53], v[158:161], v[166:169], v[50:53]
	v_mfma_f32_16x16x32_bf16 v[38:41], v[150:153], v[174:177], v[38:41]
	v_mfma_f32_16x16x32_bf16 v[34:37], v[158:161], v[174:177], v[34:37]
	v_mfma_f32_16x16x32_bf16 v[22:25], v[150:153], v[182:185], v[22:25]
	v_mfma_f32_16x16x32_bf16 v[18:21], v[158:161], v[182:185], v[18:21]
	v_mfma_f32_16x16x32_bf16 v[6:9], v[150:153], v[210:213], v[6:9]
	v_mfma_f32_16x16x32_bf16 v[2:5], v[158:161], v[210:213], v[2:5]
	s_setprio 0
	s_barrier
	s_add_i32 s86, s86, 2
	s_add_u32 s83, s83, 0x10000
	s_addc_u32 s84, s84, 0
	s_add_u32 s0, s0, 0x100
	s_addc_u32 s1, s1, 0
	s_cmp_gt_u32 s86, 5
	s_cbranch_scc0 .LBB0_1163
	s_and_b64 vcc, exec, s[12:13]
	s_cbranch_vccz .LBB0_1166
	s_barrier

; #define PG8_STAGE(bufoff, gbase, voff) do { _Pragma("unroll") for (int _i = 0; _i < 2; ++_i) \
;         __builtin_amdgcn_global_load_lds((const unsigned*)((const char*)(gbase) + (voff)[_i]), (PG8_LAS unsigned*)(lds + (bufoff) + ldsw + _i * 8192), 16, 0, 0); } while (0)
; #define PG8_LDA(dst, b, h) do { _Pragma("unroll") for (int m = 0; m < 4; ++m) _Pragma("unroll") for (int k = 0; k < 2; ++k) dst[m][k] = *(const PG8_LAS bf16x8*)(lds + PG8_SA(b, h) + aoff + m * 2048 + k * 1024); } while (0)
; #define PG8_LDB(dst, b, h) do { _Pragma("unroll") for (int n = 0; n < 2; ++n) _Pragma("unroll") for (int k = 0; k < 2; ++k) dst[n][k] = *(const PG8_LAS bf16x8*)(lds + PG8_SB(b, h) + boff + n * 2048 + k * 1024); } while (0)
; #define PG8_MMA(ai, bj, At, Bt) do { __builtin_amdgcn_s_setprio(1); _Pragma("unroll") for (int m = 0; m < 4; ++m) _Pragma("unroll") for (int n = 0; n < 2; ++n) _Pragma("unroll") for (int k = 0; k < 2; ++k) \
;         acc[ai][bj][m][n] = __builtin_amdgcn_mfma_f32_16x16x32_bf16(Bt[n][k], At[m][k], acc[ai][bj][m][n], 0, 0, 0); __builtin_amdgcn_s_setprio(0); } while (0)
; template <class Epi, class Sched, bool ALIGN_EPI = false, bool SP2 = false, bool ABLK = false, bool BBLK = false>
; __device__ __forceinline__ void gemm_phase(PG8_LAS unsigned char* lds, const Gemm g, const Sched& S, const Epi& E) {
;     ...
;             const bool last = (t == nt - 2);
;             const char* a1 = cA + (size_t)(t + 1) * kstepA;
;             const char* a2 = last ? nA : cA + (size_t)(t + 2) * kstepA; const char* b2 = last ? nB : cB + (size_t)(t + 2) * kstepB;
;             const char* a3 = a2 + kstepA; const char* b3 = b2 + kstepB;
;             if (last && has_next) S.a_ready(nxt);
;             if constexpr (SP2) {
;             PG8_LDB(B0, 0, 0); PG8_LDB(B1, 0, 1); PG8_SCHED; PG8_LDA(At, 0, 0); PG8_STAGE(PG8_SA(1, 1), a1 + hstepA, voffA);
;             PG8_WAIT_V(8); PG8_WAIT_L(0); PG8_BAR; PG8_MMA(0, 0, At, B0); PG8_MMA(0, 1, At, B1); PG8_BAR; PG8_SCHED;
;             PG8_LDA(At, 0, 1); PG8_STAGE(PG8_SB(0, 0), b2, voffB); PG8_STAGE(PG8_SB(0, 1), b2 + hstepB, voffB); PG8_STAGE(PG8_SA(0, 0), a2, voffA);
;             PG8_WAIT_V(8); PG8_WAIT_L(0); PG8_BAR; PG8_MMA(1, 0, At, B0); PG8_MMA(1, 1, At, B1); PG8_BAR; PG8_SCHED;
;             PG8_LDB(B0, 1, 0); PG8_LDB(B1, 1, 1); PG8_SCHED; PG8_LDA(At, 1, 0); PG8_STAGE(PG8_SA(0, 1), a2 + hstepA, voffA);
.LBB0_1239:
	s_add_u32 s8, s0, 0xfff80080
	s_addc_u32 s9, s1, -1
	s_add_i32 s52, 0, 0x10000
	s_cmp_eq_u32 s92, 28
	s_cselect_b32 s41, s27, s9
	s_cselect_b32 s40, s35, s8
	s_cselect_b32 s9, s25, s61
	s_cselect_b32 s8, s37, s60
	s_add_i32 s75, 0, 0x14000
	v_add_u32_e32 v142, s52, v206
	v_add_u32_e32 v158, s75, v206
	ds_read_b128 v[122:125], v142
	ds_read_b128 v[126:129], v142 offset:1024
	ds_read_b128 v[138:141], v142 offset:2048
	ds_read_b128 v[142:145], v142 offset:3072
	ds_read_b128 v[146:149], v158
	ds_read_b128 v[150:153], v158 offset:1024
	ds_read_b128 v[154:157], v158 offset:2048
	ds_read_b128 v[158:161], v158 offset:3072
	v_lshl_add_u64 v[188:189], s[0:1], 0, v[184:185]
	s_add_i32 m0, s47, 0xc000
	ds_read_b128 v[162:165], v207
	ds_read_b128 v[166:169], v207 offset:1024
	ds_read_b128 v[170:173], v207 offset:2048
	ds_read_b128 v[174:177], v207 offset:3072
	ds_read_b128 v[198:201], v207 offset:4096
	ds_read_b128 v[208:211], v207 offset:5120
	ds_read_b128 v[212:215], v207 offset:6144
	ds_read_b128 v[216:219], v207 offset:7168
	global_load_lds_dwordx4 v[188:189], off
	v_lshl_add_u64 v[188:189], s[0:1], 0, v[196:197]
	s_add_i32 m0, s47, 0xe000
	s_nop 0
	global_load_lds_dwordx4 v[188:189], off
	s_waitcnt vmcnt(8)
	s_waitcnt lgkmcnt(0)
	v_mfma_f32_16x16x32_bf16 v[118:121], v[122:125], v[162:165], v[118:121]
	v_mfma_f32_16x16x32_bf16 v[114:117], v[138:141], v[162:165], v[114:117]
	s_barrier
	s_setprio 1
	s_waitcnt lgkmcnt(0)
	v_mfma_f32_16x16x32_bf16 v[78:81], v[122:125], v[170:173], v[78:81]
	v_mfma_f32_16x16x32_bf16 v[134:137], v[138:141], v[170:173], v[134:137]
	v_mfma_f32_16x16x32_bf16 v[30:33], v[122:125], v[198:201], v[30:33]
	v_mfma_f32_16x16x32_bf16 v[22:25], v[138:141], v[198:201], v[22:25]
	v_mfma_f32_16x16x32_bf16 v[110:113], v[122:125], v[212:215], v[110:113]
	v_mfma_f32_16x16x32_bf16 v[14:17], v[138:141], v[212:215], v[14:17]
	v_mfma_f32_16x16x32_bf16 v[118:121], v[126:129], v[166:169], v[118:121]
	v_mfma_f32_16x16x32_bf16 v[114:117], v[142:145], v[166:169], v[114:117]
	v_mfma_f32_16x16x32_bf16 v[78:81], v[126:129], v[174:177], v[78:81]
	v_mfma_f32_16x16x32_bf16 v[134:137], v[142:145], v[174:177], v[134:137]
	v_mfma_f32_16x16x32_bf16 v[30:33], v[126:129], v[208:211], v[30:33]
	v_mfma_f32_16x16x32_bf16 v[22:25], v[142:145], v[208:211], v[22:25]
	v_mfma_f32_16x16x32_bf16 v[110:113], v[126:129], v[216:219], v[110:113]
	v_mfma_f32_16x16x32_bf16 v[14:17], v[142:145], v[216:219], v[14:17]
	s_setprio 0
	s_setprio 1
	v_mfma_f32_16x16x32_bf16 v[74:77], v[146:149], v[162:165], v[74:77]
	v_mfma_f32_16x16x32_bf16 v[54:57], v[154:157], v[162:165], v[54:57]
	v_mfma_f32_16x16x32_bf16 v[50:53], v[146:149], v[170:173], v[50:53]
	v_mfma_f32_16x16x32_bf16 v[26:29], v[154:157], v[170:173], v[26:29]
	v_mfma_f32_16x16x32_bf16 v[18:21], v[146:149], v[198:201], v[18:21]
	v_mfma_f32_16x16x32_bf16 v[10:13], v[154:157], v[198:201], v[10:13]
	v_mfma_f32_16x16x32_bf16 v[2:5], v[146:149], v[212:215], v[2:5]
	v_mfma_f32_16x16x32_bf16 v[6:9], v[154:157], v[212:215], v[6:9]
	v_mfma_f32_16x16x32_bf16 v[74:77], v[150:153], v[166:169], v[74:77]
	v_mfma_f32_16x16x32_bf16 v[54:57], v[158:161], v[166:169], v[54:57]
	v_mfma_f32_16x16x32_bf16 v[50:53], v[150:153], v[174:177], v[50:53]
	v_mfma_f32_16x16x32_bf16 v[26:29], v[158:161], v[174:177], v[26:29]
	v_mfma_f32_16x16x32_bf16 v[18:21], v[150:153], v[208:211], v[18:21]
	v_mfma_f32_16x16x32_bf16 v[10:13], v[158:161], v[208:211], v[10:13]
	v_mfma_f32_16x16x32_bf16 v[2:5], v[150:153], v[216:219], v[2:5]
	v_mfma_f32_16x16x32_bf16 v[6:9], v[158:161], v[216:219], v[6:9]
	s_setprio 0
	s_barrier
	s_add_i32 s52, s52, s46
	v_lshl_add_u64 v[188:189], s[8:9], 0, v[178:179]
	s_mov_b32 m0, s52
	ds_read_b128 v[162:165], v207 offset:16384
	ds_read_b128 v[166:169], v207 offset:17408
	ds_read_b128 v[170:173], v207 offset:18432
	ds_read_b128 v[174:177], v207 offset:19456
	ds_read_b128 v[198:201], v207 offset:20480
	ds_read_b128 v[208:211], v207 offset:21504
	ds_read_b128 v[212:215], v207 offset:22528
	ds_read_b128 v[216:219], v207 offset:23552
	global_load_lds_dwordx4 v[188:189], off
	s_add_i32 m0, s52, 0x2000
	s_add_u32 vcc_lo, s8, 0x4000
	v_lshl_add_u64 v[188:189], s[8:9], 0, v[182:183]
	s_addc_u32 vcc_hi, s9, 0
	s_add_i32 s52, s75, s46
	global_load_lds_dwordx4 v[188:189], off
	v_lshl_add_u64 v[188:189], vcc, 0, v[178:179]
	s_mov_b32 m0, s52
	v_lshl_add_u64 v[190:191], s[40:41], 0, v[180:181]
	global_load_lds_dwordx4 v[188:189], off
	v_lshl_add_u64 v[188:189], vcc, 0, v[182:183]
	s_add_i32 m0, s52, 0x2000
	s_nop 0
	global_load_lds_dwordx4 v[188:189], off
	v_lshl_add_u64 v[188:189], s[40:41], 0, v[186:187]
	s_mov_b32 m0, s47
	s_nop 0
	global_load_lds_dwordx4 v[188:189], off
	s_mov_b32 m0, s65
	s_nop 0
	global_load_lds_dwordx4 v[190:191], off
	s_waitcnt vmcnt(8)
	s_waitcnt lgkmcnt(0)
	v_mfma_f32_16x16x32_bf16 v[106:109], v[122:125], v[162:165], v[106:109]
	v_mfma_f32_16x16x32_bf16 v[102:105], v[138:141], v[162:165], v[102:105]
	s_barrier
; #define PG8_STAGE(bufoff, gbase, voff) do { _Pragma("unroll") for (int _i = 0; _i < 2; ++_i) \
;         __builtin_amdgcn_global_load_lds((const unsigned*)((const char*)(gbase) + (voff)[_i]), (PG8_LAS unsigned*)(lds + (bufoff) + ldsw + _i * 8192), 16, 0, 0); } while (0)
; #define PG8_LDA(dst, b, h) do { _Pragma("unroll") for (int m = 0; m < 4; ++m) _Pragma("unroll") for (int k = 0; k < 2; ++k) dst[m][k] = *(const PG8_LAS bf16x8*)(lds + PG8_SA(b, h) + aoff + m * 2048 + k * 1024); } while (0)
; #define PG8_LDB(dst, b, h) do { _Pragma("unroll") for (int n = 0; n < 2; ++n) _Pragma("unroll") for (int k = 0; k < 2; ++k) dst[n][k] = *(const PG8_LAS bf16x8*)(lds + PG8_SB(b, h) + boff + n * 2048 + k * 1024); } while (0)
; #define PG8_MMA(ai, bj, At, Bt) do { __builtin_amdgcn_s_setprio(1); _Pragma("unroll") for (int m = 0; m < 4; ++m) _Pragma("unroll") for (int n = 0; n < 2; ++n) _Pragma("unroll") for (int k = 0; k < 2; ++k) \
;         acc[ai][bj][m][n] = __builtin_amdgcn_mfma_f32_16x16x32_bf16(Bt[n][k], At[m][k], acc[ai][bj][m][n], 0, 0, 0); __builtin_amdgcn_s_setprio(0); } while (0)
; #define PG8_WAIT_V(n) asm volatile("s_waitcnt vmcnt(" #n ")" ::: "memory")
; #define PG8_WAIT_L(n) asm volatile("s_waitcnt lgkmcnt(" #n ")" ::: "memory")
; #define PG8_BAR __builtin_amdgcn_s_barrier()
; #define PG8_SCHED __builtin_amdgcn_sched_barrier(0)
; template <class Epi, class Sched, bool ALIGN_EPI = false, bool SP2 = false, bool ABLK = false, bool BBLK = false>
; __device__ __forceinline__ void gemm_phase(PG8_LAS unsigned char* lds, const Gemm g, const Sched& S, const Epi& E) {
;     ...
;             PG8_WAIT_V(8); PG8_WAIT_L(0); PG8_BAR; PG8_MMA(1, 0, At, B0); PG8_MMA(1, 1, At, B1); PG8_BAR; PG8_SCHED;
;             PG8_LDB(B0, 1, 0); PG8_LDB(B1, 1, 1); PG8_SCHED; PG8_LDA(At, 1, 0); PG8_STAGE(PG8_SA(0, 1), a2 + hstepA, voffA);
;             PG8_WAIT_V(8); PG8_WAIT_L(0); PG8_BAR; PG8_MMA(0, 0, At, B0); PG8_MMA(0, 1, At, B1); PG8_BAR; PG8_SCHED;
	s_setprio 1
	s_waitcnt lgkmcnt(0)
	v_mfma_f32_16x16x32_bf16 v[94:97], v[122:125], v[170:173], v[94:97]
	v_mfma_f32_16x16x32_bf16 v[86:89], v[138:141], v[170:173], v[86:89]
	v_mfma_f32_16x16x32_bf16 v[70:73], v[122:125], v[198:201], v[70:73]
	v_mfma_f32_16x16x32_bf16 v[62:65], v[138:141], v[198:201], v[62:65]
	v_mfma_f32_16x16x32_bf16 v[46:49], v[138:141], v[212:215], v[46:49]
	v_mfma_f32_16x16x32_bf16 v[106:109], v[126:129], v[166:169], v[106:109]
	v_mfma_f32_16x16x32_bf16 v[102:105], v[142:145], v[166:169], v[102:105]
	v_mfma_f32_16x16x32_bf16 v[94:97], v[126:129], v[174:177], v[94:97]
	v_mfma_f32_16x16x32_bf16 v[86:89], v[142:145], v[174:177], v[86:89]
	v_mfma_f32_16x16x32_bf16 v[70:73], v[126:129], v[208:211], v[70:73]
	v_mfma_f32_16x16x32_bf16 v[62:65], v[142:145], v[208:211], v[62:65]
	v_mfma_f32_16x16x32_bf16 v[122:125], v[122:125], v[212:215], v[130:133]
	v_mfma_f32_16x16x32_bf16 v[46:49], v[142:145], v[216:219], v[46:49]
	v_mfma_f32_16x16x32_bf16 v[122:125], v[126:129], v[216:219], v[122:125]
	s_setprio 0
	s_setprio 1
	v_mfma_f32_16x16x32_bf16 v[98:101], v[146:149], v[162:165], v[98:101]
	v_mfma_f32_16x16x32_bf16 v[90:93], v[154:157], v[162:165], v[90:93]
	v_mfma_f32_16x16x32_bf16 v[82:85], v[146:149], v[170:173], v[82:85]
	v_mfma_f32_16x16x32_bf16 v[66:69], v[154:157], v[170:173], v[66:69]
	v_mfma_f32_16x16x32_bf16 v[58:61], v[146:149], v[198:201], v[58:61]
	v_mfma_f32_16x16x32_bf16 v[42:45], v[154:157], v[198:201], v[42:45]
	v_mfma_f32_16x16x32_bf16 v[34:37], v[146:149], v[212:215], v[34:37]
	v_mfma_f32_16x16x32_bf16 v[38:41], v[154:157], v[212:215], v[38:41]
	v_mfma_f32_16x16x32_bf16 v[98:101], v[150:153], v[166:169], v[98:101]
	v_mfma_f32_16x16x32_bf16 v[90:93], v[158:161], v[166:169], v[90:93]
	v_mfma_f32_16x16x32_bf16 v[82:85], v[150:153], v[174:177], v[82:85]
	v_mfma_f32_16x16x32_bf16 v[66:69], v[158:161], v[174:177], v[66:69]
	v_mfma_f32_16x16x32_bf16 v[58:61], v[150:153], v[208:211], v[58:61]
	v_mfma_f32_16x16x32_bf16 v[42:45], v[158:161], v[208:211], v[42:45]
	v_mfma_f32_16x16x32_bf16 v[34:37], v[150:153], v[216:219], v[34:37]
	v_mfma_f32_16x16x32_bf16 v[38:41], v[158:161], v[216:219], v[38:41]
	s_setprio 0
	s_barrier
	s_add_i32 s52, 0, 0x18000
	s_add_i32 s75, 0, 0x1c000
	v_add_u32_e32 v142, s52, v206
	v_add_u32_e32 v158, s75, v206
	ds_read_b128 v[126:129], v142
	ds_read_b128 v[130:133], v142 offset:1024
	ds_read_b128 v[138:141], v142 offset:2048
	ds_read_b128 v[142:145], v142 offset:3072
	ds_read_b128 v[146:149], v158
	ds_read_b128 v[150:153], v158 offset:1024
	ds_read_b128 v[154:157], v158 offset:2048
	ds_read_b128 v[158:161], v158 offset:3072
	s_add_u32 s40, s40, 0x80000
	s_addc_u32 s41, s41, 0
	s_mov_b32 m0, s68
	v_lshl_add_u64 v[192:193], s[40:41], 0, v[186:187]
	ds_read_b128 v[162:165], v207 offset:32768
	ds_read_b128 v[166:169], v207 offset:33792
	ds_read_b128 v[170:173], v207 offset:34816
	ds_read_b128 v[174:177], v207 offset:35840
	ds_read_b128 v[198:201], v207 offset:36864
	ds_read_b128 v[208:211], v207 offset:37888
	ds_read_b128 v[212:215], v207 offset:38912
	ds_read_b128 v[216:219], v207 offset:39936
	global_load_lds_dwordx4 v[192:193], off
	v_lshl_add_u64 v[192:193], s[40:41], 0, v[180:181]
	s_mov_b32 m0, s72
	s_nop 0
	global_load_lds_dwordx4 v[192:193], off
	s_waitcnt vmcnt(8)
	s_waitcnt lgkmcnt(0)
	v_mfma_f32_16x16x32_bf16 v[118:121], v[126:129], v[162:165], v[118:121]
	v_mfma_f32_16x16x32_bf16 v[114:117], v[138:141], v[162:165], v[114:117]
	s_barrier
	s_setprio 1
	s_waitcnt lgkmcnt(0)
	v_mfma_f32_16x16x32_bf16 v[78:81], v[126:129], v[170:173], v[78:81]
	v_mfma_f32_16x16x32_bf16 v[134:137], v[138:141], v[170:173], v[134:137]
	v_mfma_f32_16x16x32_bf16 v[30:33], v[126:129], v[198:201], v[30:33]
	v_mfma_f32_16x16x32_bf16 v[22:25], v[138:141], v[198:201], v[22:25]
	v_mfma_f32_16x16x32_bf16 v[110:113], v[126:129], v[212:215], v[110:113]
	v_mfma_f32_16x16x32_bf16 v[14:17], v[138:141], v[212:215], v[14:17]
	v_mfma_f32_16x16x32_bf16 v[118:121], v[130:133], v[166:169], v[118:121]
	v_mfma_f32_16x16x32_bf16 v[114:117], v[142:145], v[166:169], v[114:117]
	v_mfma_f32_16x16x32_bf16 v[78:81], v[130:133], v[174:177], v[78:81]
	v_mfma_f32_16x16x32_bf16 v[134:137], v[142:145], v[174:177], v[134:137]
	v_mfma_f32_16x16x32_bf16 v[30:33], v[130:133], v[208:211], v[30:33]
	v_mfma_f32_16x16x32_bf16 v[22:25], v[142:145], v[208:211], v[22:25]
	v_mfma_f32_16x16x32_bf16 v[110:113], v[130:133], v[216:219], v[110:113]
	v_mfma_f32_16x16x32_bf16 v[14:17], v[142:145], v[216:219], v[14:17]
	s_setprio 0
	s_setprio 1
	v_mfma_f32_16x16x32_bf16 v[74:77], v[146:149], v[162:165], v[74:77]
	v_mfma_f32_16x16x32_bf16 v[54:57], v[154:157], v[162:165], v[54:57]
	v_mfma_f32_16x16x32_bf16 v[50:53], v[146:149], v[170:173], v[50:53]
	v_mfma_f32_16x16x32_bf16 v[26:29], v[154:157], v[170:173], v[26:29]
	v_mfma_f32_16x16x32_bf16 v[18:21], v[146:149], v[198:201], v[18:21]
	v_mfma_f32_16x16x32_bf16 v[10:13], v[154:157], v[198:201], v[10:13]
	v_mfma_f32_16x16x32_bf16 v[2:5], v[146:149], v[212:215], v[2:5]
	v_mfma_f32_16x16x32_bf16 v[6:9], v[154:157], v[212:215], v[6:9]
	v_mfma_f32_16x16x32_bf16 v[74:77], v[150:153], v[166:169], v[74:77]
	v_mfma_f32_16x16x32_bf16 v[54:57], v[158:161], v[166:169], v[54:57]
	v_mfma_f32_16x16x32_bf16 v[50:53], v[150:153], v[174:177], v[50:53]
	v_mfma_f32_16x16x32_bf16 v[26:29], v[158:161], v[174:177], v[26:29]
	v_mfma_f32_16x16x32_bf16 v[18:21], v[150:153], v[208:211], v[18:21]
	v_mfma_f32_16x16x32_bf16 v[10:13], v[158:161], v[208:211], v[10:13]
	v_mfma_f32_16x16x32_bf16 v[2:5], v[150:153], v[216:219], v[2:5]
	v_mfma_f32_16x16x32_bf16 v[6:9], v[158:161], v[216:219], v[6:9]
	s_setprio 0
	s_barrier
; #define PG8_STAGE(bufoff, gbase, voff) do { _Pragma("unroll") for (int _i = 0; _i < 2; ++_i) \
;         __builtin_amdgcn_global_load_lds((const unsigned*)((const char*)(gbase) + (voff)[_i]), (PG8_LAS unsigned*)(lds + (bufoff) + ldsw + _i * 8192), 16, 0, 0); } while (0)
; #define PG8_LDA(dst, b, h) do { _Pragma("unroll") for (int m = 0; m < 4; ++m) _Pragma("unroll") for (int k = 0; k < 2; ++k) dst[m][k] = *(const PG8_LAS bf16x8*)(lds + PG8_SA(b, h) + aoff + m * 2048 + k * 1024); } while (0)
; #define PG8_MMA(ai, bj, At, Bt) do { __builtin_amdgcn_s_setprio(1); _Pragma("unroll") for (int m = 0; m < 4; ++m) _Pragma("unroll") for (int n = 0; n < 2; ++n) _Pragma("unroll") for (int k = 0; k < 2; ++k) \
;         acc[ai][bj][m][n] = __builtin_amdgcn_mfma_f32_16x16x32_bf16(Bt[n][k], At[m][k], acc[ai][bj][m][n], 0, 0, 0); __builtin_amdgcn_s_setprio(0); } while (0)
; #define PG8_WAIT_V(n) asm volatile("s_waitcnt vmcnt(" #n ")" ::: "memory")
; #define PG8_WAIT_L(n) asm volatile("s_waitcnt lgkmcnt(" #n ")" ::: "memory")
; #define PG8_BAR __builtin_amdgcn_s_barrier()
; #define PG8_SCHED __builtin_amdgcn_sched_barrier(0)
; template <class Epi, class Sched, bool ALIGN_EPI = false, bool SP2 = false, bool ABLK = false, bool BBLK = false>
; __device__ __forceinline__ void gemm_phase(PG8_LAS unsigned char* lds, const Gemm g, const Sched& S, const Epi& E) {
;     ...
;             PG8_LDA(At, 1, 1); PG8_STAGE(PG8_SB(1, 0), b3, voffB); PG8_STAGE(PG8_SB(1, 1), b3 + hstepB, voffB); PG8_STAGE(PG8_SA(1, 0), a3, voffA);
;             PG8_WAIT_V(8); PG8_WAIT_L(0); PG8_BAR; PG8_MMA(1, 0, At, B0); PG8_MMA(1, 1, At, B1); PG8_BAR; PG8_SCHED;
;     ...
;         if constexpr (ALIGN_EPI) { if (wr == 0) PG8_BAR; }
	s_add_u32 s40, s8, 0x8000
	s_addc_u32 s41, s9, 0
	s_add_i32 s52, s52, s46
	v_lshl_add_u64 v[192:193], s[40:41], 0, v[178:179]
	s_mov_b32 m0, s52
	ds_read_b128 v[162:165], v207 offset:49152
	ds_read_b128 v[166:169], v207 offset:50176
	ds_read_b128 v[170:173], v207 offset:51200
	ds_read_b128 v[174:177], v207 offset:52224
	ds_read_b128 v[198:201], v207 offset:53248
	ds_read_b128 v[208:211], v207 offset:54272
	ds_read_b128 v[212:215], v207 offset:55296
	ds_read_b128 v[216:219], v207 offset:56320
	global_load_lds_dwordx4 v[192:193], off
	s_add_i32 m0, s52, 0x2000
	s_add_u32 s8, s8, 0xc000
	v_lshl_add_u64 v[192:193], s[40:41], 0, v[182:183]
	s_addc_u32 s9, s9, 0
	s_add_i32 s40, s75, s46
	global_load_lds_dwordx4 v[192:193], off
	v_lshl_add_u64 v[192:193], s[8:9], 0, v[178:179]
	s_mov_b32 m0, s40
	v_lshl_add_u64 v[188:189], v[188:189], 0, s[62:63]
	global_load_lds_dwordx4 v[192:193], off
	v_lshl_add_u64 v[192:193], s[8:9], 0, v[182:183]
	s_add_i32 m0, s40, 0x2000
	s_nop 0
	global_load_lds_dwordx4 v[192:193], off
	s_mov_b32 m0, s33
	s_nop 0
	global_load_lds_dwordx4 v[188:189], off
	v_lshl_add_u64 v[188:189], v[190:191], 0, s[62:63]
	s_mov_b32 m0, s91
	s_nop 0
	global_load_lds_dwordx4 v[188:189], off
	s_waitcnt vmcnt(8)
	s_waitcnt lgkmcnt(0)
	v_mfma_f32_16x16x32_bf16 v[106:109], v[126:129], v[162:165], v[106:109]
	v_mfma_f32_16x16x32_bf16 v[102:105], v[138:141], v[162:165], v[102:105]
	s_barrier
	s_setprio 1
	s_waitcnt lgkmcnt(0)
	v_mfma_f32_16x16x32_bf16 v[94:97], v[126:129], v[170:173], v[94:97]
	v_mfma_f32_16x16x32_bf16 v[86:89], v[138:141], v[170:173], v[86:89]
	v_mfma_f32_16x16x32_bf16 v[70:73], v[126:129], v[198:201], v[70:73]
	v_mfma_f32_16x16x32_bf16 v[62:65], v[138:141], v[198:201], v[62:65]
	v_mfma_f32_16x16x32_bf16 v[122:125], v[126:129], v[212:215], v[122:125]
	v_mfma_f32_16x16x32_bf16 v[46:49], v[138:141], v[212:215], v[46:49]
	v_mfma_f32_16x16x32_bf16 v[106:109], v[130:133], v[166:169], v[106:109]
	v_mfma_f32_16x16x32_bf16 v[102:105], v[142:145], v[166:169], v[102:105]
	v_mfma_f32_16x16x32_bf16 v[94:97], v[130:133], v[174:177], v[94:97]
	v_mfma_f32_16x16x32_bf16 v[86:89], v[142:145], v[174:177], v[86:89]
	v_mfma_f32_16x16x32_bf16 v[70:73], v[130:133], v[208:211], v[70:73]
	v_mfma_f32_16x16x32_bf16 v[62:65], v[142:145], v[208:211], v[62:65]
	v_mfma_f32_16x16x32_bf16 v[130:133], v[130:133], v[216:219], v[122:125]
	v_mfma_f32_16x16x32_bf16 v[46:49], v[142:145], v[216:219], v[46:49]
	s_setprio 0
	s_setprio 1
	v_mfma_f32_16x16x32_bf16 v[98:101], v[146:149], v[162:165], v[98:101]
	v_mfma_f32_16x16x32_bf16 v[90:93], v[154:157], v[162:165], v[90:93]
	v_mfma_f32_16x16x32_bf16 v[82:85], v[146:149], v[170:173], v[82:85]
	v_mfma_f32_16x16x32_bf16 v[66:69], v[154:157], v[170:173], v[66:69]
	v_mfma_f32_16x16x32_bf16 v[58:61], v[146:149], v[198:201], v[58:61]
	v_mfma_f32_16x16x32_bf16 v[42:45], v[154:157], v[198:201], v[42:45]
	v_mfma_f32_16x16x32_bf16 v[34:37], v[146:149], v[212:215], v[34:37]
	v_mfma_f32_16x16x32_bf16 v[38:41], v[154:157], v[212:215], v[38:41]
	v_mfma_f32_16x16x32_bf16 v[98:101], v[150:153], v[166:169], v[98:101]
	v_mfma_f32_16x16x32_bf16 v[90:93], v[158:161], v[166:169], v[90:93]
	v_mfma_f32_16x16x32_bf16 v[82:85], v[150:153], v[174:177], v[82:85]
	v_mfma_f32_16x16x32_bf16 v[66:69], v[158:161], v[174:177], v[66:69]
	v_mfma_f32_16x16x32_bf16 v[58:61], v[150:153], v[208:211], v[58:61]
	v_mfma_f32_16x16x32_bf16 v[42:45], v[158:161], v[208:211], v[42:45]
	v_mfma_f32_16x16x32_bf16 v[34:37], v[150:153], v[216:219], v[34:37]
	v_mfma_f32_16x16x32_bf16 v[38:41], v[158:161], v[216:219], v[38:41]
	s_setprio 0
	s_barrier
	s_add_i32 s92, s92, 2
	s_add_u32 s60, s60, 0x10000
	s_addc_u32 s61, s61, 0
	s_add_u32 s0, s0, 0x100
	s_addc_u32 s1, s1, 0
	s_cmp_gt_u32 s92, 29
	s_cbranch_scc0 .LBB0_1239
	s_and_b64 vcc, exec, s[18:19]
	s_cbranch_vccz .LBB0_1242
	s_barrier

; #define PG8_STAGE(bufoff, gbase, voff) do { _Pragma("unroll") for (int _i = 0; _i < 2; ++_i) \
;         __builtin_amdgcn_global_load_lds((const unsigned*)((const char*)(gbase) + (voff)[_i]), (PG8_LAS unsigned*)(lds + (bufoff) + ldsw + _i * 8192), 16, 0, 0); } while (0)
; #define PG8_LDA(dst, b, h) do { _Pragma("unroll") for (int m = 0; m < 4; ++m) _Pragma("unroll") for (int k = 0; k < 2; ++k) dst[m][k] = *(const PG8_LAS bf16x8*)(lds + PG8_SA(b, h) + aoff + m * 2048 + k * 1024); } while (0)
; #define PG8_LDB(dst, b, h) do { _Pragma("unroll") for (int n = 0; n < 2; ++n) _Pragma("unroll") for (int k = 0; k < 2; ++k) dst[n][k] = *(const PG8_LAS bf16x8*)(lds + PG8_SB(b, h) + boff + n * 2048 + k * 1024); } while (0)
; #define PG8_MMA(ai, bj, At, Bt) do { __builtin_amdgcn_s_setprio(1); _Pragma("unroll") for (int m = 0; m < 4; ++m) _Pragma("unroll") for (int n = 0; n < 2; ++n) _Pragma("unroll") for (int k = 0; k < 2; ++k) \
;         acc[ai][bj][m][n] = __builtin_amdgcn_mfma_f32_16x16x32_bf16(Bt[n][k], At[m][k], acc[ai][bj][m][n], 0, 0, 0); __builtin_amdgcn_s_setprio(0); } while (0)
; template <class Epi, class Sched, bool ALIGN_EPI = false, bool SP2 = false, bool ABLK = false, bool BBLK = false>
; __device__ __forceinline__ void gemm_phase(PG8_LAS unsigned char* lds, const Gemm g, const Sched& S, const Epi& E) {
;     ...
;             const bool last = (t == nt - 2);
;             const char* a1 = cA + (size_t)(t + 1) * kstepA;
;             const char* a2 = last ? nA : cA + (size_t)(t + 2) * kstepA; const char* b2 = last ? nB : cB + (size_t)(t + 2) * kstepB;
;             const char* a3 = a2 + kstepA; const char* b3 = b2 + kstepB;
;             if (last && has_next) S.a_ready(nxt);
;             if constexpr (SP2) {
;             PG8_LDB(B0, 0, 0); PG8_LDB(B1, 0, 1); PG8_SCHED; PG8_LDA(At, 0, 0); PG8_STAGE(PG8_SA(1, 1), a1 + hstepA, voffA);
;             PG8_WAIT_V(8); PG8_WAIT_L(0); PG8_BAR; PG8_MMA(0, 0, At, B0); PG8_MMA(0, 1, At, B1); PG8_BAR; PG8_SCHED;
;             PG8_LDA(At, 0, 1); PG8_STAGE(PG8_SB(0, 0), b2, voffB); PG8_STAGE(PG8_SB(0, 1), b2 + hstepB, voffB); PG8_STAGE(PG8_SA(0, 0), a2, voffA);
;             PG8_WAIT_V(8); PG8_WAIT_L(0); PG8_BAR; PG8_MMA(1, 0, At, B0); PG8_MMA(1, 1, At, B1); PG8_BAR; PG8_SCHED;
;             PG8_LDB(B0, 1, 0); PG8_LDB(B1, 1, 1); PG8_SCHED; PG8_LDA(At, 1, 0); PG8_STAGE(PG8_SA(0, 1), a2 + hstepA, voffA);
.LBB0_1340:
	s_add_u32 s28, s26, 0x4000
	s_addc_u32 s29, s27, 0
	s_cmp_eq_u32 s83, 28
	s_cselect_b32 s34, s19, s28
	s_cselect_b32 s35, s1, s29
	s_cselect_b32 s30, s72, s73
	s_cselect_b32 s31, s15, s81
	s_add_u32 s28, s34, 0x8000
	s_addc_u32 s29, s35, 0
	s_add_i32 s52, 0, 0x10000
	v_add_u32_e32 v142, s52, v145
	s_add_i32 s75, 0, 0x14000
	ds_read_b128 v[148:151], v142
	ds_read_b128 v[152:155], v142 offset:1024
	ds_read_b128 v[156:159], v142 offset:2048
	ds_read_b128 v[160:163], v142 offset:3072
	v_add_u32_e32 v142, s75, v145
	ds_read_b128 v[164:167], v142
	ds_read_b128 v[168:171], v142 offset:1024
	ds_read_b128 v[172:175], v142 offset:2048
	ds_read_b128 v[176:179], v142 offset:3072
	v_lshl_add_u64 v[142:143], s[26:27], 0, v[138:139]
	s_add_i32 m0, s25, 0xc000
	ds_read_b128 v[180:183], v146
	ds_read_b128 v[196:199], v146 offset:1024
	ds_read_b128 v[200:203], v146 offset:2048
	ds_read_b128 v[204:207], v146 offset:3072
	ds_read_b128 v[208:211], v146 offset:4096
	ds_read_b128 v[212:215], v146 offset:5120
	ds_read_b128 v[216:219], v146 offset:6144
	ds_read_b128 v[220:223], v146 offset:7168
	global_load_lds_dwordx4 v[142:143], off
	v_lshl_add_u64 v[142:143], s[26:27], 0, v[140:141]
	s_add_i32 m0, s25, 0xe000
	s_nop 0
	global_load_lds_dwordx4 v[142:143], off
	s_waitcnt vmcnt(8)
	s_waitcnt lgkmcnt(0)
	v_mfma_f32_16x16x32_bf16 v[126:129], v[148:151], v[180:183], v[126:129]
	v_mfma_f32_16x16x32_bf16 v[118:121], v[156:159], v[180:183], v[118:121]
	s_barrier
	s_setprio 1
	s_waitcnt lgkmcnt(0)
	v_mfma_f32_16x16x32_bf16 v[110:113], v[148:151], v[200:203], v[110:113]
	v_mfma_f32_16x16x32_bf16 v[102:105], v[156:159], v[200:203], v[102:105]
	v_mfma_f32_16x16x32_bf16 v[94:97], v[148:151], v[208:211], v[94:97]
	v_mfma_f32_16x16x32_bf16 v[86:89], v[156:159], v[208:211], v[86:89]
	v_mfma_f32_16x16x32_bf16 v[78:81], v[148:151], v[216:219], v[78:81]
	v_mfma_f32_16x16x32_bf16 v[70:73], v[156:159], v[216:219], v[70:73]
	v_mfma_f32_16x16x32_bf16 v[126:129], v[152:155], v[196:199], v[126:129]
	v_mfma_f32_16x16x32_bf16 v[118:121], v[160:163], v[196:199], v[118:121]
	v_mfma_f32_16x16x32_bf16 v[110:113], v[152:155], v[204:207], v[110:113]
	v_mfma_f32_16x16x32_bf16 v[102:105], v[160:163], v[204:207], v[102:105]
	v_mfma_f32_16x16x32_bf16 v[94:97], v[152:155], v[212:215], v[94:97]
	v_mfma_f32_16x16x32_bf16 v[86:89], v[160:163], v[212:215], v[86:89]
	v_mfma_f32_16x16x32_bf16 v[78:81], v[152:155], v[220:223], v[78:81]
	v_mfma_f32_16x16x32_bf16 v[70:73], v[160:163], v[220:223], v[70:73]
	s_setprio 0
	s_setprio 1
	v_mfma_f32_16x16x32_bf16 v[122:125], v[164:167], v[180:183], v[122:125]
	v_mfma_f32_16x16x32_bf16 v[114:117], v[172:175], v[180:183], v[114:117]
	v_mfma_f32_16x16x32_bf16 v[106:109], v[164:167], v[200:203], v[106:109]
	v_mfma_f32_16x16x32_bf16 v[98:101], v[172:175], v[200:203], v[98:101]
	v_mfma_f32_16x16x32_bf16 v[90:93], v[164:167], v[208:211], v[90:93]
	v_mfma_f32_16x16x32_bf16 v[82:85], v[172:175], v[208:211], v[82:85]
	v_mfma_f32_16x16x32_bf16 v[74:77], v[164:167], v[216:219], v[74:77]
	v_mfma_f32_16x16x32_bf16 v[66:69], v[172:175], v[216:219], v[66:69]
	v_mfma_f32_16x16x32_bf16 v[122:125], v[168:171], v[196:199], v[122:125]
	v_mfma_f32_16x16x32_bf16 v[114:117], v[176:179], v[196:199], v[114:117]
	v_mfma_f32_16x16x32_bf16 v[106:109], v[168:171], v[204:207], v[106:109]
	v_mfma_f32_16x16x32_bf16 v[98:101], v[176:179], v[204:207], v[98:101]
	v_mfma_f32_16x16x32_bf16 v[90:93], v[168:171], v[212:215], v[90:93]
	v_mfma_f32_16x16x32_bf16 v[82:85], v[176:179], v[212:215], v[82:85]
	v_mfma_f32_16x16x32_bf16 v[74:77], v[168:171], v[220:223], v[74:77]
	v_mfma_f32_16x16x32_bf16 v[66:69], v[176:179], v[220:223], v[66:69]
	s_setprio 0
	s_barrier
	s_add_i32 s52, s52, s44
	v_lshl_add_u64 v[142:143], s[30:31], 0, v[134:135]
	s_mov_b32 m0, s52
	ds_read_b128 v[180:183], v146 offset:16384
	ds_read_b128 v[196:199], v146 offset:17408
	ds_read_b128 v[200:203], v146 offset:18432
	ds_read_b128 v[204:207], v146 offset:19456
	ds_read_b128 v[208:211], v146 offset:20480
	ds_read_b128 v[212:215], v146 offset:21504
	ds_read_b128 v[216:219], v146 offset:22528
	ds_read_b128 v[220:223], v146 offset:23552
	global_load_lds_dwordx4 v[142:143], off
	s_add_i32 m0, s52, 0x2000
	s_add_u32 s88, s30, 0x4000
	v_lshl_add_u64 v[142:143], s[30:31], 0, v[130:131]
	s_addc_u32 s89, s31, 0
	s_add_i32 s52, s75, s44
	global_load_lds_dwordx4 v[142:143], off
	v_lshl_add_u64 v[142:143], s[88:89], 0, v[134:135]
	s_mov_b32 m0, s52
	s_nop 0
	global_load_lds_dwordx4 v[142:143], off
	v_lshl_add_u64 v[142:143], s[88:89], 0, v[130:131]
	s_add_i32 m0, s52, 0x2000
	s_nop 0
	global_load_lds_dwordx4 v[142:143], off
	v_lshl_add_u64 v[142:143], s[34:35], 0, v[136:137]
	s_mov_b32 m0, s25
	s_nop 0
	global_load_lds_dwordx4 v[142:143], off
	v_lshl_add_u64 v[142:143], s[34:35], 0, v[132:133]
	s_mov_b32 m0, s46
	s_nop 0
	global_load_lds_dwordx4 v[142:143], off
	s_waitcnt vmcnt(8)
	s_waitcnt lgkmcnt(0)
	v_mfma_f32_16x16x32_bf16 v[62:65], v[148:151], v[180:183], v[62:65]
	v_mfma_f32_16x16x32_bf16 v[54:57], v[156:159], v[180:183], v[54:57]
	s_barrier
; #define PG8_STAGE(bufoff, gbase, voff) do { _Pragma("unroll") for (int _i = 0; _i < 2; ++_i) \
;         __builtin_amdgcn_global_load_lds((const unsigned*)((const char*)(gbase) + (voff)[_i]), (PG8_LAS unsigned*)(lds + (bufoff) + ldsw + _i * 8192), 16, 0, 0); } while (0)
; #define PG8_LDA(dst, b, h) do { _Pragma("unroll") for (int m = 0; m < 4; ++m) _Pragma("unroll") for (int k = 0; k < 2; ++k) dst[m][k] = *(const PG8_LAS bf16x8*)(lds + PG8_SA(b, h) + aoff + m * 2048 + k * 1024); } while (0)
; #define PG8_LDB(dst, b, h) do { _Pragma("unroll") for (int n = 0; n < 2; ++n) _Pragma("unroll") for (int k = 0; k < 2; ++k) dst[n][k] = *(const PG8_LAS bf16x8*)(lds + PG8_SB(b, h) + boff + n * 2048 + k * 1024); } while (0)
; #define PG8_MMA(ai, bj, At, Bt) do { __builtin_amdgcn_s_setprio(1); _Pragma("unroll") for (int m = 0; m < 4; ++m) _Pragma("unroll") for (int n = 0; n < 2; ++n) _Pragma("unroll") for (int k = 0; k < 2; ++k) \
;         acc[ai][bj][m][n] = __builtin_amdgcn_mfma_f32_16x16x32_bf16(Bt[n][k], At[m][k], acc[ai][bj][m][n], 0, 0, 0); __builtin_amdgcn_s_setprio(0); } while (0)
; #define PG8_WAIT_V(n) asm volatile("s_waitcnt vmcnt(" #n ")" ::: "memory")
; #define PG8_WAIT_L(n) asm volatile("s_waitcnt lgkmcnt(" #n ")" ::: "memory")
; #define PG8_BAR __builtin_amdgcn_s_barrier()
; #define PG8_SCHED __builtin_amdgcn_sched_barrier(0)
; template <class Epi, class Sched, bool ALIGN_EPI = false, bool SP2 = false, bool ABLK = false, bool BBLK = false>
; __device__ __forceinline__ void gemm_phase(PG8_LAS unsigned char* lds, const Gemm g, const Sched& S, const Epi& E) {
;     ...
;             PG8_WAIT_V(8); PG8_WAIT_L(0); PG8_BAR; PG8_MMA(1, 0, At, B0); PG8_MMA(1, 1, At, B1); PG8_BAR; PG8_SCHED;
;             PG8_LDB(B0, 1, 0); PG8_LDB(B1, 1, 1); PG8_SCHED; PG8_LDA(At, 1, 0); PG8_STAGE(PG8_SA(0, 1), a2 + hstepA, voffA);
;             PG8_WAIT_V(8); PG8_WAIT_L(0); PG8_BAR; PG8_MMA(0, 0, At, B0); PG8_MMA(0, 1, At, B1); PG8_BAR; PG8_SCHED;
	s_setprio 1
	s_waitcnt lgkmcnt(0)
	v_mfma_f32_16x16x32_bf16 v[46:49], v[148:151], v[200:203], v[46:49]
	v_mfma_f32_16x16x32_bf16 v[38:41], v[156:159], v[200:203], v[38:41]
	v_mfma_f32_16x16x32_bf16 v[30:33], v[148:151], v[208:211], v[30:33]
	v_mfma_f32_16x16x32_bf16 v[22:25], v[156:159], v[208:211], v[22:25]
	v_mfma_f32_16x16x32_bf16 v[14:17], v[148:151], v[216:219], v[14:17]
	v_mfma_f32_16x16x32_bf16 v[6:9], v[156:159], v[216:219], v[6:9]
	v_mfma_f32_16x16x32_bf16 v[62:65], v[152:155], v[196:199], v[62:65]
	v_mfma_f32_16x16x32_bf16 v[54:57], v[160:163], v[196:199], v[54:57]
	v_mfma_f32_16x16x32_bf16 v[46:49], v[152:155], v[204:207], v[46:49]
	v_mfma_f32_16x16x32_bf16 v[38:41], v[160:163], v[204:207], v[38:41]
	v_mfma_f32_16x16x32_bf16 v[30:33], v[152:155], v[212:215], v[30:33]
	v_mfma_f32_16x16x32_bf16 v[22:25], v[160:163], v[212:215], v[22:25]
	v_mfma_f32_16x16x32_bf16 v[14:17], v[152:155], v[220:223], v[14:17]
	v_mfma_f32_16x16x32_bf16 v[6:9], v[160:163], v[220:223], v[6:9]
	s_setprio 0
	s_setprio 1
	v_mfma_f32_16x16x32_bf16 v[58:61], v[164:167], v[180:183], v[58:61]
	v_mfma_f32_16x16x32_bf16 v[50:53], v[172:175], v[180:183], v[50:53]
	v_mfma_f32_16x16x32_bf16 v[42:45], v[164:167], v[200:203], v[42:45]
	v_mfma_f32_16x16x32_bf16 v[34:37], v[172:175], v[200:203], v[34:37]
	v_mfma_f32_16x16x32_bf16 v[26:29], v[164:167], v[208:211], v[26:29]
	v_mfma_f32_16x16x32_bf16 v[18:21], v[172:175], v[208:211], v[18:21]
	v_mfma_f32_16x16x32_bf16 v[10:13], v[164:167], v[216:219], v[10:13]
	v_mfma_f32_16x16x32_bf16 v[2:5], v[172:175], v[216:219], v[2:5]
	v_mfma_f32_16x16x32_bf16 v[58:61], v[168:171], v[196:199], v[58:61]
	v_mfma_f32_16x16x32_bf16 v[50:53], v[176:179], v[196:199], v[50:53]
	v_mfma_f32_16x16x32_bf16 v[42:45], v[168:171], v[204:207], v[42:45]
	v_mfma_f32_16x16x32_bf16 v[34:37], v[176:179], v[204:207], v[34:37]
	v_mfma_f32_16x16x32_bf16 v[26:29], v[168:171], v[212:215], v[26:29]
	v_mfma_f32_16x16x32_bf16 v[18:21], v[176:179], v[212:215], v[18:21]
	v_mfma_f32_16x16x32_bf16 v[10:13], v[168:171], v[220:223], v[10:13]
	v_mfma_f32_16x16x32_bf16 v[2:5], v[176:179], v[220:223], v[2:5]
	s_setprio 0
	s_barrier
	s_add_i32 s52, 0, 0x18000
	v_add_u32_e32 v142, s52, v145
	s_add_i32 s75, 0, 0x1c000
	ds_read_b128 v[148:151], v142
	ds_read_b128 v[152:155], v142 offset:1024
	ds_read_b128 v[156:159], v142 offset:2048
	ds_read_b128 v[160:163], v142 offset:3072
	v_add_u32_e32 v142, s75, v145
	ds_read_b128 v[164:167], v142
	ds_read_b128 v[168:171], v142 offset:1024
	ds_read_b128 v[172:175], v142 offset:2048
	ds_read_b128 v[176:179], v142 offset:3072
	s_add_u32 s34, s34, 0x4000
	s_addc_u32 s35, s35, 0
	s_mov_b32 m0, s47
	v_lshl_add_u64 v[142:143], s[34:35], 0, v[136:137]
	ds_read_b128 v[180:183], v146 offset:32768
	ds_read_b128 v[196:199], v146 offset:33792
	ds_read_b128 v[200:203], v146 offset:34816
	ds_read_b128 v[204:207], v146 offset:35840
	ds_read_b128 v[208:211], v146 offset:36864
	ds_read_b128 v[212:215], v146 offset:37888
	ds_read_b128 v[216:219], v146 offset:38912
	ds_read_b128 v[220:223], v146 offset:39936
	global_load_lds_dwordx4 v[142:143], off
	v_lshl_add_u64 v[142:143], s[34:35], 0, v[132:133]
	s_mov_b32 m0, s50
	s_nop 0
	global_load_lds_dwordx4 v[142:143], off
	s_waitcnt vmcnt(8)
	s_waitcnt lgkmcnt(0)
	v_mfma_f32_16x16x32_bf16 v[126:129], v[148:151], v[180:183], v[126:129]
	v_mfma_f32_16x16x32_bf16 v[118:121], v[156:159], v[180:183], v[118:121]
	s_barrier
	s_setprio 1
	s_waitcnt lgkmcnt(0)
	v_mfma_f32_16x16x32_bf16 v[110:113], v[148:151], v[200:203], v[110:113]
	v_mfma_f32_16x16x32_bf16 v[102:105], v[156:159], v[200:203], v[102:105]
	v_mfma_f32_16x16x32_bf16 v[94:97], v[148:151], v[208:211], v[94:97]
	v_mfma_f32_16x16x32_bf16 v[86:89], v[156:159], v[208:211], v[86:89]
	v_mfma_f32_16x16x32_bf16 v[78:81], v[148:151], v[216:219], v[78:81]
	v_mfma_f32_16x16x32_bf16 v[70:73], v[156:159], v[216:219], v[70:73]
	v_mfma_f32_16x16x32_bf16 v[126:129], v[152:155], v[196:199], v[126:129]
	v_mfma_f32_16x16x32_bf16 v[118:121], v[160:163], v[196:199], v[118:121]
	v_mfma_f32_16x16x32_bf16 v[110:113], v[152:155], v[204:207], v[110:113]
	v_mfma_f32_16x16x32_bf16 v[102:105], v[160:163], v[204:207], v[102:105]
	v_mfma_f32_16x16x32_bf16 v[94:97], v[152:155], v[212:215], v[94:97]
	v_mfma_f32_16x16x32_bf16 v[86:89], v[160:163], v[212:215], v[86:89]
	v_mfma_f32_16x16x32_bf16 v[78:81], v[152:155], v[220:223], v[78:81]
	v_mfma_f32_16x16x32_bf16 v[70:73], v[160:163], v[220:223], v[70:73]
	s_setprio 0
	s_setprio 1
	v_mfma_f32_16x16x32_bf16 v[122:125], v[164:167], v[180:183], v[122:125]
	v_mfma_f32_16x16x32_bf16 v[114:117], v[172:175], v[180:183], v[114:117]
	v_mfma_f32_16x16x32_bf16 v[106:109], v[164:167], v[200:203], v[106:109]
	v_mfma_f32_16x16x32_bf16 v[98:101], v[172:175], v[200:203], v[98:101]
	v_mfma_f32_16x16x32_bf16 v[90:93], v[164:167], v[208:211], v[90:93]
	v_mfma_f32_16x16x32_bf16 v[82:85], v[172:175], v[208:211], v[82:85]
	v_mfma_f32_16x16x32_bf16 v[74:77], v[164:167], v[216:219], v[74:77]
	v_mfma_f32_16x16x32_bf16 v[66:69], v[172:175], v[216:219], v[66:69]
	v_mfma_f32_16x16x32_bf16 v[122:125], v[168:171], v[196:199], v[122:125]
	v_mfma_f32_16x16x32_bf16 v[114:117], v[176:179], v[196:199], v[114:117]
	v_mfma_f32_16x16x32_bf16 v[106:109], v[168:171], v[204:207], v[106:109]
	v_mfma_f32_16x16x32_bf16 v[98:101], v[176:179], v[204:207], v[98:101]
	v_mfma_f32_16x16x32_bf16 v[90:93], v[168:171], v[212:215], v[90:93]
	v_mfma_f32_16x16x32_bf16 v[82:85], v[176:179], v[212:215], v[82:85]
	v_mfma_f32_16x16x32_bf16 v[74:77], v[168:171], v[220:223], v[74:77]
	v_mfma_f32_16x16x32_bf16 v[66:69], v[176:179], v[220:223], v[66:69]
	s_setprio 0
	s_barrier
; #define PG8_STAGE(bufoff, gbase, voff) do { _Pragma("unroll") for (int _i = 0; _i < 2; ++_i) \
;         __builtin_amdgcn_global_load_lds((const unsigned*)((const char*)(gbase) + (voff)[_i]), (PG8_LAS unsigned*)(lds + (bufoff) + ldsw + _i * 8192), 16, 0, 0); } while (0)
; #define PG8_LDA(dst, b, h) do { _Pragma("unroll") for (int m = 0; m < 4; ++m) _Pragma("unroll") for (int k = 0; k < 2; ++k) dst[m][k] = *(const PG8_LAS bf16x8*)(lds + PG8_SA(b, h) + aoff + m * 2048 + k * 1024); } while (0)
; #define PG8_MMA(ai, bj, At, Bt) do { __builtin_amdgcn_s_setprio(1); _Pragma("unroll") for (int m = 0; m < 4; ++m) _Pragma("unroll") for (int n = 0; n < 2; ++n) _Pragma("unroll") for (int k = 0; k < 2; ++k) \
;         acc[ai][bj][m][n] = __builtin_amdgcn_mfma_f32_16x16x32_bf16(Bt[n][k], At[m][k], acc[ai][bj][m][n], 0, 0, 0); __builtin_amdgcn_s_setprio(0); } while (0)
; #define PG8_WAIT_V(n) asm volatile("s_waitcnt vmcnt(" #n ")" ::: "memory")
; #define PG8_WAIT_L(n) asm volatile("s_waitcnt lgkmcnt(" #n ")" ::: "memory")
; #define PG8_BAR __builtin_amdgcn_s_barrier()
; #define PG8_SCHED __builtin_amdgcn_sched_barrier(0)
; template <class Epi, class Sched, bool ALIGN_EPI = false, bool SP2 = false, bool ABLK = false, bool BBLK = false>
; __device__ __forceinline__ void gemm_phase(PG8_LAS unsigned char* lds, const Gemm g, const Sched& S, const Epi& E) {
;     ...
;             PG8_LDA(At, 1, 1); PG8_STAGE(PG8_SB(1, 0), b3, voffB); PG8_STAGE(PG8_SB(1, 1), b3 + hstepB, voffB); PG8_STAGE(PG8_SA(1, 0), a3, voffA);
;             PG8_WAIT_V(8); PG8_WAIT_L(0); PG8_BAR; PG8_MMA(1, 0, At, B0); PG8_MMA(1, 1, At, B1); PG8_BAR; PG8_SCHED;
;     ...
;         if constexpr (ALIGN_EPI) { if (wr == 0) PG8_BAR; }
	s_add_u32 s34, s30, 0x8000
	s_addc_u32 s35, s31, 0
	s_add_i32 s52, s52, s44
	v_lshl_add_u64 v[142:143], s[34:35], 0, v[134:135]
	s_mov_b32 m0, s52
	ds_read_b128 v[180:183], v146 offset:49152
	ds_read_b128 v[196:199], v146 offset:50176
	ds_read_b128 v[200:203], v146 offset:51200
	ds_read_b128 v[204:207], v146 offset:52224
	ds_read_b128 v[208:211], v146 offset:53248
	ds_read_b128 v[212:215], v146 offset:54272
	ds_read_b128 v[216:219], v146 offset:55296
	ds_read_b128 v[220:223], v146 offset:56320
	global_load_lds_dwordx4 v[142:143], off
	s_add_i32 m0, s52, 0x2000
	s_add_u32 s30, s30, 0xc000
	v_lshl_add_u64 v[142:143], s[34:35], 0, v[130:131]
	s_addc_u32 s31, s31, 0
	s_add_i32 s34, s75, s44
	global_load_lds_dwordx4 v[142:143], off
	v_lshl_add_u64 v[142:143], s[30:31], 0, v[134:135]
	s_mov_b32 m0, s34
	s_nop 0
	global_load_lds_dwordx4 v[142:143], off
	v_lshl_add_u64 v[142:143], s[30:31], 0, v[130:131]
	s_add_i32 m0, s34, 0x2000
	s_nop 0
	global_load_lds_dwordx4 v[142:143], off
	v_lshl_add_u64 v[142:143], s[28:29], 0, v[136:137]
	s_mov_b32 m0, s56
	s_nop 0
	global_load_lds_dwordx4 v[142:143], off
	v_lshl_add_u64 v[142:143], s[28:29], 0, v[132:133]
	s_mov_b32 m0, s60
	s_nop 0
	global_load_lds_dwordx4 v[142:143], off
	s_waitcnt vmcnt(8)
	s_waitcnt lgkmcnt(0)
	v_mfma_f32_16x16x32_bf16 v[62:65], v[148:151], v[180:183], v[62:65]
	v_mfma_f32_16x16x32_bf16 v[54:57], v[156:159], v[180:183], v[54:57]
	s_barrier
	s_setprio 1
	s_waitcnt lgkmcnt(0)
	v_mfma_f32_16x16x32_bf16 v[46:49], v[148:151], v[200:203], v[46:49]
	v_mfma_f32_16x16x32_bf16 v[38:41], v[156:159], v[200:203], v[38:41]
	v_mfma_f32_16x16x32_bf16 v[30:33], v[148:151], v[208:211], v[30:33]
	v_mfma_f32_16x16x32_bf16 v[22:25], v[156:159], v[208:211], v[22:25]
	v_mfma_f32_16x16x32_bf16 v[14:17], v[148:151], v[216:219], v[14:17]
	v_mfma_f32_16x16x32_bf16 v[6:9], v[156:159], v[216:219], v[6:9]
	v_mfma_f32_16x16x32_bf16 v[62:65], v[152:155], v[196:199], v[62:65]
	v_mfma_f32_16x16x32_bf16 v[54:57], v[160:163], v[196:199], v[54:57]
	v_mfma_f32_16x16x32_bf16 v[46:49], v[152:155], v[204:207], v[46:49]
	v_mfma_f32_16x16x32_bf16 v[38:41], v[160:163], v[204:207], v[38:41]
	v_mfma_f32_16x16x32_bf16 v[30:33], v[152:155], v[212:215], v[30:33]
	v_mfma_f32_16x16x32_bf16 v[22:25], v[160:163], v[212:215], v[22:25]
	v_mfma_f32_16x16x32_bf16 v[14:17], v[152:155], v[220:223], v[14:17]
	v_mfma_f32_16x16x32_bf16 v[6:9], v[160:163], v[220:223], v[6:9]
	s_setprio 0
	s_setprio 1
	v_mfma_f32_16x16x32_bf16 v[58:61], v[164:167], v[180:183], v[58:61]
	v_mfma_f32_16x16x32_bf16 v[50:53], v[172:175], v[180:183], v[50:53]
	v_mfma_f32_16x16x32_bf16 v[42:45], v[164:167], v[200:203], v[42:45]
	v_mfma_f32_16x16x32_bf16 v[34:37], v[172:175], v[200:203], v[34:37]
	v_mfma_f32_16x16x32_bf16 v[26:29], v[164:167], v[208:211], v[26:29]
	v_mfma_f32_16x16x32_bf16 v[18:21], v[172:175], v[208:211], v[18:21]
	v_mfma_f32_16x16x32_bf16 v[10:13], v[164:167], v[216:219], v[10:13]
	v_mfma_f32_16x16x32_bf16 v[2:5], v[172:175], v[216:219], v[2:5]
	v_mfma_f32_16x16x32_bf16 v[58:61], v[168:171], v[196:199], v[58:61]
	v_mfma_f32_16x16x32_bf16 v[50:53], v[176:179], v[196:199], v[50:53]
	v_mfma_f32_16x16x32_bf16 v[42:45], v[168:171], v[204:207], v[42:45]
	v_mfma_f32_16x16x32_bf16 v[34:37], v[176:179], v[204:207], v[34:37]
	v_mfma_f32_16x16x32_bf16 v[26:29], v[168:171], v[212:215], v[26:29]
	v_mfma_f32_16x16x32_bf16 v[18:21], v[176:179], v[212:215], v[18:21]
	v_mfma_f32_16x16x32_bf16 v[10:13], v[168:171], v[220:223], v[10:13]
	v_mfma_f32_16x16x32_bf16 v[2:5], v[176:179], v[220:223], v[2:5]
	s_setprio 0
	s_barrier
	s_add_i32 s83, s83, 2
	s_add_u32 s26, s26, 0x10000
	s_addc_u32 s27, s27, 0
	s_add_u32 s73, s73, 0x10000
	s_addc_u32 s81, s81, 0
	s_cmp_gt_u32 s83, 29
	s_cbranch_scc0 .LBB0_1340
	s_and_b64 vcc, exec, s[12:13]
	s_cbranch_vccz .LBB0_1343
	s_barrier

; #define PG8_STAGE(bufoff, gbase, voff) do { _Pragma("unroll") for (int _i = 0; _i < 2; ++_i) \
;         __builtin_amdgcn_global_load_lds((const unsigned*)((const char*)(gbase) + (voff)[_i]), (PG8_LAS unsigned*)(lds + (bufoff) + ldsw + _i * 8192), 16, 0, 0); } while (0)
; #define PG8_LDA(dst, b, h) do { _Pragma("unroll") for (int m = 0; m < 4; ++m) _Pragma("unroll") for (int k = 0; k < 2; ++k) dst[m][k] = *(const PG8_LAS bf16x8*)(lds + PG8_SA(b, h) + aoff + m * 2048 + k * 1024); } while (0)
; #define PG8_LDB(dst, b, h) do { _Pragma("unroll") for (int n = 0; n < 2; ++n) _Pragma("unroll") for (int k = 0; k < 2; ++k) dst[n][k] = *(const PG8_LAS bf16x8*)(lds + PG8_SB(b, h) + boff + n * 2048 + k * 1024); } while (0)
; #define PG8_MMA(ai, bj, At, Bt) do { __builtin_amdgcn_s_setprio(1); _Pragma("unroll") for (int m = 0; m < 4; ++m) _Pragma("unroll") for (int n = 0; n < 2; ++n) _Pragma("unroll") for (int k = 0; k < 2; ++k) \
;         acc[ai][bj][m][n] = __builtin_amdgcn_mfma_f32_16x16x32_bf16(Bt[n][k], At[m][k], acc[ai][bj][m][n], 0, 0, 0); __builtin_amdgcn_s_setprio(0); } while (0)
; template <class Epi, class Sched, bool ALIGN_EPI = false, bool SP2 = false, bool ABLK = false, bool BBLK = false>
; __device__ __forceinline__ void gemm_phase(PG8_LAS unsigned char* lds, const Gemm g, const Sched& S, const Epi& E) {
;     ...
;             const bool last = (t == nt - 2);
;             const char* a1 = cA + (size_t)(t + 1) * kstepA;
;             const char* a2 = last ? nA : cA + (size_t)(t + 2) * kstepA; const char* b2 = last ? nB : cB + (size_t)(t + 2) * kstepB;
;             const char* a3 = a2 + kstepA; const char* b3 = b2 + kstepB;
;             if (last && has_next) S.a_ready(nxt);
;             if constexpr (SP2) {
;             PG8_LDB(B0, 0, 0); PG8_LDB(B1, 0, 1); PG8_SCHED; PG8_LDA(At, 0, 0); PG8_STAGE(PG8_SA(1, 1), a1 + hstepA, voffA);
;             PG8_WAIT_V(8); PG8_WAIT_L(0); PG8_BAR; PG8_MMA(0, 0, At, B0); PG8_MMA(0, 1, At, B1); PG8_BAR; PG8_SCHED;
;             PG8_LDA(At, 0, 1); PG8_STAGE(PG8_SB(0, 0), b2, voffB); PG8_STAGE(PG8_SB(0, 1), b2 + hstepB, voffB); PG8_STAGE(PG8_SA(0, 0), a2, voffA);
;             PG8_WAIT_V(8); PG8_WAIT_L(0); PG8_BAR; PG8_MMA(1, 0, At, B0); PG8_MMA(1, 1, At, B1); PG8_BAR; PG8_SCHED;
;             PG8_LDB(B0, 1, 0); PG8_LDB(B1, 1, 1); PG8_SCHED; PG8_LDA(At, 1, 0); PG8_STAGE(PG8_SA(0, 1), a2 + hstepA, voffA);
.LBB0_1420:
	s_add_u32 s8, s0, 0x4000
	s_addc_u32 s9, s1, 0
	s_cmpk_eq_i32 s73, 0x54
	s_cselect_b32 s28, s18, s8
	s_cselect_b32 s29, s19, s9
	s_cselect_b32 s26, s20, s23
	s_cselect_b32 s27, s21, s25
	s_add_u32 s8, s28, 0x8000
	s_addc_u32 s9, s29, 0
	s_add_i32 s52, 0, 0x10000
	s_add_i32 s75, 0, 0x14000
	v_add_u32_e32 v142, s52, v180
	v_add_u32_e32 v168, s75, v180
	ds_read_b128 v[130:133], v142
	ds_read_b128 v[134:137], v142 offset:1024
	ds_read_b128 v[138:141], v142 offset:2048
	ds_read_b128 v[142:145], v142 offset:3072
	ds_read_b128 v[156:159], v168
	ds_read_b128 v[160:163], v168 offset:1024
	ds_read_b128 v[164:167], v168 offset:2048
	ds_read_b128 v[168:171], v168 offset:3072
	v_lshl_add_u64 v[176:177], s[0:1], 0, v[152:153]
	s_add_i32 m0, s3, 0xc000
	ds_read_b128 v[172:175], v181
	ds_read_b128 v[182:185], v181 offset:1024
	ds_read_b128 v[196:199], v181 offset:2048
	ds_read_b128 v[200:203], v181 offset:3072
	ds_read_b128 v[204:207], v181 offset:4096
	ds_read_b128 v[208:211], v181 offset:5120
	ds_read_b128 v[212:215], v181 offset:6144
	ds_read_b128 v[216:219], v181 offset:7168
	global_load_lds_dwordx4 v[176:177], off
	v_lshl_add_u64 v[176:177], s[0:1], 0, v[154:155]
	s_add_i32 m0, s3, 0xe000
	s_nop 0
	global_load_lds_dwordx4 v[176:177], off
	s_waitcnt vmcnt(8)
	s_waitcnt lgkmcnt(0)
	v_mfma_f32_16x16x32_bf16 v[58:61], v[130:133], v[172:175], v[58:61]
	v_mfma_f32_16x16x32_bf16 v[50:53], v[138:141], v[172:175], v[50:53]
	s_barrier
	s_setprio 1
	s_waitcnt lgkmcnt(0)
	v_mfma_f32_16x16x32_bf16 v[78:81], v[130:133], v[196:199], v[78:81]
	v_mfma_f32_16x16x32_bf16 v[70:73], v[138:141], v[196:199], v[70:73]
	v_mfma_f32_16x16x32_bf16 v[98:101], v[130:133], v[204:207], v[98:101]
	v_mfma_f32_16x16x32_bf16 v[102:105], v[138:141], v[204:207], v[102:105]
	v_mfma_f32_16x16x32_bf16 v[114:117], v[130:133], v[212:215], v[114:117]
	v_mfma_f32_16x16x32_bf16 v[118:121], v[138:141], v[212:215], v[118:121]
	v_mfma_f32_16x16x32_bf16 v[58:61], v[134:137], v[182:185], v[58:61]
	v_mfma_f32_16x16x32_bf16 v[50:53], v[142:145], v[182:185], v[50:53]
	v_mfma_f32_16x16x32_bf16 v[78:81], v[134:137], v[200:203], v[78:81]
	v_mfma_f32_16x16x32_bf16 v[70:73], v[142:145], v[200:203], v[70:73]
	v_mfma_f32_16x16x32_bf16 v[98:101], v[134:137], v[208:211], v[98:101]
	v_mfma_f32_16x16x32_bf16 v[102:105], v[142:145], v[208:211], v[102:105]
	v_mfma_f32_16x16x32_bf16 v[114:117], v[134:137], v[216:219], v[114:117]
	v_mfma_f32_16x16x32_bf16 v[118:121], v[142:145], v[216:219], v[118:121]
	s_setprio 0
	s_setprio 1
	v_mfma_f32_16x16x32_bf16 v[66:69], v[156:159], v[172:175], v[66:69]
	v_mfma_f32_16x16x32_bf16 v[54:57], v[164:167], v[172:175], v[54:57]
	v_mfma_f32_16x16x32_bf16 v[86:89], v[156:159], v[196:199], v[86:89]
	v_mfma_f32_16x16x32_bf16 v[94:97], v[164:167], v[196:199], v[94:97]
	v_mfma_f32_16x16x32_bf16 v[106:109], v[156:159], v[204:207], v[106:109]
	v_mfma_f32_16x16x32_bf16 v[110:113], v[164:167], v[204:207], v[110:113]
	v_mfma_f32_16x16x32_bf16 v[122:125], v[156:159], v[212:215], v[122:125]
	v_mfma_f32_16x16x32_bf16 v[126:129], v[164:167], v[212:215], v[126:129]
	v_mfma_f32_16x16x32_bf16 v[66:69], v[160:163], v[182:185], v[66:69]
	v_mfma_f32_16x16x32_bf16 v[54:57], v[168:171], v[182:185], v[54:57]
	v_mfma_f32_16x16x32_bf16 v[86:89], v[160:163], v[200:203], v[86:89]
	v_mfma_f32_16x16x32_bf16 v[94:97], v[168:171], v[200:203], v[94:97]
	v_mfma_f32_16x16x32_bf16 v[106:109], v[160:163], v[208:211], v[106:109]
	v_mfma_f32_16x16x32_bf16 v[110:113], v[168:171], v[208:211], v[110:113]
	v_mfma_f32_16x16x32_bf16 v[122:125], v[160:163], v[216:219], v[122:125]
	v_mfma_f32_16x16x32_bf16 v[126:129], v[168:171], v[216:219], v[126:129]
	s_setprio 0
	s_barrier
	s_add_i32 s52, s52, s2
	v_lshl_add_u64 v[176:177], s[26:27], 0, v[186:187]
	s_mov_b32 m0, s52
	ds_read_b128 v[172:175], v181 offset:16384
	ds_read_b128 v[182:185], v181 offset:17408
	ds_read_b128 v[196:199], v181 offset:18432
	ds_read_b128 v[200:203], v181 offset:19456
	ds_read_b128 v[204:207], v181 offset:20480
	ds_read_b128 v[208:211], v181 offset:21504
	ds_read_b128 v[212:215], v181 offset:22528
	ds_read_b128 v[216:219], v181 offset:23552
	global_load_lds_dwordx4 v[176:177], off
	s_add_i32 m0, s52, 0x2000
	s_add_u32 s80, s26, 0x4000
	v_lshl_add_u64 v[176:177], s[26:27], 0, v[150:151]
	s_addc_u32 s81, s27, 0
	s_add_i32 s52, s75, s2
	global_load_lds_dwordx4 v[176:177], off
	v_lshl_add_u64 v[176:177], s[80:81], 0, v[186:187]
	s_mov_b32 m0, s52
	s_nop 0
	global_load_lds_dwordx4 v[176:177], off
	v_lshl_add_u64 v[176:177], s[80:81], 0, v[150:151]
	s_add_i32 m0, s52, 0x2000
	s_nop 0
	global_load_lds_dwordx4 v[176:177], off
	v_lshl_add_u64 v[176:177], s[28:29], 0, v[146:147]
	s_mov_b32 m0, s3
	s_nop 0
	global_load_lds_dwordx4 v[176:177], off
	v_lshl_add_u64 v[176:177], s[28:29], 0, v[148:149]
	s_mov_b32 m0, s16
	s_nop 0
	global_load_lds_dwordx4 v[176:177], off
	s_waitcnt vmcnt(8)
	s_waitcnt lgkmcnt(0)
	v_mfma_f32_16x16x32_bf16 v[90:93], v[130:133], v[172:175], v[90:93]
	v_mfma_f32_16x16x32_bf16 v[82:85], v[138:141], v[172:175], v[82:85]
	s_barrier
; #define PG8_STAGE(bufoff, gbase, voff) do { _Pragma("unroll") for (int _i = 0; _i < 2; ++_i) \
;         __builtin_amdgcn_global_load_lds((const unsigned*)((const char*)(gbase) + (voff)[_i]), (PG8_LAS unsigned*)(lds + (bufoff) + ldsw + _i * 8192), 16, 0, 0); } while (0)
; #define PG8_LDA(dst, b, h) do { _Pragma("unroll") for (int m = 0; m < 4; ++m) _Pragma("unroll") for (int k = 0; k < 2; ++k) dst[m][k] = *(const PG8_LAS bf16x8*)(lds + PG8_SA(b, h) + aoff + m * 2048 + k * 1024); } while (0)
; #define PG8_LDB(dst, b, h) do { _Pragma("unroll") for (int n = 0; n < 2; ++n) _Pragma("unroll") for (int k = 0; k < 2; ++k) dst[n][k] = *(const PG8_LAS bf16x8*)(lds + PG8_SB(b, h) + boff + n * 2048 + k * 1024); } while (0)
; #define PG8_MMA(ai, bj, At, Bt) do { __builtin_amdgcn_s_setprio(1); _Pragma("unroll") for (int m = 0; m < 4; ++m) _Pragma("unroll") for (int n = 0; n < 2; ++n) _Pragma("unroll") for (int k = 0; k < 2; ++k) \
;         acc[ai][bj][m][n] = __builtin_amdgcn_mfma_f32_16x16x32_bf16(Bt[n][k], At[m][k], acc[ai][bj][m][n], 0, 0, 0); __builtin_amdgcn_s_setprio(0); } while (0)
; #define PG8_WAIT_V(n) asm volatile("s_waitcnt vmcnt(" #n ")" ::: "memory")
; #define PG8_WAIT_L(n) asm volatile("s_waitcnt lgkmcnt(" #n ")" ::: "memory")
; #define PG8_BAR __builtin_amdgcn_s_barrier()
; #define PG8_SCHED __builtin_amdgcn_sched_barrier(0)
; template <class Epi, class Sched, bool ALIGN_EPI = false, bool SP2 = false, bool ABLK = false, bool BBLK = false>
; __device__ __forceinline__ void gemm_phase(PG8_LAS unsigned char* lds, const Gemm g, const Sched& S, const Epi& E) {
;     ...
;             PG8_WAIT_V(8); PG8_WAIT_L(0); PG8_BAR; PG8_MMA(1, 0, At, B0); PG8_MMA(1, 1, At, B1); PG8_BAR; PG8_SCHED;
;             PG8_LDB(B0, 1, 0); PG8_LDB(B1, 1, 1); PG8_SCHED; PG8_LDA(At, 1, 0); PG8_STAGE(PG8_SA(0, 1), a2 + hstepA, voffA);
;             PG8_WAIT_V(8); PG8_WAIT_L(0); PG8_BAR; PG8_MMA(0, 0, At, B0); PG8_MMA(0, 1, At, B1); PG8_BAR; PG8_SCHED;
	s_setprio 1
	s_waitcnt lgkmcnt(0)
	v_mfma_f32_16x16x32_bf16 v[46:49], v[130:133], v[196:199], v[46:49]
	v_mfma_f32_16x16x32_bf16 v[42:45], v[138:141], v[196:199], v[42:45]
	v_mfma_f32_16x16x32_bf16 v[30:33], v[130:133], v[204:207], v[30:33]
	v_mfma_f32_16x16x32_bf16 v[26:29], v[138:141], v[204:207], v[26:29]
	v_mfma_f32_16x16x32_bf16 v[14:17], v[130:133], v[212:215], v[14:17]
	v_mfma_f32_16x16x32_bf16 v[10:13], v[138:141], v[212:215], v[10:13]
	v_mfma_f32_16x16x32_bf16 v[90:93], v[134:137], v[182:185], v[90:93]
	v_mfma_f32_16x16x32_bf16 v[82:85], v[142:145], v[182:185], v[82:85]
	v_mfma_f32_16x16x32_bf16 v[46:49], v[134:137], v[200:203], v[46:49]
	v_mfma_f32_16x16x32_bf16 v[42:45], v[142:145], v[200:203], v[42:45]
	v_mfma_f32_16x16x32_bf16 v[30:33], v[134:137], v[208:211], v[30:33]
	v_mfma_f32_16x16x32_bf16 v[26:29], v[142:145], v[208:211], v[26:29]
	v_mfma_f32_16x16x32_bf16 v[14:17], v[134:137], v[216:219], v[14:17]
	v_mfma_f32_16x16x32_bf16 v[10:13], v[142:145], v[216:219], v[10:13]
	s_setprio 0
	s_setprio 1
	v_mfma_f32_16x16x32_bf16 v[74:77], v[156:159], v[172:175], v[74:77]
	v_mfma_f32_16x16x32_bf16 v[62:65], v[164:167], v[172:175], v[62:65]
	v_mfma_f32_16x16x32_bf16 v[38:41], v[156:159], v[196:199], v[38:41]
	v_mfma_f32_16x16x32_bf16 v[34:37], v[164:167], v[196:199], v[34:37]
	v_mfma_f32_16x16x32_bf16 v[22:25], v[156:159], v[204:207], v[22:25]
	v_mfma_f32_16x16x32_bf16 v[18:21], v[164:167], v[204:207], v[18:21]
	v_mfma_f32_16x16x32_bf16 v[6:9], v[156:159], v[212:215], v[6:9]
	v_mfma_f32_16x16x32_bf16 v[2:5], v[164:167], v[212:215], v[2:5]
	v_mfma_f32_16x16x32_bf16 v[74:77], v[160:163], v[182:185], v[74:77]
	v_mfma_f32_16x16x32_bf16 v[62:65], v[168:171], v[182:185], v[62:65]
	v_mfma_f32_16x16x32_bf16 v[38:41], v[160:163], v[200:203], v[38:41]
	v_mfma_f32_16x16x32_bf16 v[34:37], v[168:171], v[200:203], v[34:37]
	v_mfma_f32_16x16x32_bf16 v[22:25], v[160:163], v[208:211], v[22:25]
	v_mfma_f32_16x16x32_bf16 v[18:21], v[168:171], v[208:211], v[18:21]
	v_mfma_f32_16x16x32_bf16 v[6:9], v[160:163], v[216:219], v[6:9]
	v_mfma_f32_16x16x32_bf16 v[2:5], v[168:171], v[216:219], v[2:5]
	s_setprio 0
	s_barrier
	s_add_i32 s52, 0, 0x18000
	s_add_i32 s75, 0, 0x1c000
	v_add_u32_e32 v142, s52, v180
	v_add_u32_e32 v168, s75, v180
	ds_read_b128 v[130:133], v142
	ds_read_b128 v[134:137], v142 offset:1024
	ds_read_b128 v[138:141], v142 offset:2048
	ds_read_b128 v[142:145], v142 offset:3072
	ds_read_b128 v[156:159], v168
	ds_read_b128 v[160:163], v168 offset:1024
	ds_read_b128 v[164:167], v168 offset:2048
	ds_read_b128 v[168:171], v168 offset:3072
	s_add_u32 s28, s28, 0x4000
	s_addc_u32 s29, s29, 0
	s_mov_b32 m0, s30
	v_lshl_add_u64 v[176:177], s[28:29], 0, v[146:147]
	ds_read_b128 v[172:175], v181 offset:32768
	ds_read_b128 v[182:185], v181 offset:33792
	ds_read_b128 v[196:199], v181 offset:34816
	ds_read_b128 v[200:203], v181 offset:35840
	ds_read_b128 v[204:207], v181 offset:36864
	ds_read_b128 v[208:211], v181 offset:37888
	ds_read_b128 v[212:215], v181 offset:38912
	ds_read_b128 v[216:219], v181 offset:39936
	global_load_lds_dwordx4 v[176:177], off
	v_lshl_add_u64 v[176:177], s[28:29], 0, v[148:149]
	s_mov_b32 m0, s31
	s_nop 0
	global_load_lds_dwordx4 v[176:177], off
	s_waitcnt vmcnt(8)
	s_waitcnt lgkmcnt(0)
	v_mfma_f32_16x16x32_bf16 v[58:61], v[130:133], v[172:175], v[58:61]
	v_mfma_f32_16x16x32_bf16 v[50:53], v[138:141], v[172:175], v[50:53]
	s_barrier
	s_setprio 1
	s_waitcnt lgkmcnt(0)
	v_mfma_f32_16x16x32_bf16 v[78:81], v[130:133], v[196:199], v[78:81]
	v_mfma_f32_16x16x32_bf16 v[70:73], v[138:141], v[196:199], v[70:73]
	v_mfma_f32_16x16x32_bf16 v[98:101], v[130:133], v[204:207], v[98:101]
	v_mfma_f32_16x16x32_bf16 v[102:105], v[138:141], v[204:207], v[102:105]
	v_mfma_f32_16x16x32_bf16 v[114:117], v[130:133], v[212:215], v[114:117]
	v_mfma_f32_16x16x32_bf16 v[118:121], v[138:141], v[212:215], v[118:121]
	v_mfma_f32_16x16x32_bf16 v[58:61], v[134:137], v[182:185], v[58:61]
	v_mfma_f32_16x16x32_bf16 v[50:53], v[142:145], v[182:185], v[50:53]
	v_mfma_f32_16x16x32_bf16 v[78:81], v[134:137], v[200:203], v[78:81]
	v_mfma_f32_16x16x32_bf16 v[70:73], v[142:145], v[200:203], v[70:73]
	v_mfma_f32_16x16x32_bf16 v[98:101], v[134:137], v[208:211], v[98:101]
	v_mfma_f32_16x16x32_bf16 v[102:105], v[142:145], v[208:211], v[102:105]
	v_mfma_f32_16x16x32_bf16 v[114:117], v[134:137], v[216:219], v[114:117]
	v_mfma_f32_16x16x32_bf16 v[118:121], v[142:145], v[216:219], v[118:121]
	s_setprio 0
	s_setprio 1
	v_mfma_f32_16x16x32_bf16 v[66:69], v[156:159], v[172:175], v[66:69]
	v_mfma_f32_16x16x32_bf16 v[54:57], v[164:167], v[172:175], v[54:57]
	v_mfma_f32_16x16x32_bf16 v[86:89], v[156:159], v[196:199], v[86:89]
	v_mfma_f32_16x16x32_bf16 v[94:97], v[164:167], v[196:199], v[94:97]
	v_mfma_f32_16x16x32_bf16 v[106:109], v[156:159], v[204:207], v[106:109]
	v_mfma_f32_16x16x32_bf16 v[110:113], v[164:167], v[204:207], v[110:113]
	v_mfma_f32_16x16x32_bf16 v[122:125], v[156:159], v[212:215], v[122:125]
	v_mfma_f32_16x16x32_bf16 v[126:129], v[164:167], v[212:215], v[126:129]
	v_mfma_f32_16x16x32_bf16 v[66:69], v[160:163], v[182:185], v[66:69]
	v_mfma_f32_16x16x32_bf16 v[54:57], v[168:171], v[182:185], v[54:57]
	v_mfma_f32_16x16x32_bf16 v[86:89], v[160:163], v[200:203], v[86:89]
	v_mfma_f32_16x16x32_bf16 v[94:97], v[168:171], v[200:203], v[94:97]
	v_mfma_f32_16x16x32_bf16 v[106:109], v[160:163], v[208:211], v[106:109]
	v_mfma_f32_16x16x32_bf16 v[110:113], v[168:171], v[208:211], v[110:113]
	v_mfma_f32_16x16x32_bf16 v[122:125], v[160:163], v[216:219], v[122:125]
	v_mfma_f32_16x16x32_bf16 v[126:129], v[168:171], v[216:219], v[126:129]
	s_setprio 0
	s_barrier
; #define PG8_STAGE(bufoff, gbase, voff) do { _Pragma("unroll") for (int _i = 0; _i < 2; ++_i) \
;         __builtin_amdgcn_global_load_lds((const unsigned*)((const char*)(gbase) + (voff)[_i]), (PG8_LAS unsigned*)(lds + (bufoff) + ldsw + _i * 8192), 16, 0, 0); } while (0)
; #define PG8_LDA(dst, b, h) do { _Pragma("unroll") for (int m = 0; m < 4; ++m) _Pragma("unroll") for (int k = 0; k < 2; ++k) dst[m][k] = *(const PG8_LAS bf16x8*)(lds + PG8_SA(b, h) + aoff + m * 2048 + k * 1024); } while (0)
; #define PG8_MMA(ai, bj, At, Bt) do { __builtin_amdgcn_s_setprio(1); _Pragma("unroll") for (int m = 0; m < 4; ++m) _Pragma("unroll") for (int n = 0; n < 2; ++n) _Pragma("unroll") for (int k = 0; k < 2; ++k) \
;         acc[ai][bj][m][n] = __builtin_amdgcn_mfma_f32_16x16x32_bf16(Bt[n][k], At[m][k], acc[ai][bj][m][n], 0, 0, 0); __builtin_amdgcn_s_setprio(0); } while (0)
; #define PG8_WAIT_V(n) asm volatile("s_waitcnt vmcnt(" #n ")" ::: "memory")
; #define PG8_WAIT_L(n) asm volatile("s_waitcnt lgkmcnt(" #n ")" ::: "memory")
; #define PG8_BAR __builtin_amdgcn_s_barrier()
; #define PG8_SCHED __builtin_amdgcn_sched_barrier(0)
; template <class Epi, class Sched, bool ALIGN_EPI = false, bool SP2 = false, bool ABLK = false, bool BBLK = false>
; __device__ __forceinline__ void gemm_phase(PG8_LAS unsigned char* lds, const Gemm g, const Sched& S, const Epi& E) {
;     ...
;             PG8_LDA(At, 1, 1); PG8_STAGE(PG8_SB(1, 0), b3, voffB); PG8_STAGE(PG8_SB(1, 1), b3 + hstepB, voffB); PG8_STAGE(PG8_SA(1, 0), a3, voffA);
;             PG8_WAIT_V(8); PG8_WAIT_L(0); PG8_BAR; PG8_MMA(1, 0, At, B0); PG8_MMA(1, 1, At, B1); PG8_BAR; PG8_SCHED;
;     ...
;         if constexpr (ALIGN_EPI) { if (wr == 0) PG8_BAR; }
	s_add_u32 s28, s26, 0x8000
	s_addc_u32 s29, s27, 0
	s_add_i32 s52, s52, s2
	v_lshl_add_u64 v[176:177], s[28:29], 0, v[186:187]
	s_mov_b32 m0, s52
	ds_read_b128 v[172:175], v181 offset:49152
	ds_read_b128 v[182:185], v181 offset:50176
	ds_read_b128 v[196:199], v181 offset:51200
	ds_read_b128 v[200:203], v181 offset:52224
	ds_read_b128 v[204:207], v181 offset:53248
	ds_read_b128 v[208:211], v181 offset:54272
	ds_read_b128 v[212:215], v181 offset:55296
	ds_read_b128 v[216:219], v181 offset:56320
	global_load_lds_dwordx4 v[176:177], off
	s_add_i32 m0, s52, 0x2000
	s_add_u32 s26, s26, 0xc000
	v_lshl_add_u64 v[176:177], s[28:29], 0, v[150:151]
	s_addc_u32 s27, s27, 0
	s_add_i32 s28, s75, s2
	global_load_lds_dwordx4 v[176:177], off
	v_lshl_add_u64 v[176:177], s[26:27], 0, v[186:187]
	s_mov_b32 m0, s28
	s_nop 0
	global_load_lds_dwordx4 v[176:177], off
	v_lshl_add_u64 v[176:177], s[26:27], 0, v[150:151]
	s_add_i32 m0, s28, 0x2000
	s_nop 0
	global_load_lds_dwordx4 v[176:177], off
	v_lshl_add_u64 v[176:177], s[8:9], 0, v[146:147]
	s_mov_b32 m0, s45
	s_nop 0
	global_load_lds_dwordx4 v[176:177], off
	v_lshl_add_u64 v[176:177], s[8:9], 0, v[148:149]
	s_mov_b32 m0, s46
	s_nop 0
	global_load_lds_dwordx4 v[176:177], off
	s_waitcnt vmcnt(8)
	s_waitcnt lgkmcnt(0)
	v_mfma_f32_16x16x32_bf16 v[90:93], v[130:133], v[172:175], v[90:93]
	v_mfma_f32_16x16x32_bf16 v[82:85], v[138:141], v[172:175], v[82:85]
	s_barrier
	s_setprio 1
	s_waitcnt lgkmcnt(0)
	v_mfma_f32_16x16x32_bf16 v[46:49], v[130:133], v[196:199], v[46:49]
	v_mfma_f32_16x16x32_bf16 v[42:45], v[138:141], v[196:199], v[42:45]
	v_mfma_f32_16x16x32_bf16 v[30:33], v[130:133], v[204:207], v[30:33]
	v_mfma_f32_16x16x32_bf16 v[26:29], v[138:141], v[204:207], v[26:29]
	v_mfma_f32_16x16x32_bf16 v[14:17], v[130:133], v[212:215], v[14:17]
	v_mfma_f32_16x16x32_bf16 v[10:13], v[138:141], v[212:215], v[10:13]
	v_mfma_f32_16x16x32_bf16 v[90:93], v[134:137], v[182:185], v[90:93]
	v_mfma_f32_16x16x32_bf16 v[82:85], v[142:145], v[182:185], v[82:85]
	v_mfma_f32_16x16x32_bf16 v[46:49], v[134:137], v[200:203], v[46:49]
	v_mfma_f32_16x16x32_bf16 v[42:45], v[142:145], v[200:203], v[42:45]
	v_mfma_f32_16x16x32_bf16 v[30:33], v[134:137], v[208:211], v[30:33]
	v_mfma_f32_16x16x32_bf16 v[26:29], v[142:145], v[208:211], v[26:29]
	v_mfma_f32_16x16x32_bf16 v[14:17], v[134:137], v[216:219], v[14:17]
	v_mfma_f32_16x16x32_bf16 v[10:13], v[142:145], v[216:219], v[10:13]
	s_setprio 0
	s_setprio 1
	v_mfma_f32_16x16x32_bf16 v[74:77], v[156:159], v[172:175], v[74:77]
	v_mfma_f32_16x16x32_bf16 v[62:65], v[164:167], v[172:175], v[62:65]
	v_mfma_f32_16x16x32_bf16 v[38:41], v[156:159], v[196:199], v[38:41]
	v_mfma_f32_16x16x32_bf16 v[34:37], v[164:167], v[196:199], v[34:37]
	v_mfma_f32_16x16x32_bf16 v[22:25], v[156:159], v[204:207], v[22:25]
	v_mfma_f32_16x16x32_bf16 v[18:21], v[164:167], v[204:207], v[18:21]
	v_mfma_f32_16x16x32_bf16 v[6:9], v[156:159], v[212:215], v[6:9]
	v_mfma_f32_16x16x32_bf16 v[2:5], v[164:167], v[212:215], v[2:5]
	v_mfma_f32_16x16x32_bf16 v[74:77], v[160:163], v[182:185], v[74:77]
	v_mfma_f32_16x16x32_bf16 v[62:65], v[168:171], v[182:185], v[62:65]
	v_mfma_f32_16x16x32_bf16 v[38:41], v[160:163], v[200:203], v[38:41]
	v_mfma_f32_16x16x32_bf16 v[34:37], v[168:171], v[200:203], v[34:37]
	v_mfma_f32_16x16x32_bf16 v[22:25], v[160:163], v[208:211], v[22:25]
	v_mfma_f32_16x16x32_bf16 v[18:21], v[168:171], v[208:211], v[18:21]
	v_mfma_f32_16x16x32_bf16 v[6:9], v[160:163], v[216:219], v[6:9]
	v_mfma_f32_16x16x32_bf16 v[2:5], v[168:171], v[216:219], v[2:5]
	s_setprio 0
	s_barrier
	s_add_i32 s73, s73, 2
	s_add_u32 s0, s0, 0x10000
	s_addc_u32 s1, s1, 0
	s_add_u32 s23, s23, 0x10000
	s_addc_u32 s25, s25, 0
	s_cmpk_gt_u32 s73, 0x55
	s_cbranch_scc0 .LBB0_1420
	s_and_b64 vcc, exec, s[14:15]
	s_cbranch_vccz .LBB0_1423
	s_barrier

; #define PG8_STAGE(bufoff, gbase, voff) do { _Pragma("unroll") for (int _i = 0; _i < 2; ++_i) \
;         __builtin_amdgcn_global_load_lds((const unsigned*)((const char*)(gbase) + (voff)[_i]), (PG8_LAS unsigned*)(lds + (bufoff) + ldsw + _i * 8192), 16, 0, 0); } while (0)
; #define PG8_LDA(dst, b, h) do { _Pragma("unroll") for (int m = 0; m < 4; ++m) _Pragma("unroll") for (int k = 0; k < 2; ++k) dst[m][k] = *(const PG8_LAS bf16x8*)(lds + PG8_SA(b, h) + aoff + m * 2048 + k * 1024); } while (0)
; #define PG8_LDB(dst, b, h) do { _Pragma("unroll") for (int n = 0; n < 2; ++n) _Pragma("unroll") for (int k = 0; k < 2; ++k) dst[n][k] = *(const PG8_LAS bf16x8*)(lds + PG8_SB(b, h) + boff + n * 2048 + k * 1024); } while (0)
; #define PG8_MMA(ai, bj, At, Bt) do { __builtin_amdgcn_s_setprio(1); _Pragma("unroll") for (int m = 0; m < 4; ++m) _Pragma("unroll") for (int n = 0; n < 2; ++n) _Pragma("unroll") for (int k = 0; k < 2; ++k) \
;         acc[ai][bj][m][n] = __builtin_amdgcn_mfma_f32_16x16x32_bf16(Bt[n][k], At[m][k], acc[ai][bj][m][n], 0, 0, 0); __builtin_amdgcn_s_setprio(0); } while (0)
; template <class Epi, class Sched, bool ALIGN_EPI = false, bool SP2 = false, bool ABLK = false, bool BBLK = false>
; __device__ __forceinline__ void gemm_phase(PG8_LAS unsigned char* lds, const Gemm g, const Sched& S, const Epi& E) {
;     ...
;             const bool last = (t == nt - 2);
;             const char* a1 = cA + (size_t)(t + 1) * kstepA;
;             const char* a2 = last ? nA : cA + (size_t)(t + 2) * kstepA; const char* b2 = last ? nB : cB + (size_t)(t + 2) * kstepB;
;             const char* a3 = a2 + kstepA; const char* b3 = b2 + kstepB;
;             if (last && has_next) S.a_ready(nxt);
;             if constexpr (SP2) {
;             PG8_LDB(B0, 0, 0); PG8_LDB(B1, 0, 1); PG8_SCHED; PG8_LDA(At, 0, 0); PG8_STAGE(PG8_SA(1, 1), a1 + hstepA, voffA);
;             PG8_WAIT_V(8); PG8_WAIT_L(0); PG8_BAR; PG8_MMA(0, 0, At, B0); PG8_MMA(0, 1, At, B1); PG8_BAR; PG8_SCHED;
;             PG8_LDA(At, 0, 1); PG8_STAGE(PG8_SB(0, 0), b2, voffB); PG8_STAGE(PG8_SB(0, 1), b2 + hstepB, voffB); PG8_STAGE(PG8_SA(0, 0), a2, voffA);
;             PG8_WAIT_V(8); PG8_WAIT_L(0); PG8_BAR; PG8_MMA(1, 0, At, B0); PG8_MMA(1, 1, At, B1); PG8_BAR; PG8_SCHED;
;             PG8_LDB(B0, 1, 0); PG8_LDB(B1, 1, 1); PG8_SCHED; PG8_LDA(At, 1, 0); PG8_STAGE(PG8_SA(0, 1), a2 + hstepA, voffA);
.LBB0_1483:
	s_add_u32 s8, s0, 0x4000
	s_addc_u32 s9, s1, 0
	s_cmpk_eq_i32 s35, 0x54
	s_cselect_b32 s40, s26, s8
	s_cselect_b32 s41, s27, s9
	s_cselect_b32 s36, s28, s31
	s_cselect_b32 s37, s29, s33
	s_add_u32 s8, s40, 0x8000
	s_addc_u32 s9, s41, 0
	s_add_i32 s44, 0, 0x10000
	s_add_i32 s52, 0, 0x14000
	v_add_u32_e32 v142, s44, v206
	v_add_u32_e32 v158, s52, v206
	ds_read_b128 v[130:133], v142
	ds_read_b128 v[134:137], v142 offset:1024
	ds_read_b128 v[138:141], v142 offset:2048
	ds_read_b128 v[142:145], v142 offset:3072
	ds_read_b128 v[146:149], v158
	ds_read_b128 v[150:153], v158 offset:1024
	ds_read_b128 v[154:157], v158 offset:2048
	ds_read_b128 v[158:161], v158 offset:3072
	v_lshl_add_u64 v[188:189], s[0:1], 0, v[184:185]
	s_add_i32 m0, s68, 0xc000
	ds_read_b128 v[162:165], v207
	ds_read_b128 v[166:169], v207 offset:1024
	ds_read_b128 v[170:173], v207 offset:2048
	ds_read_b128 v[174:177], v207 offset:3072
	ds_read_b128 v[198:201], v207 offset:4096
	ds_read_b128 v[208:211], v207 offset:5120
	ds_read_b128 v[212:215], v207 offset:6144
	ds_read_b128 v[216:219], v207 offset:7168
	global_load_lds_dwordx4 v[188:189], off
	v_lshl_add_u64 v[188:189], s[0:1], 0, v[196:197]
	s_add_i32 m0, s68, 0xe000
	s_nop 0
	global_load_lds_dwordx4 v[188:189], off
	s_waitcnt vmcnt(8)
	s_waitcnt lgkmcnt(0)
	v_mfma_f32_16x16x32_bf16 v[30:33], v[130:133], v[162:165], v[30:33]
	v_mfma_f32_16x16x32_bf16 v[22:25], v[138:141], v[162:165], v[22:25]
	s_barrier
	s_setprio 1
	s_waitcnt lgkmcnt(0)
	v_mfma_f32_16x16x32_bf16 v[18:21], v[130:133], v[170:173], v[18:21]
	v_mfma_f32_16x16x32_bf16 v[10:13], v[138:141], v[170:173], v[10:13]
	v_mfma_f32_16x16x32_bf16 v[50:53], v[130:133], v[198:201], v[50:53]
	v_mfma_f32_16x16x32_bf16 v[54:57], v[138:141], v[198:201], v[54:57]
	v_mfma_f32_16x16x32_bf16 v[74:77], v[130:133], v[212:215], v[74:77]
	v_mfma_f32_16x16x32_bf16 v[78:81], v[138:141], v[212:215], v[78:81]
	v_mfma_f32_16x16x32_bf16 v[30:33], v[134:137], v[166:169], v[30:33]
	v_mfma_f32_16x16x32_bf16 v[22:25], v[142:145], v[166:169], v[22:25]
	v_mfma_f32_16x16x32_bf16 v[18:21], v[134:137], v[174:177], v[18:21]
	v_mfma_f32_16x16x32_bf16 v[10:13], v[142:145], v[174:177], v[10:13]
	v_mfma_f32_16x16x32_bf16 v[50:53], v[134:137], v[208:211], v[50:53]
	v_mfma_f32_16x16x32_bf16 v[54:57], v[142:145], v[208:211], v[54:57]
	v_mfma_f32_16x16x32_bf16 v[74:77], v[134:137], v[216:219], v[74:77]
	v_mfma_f32_16x16x32_bf16 v[78:81], v[142:145], v[216:219], v[78:81]
	s_setprio 0
	s_setprio 1
	v_mfma_f32_16x16x32_bf16 v[26:29], v[146:149], v[162:165], v[26:29]
	v_mfma_f32_16x16x32_bf16 v[14:17], v[154:157], v[162:165], v[14:17]
	v_mfma_f32_16x16x32_bf16 v[42:45], v[146:149], v[170:173], v[42:45]
	v_mfma_f32_16x16x32_bf16 v[46:49], v[154:157], v[170:173], v[46:49]
	v_mfma_f32_16x16x32_bf16 v[66:69], v[146:149], v[198:201], v[66:69]
	v_mfma_f32_16x16x32_bf16 v[70:73], v[154:157], v[198:201], v[70:73]
	v_mfma_f32_16x16x32_bf16 v[82:85], v[146:149], v[212:215], v[82:85]
	v_mfma_f32_16x16x32_bf16 v[86:89], v[154:157], v[212:215], v[86:89]
	v_mfma_f32_16x16x32_bf16 v[26:29], v[150:153], v[166:169], v[26:29]
	v_mfma_f32_16x16x32_bf16 v[14:17], v[158:161], v[166:169], v[14:17]
	v_mfma_f32_16x16x32_bf16 v[42:45], v[150:153], v[174:177], v[42:45]
	v_mfma_f32_16x16x32_bf16 v[46:49], v[158:161], v[174:177], v[46:49]
	v_mfma_f32_16x16x32_bf16 v[66:69], v[150:153], v[208:211], v[66:69]
	v_mfma_f32_16x16x32_bf16 v[70:73], v[158:161], v[208:211], v[70:73]
	v_mfma_f32_16x16x32_bf16 v[82:85], v[150:153], v[216:219], v[82:85]
	v_mfma_f32_16x16x32_bf16 v[86:89], v[158:161], v[216:219], v[86:89]
	s_setprio 0
	s_barrier
	s_add_i32 s44, s44, s65
	v_lshl_add_u64 v[188:189], s[36:37], 0, v[186:187]
	s_mov_b32 m0, s44
	ds_read_b128 v[162:165], v207 offset:16384
	ds_read_b128 v[166:169], v207 offset:17408
	ds_read_b128 v[170:173], v207 offset:18432
	ds_read_b128 v[174:177], v207 offset:19456
	ds_read_b128 v[198:201], v207 offset:20480
	ds_read_b128 v[208:211], v207 offset:21504
	ds_read_b128 v[212:215], v207 offset:22528
	ds_read_b128 v[216:219], v207 offset:23552
	global_load_lds_dwordx4 v[188:189], off
	s_add_i32 m0, s44, 0x2000
	s_add_u32 s44, s36, 0x4000
	v_lshl_add_u64 v[188:189], s[36:37], 0, v[182:183]
	s_addc_u32 s45, s37, 0
	s_add_i32 s52, s52, s65
	global_load_lds_dwordx4 v[188:189], off
	v_lshl_add_u64 v[188:189], s[44:45], 0, v[186:187]
	s_mov_b32 m0, s52
	s_nop 0
	global_load_lds_dwordx4 v[188:189], off
	v_lshl_add_u64 v[188:189], s[44:45], 0, v[182:183]
	s_add_i32 m0, s52, 0x2000
	s_nop 0
	global_load_lds_dwordx4 v[188:189], off
	v_lshl_add_u64 v[188:189], s[40:41], 0, v[178:179]
	s_mov_b32 m0, s68
	s_nop 0
	global_load_lds_dwordx4 v[188:189], off
	v_lshl_add_u64 v[188:189], s[40:41], 0, v[180:181]
	s_mov_b32 m0, s72
	s_nop 0
	global_load_lds_dwordx4 v[188:189], off
	s_waitcnt vmcnt(8)
	s_waitcnt lgkmcnt(0)
	v_mfma_f32_16x16x32_bf16 v[106:109], v[130:133], v[162:165], v[106:109]
	v_mfma_f32_16x16x32_bf16 v[110:113], v[138:141], v[162:165], v[110:113]
	s_barrier
; #define PG8_STAGE(bufoff, gbase, voff) do { _Pragma("unroll") for (int _i = 0; _i < 2; ++_i) \
;         __builtin_amdgcn_global_load_lds((const unsigned*)((const char*)(gbase) + (voff)[_i]), (PG8_LAS unsigned*)(lds + (bufoff) + ldsw + _i * 8192), 16, 0, 0); } while (0)
; #define PG8_LDA(dst, b, h) do { _Pragma("unroll") for (int m = 0; m < 4; ++m) _Pragma("unroll") for (int k = 0; k < 2; ++k) dst[m][k] = *(const PG8_LAS bf16x8*)(lds + PG8_SA(b, h) + aoff + m * 2048 + k * 1024); } while (0)
; #define PG8_LDB(dst, b, h) do { _Pragma("unroll") for (int n = 0; n < 2; ++n) _Pragma("unroll") for (int k = 0; k < 2; ++k) dst[n][k] = *(const PG8_LAS bf16x8*)(lds + PG8_SB(b, h) + boff + n * 2048 + k * 1024); } while (0)
; #define PG8_MMA(ai, bj, At, Bt) do { __builtin_amdgcn_s_setprio(1); _Pragma("unroll") for (int m = 0; m < 4; ++m) _Pragma("unroll") for (int n = 0; n < 2; ++n) _Pragma("unroll") for (int k = 0; k < 2; ++k) \
;         acc[ai][bj][m][n] = __builtin_amdgcn_mfma_f32_16x16x32_bf16(Bt[n][k], At[m][k], acc[ai][bj][m][n], 0, 0, 0); __builtin_amdgcn_s_setprio(0); } while (0)
; #define PG8_WAIT_V(n) asm volatile("s_waitcnt vmcnt(" #n ")" ::: "memory")
; #define PG8_WAIT_L(n) asm volatile("s_waitcnt lgkmcnt(" #n ")" ::: "memory")
; #define PG8_BAR __builtin_amdgcn_s_barrier()
; #define PG8_SCHED __builtin_amdgcn_sched_barrier(0)
; template <class Epi, class Sched, bool ALIGN_EPI = false, bool SP2 = false, bool ABLK = false, bool BBLK = false>
; __device__ __forceinline__ void gemm_phase(PG8_LAS unsigned char* lds, const Gemm g, const Sched& S, const Epi& E) {
;     ...
;             PG8_WAIT_V(8); PG8_WAIT_L(0); PG8_BAR; PG8_MMA(1, 0, At, B0); PG8_MMA(1, 1, At, B1); PG8_BAR; PG8_SCHED;
;             PG8_LDB(B0, 1, 0); PG8_LDB(B1, 1, 1); PG8_SCHED; PG8_LDA(At, 1, 0); PG8_STAGE(PG8_SA(0, 1), a2 + hstepA, voffA);
;             PG8_WAIT_V(8); PG8_WAIT_L(0); PG8_BAR; PG8_MMA(0, 0, At, B0); PG8_MMA(0, 1, At, B1); PG8_BAR; PG8_SCHED;
	s_setprio 1
	s_waitcnt lgkmcnt(0)
	v_mfma_f32_16x16x32_bf16 v[122:125], v[130:133], v[170:173], v[122:125]
	v_mfma_f32_16x16x32_bf16 v[126:129], v[138:141], v[170:173], v[126:129]
	v_mfma_f32_16x16x32_bf16 v[94:97], v[130:133], v[198:201], v[94:97]
	v_mfma_f32_16x16x32_bf16 v[90:93], v[138:141], v[198:201], v[90:93]
	v_mfma_f32_16x16x32_bf16 v[38:41], v[130:133], v[212:215], v[38:41]
	v_mfma_f32_16x16x32_bf16 v[34:37], v[138:141], v[212:215], v[34:37]
	v_mfma_f32_16x16x32_bf16 v[106:109], v[134:137], v[166:169], v[106:109]
	v_mfma_f32_16x16x32_bf16 v[110:113], v[142:145], v[166:169], v[110:113]
	v_mfma_f32_16x16x32_bf16 v[122:125], v[134:137], v[174:177], v[122:125]
	v_mfma_f32_16x16x32_bf16 v[126:129], v[142:145], v[174:177], v[126:129]
	v_mfma_f32_16x16x32_bf16 v[94:97], v[134:137], v[208:211], v[94:97]
	v_mfma_f32_16x16x32_bf16 v[90:93], v[142:145], v[208:211], v[90:93]
	v_mfma_f32_16x16x32_bf16 v[38:41], v[134:137], v[216:219], v[38:41]
	v_mfma_f32_16x16x32_bf16 v[34:37], v[142:145], v[216:219], v[34:37]
	s_setprio 0
	s_setprio 1
	v_mfma_f32_16x16x32_bf16 v[114:117], v[146:149], v[162:165], v[114:117]
	v_mfma_f32_16x16x32_bf16 v[118:121], v[154:157], v[162:165], v[118:121]
	v_mfma_f32_16x16x32_bf16 v[102:105], v[146:149], v[170:173], v[102:105]
	v_mfma_f32_16x16x32_bf16 v[98:101], v[154:157], v[170:173], v[98:101]
	v_mfma_f32_16x16x32_bf16 v[62:65], v[146:149], v[198:201], v[62:65]
	v_mfma_f32_16x16x32_bf16 v[58:61], v[154:157], v[198:201], v[58:61]
	v_mfma_f32_16x16x32_bf16 v[6:9], v[146:149], v[212:215], v[6:9]
	v_mfma_f32_16x16x32_bf16 v[2:5], v[154:157], v[212:215], v[2:5]
	v_mfma_f32_16x16x32_bf16 v[114:117], v[150:153], v[166:169], v[114:117]
	v_mfma_f32_16x16x32_bf16 v[118:121], v[158:161], v[166:169], v[118:121]
	v_mfma_f32_16x16x32_bf16 v[102:105], v[150:153], v[174:177], v[102:105]
	v_mfma_f32_16x16x32_bf16 v[98:101], v[158:161], v[174:177], v[98:101]
	v_mfma_f32_16x16x32_bf16 v[62:65], v[150:153], v[208:211], v[62:65]
	v_mfma_f32_16x16x32_bf16 v[58:61], v[158:161], v[208:211], v[58:61]
	v_mfma_f32_16x16x32_bf16 v[6:9], v[150:153], v[216:219], v[6:9]
	v_mfma_f32_16x16x32_bf16 v[2:5], v[158:161], v[216:219], v[2:5]
	s_setprio 0
	s_barrier
	s_add_i32 s44, 0, 0x18000
	s_add_i32 s45, 0, 0x1c000
	v_add_u32_e32 v142, s44, v206
	v_add_u32_e32 v158, s45, v206
	ds_read_b128 v[130:133], v142
	ds_read_b128 v[134:137], v142 offset:1024
	ds_read_b128 v[138:141], v142 offset:2048
	ds_read_b128 v[142:145], v142 offset:3072
	ds_read_b128 v[146:149], v158
	ds_read_b128 v[150:153], v158 offset:1024
	ds_read_b128 v[154:157], v158 offset:2048
	ds_read_b128 v[158:161], v158 offset:3072
	s_add_u32 s40, s40, 0x4000
	s_addc_u32 s41, s41, 0
	s_mov_b32 m0, s73
	v_lshl_add_u64 v[188:189], s[40:41], 0, v[178:179]
	ds_read_b128 v[162:165], v207 offset:32768
	ds_read_b128 v[166:169], v207 offset:33792
	ds_read_b128 v[170:173], v207 offset:34816
	ds_read_b128 v[174:177], v207 offset:35840
	ds_read_b128 v[198:201], v207 offset:36864
	ds_read_b128 v[208:211], v207 offset:37888
	ds_read_b128 v[212:215], v207 offset:38912
	ds_read_b128 v[216:219], v207 offset:39936
	global_load_lds_dwordx4 v[188:189], off
	v_lshl_add_u64 v[188:189], s[40:41], 0, v[180:181]
	s_mov_b32 m0, s84
	s_nop 0
	global_load_lds_dwordx4 v[188:189], off
	s_waitcnt vmcnt(8)
	s_waitcnt lgkmcnt(0)
	v_mfma_f32_16x16x32_bf16 v[30:33], v[130:133], v[162:165], v[30:33]
	v_mfma_f32_16x16x32_bf16 v[22:25], v[138:141], v[162:165], v[22:25]
	s_barrier
	s_setprio 1
	s_waitcnt lgkmcnt(0)
	v_mfma_f32_16x16x32_bf16 v[18:21], v[130:133], v[170:173], v[18:21]
	v_mfma_f32_16x16x32_bf16 v[10:13], v[138:141], v[170:173], v[10:13]
	v_mfma_f32_16x16x32_bf16 v[50:53], v[130:133], v[198:201], v[50:53]
	v_mfma_f32_16x16x32_bf16 v[54:57], v[138:141], v[198:201], v[54:57]
	v_mfma_f32_16x16x32_bf16 v[74:77], v[130:133], v[212:215], v[74:77]
	v_mfma_f32_16x16x32_bf16 v[78:81], v[138:141], v[212:215], v[78:81]
	v_mfma_f32_16x16x32_bf16 v[30:33], v[134:137], v[166:169], v[30:33]
	v_mfma_f32_16x16x32_bf16 v[22:25], v[142:145], v[166:169], v[22:25]
	v_mfma_f32_16x16x32_bf16 v[18:21], v[134:137], v[174:177], v[18:21]
	v_mfma_f32_16x16x32_bf16 v[10:13], v[142:145], v[174:177], v[10:13]
	v_mfma_f32_16x16x32_bf16 v[50:53], v[134:137], v[208:211], v[50:53]
	v_mfma_f32_16x16x32_bf16 v[54:57], v[142:145], v[208:211], v[54:57]
	v_mfma_f32_16x16x32_bf16 v[74:77], v[134:137], v[216:219], v[74:77]
	v_mfma_f32_16x16x32_bf16 v[78:81], v[142:145], v[216:219], v[78:81]
	s_setprio 0
	s_setprio 1
	v_mfma_f32_16x16x32_bf16 v[26:29], v[146:149], v[162:165], v[26:29]
	v_mfma_f32_16x16x32_bf16 v[14:17], v[154:157], v[162:165], v[14:17]
	v_mfma_f32_16x16x32_bf16 v[42:45], v[146:149], v[170:173], v[42:45]
	v_mfma_f32_16x16x32_bf16 v[46:49], v[154:157], v[170:173], v[46:49]
	v_mfma_f32_16x16x32_bf16 v[66:69], v[146:149], v[198:201], v[66:69]
	v_mfma_f32_16x16x32_bf16 v[70:73], v[154:157], v[198:201], v[70:73]
	v_mfma_f32_16x16x32_bf16 v[82:85], v[146:149], v[212:215], v[82:85]
	v_mfma_f32_16x16x32_bf16 v[86:89], v[154:157], v[212:215], v[86:89]
	v_mfma_f32_16x16x32_bf16 v[26:29], v[150:153], v[166:169], v[26:29]
	v_mfma_f32_16x16x32_bf16 v[14:17], v[158:161], v[166:169], v[14:17]
	v_mfma_f32_16x16x32_bf16 v[42:45], v[150:153], v[174:177], v[42:45]
	v_mfma_f32_16x16x32_bf16 v[46:49], v[158:161], v[174:177], v[46:49]
	v_mfma_f32_16x16x32_bf16 v[66:69], v[150:153], v[208:211], v[66:69]
	v_mfma_f32_16x16x32_bf16 v[70:73], v[158:161], v[208:211], v[70:73]
	v_mfma_f32_16x16x32_bf16 v[82:85], v[150:153], v[216:219], v[82:85]
	v_mfma_f32_16x16x32_bf16 v[86:89], v[158:161], v[216:219], v[86:89]
	s_setprio 0
	s_barrier
; #define PG8_STAGE(bufoff, gbase, voff) do { _Pragma("unroll") for (int _i = 0; _i < 2; ++_i) \
;         __builtin_amdgcn_global_load_lds((const unsigned*)((const char*)(gbase) + (voff)[_i]), (PG8_LAS unsigned*)(lds + (bufoff) + ldsw + _i * 8192), 16, 0, 0); } while (0)
; #define PG8_LDA(dst, b, h) do { _Pragma("unroll") for (int m = 0; m < 4; ++m) _Pragma("unroll") for (int k = 0; k < 2; ++k) dst[m][k] = *(const PG8_LAS bf16x8*)(lds + PG8_SA(b, h) + aoff + m * 2048 + k * 1024); } while (0)
; #define PG8_MMA(ai, bj, At, Bt) do { __builtin_amdgcn_s_setprio(1); _Pragma("unroll") for (int m = 0; m < 4; ++m) _Pragma("unroll") for (int n = 0; n < 2; ++n) _Pragma("unroll") for (int k = 0; k < 2; ++k) \
;         acc[ai][bj][m][n] = __builtin_amdgcn_mfma_f32_16x16x32_bf16(Bt[n][k], At[m][k], acc[ai][bj][m][n], 0, 0, 0); __builtin_amdgcn_s_setprio(0); } while (0)
; #define PG8_WAIT_V(n) asm volatile("s_waitcnt vmcnt(" #n ")" ::: "memory")
; #define PG8_WAIT_L(n) asm volatile("s_waitcnt lgkmcnt(" #n ")" ::: "memory")
; #define PG8_BAR __builtin_amdgcn_s_barrier()
; #define PG8_SCHED __builtin_amdgcn_sched_barrier(0)
; template <class Epi, class Sched, bool ALIGN_EPI = false, bool SP2 = false, bool ABLK = false, bool BBLK = false>
; __device__ __forceinline__ void gemm_phase(PG8_LAS unsigned char* lds, const Gemm g, const Sched& S, const Epi& E) {
;     ...
;             PG8_LDA(At, 1, 1); PG8_STAGE(PG8_SB(1, 0), b3, voffB); PG8_STAGE(PG8_SB(1, 1), b3 + hstepB, voffB); PG8_STAGE(PG8_SA(1, 0), a3, voffA);
;             PG8_WAIT_V(8); PG8_WAIT_L(0); PG8_BAR; PG8_MMA(1, 0, At, B0); PG8_MMA(1, 1, At, B1); PG8_BAR; PG8_SCHED;
;     ...
;         if constexpr (ALIGN_EPI) { if (wr == 0) PG8_BAR; }
	s_add_u32 s40, s36, 0x8000
	s_addc_u32 s41, s37, 0
	s_add_i32 s44, s44, s65
	v_lshl_add_u64 v[188:189], s[40:41], 0, v[186:187]
	s_mov_b32 m0, s44
	ds_read_b128 v[162:165], v207 offset:49152
	ds_read_b128 v[166:169], v207 offset:50176
	ds_read_b128 v[170:173], v207 offset:51200
	ds_read_b128 v[174:177], v207 offset:52224
	ds_read_b128 v[198:201], v207 offset:53248
	ds_read_b128 v[208:211], v207 offset:54272
	ds_read_b128 v[212:215], v207 offset:55296
	ds_read_b128 v[216:219], v207 offset:56320
	global_load_lds_dwordx4 v[188:189], off
	s_add_i32 m0, s44, 0x2000
	s_add_u32 s36, s36, 0xc000
	v_lshl_add_u64 v[188:189], s[40:41], 0, v[182:183]
	s_addc_u32 s37, s37, 0
	s_add_i32 s40, s45, s65
	global_load_lds_dwordx4 v[188:189], off
	v_lshl_add_u64 v[188:189], s[36:37], 0, v[186:187]
	s_mov_b32 m0, s40
	s_nop 0
	global_load_lds_dwordx4 v[188:189], off
	v_lshl_add_u64 v[188:189], s[36:37], 0, v[182:183]
	s_add_i32 m0, s40, 0x2000
	s_nop 0
	global_load_lds_dwordx4 v[188:189], off
	v_lshl_add_u64 v[188:189], s[8:9], 0, v[178:179]
	s_mov_b32 m0, s24
	s_nop 0
	global_load_lds_dwordx4 v[188:189], off
	v_lshl_add_u64 v[188:189], s[8:9], 0, v[180:181]
	s_mov_b32 m0, s25
	s_nop 0
	global_load_lds_dwordx4 v[188:189], off
	s_waitcnt vmcnt(8)
	s_waitcnt lgkmcnt(0)
	v_mfma_f32_16x16x32_bf16 v[106:109], v[130:133], v[162:165], v[106:109]
	v_mfma_f32_16x16x32_bf16 v[110:113], v[138:141], v[162:165], v[110:113]
	s_barrier
	s_setprio 1
	s_waitcnt lgkmcnt(0)
	v_mfma_f32_16x16x32_bf16 v[122:125], v[130:133], v[170:173], v[122:125]
	v_mfma_f32_16x16x32_bf16 v[126:129], v[138:141], v[170:173], v[126:129]
	v_mfma_f32_16x16x32_bf16 v[94:97], v[130:133], v[198:201], v[94:97]
	v_mfma_f32_16x16x32_bf16 v[90:93], v[138:141], v[198:201], v[90:93]
	v_mfma_f32_16x16x32_bf16 v[38:41], v[130:133], v[212:215], v[38:41]
	v_mfma_f32_16x16x32_bf16 v[34:37], v[138:141], v[212:215], v[34:37]
	v_mfma_f32_16x16x32_bf16 v[106:109], v[134:137], v[166:169], v[106:109]
	v_mfma_f32_16x16x32_bf16 v[110:113], v[142:145], v[166:169], v[110:113]
	v_mfma_f32_16x16x32_bf16 v[122:125], v[134:137], v[174:177], v[122:125]
	v_mfma_f32_16x16x32_bf16 v[126:129], v[142:145], v[174:177], v[126:129]
	v_mfma_f32_16x16x32_bf16 v[94:97], v[134:137], v[208:211], v[94:97]
	v_mfma_f32_16x16x32_bf16 v[90:93], v[142:145], v[208:211], v[90:93]
	v_mfma_f32_16x16x32_bf16 v[38:41], v[134:137], v[216:219], v[38:41]
	v_mfma_f32_16x16x32_bf16 v[34:37], v[142:145], v[216:219], v[34:37]
	s_setprio 0
	s_setprio 1
	v_mfma_f32_16x16x32_bf16 v[114:117], v[146:149], v[162:165], v[114:117]
	v_mfma_f32_16x16x32_bf16 v[118:121], v[154:157], v[162:165], v[118:121]
	v_mfma_f32_16x16x32_bf16 v[102:105], v[146:149], v[170:173], v[102:105]
	v_mfma_f32_16x16x32_bf16 v[98:101], v[154:157], v[170:173], v[98:101]
	v_mfma_f32_16x16x32_bf16 v[62:65], v[146:149], v[198:201], v[62:65]
	v_mfma_f32_16x16x32_bf16 v[58:61], v[154:157], v[198:201], v[58:61]
	v_mfma_f32_16x16x32_bf16 v[6:9], v[146:149], v[212:215], v[6:9]
	v_mfma_f32_16x16x32_bf16 v[2:5], v[154:157], v[212:215], v[2:5]
	v_mfma_f32_16x16x32_bf16 v[114:117], v[150:153], v[166:169], v[114:117]
	v_mfma_f32_16x16x32_bf16 v[118:121], v[158:161], v[166:169], v[118:121]
	v_mfma_f32_16x16x32_bf16 v[102:105], v[150:153], v[174:177], v[102:105]
	v_mfma_f32_16x16x32_bf16 v[98:101], v[158:161], v[174:177], v[98:101]
	v_mfma_f32_16x16x32_bf16 v[62:65], v[150:153], v[208:211], v[62:65]
	v_mfma_f32_16x16x32_bf16 v[58:61], v[158:161], v[208:211], v[58:61]
	v_mfma_f32_16x16x32_bf16 v[6:9], v[150:153], v[216:219], v[6:9]
	v_mfma_f32_16x16x32_bf16 v[2:5], v[158:161], v[216:219], v[2:5]
	s_setprio 0
	s_barrier
	s_add_i32 s35, s35, 2
	s_add_u32 s0, s0, 0x10000
	s_addc_u32 s1, s1, 0
	s_add_u32 s31, s31, 0x10000
	s_addc_u32 s33, s33, 0
	s_cmpk_gt_u32 s35, 0x55
	s_cbranch_scc0 .LBB0_1483
	s_and_b64 vcc, exec, s[20:21]
	s_cbranch_vccz .LBB0_1486
	s_barrier
